# 52 genuinely redundant lgkmcnt(0) after the K-loop barriers removed; 31 canonicalising v_max folded into the following max in the stick-breaking softplus
# speedup vs baseline: 1.0104x; 1.0104x over previous
; #define PG8_STAGE(bufoff, gbase, voff) do { _Pragma("unroll") for (int _i = 0; _i < 2; ++_i) \
;         __builtin_amdgcn_global_load_lds((const unsigned*)((const char*)(gbase) + (voff)[_i]), (PG8_LAS unsigned*)(lds + (bufoff) + ldsw + _i * 8192), 16, 0, 0); } while (0)
; #define PG8_LDA(dst, b, h) do { _Pragma("unroll") for (int m = 0; m < 4; ++m) _Pragma("unroll") for (int k = 0; k < 2; ++k) dst[m][k] = *(const PG8_LAS bf16x8*)(lds + PG8_SA(b, h) + aoff + m * 2048 + k * 1024); } while (0)
; #define PG8_LDB(dst, b, h) do { _Pragma("unroll") for (int n = 0; n < 2; ++n) _Pragma("unroll") for (int k = 0; k < 2; ++k) dst[n][k] = *(const PG8_LAS bf16x8*)(lds + PG8_SB(b, h) + boff + n * 2048 + k * 1024); } while (0)
; #define PG8_MMA(ai, bj, At, Bt) do { __builtin_amdgcn_s_setprio(1); _Pragma("unroll") for (int m = 0; m < 4; ++m) _Pragma("unroll") for (int n = 0; n < 2; ++n) _Pragma("unroll") for (int k = 0; k < 2; ++k) \
;         acc[ai][bj][m][n] = __builtin_amdgcn_mfma_f32_16x16x32_bf16(Bt[n][k], At[m][k], acc[ai][bj][m][n], 0, 0, 0); __builtin_amdgcn_s_setprio(0); } while (0)
; #define PG8_BAR __builtin_amdgcn_s_barrier()
; template <class Epi, class Sched, bool ALIGN_EPI = false, bool SP2 = false>
; __device__ __forceinline__ void gemm_phase(PG8_LAS unsigned char* lds, const Gemm g, const Sched& S, const Epi& E) {
;     ...
;         for (int t = 0; t < nt; t += 2) {
;             if constexpr (Epi::MID) { if (t == (nt >> 1)) E.mid(acc, wr, fr, lds); }
;             const bool last = (t == nt - 2);
;             const char* a1 = cA + (size_t)(t + 1) * kstep;
;             const char* a2 = last ? nA : cA + (size_t)(t + 2) * kstep; const char* b2 = last ? nB : cB + (size_t)(t + 2) * kstep;
;             const char* a3 = a2 + kstep; const char* b3 = b2 + kstep;
;             if (last && has_next) S.a_ready(nxt);
;             if constexpr (SP2) {
;             PG8_LDB(B0, 0, 0); PG8_LDB(B1, 0, 1); PG8_SCHED; PG8_LDA(At, 0, 0); PG8_STAGE(PG8_SA(1, 1), a1 + hstep, voffA);
;             PG8_WAIT_V(8); PG8_WAIT_L(0); PG8_BAR; PG8_MMA(0, 0, At, B0); PG8_MMA(0, 1, At, B1); PG8_BAR; PG8_SCHED;
;             PG8_LDA(At, 0, 1); PG8_STAGE(PG8_SB(0, 0), b2, voffB); PG8_STAGE(PG8_SB(0, 1), b2 + hstep, voffB); PG8_STAGE(PG8_SA(0, 0), a2, voffA);
;             PG8_WAIT_V(8); PG8_WAIT_L(0); PG8_BAR; PG8_MMA(1, 0, At, B0); PG8_MMA(1, 1, At, B1); PG8_BAR; PG8_SCHED;
.LBB0_499:
	s_add_i32 s22, s17, 2
	s_add_u32 s28, s2, 0x80
	s_addc_u32 s30, s3, 0
	s_add_i32 s33, 0, 0x10000
	s_cmp_eq_u32 s72, s17
	s_cselect_b32 s35, s53, s30
	s_cselect_b32 s34, s52, s28
	v_add_u32_e32 v146, s33, v148
	s_cselect_b32 s31, s55, s16
	s_cselect_b32 s30, s54, s4
	s_add_i32 s17, 0, 0x14000
	ds_read_b128 v[142:145], v146
	ds_read_b128 v[154:157], v146 offset:1024
	ds_read_b128 v[158:161], v146 offset:2048
	ds_read_b128 v[162:165], v146 offset:3072
	v_add_u32_e32 v146, s17, v148
	ds_read_b128 v[166:169], v146
	ds_read_b128 v[170:173], v146 offset:1024
	ds_read_b128 v[174:177], v146 offset:2048
	ds_read_b128 v[178:181], v146 offset:3072
	v_lshl_add_u64 v[146:147], s[2:3], 0, v[138:139]
	s_add_i32 m0, s65, 0xc000
	ds_read_b128 v[182:185], v153
	ds_read_b128 v[186:189], v153 offset:1024
	ds_read_b128 v[190:193], v153 offset:2048
	ds_read_b128 v[208:211], v153 offset:3072
	ds_read_b128 v[212:215], v153 offset:4096
	ds_read_b128 v[216:219], v153 offset:5120
	ds_read_b128 v[220:223], v153 offset:6144
	ds_read_b128 v[228:231], v153 offset:7168
	global_load_lds_dwordx4 v[146:147], off
	v_lshl_add_u64 v[146:147], s[2:3], 0, v[140:141]
	s_add_i32 m0, s65, 0xe000
	s_nop 0
	global_load_lds_dwordx4 v[146:147], off
	s_waitcnt vmcnt(8)
	s_waitcnt lgkmcnt(0)
	s_barrier
	s_setprio 1
	v_mfma_f32_16x16x32_bf16 v[124:127], v[142:145], v[182:185], v[124:127]
	v_mfma_f32_16x16x32_bf16 v[120:123], v[158:161], v[182:185], v[120:123]
	v_mfma_f32_16x16x32_bf16 v[112:115], v[142:145], v[190:193], v[112:115]
	v_mfma_f32_16x16x32_bf16 v[104:107], v[158:161], v[190:193], v[104:107]
	v_mfma_f32_16x16x32_bf16 v[94:97], v[142:145], v[212:215], v[94:97]
	v_mfma_f32_16x16x32_bf16 v[86:89], v[158:161], v[212:215], v[86:89]
	v_mfma_f32_16x16x32_bf16 v[78:81], v[142:145], v[220:223], v[78:81]
	v_mfma_f32_16x16x32_bf16 v[70:73], v[158:161], v[220:223], v[70:73]
	v_mfma_f32_16x16x32_bf16 v[124:127], v[154:157], v[186:189], v[124:127]
	v_mfma_f32_16x16x32_bf16 v[120:123], v[162:165], v[186:189], v[120:123]
	v_mfma_f32_16x16x32_bf16 v[112:115], v[154:157], v[208:211], v[112:115]
	v_mfma_f32_16x16x32_bf16 v[104:107], v[162:165], v[208:211], v[104:107]
	v_mfma_f32_16x16x32_bf16 v[94:97], v[154:157], v[216:219], v[94:97]
	v_mfma_f32_16x16x32_bf16 v[86:89], v[162:165], v[216:219], v[86:89]
	v_mfma_f32_16x16x32_bf16 v[78:81], v[154:157], v[228:231], v[78:81]
	v_mfma_f32_16x16x32_bf16 v[70:73], v[162:165], v[228:231], v[70:73]
	s_setprio 0
	s_setprio 1
	v_mfma_f32_16x16x32_bf16 v[128:131], v[166:169], v[182:185], v[128:131]
	v_mfma_f32_16x16x32_bf16 v[116:119], v[174:177], v[182:185], v[116:119]
	v_mfma_f32_16x16x32_bf16 v[108:111], v[166:169], v[190:193], v[108:111]
	v_mfma_f32_16x16x32_bf16 v[100:103], v[174:177], v[190:193], v[100:103]
	v_mfma_f32_16x16x32_bf16 v[90:93], v[166:169], v[212:215], v[90:93]
	v_mfma_f32_16x16x32_bf16 v[82:85], v[174:177], v[212:215], v[82:85]
	v_mfma_f32_16x16x32_bf16 v[74:77], v[166:169], v[220:223], v[74:77]
	v_mfma_f32_16x16x32_bf16 v[66:69], v[174:177], v[220:223], v[66:69]
	v_mfma_f32_16x16x32_bf16 v[128:131], v[170:173], v[186:189], v[128:131]
	v_mfma_f32_16x16x32_bf16 v[116:119], v[178:181], v[186:189], v[116:119]
	v_mfma_f32_16x16x32_bf16 v[108:111], v[170:173], v[208:211], v[108:111]
	v_mfma_f32_16x16x32_bf16 v[100:103], v[178:181], v[208:211], v[100:103]
	v_mfma_f32_16x16x32_bf16 v[90:93], v[170:173], v[216:219], v[90:93]
	v_mfma_f32_16x16x32_bf16 v[82:85], v[178:181], v[216:219], v[82:85]
	v_mfma_f32_16x16x32_bf16 v[74:77], v[170:173], v[228:231], v[74:77]
	v_mfma_f32_16x16x32_bf16 v[66:69], v[178:181], v[228:231], v[66:69]
	s_setprio 0
	s_barrier
	s_add_i32 s28, s33, s58
	v_lshl_add_u64 v[146:147], s[30:31], 0, v[98:99]
	s_mov_b32 m0, s28
	ds_read_b128 v[182:185], v153 offset:16384
	ds_read_b128 v[186:189], v153 offset:17408
	ds_read_b128 v[190:193], v153 offset:18432
	ds_read_b128 v[208:211], v153 offset:19456
	ds_read_b128 v[212:215], v153 offset:20480
	ds_read_b128 v[216:219], v153 offset:21504
	ds_read_b128 v[220:223], v153 offset:22528
	ds_read_b128 v[228:231], v153 offset:23552
	global_load_lds_dwordx4 v[146:147], off
	s_add_i32 m0, s28, 0x2000
	v_lshl_add_u64 v[224:225], s[30:31], 0, v[132:133]
	s_add_u32 s30, s30, s8
	s_addc_u32 s31, s31, s9
	s_add_i32 s17, s17, s58
	global_load_lds_dwordx4 v[224:225], off
	v_lshl_add_u64 v[232:233], s[30:31], 0, v[98:99]
	s_mov_b32 m0, s17
	v_lshl_add_u64 v[234:235], s[30:31], 0, v[132:133]
	global_load_lds_dwordx4 v[232:233], off
	s_add_i32 m0, s17, 0x2000
	v_lshl_add_u64 v[236:237], s[34:35], 0, v[136:137]
	global_load_lds_dwordx4 v[234:235], off
	s_mov_b32 m0, s65
	v_lshl_add_u64 v[238:239], s[34:35], 0, v[134:135]
	global_load_lds_dwordx4 v[236:237], off
	s_mov_b32 m0, s66
	s_nop 0
	global_load_lds_dwordx4 v[238:239], off
	s_waitcnt vmcnt(8)
	s_waitcnt lgkmcnt(0)
	s_barrier
; #define PG8_STAGE(bufoff, gbase, voff) do { _Pragma("unroll") for (int _i = 0; _i < 2; ++_i) \
;         __builtin_amdgcn_global_load_lds((const unsigned*)((const char*)(gbase) + (voff)[_i]), (PG8_LAS unsigned*)(lds + (bufoff) + ldsw + _i * 8192), 16, 0, 0); } while (0)
; #define PG8_LDA(dst, b, h) do { _Pragma("unroll") for (int m = 0; m < 4; ++m) _Pragma("unroll") for (int k = 0; k < 2; ++k) dst[m][k] = *(const PG8_LAS bf16x8*)(lds + PG8_SA(b, h) + aoff + m * 2048 + k * 1024); } while (0)
; #define PG8_LDB(dst, b, h) do { _Pragma("unroll") for (int n = 0; n < 2; ++n) _Pragma("unroll") for (int k = 0; k < 2; ++k) dst[n][k] = *(const PG8_LAS bf16x8*)(lds + PG8_SB(b, h) + boff + n * 2048 + k * 1024); } while (0)
; #define PG8_MMA(ai, bj, At, Bt) do { __builtin_amdgcn_s_setprio(1); _Pragma("unroll") for (int m = 0; m < 4; ++m) _Pragma("unroll") for (int n = 0; n < 2; ++n) _Pragma("unroll") for (int k = 0; k < 2; ++k) \
;         acc[ai][bj][m][n] = __builtin_amdgcn_mfma_f32_16x16x32_bf16(Bt[n][k], At[m][k], acc[ai][bj][m][n], 0, 0, 0); __builtin_amdgcn_s_setprio(0); } while (0)
; #define PG8_WAIT_V(n) asm volatile("s_waitcnt vmcnt(" #n ")" ::: "memory")
; #define PG8_WAIT_L(n) asm volatile("s_waitcnt lgkmcnt(" #n ")" ::: "memory")
; #define PG8_BAR __builtin_amdgcn_s_barrier()
; #define PG8_SCHED __builtin_amdgcn_sched_barrier(0)
; template <class Epi, class Sched, bool ALIGN_EPI = false, bool SP2 = false>
; __device__ __forceinline__ void gemm_phase(PG8_LAS unsigned char* lds, const Gemm g, const Sched& S, const Epi& E) {
;     ...
;             PG8_WAIT_V(8); PG8_WAIT_L(0); PG8_BAR; PG8_MMA(1, 0, At, B0); PG8_MMA(1, 1, At, B1); PG8_BAR; PG8_SCHED;
;             PG8_LDB(B0, 1, 0); PG8_LDB(B1, 1, 1); PG8_SCHED; PG8_LDA(At, 1, 0); PG8_STAGE(PG8_SA(0, 1), a2 + hstep, voffA);
;             PG8_WAIT_V(8); PG8_WAIT_L(0); PG8_BAR; PG8_MMA(0, 0, At, B0); PG8_MMA(0, 1, At, B1); PG8_BAR; PG8_SCHED;
	s_setprio 1
	v_mfma_f32_16x16x32_bf16 v[62:65], v[142:145], v[182:185], v[62:65]
	v_mfma_f32_16x16x32_bf16 v[54:57], v[158:161], v[182:185], v[54:57]
	v_mfma_f32_16x16x32_bf16 v[46:49], v[142:145], v[190:193], v[46:49]
	v_mfma_f32_16x16x32_bf16 v[38:41], v[158:161], v[190:193], v[38:41]
	v_mfma_f32_16x16x32_bf16 v[30:33], v[142:145], v[212:215], v[30:33]
	v_mfma_f32_16x16x32_bf16 v[22:25], v[158:161], v[212:215], v[22:25]
	v_mfma_f32_16x16x32_bf16 v[14:17], v[142:145], v[220:223], v[14:17]
	v_mfma_f32_16x16x32_bf16 v[6:9], v[158:161], v[220:223], v[6:9]
	v_mfma_f32_16x16x32_bf16 v[62:65], v[154:157], v[186:189], v[62:65]
	v_mfma_f32_16x16x32_bf16 v[54:57], v[162:165], v[186:189], v[54:57]
	v_mfma_f32_16x16x32_bf16 v[46:49], v[154:157], v[208:211], v[46:49]
	v_mfma_f32_16x16x32_bf16 v[38:41], v[162:165], v[208:211], v[38:41]
	v_mfma_f32_16x16x32_bf16 v[30:33], v[154:157], v[216:219], v[30:33]
	v_mfma_f32_16x16x32_bf16 v[22:25], v[162:165], v[216:219], v[22:25]
	v_mfma_f32_16x16x32_bf16 v[14:17], v[154:157], v[228:231], v[14:17]
	v_mfma_f32_16x16x32_bf16 v[6:9], v[162:165], v[228:231], v[6:9]
	s_setprio 0
	s_setprio 1
	v_mfma_f32_16x16x32_bf16 v[58:61], v[166:169], v[182:185], v[58:61]
	v_mfma_f32_16x16x32_bf16 v[50:53], v[174:177], v[182:185], v[50:53]
	v_mfma_f32_16x16x32_bf16 v[42:45], v[166:169], v[190:193], v[42:45]
	v_mfma_f32_16x16x32_bf16 v[34:37], v[174:177], v[190:193], v[34:37]
	v_mfma_f32_16x16x32_bf16 v[26:29], v[166:169], v[212:215], v[26:29]
	v_mfma_f32_16x16x32_bf16 v[18:21], v[174:177], v[212:215], v[18:21]
	v_mfma_f32_16x16x32_bf16 v[10:13], v[166:169], v[220:223], v[10:13]
	v_mfma_f32_16x16x32_bf16 v[2:5], v[174:177], v[220:223], v[2:5]
	v_mfma_f32_16x16x32_bf16 v[58:61], v[170:173], v[186:189], v[58:61]
	v_mfma_f32_16x16x32_bf16 v[50:53], v[178:181], v[186:189], v[50:53]
	v_mfma_f32_16x16x32_bf16 v[42:45], v[170:173], v[208:211], v[42:45]
	v_mfma_f32_16x16x32_bf16 v[34:37], v[178:181], v[208:211], v[34:37]
	v_mfma_f32_16x16x32_bf16 v[26:29], v[170:173], v[216:219], v[26:29]
	v_mfma_f32_16x16x32_bf16 v[18:21], v[178:181], v[216:219], v[18:21]
	v_mfma_f32_16x16x32_bf16 v[10:13], v[170:173], v[228:231], v[10:13]
	v_mfma_f32_16x16x32_bf16 v[2:5], v[178:181], v[228:231], v[2:5]
	s_setprio 0
	s_barrier
	s_add_i32 s17, 0, 0x18000
	s_add_i32 s28, 0, 0x1c000
	v_add_u32_e32 v162, s17, v148
	v_add_u32_e32 v178, s28, v148
	ds_read_b128 v[142:145], v162
	ds_read_b128 v[154:157], v162 offset:1024
	ds_read_b128 v[158:161], v162 offset:2048
	ds_read_b128 v[162:165], v162 offset:3072
	ds_read_b128 v[166:169], v178
	ds_read_b128 v[170:173], v178 offset:1024
	ds_read_b128 v[174:177], v178 offset:2048
	ds_read_b128 v[178:181], v178 offset:3072
	s_add_u32 s30, s34, s8
	s_addc_u32 s31, s35, s9
	s_mov_b32 m0, s67
	v_lshl_add_u64 v[240:241], s[30:31], 0, v[136:137]
	ds_read_b128 v[182:185], v153 offset:32768
	ds_read_b128 v[186:189], v153 offset:33792
	ds_read_b128 v[190:193], v153 offset:34816
	ds_read_b128 v[208:211], v153 offset:35840
	ds_read_b128 v[212:215], v153 offset:36864
	ds_read_b128 v[216:219], v153 offset:37888
	ds_read_b128 v[220:223], v153 offset:38912
	ds_read_b128 v[228:231], v153 offset:39936
	global_load_lds_dwordx4 v[240:241], off
	v_lshl_add_u64 v[240:241], s[30:31], 0, v[134:135]
	s_mov_b32 m0, s68
	s_nop 0
	global_load_lds_dwordx4 v[240:241], off
	s_waitcnt vmcnt(8)
	s_waitcnt lgkmcnt(0)
	s_barrier
	s_setprio 1
	v_mfma_f32_16x16x32_bf16 v[124:127], v[142:145], v[182:185], v[124:127]
	v_mfma_f32_16x16x32_bf16 v[120:123], v[158:161], v[182:185], v[120:123]
	v_mfma_f32_16x16x32_bf16 v[112:115], v[142:145], v[190:193], v[112:115]
	v_mfma_f32_16x16x32_bf16 v[104:107], v[158:161], v[190:193], v[104:107]
	v_mfma_f32_16x16x32_bf16 v[94:97], v[142:145], v[212:215], v[94:97]
	v_mfma_f32_16x16x32_bf16 v[86:89], v[158:161], v[212:215], v[86:89]
	v_mfma_f32_16x16x32_bf16 v[78:81], v[142:145], v[220:223], v[78:81]
	v_mfma_f32_16x16x32_bf16 v[70:73], v[158:161], v[220:223], v[70:73]
	v_mfma_f32_16x16x32_bf16 v[124:127], v[154:157], v[186:189], v[124:127]
	v_mfma_f32_16x16x32_bf16 v[120:123], v[162:165], v[186:189], v[120:123]
	v_mfma_f32_16x16x32_bf16 v[112:115], v[154:157], v[208:211], v[112:115]
	v_mfma_f32_16x16x32_bf16 v[104:107], v[162:165], v[208:211], v[104:107]
	v_mfma_f32_16x16x32_bf16 v[94:97], v[154:157], v[216:219], v[94:97]
	v_mfma_f32_16x16x32_bf16 v[86:89], v[162:165], v[216:219], v[86:89]
	v_mfma_f32_16x16x32_bf16 v[78:81], v[154:157], v[228:231], v[78:81]
	v_mfma_f32_16x16x32_bf16 v[70:73], v[162:165], v[228:231], v[70:73]
	s_setprio 0
	s_setprio 1
	v_mfma_f32_16x16x32_bf16 v[128:131], v[166:169], v[182:185], v[128:131]
	v_mfma_f32_16x16x32_bf16 v[116:119], v[174:177], v[182:185], v[116:119]
	v_mfma_f32_16x16x32_bf16 v[108:111], v[166:169], v[190:193], v[108:111]
	v_mfma_f32_16x16x32_bf16 v[100:103], v[174:177], v[190:193], v[100:103]
	v_mfma_f32_16x16x32_bf16 v[90:93], v[166:169], v[212:215], v[90:93]
	v_mfma_f32_16x16x32_bf16 v[82:85], v[174:177], v[212:215], v[82:85]
	v_mfma_f32_16x16x32_bf16 v[74:77], v[166:169], v[220:223], v[74:77]
	v_mfma_f32_16x16x32_bf16 v[66:69], v[174:177], v[220:223], v[66:69]
	v_mfma_f32_16x16x32_bf16 v[128:131], v[170:173], v[186:189], v[128:131]
	v_mfma_f32_16x16x32_bf16 v[116:119], v[178:181], v[186:189], v[116:119]
	v_mfma_f32_16x16x32_bf16 v[108:111], v[170:173], v[208:211], v[108:111]
	v_mfma_f32_16x16x32_bf16 v[100:103], v[178:181], v[208:211], v[100:103]
	v_mfma_f32_16x16x32_bf16 v[90:93], v[170:173], v[216:219], v[90:93]
	v_mfma_f32_16x16x32_bf16 v[82:85], v[178:181], v[216:219], v[82:85]
	v_mfma_f32_16x16x32_bf16 v[74:77], v[170:173], v[228:231], v[74:77]
	v_mfma_f32_16x16x32_bf16 v[66:69], v[178:181], v[228:231], v[66:69]
	s_setprio 0
	s_barrier
; #define PG8_STAGE(bufoff, gbase, voff) do { _Pragma("unroll") for (int _i = 0; _i < 2; ++_i) \
;         __builtin_amdgcn_global_load_lds((const unsigned*)((const char*)(gbase) + (voff)[_i]), (PG8_LAS unsigned*)(lds + (bufoff) + ldsw + _i * 8192), 16, 0, 0); } while (0)
; #define PG8_LDA(dst, b, h) do { _Pragma("unroll") for (int m = 0; m < 4; ++m) _Pragma("unroll") for (int k = 0; k < 2; ++k) dst[m][k] = *(const PG8_LAS bf16x8*)(lds + PG8_SA(b, h) + aoff + m * 2048 + k * 1024); } while (0)
; #define PG8_MMA(ai, bj, At, Bt) do { __builtin_amdgcn_s_setprio(1); _Pragma("unroll") for (int m = 0; m < 4; ++m) _Pragma("unroll") for (int n = 0; n < 2; ++n) _Pragma("unroll") for (int k = 0; k < 2; ++k) \
;         acc[ai][bj][m][n] = __builtin_amdgcn_mfma_f32_16x16x32_bf16(Bt[n][k], At[m][k], acc[ai][bj][m][n], 0, 0, 0); __builtin_amdgcn_s_setprio(0); } while (0)
; #define PG8_WAIT_V(n) asm volatile("s_waitcnt vmcnt(" #n ")" ::: "memory")
; #define PG8_WAIT_L(n) asm volatile("s_waitcnt lgkmcnt(" #n ")" ::: "memory")
; #define PG8_BAR __builtin_amdgcn_s_barrier()
; #define PG8_SCHED __builtin_amdgcn_sched_barrier(0)
; template <class Epi, class Sched, bool ALIGN_EPI = false, bool SP2 = false>
; __device__ __forceinline__ void gemm_phase(PG8_LAS unsigned char* lds, const Gemm g, const Sched& S, const Epi& E) {
;     ...
;             PG8_LDA(At, 1, 1); PG8_STAGE(PG8_SB(1, 0), b3, voffB); PG8_STAGE(PG8_SB(1, 1), b3 + hstep, voffB); PG8_STAGE(PG8_SA(1, 0), a3, voffA);
;             PG8_WAIT_V(8); PG8_WAIT_L(0); PG8_BAR; PG8_MMA(1, 0, At, B0); PG8_MMA(1, 1, At, B1); PG8_BAR; PG8_SCHED;
	s_add_i32 s17, s17, s58
	v_lshl_add_u64 v[146:147], v[146:147], 0, s[24:25]
	s_mov_b32 m0, s17
	ds_read_b128 v[182:185], v153 offset:49152
	ds_read_b128 v[186:189], v153 offset:50176
	ds_read_b128 v[190:193], v153 offset:51200
	ds_read_b128 v[208:211], v153 offset:52224
	ds_read_b128 v[212:215], v153 offset:53248
	ds_read_b128 v[216:219], v153 offset:54272
	ds_read_b128 v[220:223], v153 offset:55296
	ds_read_b128 v[228:231], v153 offset:56320
	global_load_lds_dwordx4 v[146:147], off
	v_lshl_add_u64 v[146:147], v[224:225], 0, s[24:25]
	s_add_i32 m0, s17, 0x2000
	s_add_i32 s17, s28, s58
	global_load_lds_dwordx4 v[146:147], off
	v_lshl_add_u64 v[146:147], v[232:233], 0, s[24:25]
	s_mov_b32 m0, s17
	s_nop 0
	global_load_lds_dwordx4 v[146:147], off
	v_lshl_add_u64 v[146:147], v[234:235], 0, s[24:25]
	s_add_i32 m0, s17, 0x2000
	s_nop 0
	global_load_lds_dwordx4 v[146:147], off
	v_lshl_add_u64 v[146:147], v[236:237], 0, s[24:25]
	s_mov_b32 m0, s69
	s_nop 0
	global_load_lds_dwordx4 v[146:147], off
	v_lshl_add_u64 v[146:147], v[238:239], 0, s[24:25]
	s_mov_b32 m0, s70
	s_nop 0
	global_load_lds_dwordx4 v[146:147], off
	s_waitcnt vmcnt(8)
	s_waitcnt lgkmcnt(0)
	s_barrier
	s_setprio 1
	v_mfma_f32_16x16x32_bf16 v[62:65], v[142:145], v[182:185], v[62:65]
	v_mfma_f32_16x16x32_bf16 v[54:57], v[158:161], v[182:185], v[54:57]
	v_mfma_f32_16x16x32_bf16 v[46:49], v[142:145], v[190:193], v[46:49]
	v_mfma_f32_16x16x32_bf16 v[38:41], v[158:161], v[190:193], v[38:41]
	v_mfma_f32_16x16x32_bf16 v[30:33], v[142:145], v[212:215], v[30:33]
	v_mfma_f32_16x16x32_bf16 v[22:25], v[158:161], v[212:215], v[22:25]
	v_mfma_f32_16x16x32_bf16 v[14:17], v[142:145], v[220:223], v[14:17]
	v_mfma_f32_16x16x32_bf16 v[6:9], v[158:161], v[220:223], v[6:9]
	v_mfma_f32_16x16x32_bf16 v[62:65], v[154:157], v[186:189], v[62:65]
	v_mfma_f32_16x16x32_bf16 v[54:57], v[162:165], v[186:189], v[54:57]
	v_mfma_f32_16x16x32_bf16 v[46:49], v[154:157], v[208:211], v[46:49]
	v_mfma_f32_16x16x32_bf16 v[38:41], v[162:165], v[208:211], v[38:41]
	v_mfma_f32_16x16x32_bf16 v[30:33], v[154:157], v[216:219], v[30:33]
	v_mfma_f32_16x16x32_bf16 v[22:25], v[162:165], v[216:219], v[22:25]
	v_mfma_f32_16x16x32_bf16 v[14:17], v[154:157], v[228:231], v[14:17]
	v_mfma_f32_16x16x32_bf16 v[6:9], v[162:165], v[228:231], v[6:9]
	s_setprio 0
	s_setprio 1
	v_mfma_f32_16x16x32_bf16 v[58:61], v[166:169], v[182:185], v[58:61]
	v_mfma_f32_16x16x32_bf16 v[50:53], v[174:177], v[182:185], v[50:53]
	v_mfma_f32_16x16x32_bf16 v[42:45], v[166:169], v[190:193], v[42:45]
	v_mfma_f32_16x16x32_bf16 v[34:37], v[174:177], v[190:193], v[34:37]
	v_mfma_f32_16x16x32_bf16 v[26:29], v[166:169], v[212:215], v[26:29]
	v_mfma_f32_16x16x32_bf16 v[18:21], v[174:177], v[212:215], v[18:21]
	v_mfma_f32_16x16x32_bf16 v[10:13], v[166:169], v[220:223], v[10:13]
	v_mfma_f32_16x16x32_bf16 v[2:5], v[174:177], v[220:223], v[2:5]
	v_mfma_f32_16x16x32_bf16 v[58:61], v[170:173], v[186:189], v[58:61]
	v_mfma_f32_16x16x32_bf16 v[50:53], v[178:181], v[186:189], v[50:53]
	v_mfma_f32_16x16x32_bf16 v[42:45], v[170:173], v[208:211], v[42:45]
	v_mfma_f32_16x16x32_bf16 v[34:37], v[178:181], v[208:211], v[34:37]
	v_mfma_f32_16x16x32_bf16 v[26:29], v[170:173], v[216:219], v[26:29]
	v_mfma_f32_16x16x32_bf16 v[18:21], v[178:181], v[216:219], v[18:21]
	v_mfma_f32_16x16x32_bf16 v[10:13], v[170:173], v[228:231], v[10:13]
	v_mfma_f32_16x16x32_bf16 v[2:5], v[178:181], v[228:231], v[2:5]
	s_setprio 0
	s_barrier
	s_add_u32 s2, s2, 0x100
	s_addc_u32 s3, s3, 0
	s_add_u32 s4, s4, 0x100
	s_addc_u32 s16, s16, 0
	s_cmp_ge_i32 s22, s71
	s_mov_b32 s17, s22
	s_cbranch_scc0 .LBB0_499

; #define PG8_STAGE(bufoff, gbase, voff) do { _Pragma("unroll") for (int _i = 0; _i < 2; ++_i) \
;         __builtin_amdgcn_global_load_lds((const unsigned*)((const char*)(gbase) + (voff)[_i]), (PG8_LAS unsigned*)(lds + (bufoff) + ldsw + _i * 8192), 16, 0, 0); } while (0)
; #define PG8_LDA(dst, b, h) do { _Pragma("unroll") for (int m = 0; m < 4; ++m) _Pragma("unroll") for (int k = 0; k < 2; ++k) dst[m][k] = *(const PG8_LAS bf16x8*)(lds + PG8_SA(b, h) + aoff + m * 2048 + k * 1024); } while (0)
; #define PG8_LDB(dst, b, h) do { _Pragma("unroll") for (int n = 0; n < 2; ++n) _Pragma("unroll") for (int k = 0; k < 2; ++k) dst[n][k] = *(const PG8_LAS bf16x8*)(lds + PG8_SB(b, h) + boff + n * 2048 + k * 1024); } while (0)
; #define PG8_MMA(ai, bj, At, Bt) do { __builtin_amdgcn_s_setprio(1); _Pragma("unroll") for (int m = 0; m < 4; ++m) _Pragma("unroll") for (int n = 0; n < 2; ++n) _Pragma("unroll") for (int k = 0; k < 2; ++k) \
;         acc[ai][bj][m][n] = __builtin_amdgcn_mfma_f32_16x16x32_bf16(Bt[n][k], At[m][k], acc[ai][bj][m][n], 0, 0, 0); __builtin_amdgcn_s_setprio(0); } while (0)
; #define PG8_WAIT_V(n) asm volatile("s_waitcnt vmcnt(" #n ")" ::: "memory")
; #define PG8_WAIT_L(n) asm volatile("s_waitcnt lgkmcnt(" #n ")" ::: "memory")
; #define PG8_BAR __builtin_amdgcn_s_barrier()
; #define PG8_SCHED __builtin_amdgcn_sched_barrier(0)
; template <class Epi, class Sched, bool ALIGN_EPI = false, bool SP2 = false>
; __device__ __forceinline__ void gemm_phase(PG8_LAS unsigned char* lds, const Gemm g, const Sched& S, const Epi& E) {
;     ...
;             const bool last = (t == nt - 2);
;             const char* a1 = cA + (size_t)(t + 1) * kstep;
;             const char* a2 = last ? nA : cA + (size_t)(t + 2) * kstep; const char* b2 = last ? nB : cB + (size_t)(t + 2) * kstep;
;             const char* a3 = a2 + kstep; const char* b3 = b2 + kstep;
;             if (last && has_next) S.a_ready(nxt);
;             if constexpr (SP2) {
;             PG8_LDB(B0, 0, 0); PG8_LDB(B1, 0, 1); PG8_SCHED; PG8_LDA(At, 0, 0); PG8_STAGE(PG8_SA(1, 1), a1 + hstep, voffA);
;             PG8_WAIT_V(8); PG8_WAIT_L(0); PG8_BAR; PG8_MMA(0, 0, At, B0); PG8_MMA(0, 1, At, B1); PG8_BAR; PG8_SCHED;
;             PG8_LDA(At, 0, 1); PG8_STAGE(PG8_SB(0, 0), b2, voffB); PG8_STAGE(PG8_SB(0, 1), b2 + hstep, voffB); PG8_STAGE(PG8_SA(0, 0), a2, voffA);
.LBB0_521:
	s_add_i32 s22, s17, 2
	s_add_u32 s28, s34, 0x80
	s_addc_u32 s30, s35, 0
	s_add_i32 s33, 0, 0x10000
	s_cmp_eq_u32 s70, s17
	s_cselect_b32 s37, s3, s30
	s_cselect_b32 s36, s2, s28
	v_add_u32_e32 v145, s33, v142
	s_cselect_b32 s31, s51, s16
	s_cselect_b32 s30, s50, s4
	s_add_i32 s17, 0, 0x14000
	ds_read_b128 v[146:149], v145
	ds_read_b128 v[150:153], v145 offset:1024
	ds_read_b128 v[154:157], v145 offset:2048
	ds_read_b128 v[158:161], v145 offset:3072
	v_add_u32_e32 v145, s17, v142
	ds_read_b128 v[162:165], v145
	ds_read_b128 v[166:169], v145 offset:1024
	ds_read_b128 v[170:173], v145 offset:2048
	ds_read_b128 v[174:177], v145 offset:3072
	v_lshl_add_u64 v[224:225], s[34:35], 0, v[138:139]
	s_add_i32 m0, s61, 0xc000
	ds_read_b128 v[178:181], v144
	ds_read_b128 v[182:185], v144 offset:1024
	ds_read_b128 v[186:189], v144 offset:2048
	ds_read_b128 v[190:193], v144 offset:3072
	ds_read_b128 v[208:211], v144 offset:4096
	ds_read_b128 v[212:215], v144 offset:5120
	ds_read_b128 v[216:219], v144 offset:6144
	ds_read_b128 v[220:223], v144 offset:7168
	global_load_lds_dwordx4 v[224:225], off
	v_lshl_add_u64 v[224:225], s[34:35], 0, v[140:141]
	s_add_i32 m0, s61, 0xe000
	s_nop 0
	global_load_lds_dwordx4 v[224:225], off
	s_waitcnt vmcnt(8)
	s_waitcnt lgkmcnt(0)
	s_barrier
	s_setprio 1
	v_mfma_f32_16x16x32_bf16 v[124:127], v[146:149], v[178:181], v[124:127]
	v_mfma_f32_16x16x32_bf16 v[128:131], v[154:157], v[178:181], v[128:131]
	v_mfma_f32_16x16x32_bf16 v[112:115], v[146:149], v[186:189], v[112:115]
	v_mfma_f32_16x16x32_bf16 v[108:111], v[154:157], v[186:189], v[108:111]
	v_mfma_f32_16x16x32_bf16 v[94:97], v[146:149], v[208:211], v[94:97]
	v_mfma_f32_16x16x32_bf16 v[90:93], v[154:157], v[208:211], v[90:93]
	v_mfma_f32_16x16x32_bf16 v[78:81], v[146:149], v[216:219], v[78:81]
	v_mfma_f32_16x16x32_bf16 v[74:77], v[154:157], v[216:219], v[74:77]
	v_mfma_f32_16x16x32_bf16 v[124:127], v[150:153], v[182:185], v[124:127]
	v_mfma_f32_16x16x32_bf16 v[128:131], v[158:161], v[182:185], v[128:131]
	v_mfma_f32_16x16x32_bf16 v[112:115], v[150:153], v[190:193], v[112:115]
	v_mfma_f32_16x16x32_bf16 v[108:111], v[158:161], v[190:193], v[108:111]
	v_mfma_f32_16x16x32_bf16 v[94:97], v[150:153], v[212:215], v[94:97]
	v_mfma_f32_16x16x32_bf16 v[90:93], v[158:161], v[212:215], v[90:93]
	v_mfma_f32_16x16x32_bf16 v[78:81], v[150:153], v[220:223], v[78:81]
	v_mfma_f32_16x16x32_bf16 v[74:77], v[158:161], v[220:223], v[74:77]
	s_setprio 0
	s_setprio 1
	v_mfma_f32_16x16x32_bf16 v[120:123], v[162:165], v[178:181], v[120:123]
	v_mfma_f32_16x16x32_bf16 v[116:119], v[170:173], v[178:181], v[116:119]
	v_mfma_f32_16x16x32_bf16 v[104:107], v[162:165], v[186:189], v[104:107]
	v_mfma_f32_16x16x32_bf16 v[100:103], v[170:173], v[186:189], v[100:103]
	v_mfma_f32_16x16x32_bf16 v[86:89], v[162:165], v[208:211], v[86:89]
	v_mfma_f32_16x16x32_bf16 v[82:85], v[170:173], v[208:211], v[82:85]
	v_mfma_f32_16x16x32_bf16 v[70:73], v[162:165], v[216:219], v[70:73]
	v_mfma_f32_16x16x32_bf16 v[66:69], v[170:173], v[216:219], v[66:69]
	v_mfma_f32_16x16x32_bf16 v[120:123], v[166:169], v[182:185], v[120:123]
	v_mfma_f32_16x16x32_bf16 v[116:119], v[174:177], v[182:185], v[116:119]
	v_mfma_f32_16x16x32_bf16 v[104:107], v[166:169], v[190:193], v[104:107]
	v_mfma_f32_16x16x32_bf16 v[100:103], v[174:177], v[190:193], v[100:103]
	v_mfma_f32_16x16x32_bf16 v[86:89], v[166:169], v[212:215], v[86:89]
	v_mfma_f32_16x16x32_bf16 v[82:85], v[174:177], v[212:215], v[82:85]
	v_mfma_f32_16x16x32_bf16 v[70:73], v[166:169], v[220:223], v[70:73]
	v_mfma_f32_16x16x32_bf16 v[66:69], v[174:177], v[220:223], v[66:69]
	s_setprio 0
	s_barrier
	s_add_i32 s28, s33, s54
	v_lshl_add_u64 v[224:225], s[30:31], 0, v[98:99]
	s_mov_b32 m0, s28
	ds_read_b128 v[178:181], v144 offset:16384
	ds_read_b128 v[182:185], v144 offset:17408
	ds_read_b128 v[186:189], v144 offset:18432
	ds_read_b128 v[190:193], v144 offset:19456
	ds_read_b128 v[208:211], v144 offset:20480
	ds_read_b128 v[212:215], v144 offset:21504
	ds_read_b128 v[216:219], v144 offset:22528
	ds_read_b128 v[220:223], v144 offset:23552
	global_load_lds_dwordx4 v[224:225], off
	s_add_i32 m0, s28, 0x2000
	v_lshl_add_u64 v[228:229], s[30:31], 0, v[132:133]
	s_add_u32 s30, s30, s10
	s_addc_u32 s31, s31, s11
	s_add_i32 s17, s17, s54
	global_load_lds_dwordx4 v[228:229], off
	v_lshl_add_u64 v[230:231], s[30:31], 0, v[98:99]
	s_mov_b32 m0, s17
	v_lshl_add_u64 v[232:233], s[30:31], 0, v[132:133]
	global_load_lds_dwordx4 v[230:231], off
	s_add_i32 m0, s17, 0x2000
	v_lshl_add_u64 v[234:235], s[36:37], 0, v[136:137]
	global_load_lds_dwordx4 v[232:233], off
	s_mov_b32 m0, s61
	v_lshl_add_u64 v[236:237], s[36:37], 0, v[134:135]
	global_load_lds_dwordx4 v[234:235], off
	s_mov_b32 m0, s62
	s_nop 0
	global_load_lds_dwordx4 v[236:237], off
	s_waitcnt vmcnt(8)
	s_waitcnt lgkmcnt(0)
	s_barrier
; #define PG8_STAGE(bufoff, gbase, voff) do { _Pragma("unroll") for (int _i = 0; _i < 2; ++_i) \
;         __builtin_amdgcn_global_load_lds((const unsigned*)((const char*)(gbase) + (voff)[_i]), (PG8_LAS unsigned*)(lds + (bufoff) + ldsw + _i * 8192), 16, 0, 0); } while (0)
; #define PG8_LDA(dst, b, h) do { _Pragma("unroll") for (int m = 0; m < 4; ++m) _Pragma("unroll") for (int k = 0; k < 2; ++k) dst[m][k] = *(const PG8_LAS bf16x8*)(lds + PG8_SA(b, h) + aoff + m * 2048 + k * 1024); } while (0)
; #define PG8_LDB(dst, b, h) do { _Pragma("unroll") for (int n = 0; n < 2; ++n) _Pragma("unroll") for (int k = 0; k < 2; ++k) dst[n][k] = *(const PG8_LAS bf16x8*)(lds + PG8_SB(b, h) + boff + n * 2048 + k * 1024); } while (0)
; #define PG8_MMA(ai, bj, At, Bt) do { __builtin_amdgcn_s_setprio(1); _Pragma("unroll") for (int m = 0; m < 4; ++m) _Pragma("unroll") for (int n = 0; n < 2; ++n) _Pragma("unroll") for (int k = 0; k < 2; ++k) \
;         acc[ai][bj][m][n] = __builtin_amdgcn_mfma_f32_16x16x32_bf16(Bt[n][k], At[m][k], acc[ai][bj][m][n], 0, 0, 0); __builtin_amdgcn_s_setprio(0); } while (0)
; #define PG8_WAIT_V(n) asm volatile("s_waitcnt vmcnt(" #n ")" ::: "memory")
; #define PG8_WAIT_L(n) asm volatile("s_waitcnt lgkmcnt(" #n ")" ::: "memory")
; #define PG8_BAR __builtin_amdgcn_s_barrier()
; #define PG8_SCHED __builtin_amdgcn_sched_barrier(0)
; template <class Epi, class Sched, bool ALIGN_EPI = false, bool SP2 = false>
; __device__ __forceinline__ void gemm_phase(PG8_LAS unsigned char* lds, const Gemm g, const Sched& S, const Epi& E) {
;     ...
;             PG8_WAIT_V(8); PG8_WAIT_L(0); PG8_BAR; PG8_MMA(1, 0, At, B0); PG8_MMA(1, 1, At, B1); PG8_BAR; PG8_SCHED;
;             PG8_LDB(B0, 1, 0); PG8_LDB(B1, 1, 1); PG8_SCHED; PG8_LDA(At, 1, 0); PG8_STAGE(PG8_SA(0, 1), a2 + hstep, voffA);
;             PG8_WAIT_V(8); PG8_WAIT_L(0); PG8_BAR; PG8_MMA(0, 0, At, B0); PG8_MMA(0, 1, At, B1); PG8_BAR; PG8_SCHED;
	s_setprio 1
	v_mfma_f32_16x16x32_bf16 v[62:65], v[146:149], v[178:181], v[62:65]
	v_mfma_f32_16x16x32_bf16 v[58:61], v[154:157], v[178:181], v[58:61]
	v_mfma_f32_16x16x32_bf16 v[46:49], v[146:149], v[186:189], v[46:49]
	v_mfma_f32_16x16x32_bf16 v[42:45], v[154:157], v[186:189], v[42:45]
	v_mfma_f32_16x16x32_bf16 v[30:33], v[146:149], v[208:211], v[30:33]
	v_mfma_f32_16x16x32_bf16 v[26:29], v[154:157], v[208:211], v[26:29]
	v_mfma_f32_16x16x32_bf16 v[14:17], v[146:149], v[216:219], v[14:17]
	v_mfma_f32_16x16x32_bf16 v[10:13], v[154:157], v[216:219], v[10:13]
	v_mfma_f32_16x16x32_bf16 v[62:65], v[150:153], v[182:185], v[62:65]
	v_mfma_f32_16x16x32_bf16 v[58:61], v[158:161], v[182:185], v[58:61]
	v_mfma_f32_16x16x32_bf16 v[46:49], v[150:153], v[190:193], v[46:49]
	v_mfma_f32_16x16x32_bf16 v[42:45], v[158:161], v[190:193], v[42:45]
	v_mfma_f32_16x16x32_bf16 v[30:33], v[150:153], v[212:215], v[30:33]
	v_mfma_f32_16x16x32_bf16 v[26:29], v[158:161], v[212:215], v[26:29]
	v_mfma_f32_16x16x32_bf16 v[14:17], v[150:153], v[220:223], v[14:17]
	v_mfma_f32_16x16x32_bf16 v[10:13], v[158:161], v[220:223], v[10:13]
	s_setprio 0
	s_setprio 1
	v_mfma_f32_16x16x32_bf16 v[54:57], v[162:165], v[178:181], v[54:57]
	v_mfma_f32_16x16x32_bf16 v[50:53], v[170:173], v[178:181], v[50:53]
	v_mfma_f32_16x16x32_bf16 v[38:41], v[162:165], v[186:189], v[38:41]
	v_mfma_f32_16x16x32_bf16 v[34:37], v[170:173], v[186:189], v[34:37]
	v_mfma_f32_16x16x32_bf16 v[22:25], v[162:165], v[208:211], v[22:25]
	v_mfma_f32_16x16x32_bf16 v[18:21], v[170:173], v[208:211], v[18:21]
	v_mfma_f32_16x16x32_bf16 v[6:9], v[162:165], v[216:219], v[6:9]
	v_mfma_f32_16x16x32_bf16 v[2:5], v[170:173], v[216:219], v[2:5]
	v_mfma_f32_16x16x32_bf16 v[54:57], v[166:169], v[182:185], v[54:57]
	v_mfma_f32_16x16x32_bf16 v[50:53], v[174:177], v[182:185], v[50:53]
	v_mfma_f32_16x16x32_bf16 v[38:41], v[166:169], v[190:193], v[38:41]
	v_mfma_f32_16x16x32_bf16 v[34:37], v[174:177], v[190:193], v[34:37]
	v_mfma_f32_16x16x32_bf16 v[22:25], v[166:169], v[212:215], v[22:25]
	v_mfma_f32_16x16x32_bf16 v[18:21], v[174:177], v[212:215], v[18:21]
	v_mfma_f32_16x16x32_bf16 v[6:9], v[166:169], v[220:223], v[6:9]
	v_mfma_f32_16x16x32_bf16 v[2:5], v[174:177], v[220:223], v[2:5]
	s_setprio 0
	s_barrier
	s_add_i32 s17, 0, 0x18000
	v_add_u32_e32 v145, s17, v142
	s_add_i32 s28, 0, 0x1c000
	ds_read_b128 v[146:149], v145
	ds_read_b128 v[150:153], v145 offset:1024
	ds_read_b128 v[154:157], v145 offset:2048
	ds_read_b128 v[158:161], v145 offset:3072
	v_add_u32_e32 v145, s28, v142
	ds_read_b128 v[162:165], v145
	ds_read_b128 v[166:169], v145 offset:1024
	ds_read_b128 v[170:173], v145 offset:2048
	ds_read_b128 v[174:177], v145 offset:3072
	s_add_u32 s30, s36, s10
	s_addc_u32 s31, s37, s11
	s_mov_b32 m0, s63
	v_lshl_add_u64 v[238:239], s[30:31], 0, v[136:137]
	ds_read_b128 v[178:181], v144 offset:32768
	ds_read_b128 v[182:185], v144 offset:33792
	ds_read_b128 v[186:189], v144 offset:34816
	ds_read_b128 v[190:193], v144 offset:35840
	ds_read_b128 v[208:211], v144 offset:36864
	ds_read_b128 v[212:215], v144 offset:37888
	ds_read_b128 v[216:219], v144 offset:38912
	ds_read_b128 v[220:223], v144 offset:39936
	global_load_lds_dwordx4 v[238:239], off
	v_lshl_add_u64 v[238:239], s[30:31], 0, v[134:135]
	s_mov_b32 m0, s64
	s_nop 0
	global_load_lds_dwordx4 v[238:239], off
	s_waitcnt vmcnt(8)
	s_waitcnt lgkmcnt(0)
	s_barrier
	s_setprio 1
	v_mfma_f32_16x16x32_bf16 v[124:127], v[146:149], v[178:181], v[124:127]
	v_mfma_f32_16x16x32_bf16 v[128:131], v[154:157], v[178:181], v[128:131]
	v_mfma_f32_16x16x32_bf16 v[112:115], v[146:149], v[186:189], v[112:115]
	v_mfma_f32_16x16x32_bf16 v[108:111], v[154:157], v[186:189], v[108:111]
	v_mfma_f32_16x16x32_bf16 v[94:97], v[146:149], v[208:211], v[94:97]
	v_mfma_f32_16x16x32_bf16 v[90:93], v[154:157], v[208:211], v[90:93]
	v_mfma_f32_16x16x32_bf16 v[78:81], v[146:149], v[216:219], v[78:81]
	v_mfma_f32_16x16x32_bf16 v[74:77], v[154:157], v[216:219], v[74:77]
	v_mfma_f32_16x16x32_bf16 v[124:127], v[150:153], v[182:185], v[124:127]
	v_mfma_f32_16x16x32_bf16 v[128:131], v[158:161], v[182:185], v[128:131]
	v_mfma_f32_16x16x32_bf16 v[112:115], v[150:153], v[190:193], v[112:115]
	v_mfma_f32_16x16x32_bf16 v[108:111], v[158:161], v[190:193], v[108:111]
	v_mfma_f32_16x16x32_bf16 v[94:97], v[150:153], v[212:215], v[94:97]
	v_mfma_f32_16x16x32_bf16 v[90:93], v[158:161], v[212:215], v[90:93]
	v_mfma_f32_16x16x32_bf16 v[78:81], v[150:153], v[220:223], v[78:81]
	v_mfma_f32_16x16x32_bf16 v[74:77], v[158:161], v[220:223], v[74:77]
	s_setprio 0
	s_setprio 1
	v_mfma_f32_16x16x32_bf16 v[120:123], v[162:165], v[178:181], v[120:123]
	v_mfma_f32_16x16x32_bf16 v[116:119], v[170:173], v[178:181], v[116:119]
	v_mfma_f32_16x16x32_bf16 v[104:107], v[162:165], v[186:189], v[104:107]
	v_mfma_f32_16x16x32_bf16 v[100:103], v[170:173], v[186:189], v[100:103]
	v_mfma_f32_16x16x32_bf16 v[86:89], v[162:165], v[208:211], v[86:89]
	v_mfma_f32_16x16x32_bf16 v[82:85], v[170:173], v[208:211], v[82:85]
	v_mfma_f32_16x16x32_bf16 v[70:73], v[162:165], v[216:219], v[70:73]
	v_mfma_f32_16x16x32_bf16 v[66:69], v[170:173], v[216:219], v[66:69]
	v_mfma_f32_16x16x32_bf16 v[120:123], v[166:169], v[182:185], v[120:123]
	v_mfma_f32_16x16x32_bf16 v[116:119], v[174:177], v[182:185], v[116:119]
	v_mfma_f32_16x16x32_bf16 v[104:107], v[166:169], v[190:193], v[104:107]
	v_mfma_f32_16x16x32_bf16 v[100:103], v[174:177], v[190:193], v[100:103]
	v_mfma_f32_16x16x32_bf16 v[86:89], v[166:169], v[212:215], v[86:89]
	v_mfma_f32_16x16x32_bf16 v[82:85], v[174:177], v[212:215], v[82:85]
	v_mfma_f32_16x16x32_bf16 v[70:73], v[166:169], v[220:223], v[70:73]
	v_mfma_f32_16x16x32_bf16 v[66:69], v[174:177], v[220:223], v[66:69]
	s_setprio 0
	s_barrier
; #define PG8_STAGE(bufoff, gbase, voff) do { _Pragma("unroll") for (int _i = 0; _i < 2; ++_i) \
;         __builtin_amdgcn_global_load_lds((const unsigned*)((const char*)(gbase) + (voff)[_i]), (PG8_LAS unsigned*)(lds + (bufoff) + ldsw + _i * 8192), 16, 0, 0); } while (0)
; #define PG8_LDA(dst, b, h) do { _Pragma("unroll") for (int m = 0; m < 4; ++m) _Pragma("unroll") for (int k = 0; k < 2; ++k) dst[m][k] = *(const PG8_LAS bf16x8*)(lds + PG8_SA(b, h) + aoff + m * 2048 + k * 1024); } while (0)
; #define PG8_MMA(ai, bj, At, Bt) do { __builtin_amdgcn_s_setprio(1); _Pragma("unroll") for (int m = 0; m < 4; ++m) _Pragma("unroll") for (int n = 0; n < 2; ++n) _Pragma("unroll") for (int k = 0; k < 2; ++k) \
;         acc[ai][bj][m][n] = __builtin_amdgcn_mfma_f32_16x16x32_bf16(Bt[n][k], At[m][k], acc[ai][bj][m][n], 0, 0, 0); __builtin_amdgcn_s_setprio(0); } while (0)
; #define PG8_WAIT_V(n) asm volatile("s_waitcnt vmcnt(" #n ")" ::: "memory")
; #define PG8_WAIT_L(n) asm volatile("s_waitcnt lgkmcnt(" #n ")" ::: "memory")
; #define PG8_BAR __builtin_amdgcn_s_barrier()
; #define PG8_SCHED __builtin_amdgcn_sched_barrier(0)
; template <class Epi, class Sched, bool ALIGN_EPI = false, bool SP2 = false>
; __device__ __forceinline__ void gemm_phase(PG8_LAS unsigned char* lds, const Gemm g, const Sched& S, const Epi& E) {
;     ...
;         for (int t = 0; t < nt; t += 2) {
;     ...
;             PG8_LDA(At, 1, 1); PG8_STAGE(PG8_SB(1, 0), b3, voffB); PG8_STAGE(PG8_SB(1, 1), b3 + hstep, voffB); PG8_STAGE(PG8_SA(1, 0), a3, voffA);
;             PG8_WAIT_V(8); PG8_WAIT_L(0); PG8_BAR; PG8_MMA(1, 0, At, B0); PG8_MMA(1, 1, At, B1); PG8_BAR; PG8_SCHED;
	s_add_i32 s17, s17, s54
	v_lshl_add_u64 v[224:225], v[224:225], 0, s[24:25]
	s_mov_b32 m0, s17
	ds_read_b128 v[178:181], v144 offset:49152
	ds_read_b128 v[182:185], v144 offset:50176
	ds_read_b128 v[186:189], v144 offset:51200
	ds_read_b128 v[190:193], v144 offset:52224
	ds_read_b128 v[208:211], v144 offset:53248
	ds_read_b128 v[212:215], v144 offset:54272
	ds_read_b128 v[216:219], v144 offset:55296
	ds_read_b128 v[220:223], v144 offset:56320
	global_load_lds_dwordx4 v[224:225], off
	v_lshl_add_u64 v[224:225], v[228:229], 0, s[24:25]
	s_add_i32 m0, s17, 0x2000
	s_add_i32 s17, s28, s54
	global_load_lds_dwordx4 v[224:225], off
	v_lshl_add_u64 v[224:225], v[230:231], 0, s[24:25]
	s_mov_b32 m0, s17
	s_nop 0
	global_load_lds_dwordx4 v[224:225], off
	v_lshl_add_u64 v[224:225], v[232:233], 0, s[24:25]
	s_add_i32 m0, s17, 0x2000
	s_nop 0
	global_load_lds_dwordx4 v[224:225], off
	v_lshl_add_u64 v[224:225], v[234:235], 0, s[24:25]
	s_mov_b32 m0, s68
	s_nop 0
	global_load_lds_dwordx4 v[224:225], off
	v_lshl_add_u64 v[224:225], v[236:237], 0, s[24:25]
	s_mov_b32 m0, s69
	s_nop 0
	global_load_lds_dwordx4 v[224:225], off
	s_waitcnt vmcnt(8)
	s_waitcnt lgkmcnt(0)
	s_barrier
	s_setprio 1
	v_mfma_f32_16x16x32_bf16 v[62:65], v[146:149], v[178:181], v[62:65]
	v_mfma_f32_16x16x32_bf16 v[58:61], v[154:157], v[178:181], v[58:61]
	v_mfma_f32_16x16x32_bf16 v[46:49], v[146:149], v[186:189], v[46:49]
	v_mfma_f32_16x16x32_bf16 v[42:45], v[154:157], v[186:189], v[42:45]
	v_mfma_f32_16x16x32_bf16 v[30:33], v[146:149], v[208:211], v[30:33]
	v_mfma_f32_16x16x32_bf16 v[26:29], v[154:157], v[208:211], v[26:29]
	v_mfma_f32_16x16x32_bf16 v[14:17], v[146:149], v[216:219], v[14:17]
	v_mfma_f32_16x16x32_bf16 v[10:13], v[154:157], v[216:219], v[10:13]
	v_mfma_f32_16x16x32_bf16 v[62:65], v[150:153], v[182:185], v[62:65]
	v_mfma_f32_16x16x32_bf16 v[58:61], v[158:161], v[182:185], v[58:61]
	v_mfma_f32_16x16x32_bf16 v[46:49], v[150:153], v[190:193], v[46:49]
	v_mfma_f32_16x16x32_bf16 v[42:45], v[158:161], v[190:193], v[42:45]
	v_mfma_f32_16x16x32_bf16 v[30:33], v[150:153], v[212:215], v[30:33]
	v_mfma_f32_16x16x32_bf16 v[26:29], v[158:161], v[212:215], v[26:29]
	v_mfma_f32_16x16x32_bf16 v[14:17], v[150:153], v[220:223], v[14:17]
	v_mfma_f32_16x16x32_bf16 v[10:13], v[158:161], v[220:223], v[10:13]
	s_setprio 0
	s_setprio 1
	v_mfma_f32_16x16x32_bf16 v[54:57], v[162:165], v[178:181], v[54:57]
	v_mfma_f32_16x16x32_bf16 v[50:53], v[170:173], v[178:181], v[50:53]
	v_mfma_f32_16x16x32_bf16 v[38:41], v[162:165], v[186:189], v[38:41]
	v_mfma_f32_16x16x32_bf16 v[34:37], v[170:173], v[186:189], v[34:37]
	v_mfma_f32_16x16x32_bf16 v[22:25], v[162:165], v[208:211], v[22:25]
	v_mfma_f32_16x16x32_bf16 v[18:21], v[170:173], v[208:211], v[18:21]
	v_mfma_f32_16x16x32_bf16 v[6:9], v[162:165], v[216:219], v[6:9]
	v_mfma_f32_16x16x32_bf16 v[2:5], v[170:173], v[216:219], v[2:5]
	v_mfma_f32_16x16x32_bf16 v[54:57], v[166:169], v[182:185], v[54:57]
	v_mfma_f32_16x16x32_bf16 v[50:53], v[174:177], v[182:185], v[50:53]
	v_mfma_f32_16x16x32_bf16 v[38:41], v[166:169], v[190:193], v[38:41]
	v_mfma_f32_16x16x32_bf16 v[34:37], v[174:177], v[190:193], v[34:37]
	v_mfma_f32_16x16x32_bf16 v[22:25], v[166:169], v[212:215], v[22:25]
	v_mfma_f32_16x16x32_bf16 v[18:21], v[174:177], v[212:215], v[18:21]
	v_mfma_f32_16x16x32_bf16 v[6:9], v[166:169], v[220:223], v[6:9]
	v_mfma_f32_16x16x32_bf16 v[2:5], v[174:177], v[220:223], v[2:5]
	s_setprio 0
	s_barrier
	s_add_u32 s34, s34, 0x100
	s_addc_u32 s35, s35, 0
	s_add_u32 s4, s4, 0x100
	s_addc_u32 s16, s16, 0
	s_cmp_ge_i32 s22, s65
	s_mov_b32 s17, s22
	s_cbranch_scc0 .LBB0_521

; #define PG8_STAGE(bufoff, gbase, voff) do { _Pragma("unroll") for (int _i = 0; _i < 2; ++_i) \
;         __builtin_amdgcn_global_load_lds((const unsigned*)((const char*)(gbase) + (voff)[_i]), (PG8_LAS unsigned*)(lds + (bufoff) + ldsw + _i * 8192), 16, 0, 0); } while (0)
; #define PG8_LDA(dst, b, h) do { _Pragma("unroll") for (int m = 0; m < 4; ++m) _Pragma("unroll") for (int k = 0; k < 2; ++k) dst[m][k] = *(const PG8_LAS bf16x8*)(lds + PG8_SA(b, h) + aoff + m * 2048 + k * 1024); } while (0)
; #define PG8_LDB(dst, b, h) do { _Pragma("unroll") for (int n = 0; n < 2; ++n) _Pragma("unroll") for (int k = 0; k < 2; ++k) dst[n][k] = *(const PG8_LAS bf16x8*)(lds + PG8_SB(b, h) + boff + n * 2048 + k * 1024); } while (0)
; #define PG8_MMA(ai, bj, At, Bt) do { __builtin_amdgcn_s_setprio(1); _Pragma("unroll") for (int m = 0; m < 4; ++m) _Pragma("unroll") for (int n = 0; n < 2; ++n) _Pragma("unroll") for (int k = 0; k < 2; ++k) \
;         acc[ai][bj][m][n] = __builtin_amdgcn_mfma_f32_16x16x32_bf16(Bt[n][k], At[m][k], acc[ai][bj][m][n], 0, 0, 0); __builtin_amdgcn_s_setprio(0); } while (0)
; #define PG8_WAIT_V(n) asm volatile("s_waitcnt vmcnt(" #n ")" ::: "memory")
; #define PG8_WAIT_L(n) asm volatile("s_waitcnt lgkmcnt(" #n ")" ::: "memory")
; #define PG8_BAR __builtin_amdgcn_s_barrier()
; #define PG8_SCHED __builtin_amdgcn_sched_barrier(0)
; template <class Epi, class Sched, bool ALIGN_EPI = false, bool SP2 = false>
; __device__ __forceinline__ void gemm_phase(PG8_LAS unsigned char* lds, const Gemm g, const Sched& S, const Epi& E) {
;     ...
;             const bool last = (t == nt - 2);
;             const char* a1 = cA + (size_t)(t + 1) * kstep;
;             const char* a2 = last ? nA : cA + (size_t)(t + 2) * kstep; const char* b2 = last ? nB : cB + (size_t)(t + 2) * kstep;
;             const char* a3 = a2 + kstep; const char* b3 = b2 + kstep;
;             if (last && has_next) S.a_ready(nxt);
;             if constexpr (SP2) {
;             PG8_LDB(B0, 0, 0); PG8_LDB(B1, 0, 1); PG8_SCHED; PG8_LDA(At, 0, 0); PG8_STAGE(PG8_SA(1, 1), a1 + hstep, voffA);
;             PG8_WAIT_V(8); PG8_WAIT_L(0); PG8_BAR; PG8_MMA(0, 0, At, B0); PG8_MMA(0, 1, At, B1); PG8_BAR; PG8_SCHED;
;             PG8_LDA(At, 0, 1); PG8_STAGE(PG8_SB(0, 0), b2, voffB); PG8_STAGE(PG8_SB(0, 1), b2 + hstep, voffB); PG8_STAGE(PG8_SA(0, 0), a2, voffA);
.LBB0_544:
	s_add_i32 s22, s17, 2
	s_add_u32 s28, s34, 0x80
	s_addc_u32 s30, s35, 0
	s_add_i32 s33, 0, 0x10000
	s_cmp_eq_u32 s71, s17
	s_cselect_b32 s37, s3, s30
	s_cselect_b32 s36, s2, s28
	v_add_u32_e32 v145, s33, v142
	s_cselect_b32 s31, s51, s16
	s_cselect_b32 s30, s50, s4
	s_add_i32 s17, 0, 0x14000
	ds_read_b128 v[146:149], v145
	ds_read_b128 v[150:153], v145 offset:1024
	ds_read_b128 v[154:157], v145 offset:2048
	ds_read_b128 v[158:161], v145 offset:3072
	v_add_u32_e32 v145, s17, v142
	ds_read_b128 v[162:165], v145
	ds_read_b128 v[166:169], v145 offset:1024
	ds_read_b128 v[170:173], v145 offset:2048
	ds_read_b128 v[174:177], v145 offset:3072
	v_lshl_add_u64 v[224:225], s[34:35], 0, v[138:139]
	s_add_i32 m0, s62, 0xc000
	ds_read_b128 v[178:181], v144
	ds_read_b128 v[182:185], v144 offset:1024
	ds_read_b128 v[186:189], v144 offset:2048
	ds_read_b128 v[190:193], v144 offset:3072
	ds_read_b128 v[208:211], v144 offset:4096
	ds_read_b128 v[212:215], v144 offset:5120
	ds_read_b128 v[216:219], v144 offset:6144
	ds_read_b128 v[220:223], v144 offset:7168
	global_load_lds_dwordx4 v[224:225], off
	v_lshl_add_u64 v[224:225], s[34:35], 0, v[140:141]
	s_add_i32 m0, s62, 0xe000
	s_nop 0
	global_load_lds_dwordx4 v[224:225], off
	s_waitcnt vmcnt(8)
	s_waitcnt lgkmcnt(0)
	s_barrier
	s_setprio 1
	v_mfma_f32_16x16x32_bf16 v[124:127], v[146:149], v[178:181], v[124:127]
	v_mfma_f32_16x16x32_bf16 v[128:131], v[154:157], v[178:181], v[128:131]
	v_mfma_f32_16x16x32_bf16 v[112:115], v[146:149], v[186:189], v[112:115]
	v_mfma_f32_16x16x32_bf16 v[108:111], v[154:157], v[186:189], v[108:111]
	v_mfma_f32_16x16x32_bf16 v[94:97], v[146:149], v[208:211], v[94:97]
	v_mfma_f32_16x16x32_bf16 v[90:93], v[154:157], v[208:211], v[90:93]
	v_mfma_f32_16x16x32_bf16 v[78:81], v[146:149], v[216:219], v[78:81]
	v_mfma_f32_16x16x32_bf16 v[74:77], v[154:157], v[216:219], v[74:77]
	v_mfma_f32_16x16x32_bf16 v[124:127], v[150:153], v[182:185], v[124:127]
	v_mfma_f32_16x16x32_bf16 v[128:131], v[158:161], v[182:185], v[128:131]
	v_mfma_f32_16x16x32_bf16 v[112:115], v[150:153], v[190:193], v[112:115]
	v_mfma_f32_16x16x32_bf16 v[108:111], v[158:161], v[190:193], v[108:111]
	v_mfma_f32_16x16x32_bf16 v[94:97], v[150:153], v[212:215], v[94:97]
	v_mfma_f32_16x16x32_bf16 v[90:93], v[158:161], v[212:215], v[90:93]
	v_mfma_f32_16x16x32_bf16 v[78:81], v[150:153], v[220:223], v[78:81]
	v_mfma_f32_16x16x32_bf16 v[74:77], v[158:161], v[220:223], v[74:77]
	s_setprio 0
	s_setprio 1
	v_mfma_f32_16x16x32_bf16 v[120:123], v[162:165], v[178:181], v[120:123]
	v_mfma_f32_16x16x32_bf16 v[116:119], v[170:173], v[178:181], v[116:119]
	v_mfma_f32_16x16x32_bf16 v[104:107], v[162:165], v[186:189], v[104:107]
	v_mfma_f32_16x16x32_bf16 v[100:103], v[170:173], v[186:189], v[100:103]
	v_mfma_f32_16x16x32_bf16 v[86:89], v[162:165], v[208:211], v[86:89]
	v_mfma_f32_16x16x32_bf16 v[82:85], v[170:173], v[208:211], v[82:85]
	v_mfma_f32_16x16x32_bf16 v[70:73], v[162:165], v[216:219], v[70:73]
	v_mfma_f32_16x16x32_bf16 v[66:69], v[170:173], v[216:219], v[66:69]
	v_mfma_f32_16x16x32_bf16 v[120:123], v[166:169], v[182:185], v[120:123]
	v_mfma_f32_16x16x32_bf16 v[116:119], v[174:177], v[182:185], v[116:119]
	v_mfma_f32_16x16x32_bf16 v[104:107], v[166:169], v[190:193], v[104:107]
	v_mfma_f32_16x16x32_bf16 v[100:103], v[174:177], v[190:193], v[100:103]
	v_mfma_f32_16x16x32_bf16 v[86:89], v[166:169], v[212:215], v[86:89]
	v_mfma_f32_16x16x32_bf16 v[82:85], v[174:177], v[212:215], v[82:85]
	v_mfma_f32_16x16x32_bf16 v[70:73], v[166:169], v[220:223], v[70:73]
	v_mfma_f32_16x16x32_bf16 v[66:69], v[174:177], v[220:223], v[66:69]
	s_setprio 0
	s_barrier
	s_add_i32 s28, s33, s55
	v_lshl_add_u64 v[224:225], s[30:31], 0, v[98:99]
	s_mov_b32 m0, s28
	ds_read_b128 v[178:181], v144 offset:16384
	ds_read_b128 v[182:185], v144 offset:17408
	ds_read_b128 v[186:189], v144 offset:18432
	ds_read_b128 v[190:193], v144 offset:19456
	ds_read_b128 v[208:211], v144 offset:20480
	ds_read_b128 v[212:215], v144 offset:21504
	ds_read_b128 v[216:219], v144 offset:22528
	ds_read_b128 v[220:223], v144 offset:23552
	global_load_lds_dwordx4 v[224:225], off
	s_add_i32 m0, s28, 0x2000
	v_lshl_add_u64 v[228:229], s[30:31], 0, v[132:133]
	s_add_u32 s30, s30, s10
	s_addc_u32 s31, s31, s11
	s_add_i32 s17, s17, s55
	global_load_lds_dwordx4 v[228:229], off
	v_lshl_add_u64 v[230:231], s[30:31], 0, v[98:99]
	s_mov_b32 m0, s17
	v_lshl_add_u64 v[232:233], s[30:31], 0, v[132:133]
	global_load_lds_dwordx4 v[230:231], off
	s_add_i32 m0, s17, 0x2000
	v_lshl_add_u64 v[234:235], s[36:37], 0, v[136:137]
	global_load_lds_dwordx4 v[232:233], off
	s_mov_b32 m0, s62
	v_lshl_add_u64 v[236:237], s[36:37], 0, v[134:135]
	global_load_lds_dwordx4 v[234:235], off
	s_mov_b32 m0, s63
	s_nop 0
	global_load_lds_dwordx4 v[236:237], off
	s_waitcnt vmcnt(8)
	s_waitcnt lgkmcnt(0)
	s_barrier
; #define PG8_STAGE(bufoff, gbase, voff) do { _Pragma("unroll") for (int _i = 0; _i < 2; ++_i) \
;         __builtin_amdgcn_global_load_lds((const unsigned*)((const char*)(gbase) + (voff)[_i]), (PG8_LAS unsigned*)(lds + (bufoff) + ldsw + _i * 8192), 16, 0, 0); } while (0)
; #define PG8_LDA(dst, b, h) do { _Pragma("unroll") for (int m = 0; m < 4; ++m) _Pragma("unroll") for (int k = 0; k < 2; ++k) dst[m][k] = *(const PG8_LAS bf16x8*)(lds + PG8_SA(b, h) + aoff + m * 2048 + k * 1024); } while (0)
; #define PG8_LDB(dst, b, h) do { _Pragma("unroll") for (int n = 0; n < 2; ++n) _Pragma("unroll") for (int k = 0; k < 2; ++k) dst[n][k] = *(const PG8_LAS bf16x8*)(lds + PG8_SB(b, h) + boff + n * 2048 + k * 1024); } while (0)
; #define PG8_MMA(ai, bj, At, Bt) do { __builtin_amdgcn_s_setprio(1); _Pragma("unroll") for (int m = 0; m < 4; ++m) _Pragma("unroll") for (int n = 0; n < 2; ++n) _Pragma("unroll") for (int k = 0; k < 2; ++k) \
;         acc[ai][bj][m][n] = __builtin_amdgcn_mfma_f32_16x16x32_bf16(Bt[n][k], At[m][k], acc[ai][bj][m][n], 0, 0, 0); __builtin_amdgcn_s_setprio(0); } while (0)
; #define PG8_WAIT_V(n) asm volatile("s_waitcnt vmcnt(" #n ")" ::: "memory")
; #define PG8_WAIT_L(n) asm volatile("s_waitcnt lgkmcnt(" #n ")" ::: "memory")
; #define PG8_BAR __builtin_amdgcn_s_barrier()
; #define PG8_SCHED __builtin_amdgcn_sched_barrier(0)
; template <class Epi, class Sched, bool ALIGN_EPI = false, bool SP2 = false>
; __device__ __forceinline__ void gemm_phase(PG8_LAS unsigned char* lds, const Gemm g, const Sched& S, const Epi& E) {
;     ...
;             PG8_WAIT_V(8); PG8_WAIT_L(0); PG8_BAR; PG8_MMA(1, 0, At, B0); PG8_MMA(1, 1, At, B1); PG8_BAR; PG8_SCHED;
;             PG8_LDB(B0, 1, 0); PG8_LDB(B1, 1, 1); PG8_SCHED; PG8_LDA(At, 1, 0); PG8_STAGE(PG8_SA(0, 1), a2 + hstep, voffA);
;             PG8_WAIT_V(8); PG8_WAIT_L(0); PG8_BAR; PG8_MMA(0, 0, At, B0); PG8_MMA(0, 1, At, B1); PG8_BAR; PG8_SCHED;
	s_setprio 1
	v_mfma_f32_16x16x32_bf16 v[62:65], v[146:149], v[178:181], v[62:65]
	v_mfma_f32_16x16x32_bf16 v[58:61], v[154:157], v[178:181], v[58:61]
	v_mfma_f32_16x16x32_bf16 v[46:49], v[146:149], v[186:189], v[46:49]
	v_mfma_f32_16x16x32_bf16 v[42:45], v[154:157], v[186:189], v[42:45]
	v_mfma_f32_16x16x32_bf16 v[30:33], v[146:149], v[208:211], v[30:33]
	v_mfma_f32_16x16x32_bf16 v[26:29], v[154:157], v[208:211], v[26:29]
	v_mfma_f32_16x16x32_bf16 v[14:17], v[146:149], v[216:219], v[14:17]
	v_mfma_f32_16x16x32_bf16 v[10:13], v[154:157], v[216:219], v[10:13]
	v_mfma_f32_16x16x32_bf16 v[62:65], v[150:153], v[182:185], v[62:65]
	v_mfma_f32_16x16x32_bf16 v[58:61], v[158:161], v[182:185], v[58:61]
	v_mfma_f32_16x16x32_bf16 v[46:49], v[150:153], v[190:193], v[46:49]
	v_mfma_f32_16x16x32_bf16 v[42:45], v[158:161], v[190:193], v[42:45]
	v_mfma_f32_16x16x32_bf16 v[30:33], v[150:153], v[212:215], v[30:33]
	v_mfma_f32_16x16x32_bf16 v[26:29], v[158:161], v[212:215], v[26:29]
	v_mfma_f32_16x16x32_bf16 v[14:17], v[150:153], v[220:223], v[14:17]
	v_mfma_f32_16x16x32_bf16 v[10:13], v[158:161], v[220:223], v[10:13]
	s_setprio 0
	s_setprio 1
	v_mfma_f32_16x16x32_bf16 v[54:57], v[162:165], v[178:181], v[54:57]
	v_mfma_f32_16x16x32_bf16 v[50:53], v[170:173], v[178:181], v[50:53]
	v_mfma_f32_16x16x32_bf16 v[38:41], v[162:165], v[186:189], v[38:41]
	v_mfma_f32_16x16x32_bf16 v[34:37], v[170:173], v[186:189], v[34:37]
	v_mfma_f32_16x16x32_bf16 v[22:25], v[162:165], v[208:211], v[22:25]
	v_mfma_f32_16x16x32_bf16 v[18:21], v[170:173], v[208:211], v[18:21]
	v_mfma_f32_16x16x32_bf16 v[6:9], v[162:165], v[216:219], v[6:9]
	v_mfma_f32_16x16x32_bf16 v[2:5], v[170:173], v[216:219], v[2:5]
	v_mfma_f32_16x16x32_bf16 v[54:57], v[166:169], v[182:185], v[54:57]
	v_mfma_f32_16x16x32_bf16 v[50:53], v[174:177], v[182:185], v[50:53]
	v_mfma_f32_16x16x32_bf16 v[38:41], v[166:169], v[190:193], v[38:41]
	v_mfma_f32_16x16x32_bf16 v[34:37], v[174:177], v[190:193], v[34:37]
	v_mfma_f32_16x16x32_bf16 v[22:25], v[166:169], v[212:215], v[22:25]
	v_mfma_f32_16x16x32_bf16 v[18:21], v[174:177], v[212:215], v[18:21]
	v_mfma_f32_16x16x32_bf16 v[6:9], v[166:169], v[220:223], v[6:9]
	v_mfma_f32_16x16x32_bf16 v[2:5], v[174:177], v[220:223], v[2:5]
	s_setprio 0
	s_barrier
	s_add_i32 s17, 0, 0x18000
	v_add_u32_e32 v145, s17, v142
	s_add_i32 s28, 0, 0x1c000
	ds_read_b128 v[146:149], v145
	ds_read_b128 v[150:153], v145 offset:1024
	ds_read_b128 v[154:157], v145 offset:2048
	ds_read_b128 v[158:161], v145 offset:3072
	v_add_u32_e32 v145, s28, v142
	ds_read_b128 v[162:165], v145
	ds_read_b128 v[166:169], v145 offset:1024
	ds_read_b128 v[170:173], v145 offset:2048
	ds_read_b128 v[174:177], v145 offset:3072
	s_add_u32 s30, s36, s10
	s_addc_u32 s31, s37, s11
	s_mov_b32 m0, s64
	v_lshl_add_u64 v[238:239], s[30:31], 0, v[136:137]
	ds_read_b128 v[178:181], v144 offset:32768
	ds_read_b128 v[182:185], v144 offset:33792
	ds_read_b128 v[186:189], v144 offset:34816
	ds_read_b128 v[190:193], v144 offset:35840
	ds_read_b128 v[208:211], v144 offset:36864
	ds_read_b128 v[212:215], v144 offset:37888
	ds_read_b128 v[216:219], v144 offset:38912
	ds_read_b128 v[220:223], v144 offset:39936
	global_load_lds_dwordx4 v[238:239], off
	v_lshl_add_u64 v[238:239], s[30:31], 0, v[134:135]
	s_mov_b32 m0, s65
	s_nop 0
	global_load_lds_dwordx4 v[238:239], off
	s_waitcnt vmcnt(8)
	s_waitcnt lgkmcnt(0)
	s_barrier
	s_setprio 1
	v_mfma_f32_16x16x32_bf16 v[124:127], v[146:149], v[178:181], v[124:127]
	v_mfma_f32_16x16x32_bf16 v[128:131], v[154:157], v[178:181], v[128:131]
	v_mfma_f32_16x16x32_bf16 v[112:115], v[146:149], v[186:189], v[112:115]
	v_mfma_f32_16x16x32_bf16 v[108:111], v[154:157], v[186:189], v[108:111]
	v_mfma_f32_16x16x32_bf16 v[94:97], v[146:149], v[208:211], v[94:97]
	v_mfma_f32_16x16x32_bf16 v[90:93], v[154:157], v[208:211], v[90:93]
	v_mfma_f32_16x16x32_bf16 v[78:81], v[146:149], v[216:219], v[78:81]
	v_mfma_f32_16x16x32_bf16 v[74:77], v[154:157], v[216:219], v[74:77]
	v_mfma_f32_16x16x32_bf16 v[124:127], v[150:153], v[182:185], v[124:127]
	v_mfma_f32_16x16x32_bf16 v[128:131], v[158:161], v[182:185], v[128:131]
	v_mfma_f32_16x16x32_bf16 v[112:115], v[150:153], v[190:193], v[112:115]
	v_mfma_f32_16x16x32_bf16 v[108:111], v[158:161], v[190:193], v[108:111]
	v_mfma_f32_16x16x32_bf16 v[94:97], v[150:153], v[212:215], v[94:97]
	v_mfma_f32_16x16x32_bf16 v[90:93], v[158:161], v[212:215], v[90:93]
	v_mfma_f32_16x16x32_bf16 v[78:81], v[150:153], v[220:223], v[78:81]
	v_mfma_f32_16x16x32_bf16 v[74:77], v[158:161], v[220:223], v[74:77]
	s_setprio 0
	s_setprio 1
	v_mfma_f32_16x16x32_bf16 v[120:123], v[162:165], v[178:181], v[120:123]
	v_mfma_f32_16x16x32_bf16 v[116:119], v[170:173], v[178:181], v[116:119]
	v_mfma_f32_16x16x32_bf16 v[104:107], v[162:165], v[186:189], v[104:107]
	v_mfma_f32_16x16x32_bf16 v[100:103], v[170:173], v[186:189], v[100:103]
	v_mfma_f32_16x16x32_bf16 v[86:89], v[162:165], v[208:211], v[86:89]
	v_mfma_f32_16x16x32_bf16 v[82:85], v[170:173], v[208:211], v[82:85]
	v_mfma_f32_16x16x32_bf16 v[70:73], v[162:165], v[216:219], v[70:73]
	v_mfma_f32_16x16x32_bf16 v[66:69], v[170:173], v[216:219], v[66:69]
	v_mfma_f32_16x16x32_bf16 v[120:123], v[166:169], v[182:185], v[120:123]
	v_mfma_f32_16x16x32_bf16 v[116:119], v[174:177], v[182:185], v[116:119]
	v_mfma_f32_16x16x32_bf16 v[104:107], v[166:169], v[190:193], v[104:107]
	v_mfma_f32_16x16x32_bf16 v[100:103], v[174:177], v[190:193], v[100:103]
	v_mfma_f32_16x16x32_bf16 v[86:89], v[166:169], v[212:215], v[86:89]
	v_mfma_f32_16x16x32_bf16 v[82:85], v[174:177], v[212:215], v[82:85]
	v_mfma_f32_16x16x32_bf16 v[70:73], v[166:169], v[220:223], v[70:73]
	v_mfma_f32_16x16x32_bf16 v[66:69], v[174:177], v[220:223], v[66:69]
	s_setprio 0
	s_barrier
; #define PG8_STAGE(bufoff, gbase, voff) do { _Pragma("unroll") for (int _i = 0; _i < 2; ++_i) \
;         __builtin_amdgcn_global_load_lds((const unsigned*)((const char*)(gbase) + (voff)[_i]), (PG8_LAS unsigned*)(lds + (bufoff) + ldsw + _i * 8192), 16, 0, 0); } while (0)
; #define PG8_LDA(dst, b, h) do { _Pragma("unroll") for (int m = 0; m < 4; ++m) _Pragma("unroll") for (int k = 0; k < 2; ++k) dst[m][k] = *(const PG8_LAS bf16x8*)(lds + PG8_SA(b, h) + aoff + m * 2048 + k * 1024); } while (0)
; #define PG8_MMA(ai, bj, At, Bt) do { __builtin_amdgcn_s_setprio(1); _Pragma("unroll") for (int m = 0; m < 4; ++m) _Pragma("unroll") for (int n = 0; n < 2; ++n) _Pragma("unroll") for (int k = 0; k < 2; ++k) \
;         acc[ai][bj][m][n] = __builtin_amdgcn_mfma_f32_16x16x32_bf16(Bt[n][k], At[m][k], acc[ai][bj][m][n], 0, 0, 0); __builtin_amdgcn_s_setprio(0); } while (0)
; #define PG8_WAIT_V(n) asm volatile("s_waitcnt vmcnt(" #n ")" ::: "memory")
; #define PG8_WAIT_L(n) asm volatile("s_waitcnt lgkmcnt(" #n ")" ::: "memory")
; #define PG8_BAR __builtin_amdgcn_s_barrier()
; #define PG8_SCHED __builtin_amdgcn_sched_barrier(0)
; template <class Epi, class Sched, bool ALIGN_EPI = false, bool SP2 = false>
; __device__ __forceinline__ void gemm_phase(PG8_LAS unsigned char* lds, const Gemm g, const Sched& S, const Epi& E) {
;     ...
;         for (int t = 0; t < nt; t += 2) {
;     ...
;             PG8_LDA(At, 1, 1); PG8_STAGE(PG8_SB(1, 0), b3, voffB); PG8_STAGE(PG8_SB(1, 1), b3 + hstep, voffB); PG8_STAGE(PG8_SA(1, 0), a3, voffA);
;             PG8_WAIT_V(8); PG8_WAIT_L(0); PG8_BAR; PG8_MMA(1, 0, At, B0); PG8_MMA(1, 1, At, B1); PG8_BAR; PG8_SCHED;
	s_add_i32 s17, s17, s55
	v_lshl_add_u64 v[224:225], v[224:225], 0, s[24:25]
	s_mov_b32 m0, s17
	ds_read_b128 v[178:181], v144 offset:49152
	ds_read_b128 v[182:185], v144 offset:50176
	ds_read_b128 v[186:189], v144 offset:51200
	ds_read_b128 v[190:193], v144 offset:52224
	ds_read_b128 v[208:211], v144 offset:53248
	ds_read_b128 v[212:215], v144 offset:54272
	ds_read_b128 v[216:219], v144 offset:55296
	ds_read_b128 v[220:223], v144 offset:56320
	global_load_lds_dwordx4 v[224:225], off
	v_lshl_add_u64 v[224:225], v[228:229], 0, s[24:25]
	s_add_i32 m0, s17, 0x2000
	s_add_i32 s17, s28, s55
	global_load_lds_dwordx4 v[224:225], off
	v_lshl_add_u64 v[224:225], v[230:231], 0, s[24:25]
	s_mov_b32 m0, s17
	s_nop 0
	global_load_lds_dwordx4 v[224:225], off
	v_lshl_add_u64 v[224:225], v[232:233], 0, s[24:25]
	s_add_i32 m0, s17, 0x2000
	s_nop 0
	global_load_lds_dwordx4 v[224:225], off
	v_lshl_add_u64 v[224:225], v[234:235], 0, s[24:25]
	s_mov_b32 m0, s69
	s_nop 0
	global_load_lds_dwordx4 v[224:225], off
	v_lshl_add_u64 v[224:225], v[236:237], 0, s[24:25]
	s_mov_b32 m0, s70
	s_nop 0
	global_load_lds_dwordx4 v[224:225], off
	s_waitcnt vmcnt(8)
	s_waitcnt lgkmcnt(0)
	s_barrier
	s_setprio 1
	v_mfma_f32_16x16x32_bf16 v[62:65], v[146:149], v[178:181], v[62:65]
	v_mfma_f32_16x16x32_bf16 v[58:61], v[154:157], v[178:181], v[58:61]
	v_mfma_f32_16x16x32_bf16 v[46:49], v[146:149], v[186:189], v[46:49]
	v_mfma_f32_16x16x32_bf16 v[42:45], v[154:157], v[186:189], v[42:45]
	v_mfma_f32_16x16x32_bf16 v[30:33], v[146:149], v[208:211], v[30:33]
	v_mfma_f32_16x16x32_bf16 v[26:29], v[154:157], v[208:211], v[26:29]
	v_mfma_f32_16x16x32_bf16 v[14:17], v[146:149], v[216:219], v[14:17]
	v_mfma_f32_16x16x32_bf16 v[10:13], v[154:157], v[216:219], v[10:13]
	v_mfma_f32_16x16x32_bf16 v[62:65], v[150:153], v[182:185], v[62:65]
	v_mfma_f32_16x16x32_bf16 v[58:61], v[158:161], v[182:185], v[58:61]
	v_mfma_f32_16x16x32_bf16 v[46:49], v[150:153], v[190:193], v[46:49]
	v_mfma_f32_16x16x32_bf16 v[42:45], v[158:161], v[190:193], v[42:45]
	v_mfma_f32_16x16x32_bf16 v[30:33], v[150:153], v[212:215], v[30:33]
	v_mfma_f32_16x16x32_bf16 v[26:29], v[158:161], v[212:215], v[26:29]
	v_mfma_f32_16x16x32_bf16 v[14:17], v[150:153], v[220:223], v[14:17]
	v_mfma_f32_16x16x32_bf16 v[10:13], v[158:161], v[220:223], v[10:13]
	s_setprio 0
	s_setprio 1
	v_mfma_f32_16x16x32_bf16 v[54:57], v[162:165], v[178:181], v[54:57]
	v_mfma_f32_16x16x32_bf16 v[50:53], v[170:173], v[178:181], v[50:53]
	v_mfma_f32_16x16x32_bf16 v[38:41], v[162:165], v[186:189], v[38:41]
	v_mfma_f32_16x16x32_bf16 v[34:37], v[170:173], v[186:189], v[34:37]
	v_mfma_f32_16x16x32_bf16 v[22:25], v[162:165], v[208:211], v[22:25]
	v_mfma_f32_16x16x32_bf16 v[18:21], v[170:173], v[208:211], v[18:21]
	v_mfma_f32_16x16x32_bf16 v[6:9], v[162:165], v[216:219], v[6:9]
	v_mfma_f32_16x16x32_bf16 v[2:5], v[170:173], v[216:219], v[2:5]
	v_mfma_f32_16x16x32_bf16 v[54:57], v[166:169], v[182:185], v[54:57]
	v_mfma_f32_16x16x32_bf16 v[50:53], v[174:177], v[182:185], v[50:53]
	v_mfma_f32_16x16x32_bf16 v[38:41], v[166:169], v[190:193], v[38:41]
	v_mfma_f32_16x16x32_bf16 v[34:37], v[174:177], v[190:193], v[34:37]
	v_mfma_f32_16x16x32_bf16 v[22:25], v[166:169], v[212:215], v[22:25]
	v_mfma_f32_16x16x32_bf16 v[18:21], v[174:177], v[212:215], v[18:21]
	v_mfma_f32_16x16x32_bf16 v[6:9], v[166:169], v[220:223], v[6:9]
	v_mfma_f32_16x16x32_bf16 v[2:5], v[174:177], v[220:223], v[2:5]
	s_setprio 0
	s_barrier
	s_add_u32 s34, s34, 0x100
	s_addc_u32 s35, s35, 0
	s_add_u32 s4, s4, 0x100
	s_addc_u32 s16, s16, 0
	s_cmp_ge_i32 s22, s66
	s_mov_b32 s17, s22
	s_cbranch_scc0 .LBB0_544

; #define PG8_STAGE(bufoff, gbase, voff) do { _Pragma("unroll") for (int _i = 0; _i < 2; ++_i) \
;         __builtin_amdgcn_global_load_lds((const unsigned*)((const char*)(gbase) + (voff)[_i]), (PG8_LAS unsigned*)(lds + (bufoff) + ldsw + _i * 8192), 16, 0, 0); } while (0)
; #define PG8_LDA(dst, b, h) do { _Pragma("unroll") for (int m = 0; m < 4; ++m) _Pragma("unroll") for (int k = 0; k < 2; ++k) dst[m][k] = *(const PG8_LAS bf16x8*)(lds + PG8_SA(b, h) + aoff + m * 2048 + k * 1024); } while (0)
; #define PG8_LDB(dst, b, h) do { _Pragma("unroll") for (int n = 0; n < 2; ++n) _Pragma("unroll") for (int k = 0; k < 2; ++k) dst[n][k] = *(const PG8_LAS bf16x8*)(lds + PG8_SB(b, h) + boff + n * 2048 + k * 1024); } while (0)
; #define PG8_MMA(ai, bj, At, Bt) do { __builtin_amdgcn_s_setprio(1); _Pragma("unroll") for (int m = 0; m < 4; ++m) _Pragma("unroll") for (int n = 0; n < 2; ++n) _Pragma("unroll") for (int k = 0; k < 2; ++k) \
;         acc[ai][bj][m][n] = __builtin_amdgcn_mfma_f32_16x16x32_bf16(Bt[n][k], At[m][k], acc[ai][bj][m][n], 0, 0, 0); __builtin_amdgcn_s_setprio(0); } while (0)
; #define PG8_WAIT_V(n) asm volatile("s_waitcnt vmcnt(" #n ")" ::: "memory")
; #define PG8_WAIT_L(n) asm volatile("s_waitcnt lgkmcnt(" #n ")" ::: "memory")
; #define PG8_BAR __builtin_amdgcn_s_barrier()
; #define PG8_SCHED __builtin_amdgcn_sched_barrier(0)
; template <class Epi, class Sched, bool ALIGN_EPI = false, bool SP2 = false>
; __device__ __forceinline__ void gemm_phase(PG8_LAS unsigned char* lds, const Gemm g, const Sched& S, const Epi& E) {
;     ...
;             const bool last = (t == nt - 2);
;             const char* a1 = cA + (size_t)(t + 1) * kstep;
;             const char* a2 = last ? nA : cA + (size_t)(t + 2) * kstep; const char* b2 = last ? nB : cB + (size_t)(t + 2) * kstep;
;             const char* a3 = a2 + kstep; const char* b3 = b2 + kstep;
;             if (last && has_next) S.a_ready(nxt);
;             if constexpr (SP2) {
;             PG8_LDB(B0, 0, 0); PG8_LDB(B1, 0, 1); PG8_SCHED; PG8_LDA(At, 0, 0); PG8_STAGE(PG8_SA(1, 1), a1 + hstep, voffA);
;             PG8_WAIT_V(8); PG8_WAIT_L(0); PG8_BAR; PG8_MMA(0, 0, At, B0); PG8_MMA(0, 1, At, B1); PG8_BAR; PG8_SCHED;
;             PG8_LDA(At, 0, 1); PG8_STAGE(PG8_SB(0, 0), b2, voffB); PG8_STAGE(PG8_SB(0, 1), b2 + hstep, voffB); PG8_STAGE(PG8_SA(0, 0), a2, voffA);
.LBB0_876:
	s_add_i32 s22, s17, 2
	s_add_u32 s28, s34, 0x80
	s_addc_u32 s30, s35, 0
	s_add_i32 s33, 0, 0x10000
	s_cmp_eq_u32 s67, s17
	s_cselect_b32 s37, s3, s30
	s_cselect_b32 s36, s2, s28
	v_add_u32_e32 v149, s33, v146
	s_cselect_b32 s31, s55, s16
	s_cselect_b32 s30, s54, s4
	s_add_i32 s17, 0, 0x14000
	ds_read_b128 v[142:145], v149
	ds_read_b128 v[150:153], v149 offset:1024
	ds_read_b128 v[154:157], v149 offset:2048
	ds_read_b128 v[158:161], v149 offset:3072
	v_add_u32_e32 v149, s17, v146
	ds_read_b128 v[162:165], v149
	ds_read_b128 v[166:169], v149 offset:1024
	ds_read_b128 v[170:173], v149 offset:2048
	ds_read_b128 v[174:177], v149 offset:3072
	v_lshl_add_u64 v[224:225], s[34:35], 0, v[138:139]
	s_add_i32 m0, s60, 0xc000
	ds_read_b128 v[178:181], v148
	ds_read_b128 v[182:185], v148 offset:1024
	ds_read_b128 v[186:189], v148 offset:2048
	ds_read_b128 v[190:193], v148 offset:3072
	ds_read_b128 v[208:211], v148 offset:4096
	ds_read_b128 v[212:215], v148 offset:5120
	ds_read_b128 v[216:219], v148 offset:6144
	ds_read_b128 v[220:223], v148 offset:7168
	global_load_lds_dwordx4 v[224:225], off
	v_lshl_add_u64 v[224:225], s[34:35], 0, v[140:141]
	s_add_i32 m0, s60, 0xe000
	s_nop 0
	global_load_lds_dwordx4 v[224:225], off
	s_waitcnt vmcnt(8)
	s_waitcnt lgkmcnt(0)
	s_barrier
	s_setprio 1
	v_mfma_f32_16x16x32_bf16 v[128:131], v[142:145], v[178:181], v[128:131]
	v_mfma_f32_16x16x32_bf16 v[124:127], v[154:157], v[178:181], v[124:127]
	v_mfma_f32_16x16x32_bf16 v[112:115], v[142:145], v[186:189], v[112:115]
	v_mfma_f32_16x16x32_bf16 v[108:111], v[154:157], v[186:189], v[108:111]
	v_mfma_f32_16x16x32_bf16 v[94:97], v[142:145], v[208:211], v[94:97]
	v_mfma_f32_16x16x32_bf16 v[90:93], v[154:157], v[208:211], v[90:93]
	v_mfma_f32_16x16x32_bf16 v[78:81], v[142:145], v[216:219], v[78:81]
	v_mfma_f32_16x16x32_bf16 v[74:77], v[154:157], v[216:219], v[74:77]
	v_mfma_f32_16x16x32_bf16 v[128:131], v[150:153], v[182:185], v[128:131]
	v_mfma_f32_16x16x32_bf16 v[124:127], v[158:161], v[182:185], v[124:127]
	v_mfma_f32_16x16x32_bf16 v[112:115], v[150:153], v[190:193], v[112:115]
	v_mfma_f32_16x16x32_bf16 v[108:111], v[158:161], v[190:193], v[108:111]
	v_mfma_f32_16x16x32_bf16 v[94:97], v[150:153], v[212:215], v[94:97]
	v_mfma_f32_16x16x32_bf16 v[90:93], v[158:161], v[212:215], v[90:93]
	v_mfma_f32_16x16x32_bf16 v[78:81], v[150:153], v[220:223], v[78:81]
	v_mfma_f32_16x16x32_bf16 v[74:77], v[158:161], v[220:223], v[74:77]
	s_setprio 0
	s_setprio 1
	v_mfma_f32_16x16x32_bf16 v[120:123], v[162:165], v[178:181], v[120:123]
	v_mfma_f32_16x16x32_bf16 v[116:119], v[170:173], v[178:181], v[116:119]
	v_mfma_f32_16x16x32_bf16 v[104:107], v[162:165], v[186:189], v[104:107]
	v_mfma_f32_16x16x32_bf16 v[100:103], v[170:173], v[186:189], v[100:103]
	v_mfma_f32_16x16x32_bf16 v[86:89], v[162:165], v[208:211], v[86:89]
	v_mfma_f32_16x16x32_bf16 v[82:85], v[170:173], v[208:211], v[82:85]
	v_mfma_f32_16x16x32_bf16 v[70:73], v[162:165], v[216:219], v[70:73]
	v_mfma_f32_16x16x32_bf16 v[66:69], v[170:173], v[216:219], v[66:69]
	v_mfma_f32_16x16x32_bf16 v[120:123], v[166:169], v[182:185], v[120:123]
	v_mfma_f32_16x16x32_bf16 v[116:119], v[174:177], v[182:185], v[116:119]
	v_mfma_f32_16x16x32_bf16 v[104:107], v[166:169], v[190:193], v[104:107]
	v_mfma_f32_16x16x32_bf16 v[100:103], v[174:177], v[190:193], v[100:103]
	v_mfma_f32_16x16x32_bf16 v[86:89], v[166:169], v[212:215], v[86:89]
	v_mfma_f32_16x16x32_bf16 v[82:85], v[174:177], v[212:215], v[82:85]
	v_mfma_f32_16x16x32_bf16 v[70:73], v[166:169], v[220:223], v[70:73]
	v_mfma_f32_16x16x32_bf16 v[66:69], v[174:177], v[220:223], v[66:69]
	s_setprio 0
	s_barrier
	s_add_i32 s28, s33, s59
	v_lshl_add_u64 v[224:225], s[30:31], 0, v[98:99]
	s_mov_b32 m0, s28
	ds_read_b128 v[178:181], v148 offset:16384
	ds_read_b128 v[182:185], v148 offset:17408
	ds_read_b128 v[186:189], v148 offset:18432
	ds_read_b128 v[190:193], v148 offset:19456
	ds_read_b128 v[208:211], v148 offset:20480
	ds_read_b128 v[212:215], v148 offset:21504
	ds_read_b128 v[216:219], v148 offset:22528
	ds_read_b128 v[220:223], v148 offset:23552
	global_load_lds_dwordx4 v[224:225], off
	s_add_i32 m0, s28, 0x2000
	v_lshl_add_u64 v[228:229], s[30:31], 0, v[136:137]
	s_add_u32 s30, s30, s8
	s_addc_u32 s31, s31, s9
	s_add_i32 s17, s17, s59
	global_load_lds_dwordx4 v[228:229], off
	v_lshl_add_u64 v[230:231], s[30:31], 0, v[98:99]
	s_mov_b32 m0, s17
	v_lshl_add_u64 v[232:233], s[30:31], 0, v[136:137]
	global_load_lds_dwordx4 v[230:231], off
	s_add_i32 m0, s17, 0x2000
	v_lshl_add_u64 v[234:235], s[36:37], 0, v[132:133]
	global_load_lds_dwordx4 v[232:233], off
	s_mov_b32 m0, s60
	v_lshl_add_u64 v[236:237], s[36:37], 0, v[134:135]
	global_load_lds_dwordx4 v[234:235], off
	s_mov_b32 m0, s61
	s_nop 0
	global_load_lds_dwordx4 v[236:237], off
	s_waitcnt vmcnt(8)
	s_waitcnt lgkmcnt(0)
	s_barrier
; #define PG8_STAGE(bufoff, gbase, voff) do { _Pragma("unroll") for (int _i = 0; _i < 2; ++_i) \
;         __builtin_amdgcn_global_load_lds((const unsigned*)((const char*)(gbase) + (voff)[_i]), (PG8_LAS unsigned*)(lds + (bufoff) + ldsw + _i * 8192), 16, 0, 0); } while (0)
; #define PG8_LDA(dst, b, h) do { _Pragma("unroll") for (int m = 0; m < 4; ++m) _Pragma("unroll") for (int k = 0; k < 2; ++k) dst[m][k] = *(const PG8_LAS bf16x8*)(lds + PG8_SA(b, h) + aoff + m * 2048 + k * 1024); } while (0)
; #define PG8_LDB(dst, b, h) do { _Pragma("unroll") for (int n = 0; n < 2; ++n) _Pragma("unroll") for (int k = 0; k < 2; ++k) dst[n][k] = *(const PG8_LAS bf16x8*)(lds + PG8_SB(b, h) + boff + n * 2048 + k * 1024); } while (0)
; #define PG8_MMA(ai, bj, At, Bt) do { __builtin_amdgcn_s_setprio(1); _Pragma("unroll") for (int m = 0; m < 4; ++m) _Pragma("unroll") for (int n = 0; n < 2; ++n) _Pragma("unroll") for (int k = 0; k < 2; ++k) \
;         acc[ai][bj][m][n] = __builtin_amdgcn_mfma_f32_16x16x32_bf16(Bt[n][k], At[m][k], acc[ai][bj][m][n], 0, 0, 0); __builtin_amdgcn_s_setprio(0); } while (0)
; #define PG8_WAIT_V(n) asm volatile("s_waitcnt vmcnt(" #n ")" ::: "memory")
; #define PG8_WAIT_L(n) asm volatile("s_waitcnt lgkmcnt(" #n ")" ::: "memory")
; #define PG8_BAR __builtin_amdgcn_s_barrier()
; #define PG8_SCHED __builtin_amdgcn_sched_barrier(0)
; template <class Epi, class Sched, bool ALIGN_EPI = false, bool SP2 = false>
; __device__ __forceinline__ void gemm_phase(PG8_LAS unsigned char* lds, const Gemm g, const Sched& S, const Epi& E) {
;     ...
;             PG8_WAIT_V(8); PG8_WAIT_L(0); PG8_BAR; PG8_MMA(1, 0, At, B0); PG8_MMA(1, 1, At, B1); PG8_BAR; PG8_SCHED;
;             PG8_LDB(B0, 1, 0); PG8_LDB(B1, 1, 1); PG8_SCHED; PG8_LDA(At, 1, 0); PG8_STAGE(PG8_SA(0, 1), a2 + hstep, voffA);
;             PG8_WAIT_V(8); PG8_WAIT_L(0); PG8_BAR; PG8_MMA(0, 0, At, B0); PG8_MMA(0, 1, At, B1); PG8_BAR; PG8_SCHED;
	s_setprio 1
	v_mfma_f32_16x16x32_bf16 v[62:65], v[142:145], v[178:181], v[62:65]
	v_mfma_f32_16x16x32_bf16 v[58:61], v[154:157], v[178:181], v[58:61]
	v_mfma_f32_16x16x32_bf16 v[46:49], v[142:145], v[186:189], v[46:49]
	v_mfma_f32_16x16x32_bf16 v[42:45], v[154:157], v[186:189], v[42:45]
	v_mfma_f32_16x16x32_bf16 v[30:33], v[142:145], v[208:211], v[30:33]
	v_mfma_f32_16x16x32_bf16 v[26:29], v[154:157], v[208:211], v[26:29]
	v_mfma_f32_16x16x32_bf16 v[14:17], v[142:145], v[216:219], v[14:17]
	v_mfma_f32_16x16x32_bf16 v[10:13], v[154:157], v[216:219], v[10:13]
	v_mfma_f32_16x16x32_bf16 v[62:65], v[150:153], v[182:185], v[62:65]
	v_mfma_f32_16x16x32_bf16 v[58:61], v[158:161], v[182:185], v[58:61]
	v_mfma_f32_16x16x32_bf16 v[46:49], v[150:153], v[190:193], v[46:49]
	v_mfma_f32_16x16x32_bf16 v[42:45], v[158:161], v[190:193], v[42:45]
	v_mfma_f32_16x16x32_bf16 v[30:33], v[150:153], v[212:215], v[30:33]
	v_mfma_f32_16x16x32_bf16 v[26:29], v[158:161], v[212:215], v[26:29]
	v_mfma_f32_16x16x32_bf16 v[14:17], v[150:153], v[220:223], v[14:17]
	v_mfma_f32_16x16x32_bf16 v[10:13], v[158:161], v[220:223], v[10:13]
	s_setprio 0
	s_setprio 1
	v_mfma_f32_16x16x32_bf16 v[54:57], v[162:165], v[178:181], v[54:57]
	v_mfma_f32_16x16x32_bf16 v[50:53], v[170:173], v[178:181], v[50:53]
	v_mfma_f32_16x16x32_bf16 v[38:41], v[162:165], v[186:189], v[38:41]
	v_mfma_f32_16x16x32_bf16 v[34:37], v[170:173], v[186:189], v[34:37]
	v_mfma_f32_16x16x32_bf16 v[22:25], v[162:165], v[208:211], v[22:25]
	v_mfma_f32_16x16x32_bf16 v[18:21], v[170:173], v[208:211], v[18:21]
	v_mfma_f32_16x16x32_bf16 v[6:9], v[162:165], v[216:219], v[6:9]
	v_mfma_f32_16x16x32_bf16 v[2:5], v[170:173], v[216:219], v[2:5]
	v_mfma_f32_16x16x32_bf16 v[54:57], v[166:169], v[182:185], v[54:57]
	v_mfma_f32_16x16x32_bf16 v[50:53], v[174:177], v[182:185], v[50:53]
	v_mfma_f32_16x16x32_bf16 v[38:41], v[166:169], v[190:193], v[38:41]
	v_mfma_f32_16x16x32_bf16 v[34:37], v[174:177], v[190:193], v[34:37]
	v_mfma_f32_16x16x32_bf16 v[22:25], v[166:169], v[212:215], v[22:25]
	v_mfma_f32_16x16x32_bf16 v[18:21], v[174:177], v[212:215], v[18:21]
	v_mfma_f32_16x16x32_bf16 v[6:9], v[166:169], v[220:223], v[6:9]
	v_mfma_f32_16x16x32_bf16 v[2:5], v[174:177], v[220:223], v[2:5]
	s_setprio 0
	s_barrier
	s_add_i32 s17, 0, 0x18000
	v_add_u32_e32 v149, s17, v146
	s_add_i32 s28, 0, 0x1c000
	ds_read_b128 v[142:145], v149
	ds_read_b128 v[150:153], v149 offset:1024
	ds_read_b128 v[154:157], v149 offset:2048
	ds_read_b128 v[158:161], v149 offset:3072
	v_add_u32_e32 v149, s28, v146
	ds_read_b128 v[162:165], v149
	ds_read_b128 v[166:169], v149 offset:1024
	ds_read_b128 v[170:173], v149 offset:2048
	ds_read_b128 v[174:177], v149 offset:3072
	s_add_u32 s30, s36, s8
	s_addc_u32 s31, s37, s9
	s_mov_b32 m0, s62
	v_lshl_add_u64 v[238:239], s[30:31], 0, v[132:133]
	ds_read_b128 v[178:181], v148 offset:32768
	ds_read_b128 v[182:185], v148 offset:33792
	ds_read_b128 v[186:189], v148 offset:34816
	ds_read_b128 v[190:193], v148 offset:35840
	ds_read_b128 v[208:211], v148 offset:36864
	ds_read_b128 v[212:215], v148 offset:37888
	ds_read_b128 v[216:219], v148 offset:38912
	ds_read_b128 v[220:223], v148 offset:39936
	global_load_lds_dwordx4 v[238:239], off
	v_lshl_add_u64 v[238:239], s[30:31], 0, v[134:135]
	s_mov_b32 m0, s63
	s_nop 0
	global_load_lds_dwordx4 v[238:239], off
	s_waitcnt vmcnt(8)
	s_waitcnt lgkmcnt(0)
	s_barrier
	s_setprio 1
	v_mfma_f32_16x16x32_bf16 v[128:131], v[142:145], v[178:181], v[128:131]
	v_mfma_f32_16x16x32_bf16 v[124:127], v[154:157], v[178:181], v[124:127]
	v_mfma_f32_16x16x32_bf16 v[112:115], v[142:145], v[186:189], v[112:115]
	v_mfma_f32_16x16x32_bf16 v[108:111], v[154:157], v[186:189], v[108:111]
	v_mfma_f32_16x16x32_bf16 v[94:97], v[142:145], v[208:211], v[94:97]
	v_mfma_f32_16x16x32_bf16 v[90:93], v[154:157], v[208:211], v[90:93]
	v_mfma_f32_16x16x32_bf16 v[78:81], v[142:145], v[216:219], v[78:81]
	v_mfma_f32_16x16x32_bf16 v[74:77], v[154:157], v[216:219], v[74:77]
	v_mfma_f32_16x16x32_bf16 v[128:131], v[150:153], v[182:185], v[128:131]
	v_mfma_f32_16x16x32_bf16 v[124:127], v[158:161], v[182:185], v[124:127]
	v_mfma_f32_16x16x32_bf16 v[112:115], v[150:153], v[190:193], v[112:115]
	v_mfma_f32_16x16x32_bf16 v[108:111], v[158:161], v[190:193], v[108:111]
	v_mfma_f32_16x16x32_bf16 v[94:97], v[150:153], v[212:215], v[94:97]
	v_mfma_f32_16x16x32_bf16 v[90:93], v[158:161], v[212:215], v[90:93]
	v_mfma_f32_16x16x32_bf16 v[78:81], v[150:153], v[220:223], v[78:81]
	v_mfma_f32_16x16x32_bf16 v[74:77], v[158:161], v[220:223], v[74:77]
	s_setprio 0
	s_setprio 1
	v_mfma_f32_16x16x32_bf16 v[120:123], v[162:165], v[178:181], v[120:123]
	v_mfma_f32_16x16x32_bf16 v[116:119], v[170:173], v[178:181], v[116:119]
	v_mfma_f32_16x16x32_bf16 v[104:107], v[162:165], v[186:189], v[104:107]
	v_mfma_f32_16x16x32_bf16 v[100:103], v[170:173], v[186:189], v[100:103]
	v_mfma_f32_16x16x32_bf16 v[86:89], v[162:165], v[208:211], v[86:89]
	v_mfma_f32_16x16x32_bf16 v[82:85], v[170:173], v[208:211], v[82:85]
	v_mfma_f32_16x16x32_bf16 v[70:73], v[162:165], v[216:219], v[70:73]
	v_mfma_f32_16x16x32_bf16 v[66:69], v[170:173], v[216:219], v[66:69]
	v_mfma_f32_16x16x32_bf16 v[120:123], v[166:169], v[182:185], v[120:123]
	v_mfma_f32_16x16x32_bf16 v[116:119], v[174:177], v[182:185], v[116:119]
	v_mfma_f32_16x16x32_bf16 v[104:107], v[166:169], v[190:193], v[104:107]
	v_mfma_f32_16x16x32_bf16 v[100:103], v[174:177], v[190:193], v[100:103]
	v_mfma_f32_16x16x32_bf16 v[86:89], v[166:169], v[212:215], v[86:89]
	v_mfma_f32_16x16x32_bf16 v[82:85], v[174:177], v[212:215], v[82:85]
	v_mfma_f32_16x16x32_bf16 v[70:73], v[166:169], v[220:223], v[70:73]
	v_mfma_f32_16x16x32_bf16 v[66:69], v[174:177], v[220:223], v[66:69]
	s_setprio 0
	s_barrier
; #define PG8_STAGE(bufoff, gbase, voff) do { _Pragma("unroll") for (int _i = 0; _i < 2; ++_i) \
;         __builtin_amdgcn_global_load_lds((const unsigned*)((const char*)(gbase) + (voff)[_i]), (PG8_LAS unsigned*)(lds + (bufoff) + ldsw + _i * 8192), 16, 0, 0); } while (0)
; #define PG8_LDA(dst, b, h) do { _Pragma("unroll") for (int m = 0; m < 4; ++m) _Pragma("unroll") for (int k = 0; k < 2; ++k) dst[m][k] = *(const PG8_LAS bf16x8*)(lds + PG8_SA(b, h) + aoff + m * 2048 + k * 1024); } while (0)
; #define PG8_MMA(ai, bj, At, Bt) do { __builtin_amdgcn_s_setprio(1); _Pragma("unroll") for (int m = 0; m < 4; ++m) _Pragma("unroll") for (int n = 0; n < 2; ++n) _Pragma("unroll") for (int k = 0; k < 2; ++k) \
;         acc[ai][bj][m][n] = __builtin_amdgcn_mfma_f32_16x16x32_bf16(Bt[n][k], At[m][k], acc[ai][bj][m][n], 0, 0, 0); __builtin_amdgcn_s_setprio(0); } while (0)
; #define PG8_WAIT_V(n) asm volatile("s_waitcnt vmcnt(" #n ")" ::: "memory")
; #define PG8_WAIT_L(n) asm volatile("s_waitcnt lgkmcnt(" #n ")" ::: "memory")
; #define PG8_BAR __builtin_amdgcn_s_barrier()
; #define PG8_SCHED __builtin_amdgcn_sched_barrier(0)
; template <class Epi, class Sched, bool ALIGN_EPI = false, bool SP2 = false>
; __device__ __forceinline__ void gemm_phase(PG8_LAS unsigned char* lds, const Gemm g, const Sched& S, const Epi& E) {
;     ...
;         for (int t = 0; t < nt; t += 2) {
;     ...
;             PG8_LDA(At, 1, 1); PG8_STAGE(PG8_SB(1, 0), b3, voffB); PG8_STAGE(PG8_SB(1, 1), b3 + hstep, voffB); PG8_STAGE(PG8_SA(1, 0), a3, voffA);
;             PG8_WAIT_V(8); PG8_WAIT_L(0); PG8_BAR; PG8_MMA(1, 0, At, B0); PG8_MMA(1, 1, At, B1); PG8_BAR; PG8_SCHED;
	s_add_i32 s17, s17, s59
	v_lshl_add_u64 v[224:225], v[224:225], 0, s[24:25]
	s_mov_b32 m0, s17
	ds_read_b128 v[178:181], v148 offset:49152
	ds_read_b128 v[182:185], v148 offset:50176
	ds_read_b128 v[186:189], v148 offset:51200
	ds_read_b128 v[190:193], v148 offset:52224
	ds_read_b128 v[208:211], v148 offset:53248
	ds_read_b128 v[212:215], v148 offset:54272
	ds_read_b128 v[216:219], v148 offset:55296
	ds_read_b128 v[220:223], v148 offset:56320
	global_load_lds_dwordx4 v[224:225], off
	v_lshl_add_u64 v[224:225], v[228:229], 0, s[24:25]
	s_add_i32 m0, s17, 0x2000
	s_add_i32 s17, s28, s59
	global_load_lds_dwordx4 v[224:225], off
	v_lshl_add_u64 v[224:225], v[230:231], 0, s[24:25]
	s_mov_b32 m0, s17
	s_nop 0
	global_load_lds_dwordx4 v[224:225], off
	v_lshl_add_u64 v[224:225], v[232:233], 0, s[24:25]
	s_add_i32 m0, s17, 0x2000
	s_nop 0
	global_load_lds_dwordx4 v[224:225], off
	v_lshl_add_u64 v[224:225], v[234:235], 0, s[24:25]
	s_mov_b32 m0, s65
	s_nop 0
	global_load_lds_dwordx4 v[224:225], off
	v_lshl_add_u64 v[224:225], v[236:237], 0, s[24:25]
	s_mov_b32 m0, s66
	s_nop 0
	global_load_lds_dwordx4 v[224:225], off
	s_waitcnt vmcnt(8)
	s_waitcnt lgkmcnt(0)
	s_barrier
	s_setprio 1
	v_mfma_f32_16x16x32_bf16 v[62:65], v[142:145], v[178:181], v[62:65]
	v_mfma_f32_16x16x32_bf16 v[58:61], v[154:157], v[178:181], v[58:61]
	v_mfma_f32_16x16x32_bf16 v[46:49], v[142:145], v[186:189], v[46:49]
	v_mfma_f32_16x16x32_bf16 v[42:45], v[154:157], v[186:189], v[42:45]
	v_mfma_f32_16x16x32_bf16 v[30:33], v[142:145], v[208:211], v[30:33]
	v_mfma_f32_16x16x32_bf16 v[26:29], v[154:157], v[208:211], v[26:29]
	v_mfma_f32_16x16x32_bf16 v[14:17], v[142:145], v[216:219], v[14:17]
	v_mfma_f32_16x16x32_bf16 v[10:13], v[154:157], v[216:219], v[10:13]
	v_mfma_f32_16x16x32_bf16 v[62:65], v[150:153], v[182:185], v[62:65]
	v_mfma_f32_16x16x32_bf16 v[58:61], v[158:161], v[182:185], v[58:61]
	v_mfma_f32_16x16x32_bf16 v[46:49], v[150:153], v[190:193], v[46:49]
	v_mfma_f32_16x16x32_bf16 v[42:45], v[158:161], v[190:193], v[42:45]
	v_mfma_f32_16x16x32_bf16 v[30:33], v[150:153], v[212:215], v[30:33]
	v_mfma_f32_16x16x32_bf16 v[26:29], v[158:161], v[212:215], v[26:29]
	v_mfma_f32_16x16x32_bf16 v[14:17], v[150:153], v[220:223], v[14:17]
	v_mfma_f32_16x16x32_bf16 v[10:13], v[158:161], v[220:223], v[10:13]
	s_setprio 0
	s_setprio 1
	v_mfma_f32_16x16x32_bf16 v[54:57], v[162:165], v[178:181], v[54:57]
	v_mfma_f32_16x16x32_bf16 v[50:53], v[170:173], v[178:181], v[50:53]
	v_mfma_f32_16x16x32_bf16 v[38:41], v[162:165], v[186:189], v[38:41]
	v_mfma_f32_16x16x32_bf16 v[34:37], v[170:173], v[186:189], v[34:37]
	v_mfma_f32_16x16x32_bf16 v[22:25], v[162:165], v[208:211], v[22:25]
	v_mfma_f32_16x16x32_bf16 v[18:21], v[170:173], v[208:211], v[18:21]
	v_mfma_f32_16x16x32_bf16 v[6:9], v[162:165], v[216:219], v[6:9]
	v_mfma_f32_16x16x32_bf16 v[2:5], v[170:173], v[216:219], v[2:5]
	v_mfma_f32_16x16x32_bf16 v[54:57], v[166:169], v[182:185], v[54:57]
	v_mfma_f32_16x16x32_bf16 v[50:53], v[174:177], v[182:185], v[50:53]
	v_mfma_f32_16x16x32_bf16 v[38:41], v[166:169], v[190:193], v[38:41]
	v_mfma_f32_16x16x32_bf16 v[34:37], v[174:177], v[190:193], v[34:37]
	v_mfma_f32_16x16x32_bf16 v[22:25], v[166:169], v[212:215], v[22:25]
	v_mfma_f32_16x16x32_bf16 v[18:21], v[174:177], v[212:215], v[18:21]
	v_mfma_f32_16x16x32_bf16 v[6:9], v[166:169], v[220:223], v[6:9]
	v_mfma_f32_16x16x32_bf16 v[2:5], v[174:177], v[220:223], v[2:5]
	s_setprio 0
	s_barrier
	s_add_u32 s34, s34, 0x100
	s_addc_u32 s35, s35, 0
	s_add_u32 s4, s4, 0x100
	s_addc_u32 s16, s16, 0
	s_cmp_ge_i32 s22, s64
	s_mov_b32 s17, s22
	s_cbranch_scc0 .LBB0_876

; #define PG8_STAGE(bufoff, gbase, voff) do { _Pragma("unroll") for (int _i = 0; _i < 2; ++_i) \
;         __builtin_amdgcn_global_load_lds((const unsigned*)((const char*)(gbase) + (voff)[_i]), (PG8_LAS unsigned*)(lds + (bufoff) + ldsw + _i * 8192), 16, 0, 0); } while (0)
; #define PG8_LDA(dst, b, h) do { _Pragma("unroll") for (int m = 0; m < 4; ++m) _Pragma("unroll") for (int k = 0; k < 2; ++k) dst[m][k] = *(const PG8_LAS bf16x8*)(lds + PG8_SA(b, h) + aoff + m * 2048 + k * 1024); } while (0)
; #define PG8_LDB(dst, b, h) do { _Pragma("unroll") for (int n = 0; n < 2; ++n) _Pragma("unroll") for (int k = 0; k < 2; ++k) dst[n][k] = *(const PG8_LAS bf16x8*)(lds + PG8_SB(b, h) + boff + n * 2048 + k * 1024); } while (0)
; #define PG8_MMA(ai, bj, At, Bt) do { __builtin_amdgcn_s_setprio(1); _Pragma("unroll") for (int m = 0; m < 4; ++m) _Pragma("unroll") for (int n = 0; n < 2; ++n) _Pragma("unroll") for (int k = 0; k < 2; ++k) \
;         acc[ai][bj][m][n] = __builtin_amdgcn_mfma_f32_16x16x32_bf16(Bt[n][k], At[m][k], acc[ai][bj][m][n], 0, 0, 0); __builtin_amdgcn_s_setprio(0); } while (0)
; #define PG8_WAIT_V(n) asm volatile("s_waitcnt vmcnt(" #n ")" ::: "memory")
; #define PG8_WAIT_L(n) asm volatile("s_waitcnt lgkmcnt(" #n ")" ::: "memory")
; #define PG8_BAR __builtin_amdgcn_s_barrier()
; #define PG8_SCHED __builtin_amdgcn_sched_barrier(0)
; template <class Epi, class Sched, bool ALIGN_EPI = false, bool SP2 = false>
; __device__ __forceinline__ void gemm_phase(PG8_LAS unsigned char* lds, const Gemm g, const Sched& S, const Epi& E) {
;     ...
;             const bool last = (t == nt - 2);
;             const char* a1 = cA + (size_t)(t + 1) * kstep;
;             const char* a2 = last ? nA : cA + (size_t)(t + 2) * kstep; const char* b2 = last ? nB : cB + (size_t)(t + 2) * kstep;
;             const char* a3 = a2 + kstep; const char* b3 = b2 + kstep;
;             if (last && has_next) S.a_ready(nxt);
;             if constexpr (SP2) {
;             PG8_LDB(B0, 0, 0); PG8_LDB(B1, 0, 1); PG8_SCHED; PG8_LDA(At, 0, 0); PG8_STAGE(PG8_SA(1, 1), a1 + hstep, voffA);
;             PG8_WAIT_V(8); PG8_WAIT_L(0); PG8_BAR; PG8_MMA(0, 0, At, B0); PG8_MMA(0, 1, At, B1); PG8_BAR; PG8_SCHED;
;             PG8_LDA(At, 0, 1); PG8_STAGE(PG8_SB(0, 0), b2, voffB); PG8_STAGE(PG8_SB(0, 1), b2 + hstep, voffB); PG8_STAGE(PG8_SA(0, 0), a2, voffA);
.LBB0_967:
	s_add_i32 s22, s17, 2
	s_add_u32 s28, s34, 0x80
	s_addc_u32 s30, s35, 0
	s_add_i32 s33, 0, 0x10000
	s_cmp_eq_u32 s88, s17
	s_cselect_b32 s37, s3, s30
	s_cselect_b32 s36, s2, s28
	v_add_u32_e32 v98, s33, v145
	s_cselect_b32 s31, s59, s16
	s_cselect_b32 s30, s58, s4
	s_add_i32 s17, 0, 0x14000
	ds_read_b128 v[132:135], v98
	ds_read_b128 v[156:159], v98 offset:1024
	ds_read_b128 v[160:163], v98 offset:2048
	ds_read_b128 v[164:167], v98 offset:3072
	v_add_u32_e32 v98, s17, v145
	ds_read_b128 v[168:171], v98
	ds_read_b128 v[172:175], v98 offset:1024
	ds_read_b128 v[180:183], v98 offset:2048
	ds_read_b128 v[184:187], v98 offset:3072
	v_lshl_add_u64 v[176:177], s[34:35], 0, v[150:151]
	s_add_i32 m0, s70, 0xc000
	ds_read_b128 v[188:191], v178
	ds_read_b128 v[208:211], v178 offset:1024
	ds_read_b128 v[212:215], v178 offset:2048
	ds_read_b128 v[216:219], v178 offset:3072
	ds_read_b128 v[220:223], v178 offset:4096
	ds_read_b128 v[228:231], v178 offset:5120
	ds_read_b128 v[232:235], v178 offset:6144
	ds_read_b128 v[236:239], v178 offset:7168
	global_load_lds_dwordx4 v[176:177], off
	v_lshl_add_u64 v[176:177], s[34:35], 0, v[152:153]
	s_add_i32 m0, s70, 0xe000
	s_nop 0
	global_load_lds_dwordx4 v[176:177], off
	s_waitcnt vmcnt(8)
	s_waitcnt lgkmcnt(0)
	s_barrier
	s_setprio 1
	v_mfma_f32_16x16x32_bf16 v[128:131], v[132:135], v[188:191], v[128:131]
	v_mfma_f32_16x16x32_bf16 v[124:127], v[160:163], v[188:191], v[124:127]
	v_mfma_f32_16x16x32_bf16 v[112:115], v[132:135], v[212:215], v[112:115]
	v_mfma_f32_16x16x32_bf16 v[108:111], v[160:163], v[212:215], v[108:111]
	v_mfma_f32_16x16x32_bf16 v[94:97], v[132:135], v[220:223], v[94:97]
	v_mfma_f32_16x16x32_bf16 v[90:93], v[160:163], v[220:223], v[90:93]
	v_mfma_f32_16x16x32_bf16 v[78:81], v[132:135], v[232:235], v[78:81]
	v_mfma_f32_16x16x32_bf16 v[74:77], v[160:163], v[232:235], v[74:77]
	v_mfma_f32_16x16x32_bf16 v[128:131], v[156:159], v[208:211], v[128:131]
	v_mfma_f32_16x16x32_bf16 v[124:127], v[164:167], v[208:211], v[124:127]
	v_mfma_f32_16x16x32_bf16 v[112:115], v[156:159], v[216:219], v[112:115]
	v_mfma_f32_16x16x32_bf16 v[108:111], v[164:167], v[216:219], v[108:111]
	v_mfma_f32_16x16x32_bf16 v[94:97], v[156:159], v[228:231], v[94:97]
	v_mfma_f32_16x16x32_bf16 v[90:93], v[164:167], v[228:231], v[90:93]
	v_mfma_f32_16x16x32_bf16 v[78:81], v[156:159], v[236:239], v[78:81]
	v_mfma_f32_16x16x32_bf16 v[74:77], v[164:167], v[236:239], v[74:77]
	s_setprio 0
	s_setprio 1
	v_mfma_f32_16x16x32_bf16 v[120:123], v[168:171], v[188:191], v[120:123]
	v_mfma_f32_16x16x32_bf16 v[116:119], v[180:183], v[188:191], v[116:119]
	v_mfma_f32_16x16x32_bf16 v[104:107], v[168:171], v[212:215], v[104:107]
	v_mfma_f32_16x16x32_bf16 v[100:103], v[180:183], v[212:215], v[100:103]
	v_mfma_f32_16x16x32_bf16 v[86:89], v[168:171], v[220:223], v[86:89]
	v_mfma_f32_16x16x32_bf16 v[82:85], v[180:183], v[220:223], v[82:85]
	v_mfma_f32_16x16x32_bf16 v[70:73], v[168:171], v[232:235], v[70:73]
	v_mfma_f32_16x16x32_bf16 v[66:69], v[180:183], v[232:235], v[66:69]
	v_mfma_f32_16x16x32_bf16 v[120:123], v[172:175], v[208:211], v[120:123]
	v_mfma_f32_16x16x32_bf16 v[116:119], v[184:187], v[208:211], v[116:119]
	v_mfma_f32_16x16x32_bf16 v[104:107], v[172:175], v[216:219], v[104:107]
	v_mfma_f32_16x16x32_bf16 v[100:103], v[184:187], v[216:219], v[100:103]
	v_mfma_f32_16x16x32_bf16 v[86:89], v[172:175], v[228:231], v[86:89]
	v_mfma_f32_16x16x32_bf16 v[82:85], v[184:187], v[228:231], v[82:85]
	v_mfma_f32_16x16x32_bf16 v[70:73], v[172:175], v[236:239], v[70:73]
	v_mfma_f32_16x16x32_bf16 v[66:69], v[184:187], v[236:239], v[66:69]
	s_setprio 0
	s_barrier
	s_add_i32 s28, s33, s69
	v_lshl_add_u64 v[176:177], s[30:31], 0, v[138:139]
	s_mov_b32 m0, s28
	ds_read_b128 v[188:191], v178 offset:16384
	ds_read_b128 v[208:211], v178 offset:17408
	ds_read_b128 v[212:215], v178 offset:18432
	ds_read_b128 v[216:219], v178 offset:19456
	ds_read_b128 v[220:223], v178 offset:20480
	ds_read_b128 v[228:231], v178 offset:21504
	ds_read_b128 v[232:235], v178 offset:22528
	ds_read_b128 v[236:239], v178 offset:23552
	global_load_lds_dwordx4 v[176:177], off
	s_add_i32 m0, s28, 0x2000
	v_lshl_add_u64 v[192:193], s[30:31], 0, v[142:143]
	s_add_u32 s30, s30, s40
	s_addc_u32 s31, s31, s41
	s_add_i32 s17, s17, s69
	global_load_lds_dwordx4 v[192:193], off
	v_lshl_add_u64 v[224:225], s[30:31], 0, v[138:139]
	s_mov_b32 m0, s17
	v_lshl_add_u64 v[240:241], s[30:31], 0, v[142:143]
	global_load_lds_dwordx4 v[224:225], off
	s_add_i32 m0, s17, 0x2000
	v_lshl_add_u64 v[242:243], s[36:37], 0, v[136:137]
	global_load_lds_dwordx4 v[240:241], off
	s_mov_b32 m0, s70
	v_lshl_add_u64 v[244:245], s[36:37], 0, v[140:141]
	global_load_lds_dwordx4 v[242:243], off
	s_mov_b32 m0, s71
	s_nop 0
	global_load_lds_dwordx4 v[244:245], off
	s_waitcnt vmcnt(8)
	s_waitcnt lgkmcnt(0)
	s_barrier
; #define PG8_STAGE(bufoff, gbase, voff) do { _Pragma("unroll") for (int _i = 0; _i < 2; ++_i) \
;         __builtin_amdgcn_global_load_lds((const unsigned*)((const char*)(gbase) + (voff)[_i]), (PG8_LAS unsigned*)(lds + (bufoff) + ldsw + _i * 8192), 16, 0, 0); } while (0)
; #define PG8_LDA(dst, b, h) do { _Pragma("unroll") for (int m = 0; m < 4; ++m) _Pragma("unroll") for (int k = 0; k < 2; ++k) dst[m][k] = *(const PG8_LAS bf16x8*)(lds + PG8_SA(b, h) + aoff + m * 2048 + k * 1024); } while (0)
; #define PG8_LDB(dst, b, h) do { _Pragma("unroll") for (int n = 0; n < 2; ++n) _Pragma("unroll") for (int k = 0; k < 2; ++k) dst[n][k] = *(const PG8_LAS bf16x8*)(lds + PG8_SB(b, h) + boff + n * 2048 + k * 1024); } while (0)
; #define PG8_MMA(ai, bj, At, Bt) do { __builtin_amdgcn_s_setprio(1); _Pragma("unroll") for (int m = 0; m < 4; ++m) _Pragma("unroll") for (int n = 0; n < 2; ++n) _Pragma("unroll") for (int k = 0; k < 2; ++k) \
;         acc[ai][bj][m][n] = __builtin_amdgcn_mfma_f32_16x16x32_bf16(Bt[n][k], At[m][k], acc[ai][bj][m][n], 0, 0, 0); __builtin_amdgcn_s_setprio(0); } while (0)
; #define PG8_WAIT_V(n) asm volatile("s_waitcnt vmcnt(" #n ")" ::: "memory")
; #define PG8_WAIT_L(n) asm volatile("s_waitcnt lgkmcnt(" #n ")" ::: "memory")
; #define PG8_BAR __builtin_amdgcn_s_barrier()
; #define PG8_SCHED __builtin_amdgcn_sched_barrier(0)
; template <class Epi, class Sched, bool ALIGN_EPI = false, bool SP2 = false>
; __device__ __forceinline__ void gemm_phase(PG8_LAS unsigned char* lds, const Gemm g, const Sched& S, const Epi& E) {
;     ...
;             PG8_WAIT_V(8); PG8_WAIT_L(0); PG8_BAR; PG8_MMA(1, 0, At, B0); PG8_MMA(1, 1, At, B1); PG8_BAR; PG8_SCHED;
;             PG8_LDB(B0, 1, 0); PG8_LDB(B1, 1, 1); PG8_SCHED; PG8_LDA(At, 1, 0); PG8_STAGE(PG8_SA(0, 1), a2 + hstep, voffA);
;             PG8_WAIT_V(8); PG8_WAIT_L(0); PG8_BAR; PG8_MMA(0, 0, At, B0); PG8_MMA(0, 1, At, B1); PG8_BAR; PG8_SCHED;
	s_setprio 1
	v_mfma_f32_16x16x32_bf16 v[62:65], v[132:135], v[188:191], v[62:65]
	v_mfma_f32_16x16x32_bf16 v[58:61], v[160:163], v[188:191], v[58:61]
	v_mfma_f32_16x16x32_bf16 v[46:49], v[132:135], v[212:215], v[46:49]
	v_mfma_f32_16x16x32_bf16 v[42:45], v[160:163], v[212:215], v[42:45]
	v_mfma_f32_16x16x32_bf16 v[30:33], v[132:135], v[220:223], v[30:33]
	v_mfma_f32_16x16x32_bf16 v[26:29], v[160:163], v[220:223], v[26:29]
	v_mfma_f32_16x16x32_bf16 v[14:17], v[132:135], v[232:235], v[14:17]
	v_mfma_f32_16x16x32_bf16 v[10:13], v[160:163], v[232:235], v[10:13]
	v_mfma_f32_16x16x32_bf16 v[62:65], v[156:159], v[208:211], v[62:65]
	v_mfma_f32_16x16x32_bf16 v[58:61], v[164:167], v[208:211], v[58:61]
	v_mfma_f32_16x16x32_bf16 v[46:49], v[156:159], v[216:219], v[46:49]
	v_mfma_f32_16x16x32_bf16 v[42:45], v[164:167], v[216:219], v[42:45]
	v_mfma_f32_16x16x32_bf16 v[30:33], v[156:159], v[228:231], v[30:33]
	v_mfma_f32_16x16x32_bf16 v[26:29], v[164:167], v[228:231], v[26:29]
	v_mfma_f32_16x16x32_bf16 v[14:17], v[156:159], v[236:239], v[14:17]
	v_mfma_f32_16x16x32_bf16 v[10:13], v[164:167], v[236:239], v[10:13]
	s_setprio 0
	s_setprio 1
	v_mfma_f32_16x16x32_bf16 v[54:57], v[168:171], v[188:191], v[54:57]
	v_mfma_f32_16x16x32_bf16 v[50:53], v[180:183], v[188:191], v[50:53]
	v_mfma_f32_16x16x32_bf16 v[38:41], v[168:171], v[212:215], v[38:41]
	v_mfma_f32_16x16x32_bf16 v[34:37], v[180:183], v[212:215], v[34:37]
	v_mfma_f32_16x16x32_bf16 v[22:25], v[168:171], v[220:223], v[22:25]
	v_mfma_f32_16x16x32_bf16 v[18:21], v[180:183], v[220:223], v[18:21]
	v_mfma_f32_16x16x32_bf16 v[6:9], v[168:171], v[232:235], v[6:9]
	v_mfma_f32_16x16x32_bf16 v[2:5], v[180:183], v[232:235], v[2:5]
	v_mfma_f32_16x16x32_bf16 v[54:57], v[172:175], v[208:211], v[54:57]
	v_mfma_f32_16x16x32_bf16 v[50:53], v[184:187], v[208:211], v[50:53]
	v_mfma_f32_16x16x32_bf16 v[38:41], v[172:175], v[216:219], v[38:41]
	v_mfma_f32_16x16x32_bf16 v[34:37], v[184:187], v[216:219], v[34:37]
	v_mfma_f32_16x16x32_bf16 v[22:25], v[172:175], v[228:231], v[22:25]
	v_mfma_f32_16x16x32_bf16 v[18:21], v[184:187], v[228:231], v[18:21]
	v_mfma_f32_16x16x32_bf16 v[6:9], v[172:175], v[236:239], v[6:9]
	v_mfma_f32_16x16x32_bf16 v[2:5], v[184:187], v[236:239], v[2:5]
	s_setprio 0
	s_barrier
	s_add_i32 s17, 0, 0x18000
	v_add_u32_e32 v98, s17, v145
	s_add_i32 s28, 0, 0x1c000
	ds_read_b128 v[132:135], v98
	ds_read_b128 v[156:159], v98 offset:1024
	ds_read_b128 v[160:163], v98 offset:2048
	ds_read_b128 v[164:167], v98 offset:3072
	v_add_u32_e32 v98, s28, v145
	ds_read_b128 v[168:171], v98
	ds_read_b128 v[172:175], v98 offset:1024
	ds_read_b128 v[180:183], v98 offset:2048
	ds_read_b128 v[184:187], v98 offset:3072
	s_add_u32 s30, s36, s40
	s_addc_u32 s31, s37, s41
	s_mov_b32 m0, s72
	v_lshl_add_u64 v[246:247], s[30:31], 0, v[136:137]
	ds_read_b128 v[188:191], v178 offset:32768
	ds_read_b128 v[208:211], v178 offset:33792
	ds_read_b128 v[212:215], v178 offset:34816
	ds_read_b128 v[216:219], v178 offset:35840
	ds_read_b128 v[220:223], v178 offset:36864
	ds_read_b128 v[228:231], v178 offset:37888
	ds_read_b128 v[232:235], v178 offset:38912
	ds_read_b128 v[236:239], v178 offset:39936
	global_load_lds_dwordx4 v[246:247], off
	v_lshl_add_u64 v[246:247], s[30:31], 0, v[140:141]
	s_mov_b32 m0, s73
	s_nop 0
	global_load_lds_dwordx4 v[246:247], off
	s_waitcnt vmcnt(8)
	s_waitcnt lgkmcnt(0)
	s_barrier
	s_setprio 1
	v_mfma_f32_16x16x32_bf16 v[128:131], v[132:135], v[188:191], v[128:131]
	v_mfma_f32_16x16x32_bf16 v[124:127], v[160:163], v[188:191], v[124:127]
	v_mfma_f32_16x16x32_bf16 v[112:115], v[132:135], v[212:215], v[112:115]
	v_mfma_f32_16x16x32_bf16 v[108:111], v[160:163], v[212:215], v[108:111]
	v_mfma_f32_16x16x32_bf16 v[94:97], v[132:135], v[220:223], v[94:97]
	v_mfma_f32_16x16x32_bf16 v[90:93], v[160:163], v[220:223], v[90:93]
	v_mfma_f32_16x16x32_bf16 v[78:81], v[132:135], v[232:235], v[78:81]
	v_mfma_f32_16x16x32_bf16 v[74:77], v[160:163], v[232:235], v[74:77]
	v_mfma_f32_16x16x32_bf16 v[128:131], v[156:159], v[208:211], v[128:131]
	v_mfma_f32_16x16x32_bf16 v[124:127], v[164:167], v[208:211], v[124:127]
	v_mfma_f32_16x16x32_bf16 v[112:115], v[156:159], v[216:219], v[112:115]
	v_mfma_f32_16x16x32_bf16 v[108:111], v[164:167], v[216:219], v[108:111]
	v_mfma_f32_16x16x32_bf16 v[94:97], v[156:159], v[228:231], v[94:97]
	v_mfma_f32_16x16x32_bf16 v[90:93], v[164:167], v[228:231], v[90:93]
	v_mfma_f32_16x16x32_bf16 v[78:81], v[156:159], v[236:239], v[78:81]
	v_mfma_f32_16x16x32_bf16 v[74:77], v[164:167], v[236:239], v[74:77]
	s_setprio 0
	s_setprio 1
	v_mfma_f32_16x16x32_bf16 v[120:123], v[168:171], v[188:191], v[120:123]
	v_mfma_f32_16x16x32_bf16 v[116:119], v[180:183], v[188:191], v[116:119]
	v_mfma_f32_16x16x32_bf16 v[104:107], v[168:171], v[212:215], v[104:107]
	v_mfma_f32_16x16x32_bf16 v[100:103], v[180:183], v[212:215], v[100:103]
	v_mfma_f32_16x16x32_bf16 v[86:89], v[168:171], v[220:223], v[86:89]
	v_mfma_f32_16x16x32_bf16 v[82:85], v[180:183], v[220:223], v[82:85]
	v_mfma_f32_16x16x32_bf16 v[70:73], v[168:171], v[232:235], v[70:73]
	v_mfma_f32_16x16x32_bf16 v[66:69], v[180:183], v[232:235], v[66:69]
	v_mfma_f32_16x16x32_bf16 v[120:123], v[172:175], v[208:211], v[120:123]
	v_mfma_f32_16x16x32_bf16 v[116:119], v[184:187], v[208:211], v[116:119]
	v_mfma_f32_16x16x32_bf16 v[104:107], v[172:175], v[216:219], v[104:107]
	v_mfma_f32_16x16x32_bf16 v[100:103], v[184:187], v[216:219], v[100:103]
	v_mfma_f32_16x16x32_bf16 v[86:89], v[172:175], v[228:231], v[86:89]
	v_mfma_f32_16x16x32_bf16 v[82:85], v[184:187], v[228:231], v[82:85]
	v_mfma_f32_16x16x32_bf16 v[70:73], v[172:175], v[236:239], v[70:73]
	v_mfma_f32_16x16x32_bf16 v[66:69], v[184:187], v[236:239], v[66:69]
	s_setprio 0
	s_barrier
; #define PG8_STAGE(bufoff, gbase, voff) do { _Pragma("unroll") for (int _i = 0; _i < 2; ++_i) \
;         __builtin_amdgcn_global_load_lds((const unsigned*)((const char*)(gbase) + (voff)[_i]), (PG8_LAS unsigned*)(lds + (bufoff) + ldsw + _i * 8192), 16, 0, 0); } while (0)
; #define PG8_LDA(dst, b, h) do { _Pragma("unroll") for (int m = 0; m < 4; ++m) _Pragma("unroll") for (int k = 0; k < 2; ++k) dst[m][k] = *(const PG8_LAS bf16x8*)(lds + PG8_SA(b, h) + aoff + m * 2048 + k * 1024); } while (0)
; #define PG8_MMA(ai, bj, At, Bt) do { __builtin_amdgcn_s_setprio(1); _Pragma("unroll") for (int m = 0; m < 4; ++m) _Pragma("unroll") for (int n = 0; n < 2; ++n) _Pragma("unroll") for (int k = 0; k < 2; ++k) \
;         acc[ai][bj][m][n] = __builtin_amdgcn_mfma_f32_16x16x32_bf16(Bt[n][k], At[m][k], acc[ai][bj][m][n], 0, 0, 0); __builtin_amdgcn_s_setprio(0); } while (0)
; #define PG8_WAIT_V(n) asm volatile("s_waitcnt vmcnt(" #n ")" ::: "memory")
; #define PG8_WAIT_L(n) asm volatile("s_waitcnt lgkmcnt(" #n ")" ::: "memory")
; #define PG8_BAR __builtin_amdgcn_s_barrier()
; #define PG8_SCHED __builtin_amdgcn_sched_barrier(0)
; template <class Epi, class Sched, bool ALIGN_EPI = false, bool SP2 = false>
; __device__ __forceinline__ void gemm_phase(PG8_LAS unsigned char* lds, const Gemm g, const Sched& S, const Epi& E) {
;     ...
;         for (int t = 0; t < nt; t += 2) {
;     ...
;             PG8_LDA(At, 1, 1); PG8_STAGE(PG8_SB(1, 0), b3, voffB); PG8_STAGE(PG8_SB(1, 1), b3 + hstep, voffB); PG8_STAGE(PG8_SA(1, 0), a3, voffA);
;             PG8_WAIT_V(8); PG8_WAIT_L(0); PG8_BAR; PG8_MMA(1, 0, At, B0); PG8_MMA(1, 1, At, B1); PG8_BAR; PG8_SCHED;
	s_add_i32 s17, s17, s69
	v_lshl_add_u64 v[176:177], v[176:177], 0, s[24:25]
	s_mov_b32 m0, s17
	ds_read_b128 v[188:191], v178 offset:49152
	ds_read_b128 v[208:211], v178 offset:50176
	ds_read_b128 v[212:215], v178 offset:51200
	ds_read_b128 v[216:219], v178 offset:52224
	ds_read_b128 v[220:223], v178 offset:53248
	ds_read_b128 v[228:231], v178 offset:54272
	ds_read_b128 v[232:235], v178 offset:55296
	ds_read_b128 v[236:239], v178 offset:56320
	global_load_lds_dwordx4 v[176:177], off
	v_lshl_add_u64 v[176:177], v[192:193], 0, s[24:25]
	s_add_i32 m0, s17, 0x2000
	s_add_i32 s17, s28, s69
	global_load_lds_dwordx4 v[176:177], off
	v_lshl_add_u64 v[176:177], v[224:225], 0, s[24:25]
	s_mov_b32 m0, s17
	s_nop 0
	global_load_lds_dwordx4 v[176:177], off
	v_lshl_add_u64 v[176:177], v[240:241], 0, s[24:25]
	s_add_i32 m0, s17, 0x2000
	s_nop 0
	global_load_lds_dwordx4 v[176:177], off
	v_lshl_add_u64 v[176:177], v[242:243], 0, s[24:25]
	s_mov_b32 m0, s86
	s_nop 0
	global_load_lds_dwordx4 v[176:177], off
	v_lshl_add_u64 v[176:177], v[244:245], 0, s[24:25]
	s_mov_b32 m0, s87
	s_nop 0
	global_load_lds_dwordx4 v[176:177], off
	s_waitcnt vmcnt(8)
	s_waitcnt lgkmcnt(0)
	s_barrier
	s_setprio 1
	v_mfma_f32_16x16x32_bf16 v[62:65], v[132:135], v[188:191], v[62:65]
	v_mfma_f32_16x16x32_bf16 v[58:61], v[160:163], v[188:191], v[58:61]
	v_mfma_f32_16x16x32_bf16 v[46:49], v[132:135], v[212:215], v[46:49]
	v_mfma_f32_16x16x32_bf16 v[42:45], v[160:163], v[212:215], v[42:45]
	v_mfma_f32_16x16x32_bf16 v[30:33], v[132:135], v[220:223], v[30:33]
	v_mfma_f32_16x16x32_bf16 v[26:29], v[160:163], v[220:223], v[26:29]
	v_mfma_f32_16x16x32_bf16 v[14:17], v[132:135], v[232:235], v[14:17]
	v_mfma_f32_16x16x32_bf16 v[10:13], v[160:163], v[232:235], v[10:13]
	v_mfma_f32_16x16x32_bf16 v[62:65], v[156:159], v[208:211], v[62:65]
	v_mfma_f32_16x16x32_bf16 v[58:61], v[164:167], v[208:211], v[58:61]
	v_mfma_f32_16x16x32_bf16 v[46:49], v[156:159], v[216:219], v[46:49]
	v_mfma_f32_16x16x32_bf16 v[42:45], v[164:167], v[216:219], v[42:45]
	v_mfma_f32_16x16x32_bf16 v[30:33], v[156:159], v[228:231], v[30:33]
	v_mfma_f32_16x16x32_bf16 v[26:29], v[164:167], v[228:231], v[26:29]
	v_mfma_f32_16x16x32_bf16 v[14:17], v[156:159], v[236:239], v[14:17]
	v_mfma_f32_16x16x32_bf16 v[10:13], v[164:167], v[236:239], v[10:13]
	s_setprio 0
	s_setprio 1
	v_mfma_f32_16x16x32_bf16 v[54:57], v[168:171], v[188:191], v[54:57]
	v_mfma_f32_16x16x32_bf16 v[50:53], v[180:183], v[188:191], v[50:53]
	v_mfma_f32_16x16x32_bf16 v[38:41], v[168:171], v[212:215], v[38:41]
	v_mfma_f32_16x16x32_bf16 v[34:37], v[180:183], v[212:215], v[34:37]
	v_mfma_f32_16x16x32_bf16 v[22:25], v[168:171], v[220:223], v[22:25]
	v_mfma_f32_16x16x32_bf16 v[18:21], v[180:183], v[220:223], v[18:21]
	v_mfma_f32_16x16x32_bf16 v[6:9], v[168:171], v[232:235], v[6:9]
	v_mfma_f32_16x16x32_bf16 v[2:5], v[180:183], v[232:235], v[2:5]
	v_mfma_f32_16x16x32_bf16 v[54:57], v[172:175], v[208:211], v[54:57]
	v_mfma_f32_16x16x32_bf16 v[50:53], v[184:187], v[208:211], v[50:53]
	v_mfma_f32_16x16x32_bf16 v[38:41], v[172:175], v[216:219], v[38:41]
	v_mfma_f32_16x16x32_bf16 v[34:37], v[184:187], v[216:219], v[34:37]
	v_mfma_f32_16x16x32_bf16 v[22:25], v[172:175], v[228:231], v[22:25]
	v_mfma_f32_16x16x32_bf16 v[18:21], v[184:187], v[228:231], v[18:21]
	v_mfma_f32_16x16x32_bf16 v[6:9], v[172:175], v[236:239], v[6:9]
	v_mfma_f32_16x16x32_bf16 v[2:5], v[184:187], v[236:239], v[2:5]
	s_setprio 0
	s_barrier
	s_add_u32 s34, s34, 0x100
	s_addc_u32 s35, s35, 0
	s_add_u32 s4, s4, 0x100
	s_addc_u32 s16, s16, 0
	s_cmp_ge_i32 s22, s84
	s_mov_b32 s17, s22
	s_cbranch_scc0 .LBB0_967

; #define PG8_STAGE(bufoff, gbase, voff) do { _Pragma("unroll") for (int _i = 0; _i < 2; ++_i) \
;         __builtin_amdgcn_global_load_lds((const unsigned*)((const char*)(gbase) + (voff)[_i]), (PG8_LAS unsigned*)(lds + (bufoff) + ldsw + _i * 8192), 16, 0, 0); } while (0)
; #define PG8_LDA(dst, b, h) do { _Pragma("unroll") for (int m = 0; m < 4; ++m) _Pragma("unroll") for (int k = 0; k < 2; ++k) dst[m][k] = *(const PG8_LAS bf16x8*)(lds + PG8_SA(b, h) + aoff + m * 2048 + k * 1024); } while (0)
; #define PG8_LDB(dst, b, h) do { _Pragma("unroll") for (int n = 0; n < 2; ++n) _Pragma("unroll") for (int k = 0; k < 2; ++k) dst[n][k] = *(const PG8_LAS bf16x8*)(lds + PG8_SB(b, h) + boff + n * 2048 + k * 1024); } while (0)
; #define PG8_MMA(ai, bj, At, Bt) do { __builtin_amdgcn_s_setprio(1); _Pragma("unroll") for (int m = 0; m < 4; ++m) _Pragma("unroll") for (int n = 0; n < 2; ++n) _Pragma("unroll") for (int k = 0; k < 2; ++k) \
;         acc[ai][bj][m][n] = __builtin_amdgcn_mfma_f32_16x16x32_bf16(Bt[n][k], At[m][k], acc[ai][bj][m][n], 0, 0, 0); __builtin_amdgcn_s_setprio(0); } while (0)
; #define PG8_WAIT_V(n) asm volatile("s_waitcnt vmcnt(" #n ")" ::: "memory")
; #define PG8_WAIT_L(n) asm volatile("s_waitcnt lgkmcnt(" #n ")" ::: "memory")
; #define PG8_BAR __builtin_amdgcn_s_barrier()
; #define PG8_SCHED __builtin_amdgcn_sched_barrier(0)
; template <class Epi, class Sched, bool ALIGN_EPI = false, bool SP2 = false>
; __device__ __forceinline__ void gemm_phase(PG8_LAS unsigned char* lds, const Gemm g, const Sched& S, const Epi& E) {
;     ...
;             const bool last = (t == nt - 2);
;             const char* a1 = cA + (size_t)(t + 1) * kstep;
;             const char* a2 = last ? nA : cA + (size_t)(t + 2) * kstep; const char* b2 = last ? nB : cB + (size_t)(t + 2) * kstep;
;             const char* a3 = a2 + kstep; const char* b3 = b2 + kstep;
;             if (last && has_next) S.a_ready(nxt);
;             if constexpr (SP2) {
;             PG8_LDB(B0, 0, 0); PG8_LDB(B1, 0, 1); PG8_SCHED; PG8_LDA(At, 0, 0); PG8_STAGE(PG8_SA(1, 1), a1 + hstep, voffA);
;             PG8_WAIT_V(8); PG8_WAIT_L(0); PG8_BAR; PG8_MMA(0, 0, At, B0); PG8_MMA(0, 1, At, B1); PG8_BAR; PG8_SCHED;
;             PG8_LDA(At, 0, 1); PG8_STAGE(PG8_SB(0, 0), b2, voffB); PG8_STAGE(PG8_SB(0, 1), b2 + hstep, voffB); PG8_STAGE(PG8_SA(0, 0), a2, voffA);
.LBB0_1052:
	s_add_i32 s22, s17, 2
	s_add_u32 s28, s2, 0x80
	s_addc_u32 s30, s3, 0
	s_add_i32 s33, 0, 0x10000
	s_cmp_eq_u32 s78, s17
	s_cselect_b32 s35, s55, s30
	s_cselect_b32 s34, s54, s28
	v_add_u32_e32 v98, s33, v166
	s_cselect_b32 s31, s57, s16
	s_cselect_b32 s30, s56, s4
	s_add_i32 s17, 0, 0x14000
	ds_read_b128 v[132:135], v98
	ds_read_b128 v[136:139], v98 offset:1024
	ds_read_b128 v[140:143], v98 offset:2048
	ds_read_b128 v[156:159], v98 offset:3072
	v_add_u32_e32 v98, s17, v166
	ds_read_b128 v[160:163], v98
	ds_read_b128 v[170:173], v98 offset:1024
	ds_read_b128 v[174:177], v98 offset:2048
	ds_read_b128 v[178:181], v98 offset:3072
	v_lshl_add_u64 v[164:165], s[2:3], 0, v[152:153]
	s_add_i32 m0, s72, 0xc000
	ds_read_b128 v[182:185], v168
	ds_read_b128 v[186:189], v168 offset:1024
	ds_read_b128 v[190:193], v168 offset:2048
	ds_read_b128 v[208:211], v168 offset:3072
	ds_read_b128 v[212:215], v168 offset:4096
	ds_read_b128 v[216:219], v168 offset:5120
	ds_read_b128 v[220:223], v168 offset:6144
	ds_read_b128 v[228:231], v168 offset:7168
	global_load_lds_dwordx4 v[164:165], off
	v_lshl_add_u64 v[164:165], s[2:3], 0, v[154:155]
	s_add_i32 m0, s72, 0xe000
	s_nop 0
	global_load_lds_dwordx4 v[164:165], off
	s_waitcnt vmcnt(8)
	s_waitcnt lgkmcnt(0)
	s_barrier
	s_setprio 1
	v_mfma_f32_16x16x32_bf16 v[128:131], v[132:135], v[182:185], v[128:131]
	v_mfma_f32_16x16x32_bf16 v[124:127], v[140:143], v[182:185], v[124:127]
	v_mfma_f32_16x16x32_bf16 v[120:123], v[132:135], v[190:193], v[120:123]
	v_mfma_f32_16x16x32_bf16 v[116:119], v[140:143], v[190:193], v[116:119]
	v_mfma_f32_16x16x32_bf16 v[112:115], v[132:135], v[212:215], v[112:115]
	v_mfma_f32_16x16x32_bf16 v[108:111], v[140:143], v[212:215], v[108:111]
	v_mfma_f32_16x16x32_bf16 v[104:107], v[132:135], v[220:223], v[104:107]
	v_mfma_f32_16x16x32_bf16 v[100:103], v[140:143], v[220:223], v[100:103]
	v_mfma_f32_16x16x32_bf16 v[128:131], v[136:139], v[186:189], v[128:131]
	v_mfma_f32_16x16x32_bf16 v[124:127], v[156:159], v[186:189], v[124:127]
	v_mfma_f32_16x16x32_bf16 v[120:123], v[136:139], v[208:211], v[120:123]
	v_mfma_f32_16x16x32_bf16 v[116:119], v[156:159], v[208:211], v[116:119]
	v_mfma_f32_16x16x32_bf16 v[112:115], v[136:139], v[216:219], v[112:115]
	v_mfma_f32_16x16x32_bf16 v[108:111], v[156:159], v[216:219], v[108:111]
	v_mfma_f32_16x16x32_bf16 v[104:107], v[136:139], v[228:231], v[104:107]
	v_mfma_f32_16x16x32_bf16 v[100:103], v[156:159], v[228:231], v[100:103]
	s_setprio 0
	s_setprio 1
	v_mfma_f32_16x16x32_bf16 v[62:65], v[160:163], v[182:185], v[62:65]
	v_mfma_f32_16x16x32_bf16 v[58:61], v[174:177], v[182:185], v[58:61]
	v_mfma_f32_16x16x32_bf16 v[54:57], v[160:163], v[190:193], v[54:57]
	v_mfma_f32_16x16x32_bf16 v[50:53], v[174:177], v[190:193], v[50:53]
	v_mfma_f32_16x16x32_bf16 v[46:49], v[160:163], v[212:215], v[46:49]
	v_mfma_f32_16x16x32_bf16 v[42:45], v[174:177], v[212:215], v[42:45]
	v_mfma_f32_16x16x32_bf16 v[38:41], v[160:163], v[220:223], v[38:41]
	v_mfma_f32_16x16x32_bf16 v[34:37], v[174:177], v[220:223], v[34:37]
	v_mfma_f32_16x16x32_bf16 v[62:65], v[170:173], v[186:189], v[62:65]
	v_mfma_f32_16x16x32_bf16 v[58:61], v[178:181], v[186:189], v[58:61]
	v_mfma_f32_16x16x32_bf16 v[54:57], v[170:173], v[208:211], v[54:57]
	v_mfma_f32_16x16x32_bf16 v[50:53], v[178:181], v[208:211], v[50:53]
	v_mfma_f32_16x16x32_bf16 v[46:49], v[170:173], v[216:219], v[46:49]
	v_mfma_f32_16x16x32_bf16 v[42:45], v[178:181], v[216:219], v[42:45]
	v_mfma_f32_16x16x32_bf16 v[38:41], v[170:173], v[228:231], v[38:41]
	v_mfma_f32_16x16x32_bf16 v[34:37], v[178:181], v[228:231], v[34:37]
	s_setprio 0
	s_barrier
	s_add_i32 s28, s33, s67
	v_lshl_add_u64 v[164:165], s[30:31], 0, v[146:147]
	s_mov_b32 m0, s28
	ds_read_b128 v[182:185], v168 offset:16384
	ds_read_b128 v[186:189], v168 offset:17408
	ds_read_b128 v[190:193], v168 offset:18432
	ds_read_b128 v[208:211], v168 offset:19456
	ds_read_b128 v[212:215], v168 offset:20480
	ds_read_b128 v[216:219], v168 offset:21504
	ds_read_b128 v[220:223], v168 offset:22528
	ds_read_b128 v[228:231], v168 offset:23552
	global_load_lds_dwordx4 v[164:165], off
	s_add_i32 m0, s28, 0x2000
	v_lshl_add_u64 v[224:225], s[30:31], 0, v[150:151]
	s_add_u32 s30, s30, s14
	s_addc_u32 s31, s31, s15
	s_add_i32 s17, s17, s67
	global_load_lds_dwordx4 v[224:225], off
	v_lshl_add_u64 v[232:233], s[30:31], 0, v[146:147]
	s_mov_b32 m0, s17
	v_lshl_add_u64 v[234:235], s[30:31], 0, v[150:151]
	global_load_lds_dwordx4 v[232:233], off
	s_add_i32 m0, s17, 0x2000
	v_lshl_add_u64 v[236:237], s[34:35], 0, v[144:145]
	global_load_lds_dwordx4 v[234:235], off
	s_mov_b32 m0, s72
	v_lshl_add_u64 v[238:239], s[34:35], 0, v[148:149]
	global_load_lds_dwordx4 v[236:237], off
	s_mov_b32 m0, s73
	s_nop 0
	global_load_lds_dwordx4 v[238:239], off
	s_waitcnt vmcnt(8)
	s_waitcnt lgkmcnt(0)
	s_barrier
; #define PG8_STAGE(bufoff, gbase, voff) do { _Pragma("unroll") for (int _i = 0; _i < 2; ++_i) \
;         __builtin_amdgcn_global_load_lds((const unsigned*)((const char*)(gbase) + (voff)[_i]), (PG8_LAS unsigned*)(lds + (bufoff) + ldsw + _i * 8192), 16, 0, 0); } while (0)
; #define PG8_LDA(dst, b, h) do { _Pragma("unroll") for (int m = 0; m < 4; ++m) _Pragma("unroll") for (int k = 0; k < 2; ++k) dst[m][k] = *(const PG8_LAS bf16x8*)(lds + PG8_SA(b, h) + aoff + m * 2048 + k * 1024); } while (0)
; #define PG8_LDB(dst, b, h) do { _Pragma("unroll") for (int n = 0; n < 2; ++n) _Pragma("unroll") for (int k = 0; k < 2; ++k) dst[n][k] = *(const PG8_LAS bf16x8*)(lds + PG8_SB(b, h) + boff + n * 2048 + k * 1024); } while (0)
; #define PG8_MMA(ai, bj, At, Bt) do { __builtin_amdgcn_s_setprio(1); _Pragma("unroll") for (int m = 0; m < 4; ++m) _Pragma("unroll") for (int n = 0; n < 2; ++n) _Pragma("unroll") for (int k = 0; k < 2; ++k) \
;         acc[ai][bj][m][n] = __builtin_amdgcn_mfma_f32_16x16x32_bf16(Bt[n][k], At[m][k], acc[ai][bj][m][n], 0, 0, 0); __builtin_amdgcn_s_setprio(0); } while (0)
; #define PG8_WAIT_V(n) asm volatile("s_waitcnt vmcnt(" #n ")" ::: "memory")
; #define PG8_WAIT_L(n) asm volatile("s_waitcnt lgkmcnt(" #n ")" ::: "memory")
; #define PG8_BAR __builtin_amdgcn_s_barrier()
; #define PG8_SCHED __builtin_amdgcn_sched_barrier(0)
; template <class Epi, class Sched, bool ALIGN_EPI = false, bool SP2 = false>
; __device__ __forceinline__ void gemm_phase(PG8_LAS unsigned char* lds, const Gemm g, const Sched& S, const Epi& E) {
;     ...
;             PG8_WAIT_V(8); PG8_WAIT_L(0); PG8_BAR; PG8_MMA(1, 0, At, B0); PG8_MMA(1, 1, At, B1); PG8_BAR; PG8_SCHED;
;             PG8_LDB(B0, 1, 0); PG8_LDB(B1, 1, 1); PG8_SCHED; PG8_LDA(At, 1, 0); PG8_STAGE(PG8_SA(0, 1), a2 + hstep, voffA);
;             PG8_WAIT_V(8); PG8_WAIT_L(0); PG8_BAR; PG8_MMA(0, 0, At, B0); PG8_MMA(0, 1, At, B1); PG8_BAR; PG8_SCHED;
	s_setprio 1
	v_mfma_f32_16x16x32_bf16 v[94:97], v[132:135], v[182:185], v[94:97]
	v_mfma_f32_16x16x32_bf16 v[90:93], v[140:143], v[182:185], v[90:93]
	v_mfma_f32_16x16x32_bf16 v[86:89], v[132:135], v[190:193], v[86:89]
	v_mfma_f32_16x16x32_bf16 v[82:85], v[140:143], v[190:193], v[82:85]
	v_mfma_f32_16x16x32_bf16 v[78:81], v[132:135], v[212:215], v[78:81]
	v_mfma_f32_16x16x32_bf16 v[74:77], v[140:143], v[212:215], v[74:77]
	v_mfma_f32_16x16x32_bf16 v[70:73], v[132:135], v[220:223], v[70:73]
	v_mfma_f32_16x16x32_bf16 v[66:69], v[140:143], v[220:223], v[66:69]
	v_mfma_f32_16x16x32_bf16 v[94:97], v[136:139], v[186:189], v[94:97]
	v_mfma_f32_16x16x32_bf16 v[90:93], v[156:159], v[186:189], v[90:93]
	v_mfma_f32_16x16x32_bf16 v[86:89], v[136:139], v[208:211], v[86:89]
	v_mfma_f32_16x16x32_bf16 v[82:85], v[156:159], v[208:211], v[82:85]
	v_mfma_f32_16x16x32_bf16 v[78:81], v[136:139], v[216:219], v[78:81]
	v_mfma_f32_16x16x32_bf16 v[74:77], v[156:159], v[216:219], v[74:77]
	v_mfma_f32_16x16x32_bf16 v[70:73], v[136:139], v[228:231], v[70:73]
	v_mfma_f32_16x16x32_bf16 v[66:69], v[156:159], v[228:231], v[66:69]
	s_setprio 0
	s_setprio 1
	v_mfma_f32_16x16x32_bf16 v[30:33], v[160:163], v[182:185], v[30:33]
	v_mfma_f32_16x16x32_bf16 v[26:29], v[174:177], v[182:185], v[26:29]
	v_mfma_f32_16x16x32_bf16 v[22:25], v[160:163], v[190:193], v[22:25]
	v_mfma_f32_16x16x32_bf16 v[18:21], v[174:177], v[190:193], v[18:21]
	v_mfma_f32_16x16x32_bf16 v[14:17], v[160:163], v[212:215], v[14:17]
	v_mfma_f32_16x16x32_bf16 v[10:13], v[174:177], v[212:215], v[10:13]
	v_mfma_f32_16x16x32_bf16 v[6:9], v[160:163], v[220:223], v[6:9]
	v_mfma_f32_16x16x32_bf16 v[2:5], v[174:177], v[220:223], v[2:5]
	v_mfma_f32_16x16x32_bf16 v[30:33], v[170:173], v[186:189], v[30:33]
	v_mfma_f32_16x16x32_bf16 v[26:29], v[178:181], v[186:189], v[26:29]
	v_mfma_f32_16x16x32_bf16 v[22:25], v[170:173], v[208:211], v[22:25]
	v_mfma_f32_16x16x32_bf16 v[18:21], v[178:181], v[208:211], v[18:21]
	v_mfma_f32_16x16x32_bf16 v[14:17], v[170:173], v[216:219], v[14:17]
	v_mfma_f32_16x16x32_bf16 v[10:13], v[178:181], v[216:219], v[10:13]
	v_mfma_f32_16x16x32_bf16 v[6:9], v[170:173], v[228:231], v[6:9]
	v_mfma_f32_16x16x32_bf16 v[2:5], v[178:181], v[228:231], v[2:5]
	s_setprio 0
	s_barrier
	s_add_i32 s17, 0, 0x18000
	v_add_u32_e32 v98, s17, v166
	s_add_i32 s28, 0, 0x1c000
	ds_read_b128 v[132:135], v98
	ds_read_b128 v[136:139], v98 offset:1024
	ds_read_b128 v[140:143], v98 offset:2048
	ds_read_b128 v[156:159], v98 offset:3072
	v_add_u32_e32 v98, s28, v166
	ds_read_b128 v[160:163], v98
	ds_read_b128 v[170:173], v98 offset:1024
	ds_read_b128 v[174:177], v98 offset:2048
	ds_read_b128 v[178:181], v98 offset:3072
	s_add_u32 s30, s34, s14
	s_addc_u32 s31, s35, s15
	s_mov_b32 m0, s74
	v_lshl_add_u64 v[240:241], s[30:31], 0, v[144:145]
	ds_read_b128 v[182:185], v168 offset:32768
	ds_read_b128 v[186:189], v168 offset:33792
	ds_read_b128 v[190:193], v168 offset:34816
	ds_read_b128 v[208:211], v168 offset:35840
	ds_read_b128 v[212:215], v168 offset:36864
	ds_read_b128 v[216:219], v168 offset:37888
	ds_read_b128 v[220:223], v168 offset:38912
	ds_read_b128 v[228:231], v168 offset:39936
	global_load_lds_dwordx4 v[240:241], off
	v_lshl_add_u64 v[240:241], s[30:31], 0, v[148:149]
	s_mov_b32 m0, s75
	s_nop 0
	global_load_lds_dwordx4 v[240:241], off
	s_waitcnt vmcnt(8)
	s_waitcnt lgkmcnt(0)
	s_barrier
	s_setprio 1
	v_mfma_f32_16x16x32_bf16 v[128:131], v[132:135], v[182:185], v[128:131]
	v_mfma_f32_16x16x32_bf16 v[124:127], v[140:143], v[182:185], v[124:127]
	v_mfma_f32_16x16x32_bf16 v[120:123], v[132:135], v[190:193], v[120:123]
	v_mfma_f32_16x16x32_bf16 v[116:119], v[140:143], v[190:193], v[116:119]
	v_mfma_f32_16x16x32_bf16 v[112:115], v[132:135], v[212:215], v[112:115]
	v_mfma_f32_16x16x32_bf16 v[108:111], v[140:143], v[212:215], v[108:111]
	v_mfma_f32_16x16x32_bf16 v[104:107], v[132:135], v[220:223], v[104:107]
	v_mfma_f32_16x16x32_bf16 v[100:103], v[140:143], v[220:223], v[100:103]
	v_mfma_f32_16x16x32_bf16 v[128:131], v[136:139], v[186:189], v[128:131]
	v_mfma_f32_16x16x32_bf16 v[124:127], v[156:159], v[186:189], v[124:127]
	v_mfma_f32_16x16x32_bf16 v[120:123], v[136:139], v[208:211], v[120:123]
	v_mfma_f32_16x16x32_bf16 v[116:119], v[156:159], v[208:211], v[116:119]
	v_mfma_f32_16x16x32_bf16 v[112:115], v[136:139], v[216:219], v[112:115]
	v_mfma_f32_16x16x32_bf16 v[108:111], v[156:159], v[216:219], v[108:111]
	v_mfma_f32_16x16x32_bf16 v[104:107], v[136:139], v[228:231], v[104:107]
	v_mfma_f32_16x16x32_bf16 v[100:103], v[156:159], v[228:231], v[100:103]
	s_setprio 0
	s_setprio 1
	v_mfma_f32_16x16x32_bf16 v[62:65], v[160:163], v[182:185], v[62:65]
	v_mfma_f32_16x16x32_bf16 v[58:61], v[174:177], v[182:185], v[58:61]
	v_mfma_f32_16x16x32_bf16 v[54:57], v[160:163], v[190:193], v[54:57]
	v_mfma_f32_16x16x32_bf16 v[50:53], v[174:177], v[190:193], v[50:53]
	v_mfma_f32_16x16x32_bf16 v[46:49], v[160:163], v[212:215], v[46:49]
	v_mfma_f32_16x16x32_bf16 v[42:45], v[174:177], v[212:215], v[42:45]
	v_mfma_f32_16x16x32_bf16 v[38:41], v[160:163], v[220:223], v[38:41]
	v_mfma_f32_16x16x32_bf16 v[34:37], v[174:177], v[220:223], v[34:37]
	v_mfma_f32_16x16x32_bf16 v[62:65], v[170:173], v[186:189], v[62:65]
	v_mfma_f32_16x16x32_bf16 v[58:61], v[178:181], v[186:189], v[58:61]
	v_mfma_f32_16x16x32_bf16 v[54:57], v[170:173], v[208:211], v[54:57]
	v_mfma_f32_16x16x32_bf16 v[50:53], v[178:181], v[208:211], v[50:53]
	v_mfma_f32_16x16x32_bf16 v[46:49], v[170:173], v[216:219], v[46:49]
	v_mfma_f32_16x16x32_bf16 v[42:45], v[178:181], v[216:219], v[42:45]
	v_mfma_f32_16x16x32_bf16 v[38:41], v[170:173], v[228:231], v[38:41]
	v_mfma_f32_16x16x32_bf16 v[34:37], v[178:181], v[228:231], v[34:37]
	s_setprio 0
	s_barrier
; #define PG8_STAGE(bufoff, gbase, voff) do { _Pragma("unroll") for (int _i = 0; _i < 2; ++_i) \
;         __builtin_amdgcn_global_load_lds((const unsigned*)((const char*)(gbase) + (voff)[_i]), (PG8_LAS unsigned*)(lds + (bufoff) + ldsw + _i * 8192), 16, 0, 0); } while (0)
; #define PG8_LDA(dst, b, h) do { _Pragma("unroll") for (int m = 0; m < 4; ++m) _Pragma("unroll") for (int k = 0; k < 2; ++k) dst[m][k] = *(const PG8_LAS bf16x8*)(lds + PG8_SA(b, h) + aoff + m * 2048 + k * 1024); } while (0)
; #define PG8_MMA(ai, bj, At, Bt) do { __builtin_amdgcn_s_setprio(1); _Pragma("unroll") for (int m = 0; m < 4; ++m) _Pragma("unroll") for (int n = 0; n < 2; ++n) _Pragma("unroll") for (int k = 0; k < 2; ++k) \
;         acc[ai][bj][m][n] = __builtin_amdgcn_mfma_f32_16x16x32_bf16(Bt[n][k], At[m][k], acc[ai][bj][m][n], 0, 0, 0); __builtin_amdgcn_s_setprio(0); } while (0)
; #define PG8_WAIT_V(n) asm volatile("s_waitcnt vmcnt(" #n ")" ::: "memory")
; #define PG8_WAIT_L(n) asm volatile("s_waitcnt lgkmcnt(" #n ")" ::: "memory")
; #define PG8_BAR __builtin_amdgcn_s_barrier()
; #define PG8_SCHED __builtin_amdgcn_sched_barrier(0)
; template <class Epi, class Sched, bool ALIGN_EPI = false, bool SP2 = false>
; __device__ __forceinline__ void gemm_phase(PG8_LAS unsigned char* lds, const Gemm g, const Sched& S, const Epi& E) {
;     ...
;         for (int t = 0; t < nt; t += 2) {
;     ...
;             PG8_LDA(At, 1, 1); PG8_STAGE(PG8_SB(1, 0), b3, voffB); PG8_STAGE(PG8_SB(1, 1), b3 + hstep, voffB); PG8_STAGE(PG8_SA(1, 0), a3, voffA);
;             PG8_WAIT_V(8); PG8_WAIT_L(0); PG8_BAR; PG8_MMA(1, 0, At, B0); PG8_MMA(1, 1, At, B1); PG8_BAR; PG8_SCHED;
	s_add_i32 s17, s17, s67
	v_lshl_add_u64 v[164:165], v[164:165], 0, s[24:25]
	s_mov_b32 m0, s17
	ds_read_b128 v[182:185], v168 offset:49152
	ds_read_b128 v[186:189], v168 offset:50176
	ds_read_b128 v[190:193], v168 offset:51200
	ds_read_b128 v[208:211], v168 offset:52224
	ds_read_b128 v[212:215], v168 offset:53248
	ds_read_b128 v[216:219], v168 offset:54272
	ds_read_b128 v[220:223], v168 offset:55296
	ds_read_b128 v[228:231], v168 offset:56320
	global_load_lds_dwordx4 v[164:165], off
	v_lshl_add_u64 v[164:165], v[224:225], 0, s[24:25]
	s_add_i32 m0, s17, 0x2000
	s_add_i32 s17, s28, s67
	global_load_lds_dwordx4 v[164:165], off
	v_lshl_add_u64 v[164:165], v[232:233], 0, s[24:25]
	s_mov_b32 m0, s17
	s_nop 0
	global_load_lds_dwordx4 v[164:165], off
	v_lshl_add_u64 v[164:165], v[234:235], 0, s[24:25]
	s_add_i32 m0, s17, 0x2000
	s_nop 0
	global_load_lds_dwordx4 v[164:165], off
	v_lshl_add_u64 v[164:165], v[236:237], 0, s[24:25]
	s_mov_b32 m0, s76
	s_nop 0
	global_load_lds_dwordx4 v[164:165], off
	v_lshl_add_u64 v[164:165], v[238:239], 0, s[24:25]
	s_mov_b32 m0, s77
	s_nop 0
	global_load_lds_dwordx4 v[164:165], off
	s_waitcnt vmcnt(8)
	s_waitcnt lgkmcnt(0)
	s_barrier
	s_setprio 1
	v_mfma_f32_16x16x32_bf16 v[94:97], v[132:135], v[182:185], v[94:97]
	v_mfma_f32_16x16x32_bf16 v[90:93], v[140:143], v[182:185], v[90:93]
	v_mfma_f32_16x16x32_bf16 v[86:89], v[132:135], v[190:193], v[86:89]
	v_mfma_f32_16x16x32_bf16 v[82:85], v[140:143], v[190:193], v[82:85]
	v_mfma_f32_16x16x32_bf16 v[78:81], v[132:135], v[212:215], v[78:81]
	v_mfma_f32_16x16x32_bf16 v[74:77], v[140:143], v[212:215], v[74:77]
	v_mfma_f32_16x16x32_bf16 v[70:73], v[132:135], v[220:223], v[70:73]
	v_mfma_f32_16x16x32_bf16 v[66:69], v[140:143], v[220:223], v[66:69]
	v_mfma_f32_16x16x32_bf16 v[94:97], v[136:139], v[186:189], v[94:97]
	v_mfma_f32_16x16x32_bf16 v[90:93], v[156:159], v[186:189], v[90:93]
	v_mfma_f32_16x16x32_bf16 v[86:89], v[136:139], v[208:211], v[86:89]
	v_mfma_f32_16x16x32_bf16 v[82:85], v[156:159], v[208:211], v[82:85]
	v_mfma_f32_16x16x32_bf16 v[78:81], v[136:139], v[216:219], v[78:81]
	v_mfma_f32_16x16x32_bf16 v[74:77], v[156:159], v[216:219], v[74:77]
	v_mfma_f32_16x16x32_bf16 v[70:73], v[136:139], v[228:231], v[70:73]
	v_mfma_f32_16x16x32_bf16 v[66:69], v[156:159], v[228:231], v[66:69]
	s_setprio 0
	s_setprio 1
	v_mfma_f32_16x16x32_bf16 v[30:33], v[160:163], v[182:185], v[30:33]
	v_mfma_f32_16x16x32_bf16 v[26:29], v[174:177], v[182:185], v[26:29]
	v_mfma_f32_16x16x32_bf16 v[22:25], v[160:163], v[190:193], v[22:25]
	v_mfma_f32_16x16x32_bf16 v[18:21], v[174:177], v[190:193], v[18:21]
	v_mfma_f32_16x16x32_bf16 v[14:17], v[160:163], v[212:215], v[14:17]
	v_mfma_f32_16x16x32_bf16 v[10:13], v[174:177], v[212:215], v[10:13]
	v_mfma_f32_16x16x32_bf16 v[6:9], v[160:163], v[220:223], v[6:9]
	v_mfma_f32_16x16x32_bf16 v[2:5], v[174:177], v[220:223], v[2:5]
	v_mfma_f32_16x16x32_bf16 v[30:33], v[170:173], v[186:189], v[30:33]
	v_mfma_f32_16x16x32_bf16 v[26:29], v[178:181], v[186:189], v[26:29]
	v_mfma_f32_16x16x32_bf16 v[22:25], v[170:173], v[208:211], v[22:25]
	v_mfma_f32_16x16x32_bf16 v[18:21], v[178:181], v[208:211], v[18:21]
	v_mfma_f32_16x16x32_bf16 v[14:17], v[170:173], v[216:219], v[14:17]
	v_mfma_f32_16x16x32_bf16 v[10:13], v[178:181], v[216:219], v[10:13]
	v_mfma_f32_16x16x32_bf16 v[6:9], v[170:173], v[228:231], v[6:9]
	v_mfma_f32_16x16x32_bf16 v[2:5], v[178:181], v[228:231], v[2:5]
	s_setprio 0
	s_barrier
	s_add_u32 s2, s2, 0x100
	s_addc_u32 s3, s3, 0
	s_add_u32 s4, s4, 0x100
	s_addc_u32 s16, s16, 0
	s_cmp_ge_i32 s22, s18
	s_mov_b32 s17, s22
	s_cbranch_scc0 .LBB0_1052

; #define PG8_STAGE(bufoff, gbase, voff) do { _Pragma("unroll") for (int _i = 0; _i < 2; ++_i) \
;         __builtin_amdgcn_global_load_lds((const unsigned*)((const char*)(gbase) + (voff)[_i]), (PG8_LAS unsigned*)(lds + (bufoff) + ldsw + _i * 8192), 16, 0, 0); } while (0)
; #define PG8_LDA(dst, b, h) do { _Pragma("unroll") for (int m = 0; m < 4; ++m) _Pragma("unroll") for (int k = 0; k < 2; ++k) dst[m][k] = *(const PG8_LAS bf16x8*)(lds + PG8_SA(b, h) + aoff + m * 2048 + k * 1024); } while (0)
; #define PG8_LDB(dst, b, h) do { _Pragma("unroll") for (int n = 0; n < 2; ++n) _Pragma("unroll") for (int k = 0; k < 2; ++k) dst[n][k] = *(const PG8_LAS bf16x8*)(lds + PG8_SB(b, h) + boff + n * 2048 + k * 1024); } while (0)
; #define PG8_MMA(ai, bj, At, Bt) do { __builtin_amdgcn_s_setprio(1); _Pragma("unroll") for (int m = 0; m < 4; ++m) _Pragma("unroll") for (int n = 0; n < 2; ++n) _Pragma("unroll") for (int k = 0; k < 2; ++k) \
;         acc[ai][bj][m][n] = __builtin_amdgcn_mfma_f32_16x16x32_bf16(Bt[n][k], At[m][k], acc[ai][bj][m][n], 0, 0, 0); __builtin_amdgcn_s_setprio(0); } while (0)
; #define PG8_WAIT_V(n) asm volatile("s_waitcnt vmcnt(" #n ")" ::: "memory")
; #define PG8_WAIT_L(n) asm volatile("s_waitcnt lgkmcnt(" #n ")" ::: "memory")
; #define PG8_BAR __builtin_amdgcn_s_barrier()
; #define PG8_SCHED __builtin_amdgcn_sched_barrier(0)
; template <class Epi, class Sched, bool ALIGN_EPI = false, bool SP2 = false>
; __device__ __forceinline__ void gemm_phase(PG8_LAS unsigned char* lds, const Gemm g, const Sched& S, const Epi& E) {
;     ...
;             const bool last = (t == nt - 2);
;             const char* a1 = cA + (size_t)(t + 1) * kstep;
;             const char* a2 = last ? nA : cA + (size_t)(t + 2) * kstep; const char* b2 = last ? nB : cB + (size_t)(t + 2) * kstep;
;             const char* a3 = a2 + kstep; const char* b3 = b2 + kstep;
;             if (last && has_next) S.a_ready(nxt);
;             if constexpr (SP2) {
;             PG8_LDB(B0, 0, 0); PG8_LDB(B1, 0, 1); PG8_SCHED; PG8_LDA(At, 0, 0); PG8_STAGE(PG8_SA(1, 1), a1 + hstep, voffA);
;             PG8_WAIT_V(8); PG8_WAIT_L(0); PG8_BAR; PG8_MMA(0, 0, At, B0); PG8_MMA(0, 1, At, B1); PG8_BAR; PG8_SCHED;
;             PG8_LDA(At, 0, 1); PG8_STAGE(PG8_SB(0, 0), b2, voffB); PG8_STAGE(PG8_SB(0, 1), b2 + hstep, voffB); PG8_STAGE(PG8_SA(0, 0), a2, voffA);
.LBB0_1127:
	s_add_i32 s22, s17, 2
	s_add_u32 s28, s2, 0x80
	s_addc_u32 s30, s3, 0
	s_add_i32 s33, 0, 0x10000
	s_cmp_eq_u32 s70, s17
	s_cselect_b32 s35, s57, s30
	s_cselect_b32 s34, s56, s28
	v_add_u32_e32 v98, s33, v154
	s_cselect_b32 s31, s59, s16
	s_cselect_b32 s30, s58, s4
	s_add_i32 s17, 0, 0x14000
	ds_read_b128 v[144:147], v98
	ds_read_b128 v[148:151], v98 offset:1024
	ds_read_b128 v[158:161], v98 offset:2048
	ds_read_b128 v[162:165], v98 offset:3072
	v_add_u32_e32 v98, s17, v154
	ds_read_b128 v[166:169], v98
	ds_read_b128 v[170:173], v98 offset:1024
	ds_read_b128 v[174:177], v98 offset:2048
	ds_read_b128 v[178:181], v98 offset:3072
	v_lshl_add_u64 v[152:153], s[2:3], 0, v[140:141]
	s_add_i32 m0, s63, 0xc000
	ds_read_b128 v[182:185], v156
	ds_read_b128 v[186:189], v156 offset:1024
	ds_read_b128 v[190:193], v156 offset:2048
	ds_read_b128 v[208:211], v156 offset:3072
	ds_read_b128 v[212:215], v156 offset:4096
	ds_read_b128 v[216:219], v156 offset:5120
	ds_read_b128 v[220:223], v156 offset:6144
	ds_read_b128 v[228:231], v156 offset:7168
	global_load_lds_dwordx4 v[152:153], off
	v_lshl_add_u64 v[152:153], s[2:3], 0, v[142:143]
	s_add_i32 m0, s63, 0xe000
	s_nop 0
	global_load_lds_dwordx4 v[152:153], off
	s_waitcnt vmcnt(8)
	s_waitcnt lgkmcnt(0)
	s_barrier
	s_setprio 1
	v_mfma_f32_16x16x32_bf16 v[124:127], v[144:147], v[182:185], v[124:127]
	v_mfma_f32_16x16x32_bf16 v[128:131], v[158:161], v[182:185], v[128:131]
	v_mfma_f32_16x16x32_bf16 v[112:115], v[144:147], v[190:193], v[112:115]
	v_mfma_f32_16x16x32_bf16 v[108:111], v[158:161], v[190:193], v[108:111]
	v_mfma_f32_16x16x32_bf16 v[94:97], v[144:147], v[212:215], v[94:97]
	v_mfma_f32_16x16x32_bf16 v[90:93], v[158:161], v[212:215], v[90:93]
	v_mfma_f32_16x16x32_bf16 v[78:81], v[144:147], v[220:223], v[78:81]
	v_mfma_f32_16x16x32_bf16 v[74:77], v[158:161], v[220:223], v[74:77]
	v_mfma_f32_16x16x32_bf16 v[124:127], v[148:151], v[186:189], v[124:127]
	v_mfma_f32_16x16x32_bf16 v[128:131], v[162:165], v[186:189], v[128:131]
	v_mfma_f32_16x16x32_bf16 v[112:115], v[148:151], v[208:211], v[112:115]
	v_mfma_f32_16x16x32_bf16 v[108:111], v[162:165], v[208:211], v[108:111]
	v_mfma_f32_16x16x32_bf16 v[94:97], v[148:151], v[216:219], v[94:97]
	v_mfma_f32_16x16x32_bf16 v[90:93], v[162:165], v[216:219], v[90:93]
	v_mfma_f32_16x16x32_bf16 v[78:81], v[148:151], v[228:231], v[78:81]
	v_mfma_f32_16x16x32_bf16 v[74:77], v[162:165], v[228:231], v[74:77]
	s_setprio 0
	s_setprio 1
	v_mfma_f32_16x16x32_bf16 v[120:123], v[166:169], v[182:185], v[120:123]
	v_mfma_f32_16x16x32_bf16 v[116:119], v[174:177], v[182:185], v[116:119]
	v_mfma_f32_16x16x32_bf16 v[104:107], v[166:169], v[190:193], v[104:107]
	v_mfma_f32_16x16x32_bf16 v[100:103], v[174:177], v[190:193], v[100:103]
	v_mfma_f32_16x16x32_bf16 v[86:89], v[166:169], v[212:215], v[86:89]
	v_mfma_f32_16x16x32_bf16 v[82:85], v[174:177], v[212:215], v[82:85]
	v_mfma_f32_16x16x32_bf16 v[70:73], v[166:169], v[220:223], v[70:73]
	v_mfma_f32_16x16x32_bf16 v[66:69], v[174:177], v[220:223], v[66:69]
	v_mfma_f32_16x16x32_bf16 v[120:123], v[170:173], v[186:189], v[120:123]
	v_mfma_f32_16x16x32_bf16 v[116:119], v[178:181], v[186:189], v[116:119]
	v_mfma_f32_16x16x32_bf16 v[104:107], v[170:173], v[208:211], v[104:107]
	v_mfma_f32_16x16x32_bf16 v[100:103], v[178:181], v[208:211], v[100:103]
	v_mfma_f32_16x16x32_bf16 v[86:89], v[170:173], v[216:219], v[86:89]
	v_mfma_f32_16x16x32_bf16 v[82:85], v[178:181], v[216:219], v[82:85]
	v_mfma_f32_16x16x32_bf16 v[70:73], v[170:173], v[228:231], v[70:73]
	v_mfma_f32_16x16x32_bf16 v[66:69], v[178:181], v[228:231], v[66:69]
	s_setprio 0
	s_barrier
	s_add_i32 s28, s33, s62
	v_lshl_add_u64 v[152:153], s[30:31], 0, v[134:135]
	s_mov_b32 m0, s28
	ds_read_b128 v[182:185], v156 offset:16384
	ds_read_b128 v[186:189], v156 offset:17408
	ds_read_b128 v[190:193], v156 offset:18432
	ds_read_b128 v[208:211], v156 offset:19456
	ds_read_b128 v[212:215], v156 offset:20480
	ds_read_b128 v[216:219], v156 offset:21504
	ds_read_b128 v[220:223], v156 offset:22528
	ds_read_b128 v[228:231], v156 offset:23552
	global_load_lds_dwordx4 v[152:153], off
	s_add_i32 m0, s28, 0x2000
	v_lshl_add_u64 v[224:225], s[30:31], 0, v[138:139]
	s_add_u32 s30, s30, s14
	s_addc_u32 s31, s31, s15
	s_add_i32 s17, s17, s62
	global_load_lds_dwordx4 v[224:225], off
	v_lshl_add_u64 v[232:233], s[30:31], 0, v[134:135]
	s_mov_b32 m0, s17
	v_lshl_add_u64 v[234:235], s[30:31], 0, v[138:139]
	global_load_lds_dwordx4 v[232:233], off
	s_add_i32 m0, s17, 0x2000
	v_lshl_add_u64 v[236:237], s[34:35], 0, v[132:133]
	global_load_lds_dwordx4 v[234:235], off
	s_mov_b32 m0, s63
	v_lshl_add_u64 v[238:239], s[34:35], 0, v[136:137]
	global_load_lds_dwordx4 v[236:237], off
	s_mov_b32 m0, s64
	s_nop 0
	global_load_lds_dwordx4 v[238:239], off
	s_waitcnt vmcnt(8)
	s_waitcnt lgkmcnt(0)
	s_barrier
; #define PG8_STAGE(bufoff, gbase, voff) do { _Pragma("unroll") for (int _i = 0; _i < 2; ++_i) \
;         __builtin_amdgcn_global_load_lds((const unsigned*)((const char*)(gbase) + (voff)[_i]), (PG8_LAS unsigned*)(lds + (bufoff) + ldsw + _i * 8192), 16, 0, 0); } while (0)
; #define PG8_LDA(dst, b, h) do { _Pragma("unroll") for (int m = 0; m < 4; ++m) _Pragma("unroll") for (int k = 0; k < 2; ++k) dst[m][k] = *(const PG8_LAS bf16x8*)(lds + PG8_SA(b, h) + aoff + m * 2048 + k * 1024); } while (0)
; #define PG8_LDB(dst, b, h) do { _Pragma("unroll") for (int n = 0; n < 2; ++n) _Pragma("unroll") for (int k = 0; k < 2; ++k) dst[n][k] = *(const PG8_LAS bf16x8*)(lds + PG8_SB(b, h) + boff + n * 2048 + k * 1024); } while (0)
; #define PG8_MMA(ai, bj, At, Bt) do { __builtin_amdgcn_s_setprio(1); _Pragma("unroll") for (int m = 0; m < 4; ++m) _Pragma("unroll") for (int n = 0; n < 2; ++n) _Pragma("unroll") for (int k = 0; k < 2; ++k) \
;         acc[ai][bj][m][n] = __builtin_amdgcn_mfma_f32_16x16x32_bf16(Bt[n][k], At[m][k], acc[ai][bj][m][n], 0, 0, 0); __builtin_amdgcn_s_setprio(0); } while (0)
; #define PG8_WAIT_V(n) asm volatile("s_waitcnt vmcnt(" #n ")" ::: "memory")
; #define PG8_WAIT_L(n) asm volatile("s_waitcnt lgkmcnt(" #n ")" ::: "memory")
; #define PG8_BAR __builtin_amdgcn_s_barrier()
; #define PG8_SCHED __builtin_amdgcn_sched_barrier(0)
; template <class Epi, class Sched, bool ALIGN_EPI = false, bool SP2 = false>
; __device__ __forceinline__ void gemm_phase(PG8_LAS unsigned char* lds, const Gemm g, const Sched& S, const Epi& E) {
;     ...
;             PG8_WAIT_V(8); PG8_WAIT_L(0); PG8_BAR; PG8_MMA(1, 0, At, B0); PG8_MMA(1, 1, At, B1); PG8_BAR; PG8_SCHED;
;             PG8_LDB(B0, 1, 0); PG8_LDB(B1, 1, 1); PG8_SCHED; PG8_LDA(At, 1, 0); PG8_STAGE(PG8_SA(0, 1), a2 + hstep, voffA);
;             PG8_WAIT_V(8); PG8_WAIT_L(0); PG8_BAR; PG8_MMA(0, 0, At, B0); PG8_MMA(0, 1, At, B1); PG8_BAR; PG8_SCHED;
	s_setprio 1
	v_mfma_f32_16x16x32_bf16 v[62:65], v[144:147], v[182:185], v[62:65]
	v_mfma_f32_16x16x32_bf16 v[58:61], v[158:161], v[182:185], v[58:61]
	v_mfma_f32_16x16x32_bf16 v[46:49], v[144:147], v[190:193], v[46:49]
	v_mfma_f32_16x16x32_bf16 v[42:45], v[158:161], v[190:193], v[42:45]
	v_mfma_f32_16x16x32_bf16 v[30:33], v[144:147], v[212:215], v[30:33]
	v_mfma_f32_16x16x32_bf16 v[26:29], v[158:161], v[212:215], v[26:29]
	v_mfma_f32_16x16x32_bf16 v[14:17], v[144:147], v[220:223], v[14:17]
	v_mfma_f32_16x16x32_bf16 v[10:13], v[158:161], v[220:223], v[10:13]
	v_mfma_f32_16x16x32_bf16 v[62:65], v[148:151], v[186:189], v[62:65]
	v_mfma_f32_16x16x32_bf16 v[58:61], v[162:165], v[186:189], v[58:61]
	v_mfma_f32_16x16x32_bf16 v[46:49], v[148:151], v[208:211], v[46:49]
	v_mfma_f32_16x16x32_bf16 v[42:45], v[162:165], v[208:211], v[42:45]
	v_mfma_f32_16x16x32_bf16 v[30:33], v[148:151], v[216:219], v[30:33]
	v_mfma_f32_16x16x32_bf16 v[26:29], v[162:165], v[216:219], v[26:29]
	v_mfma_f32_16x16x32_bf16 v[14:17], v[148:151], v[228:231], v[14:17]
	v_mfma_f32_16x16x32_bf16 v[10:13], v[162:165], v[228:231], v[10:13]
	s_setprio 0
	s_setprio 1
	v_mfma_f32_16x16x32_bf16 v[54:57], v[166:169], v[182:185], v[54:57]
	v_mfma_f32_16x16x32_bf16 v[50:53], v[174:177], v[182:185], v[50:53]
	v_mfma_f32_16x16x32_bf16 v[38:41], v[166:169], v[190:193], v[38:41]
	v_mfma_f32_16x16x32_bf16 v[34:37], v[174:177], v[190:193], v[34:37]
	v_mfma_f32_16x16x32_bf16 v[22:25], v[166:169], v[212:215], v[22:25]
	v_mfma_f32_16x16x32_bf16 v[18:21], v[174:177], v[212:215], v[18:21]
	v_mfma_f32_16x16x32_bf16 v[6:9], v[166:169], v[220:223], v[6:9]
	v_mfma_f32_16x16x32_bf16 v[2:5], v[174:177], v[220:223], v[2:5]
	v_mfma_f32_16x16x32_bf16 v[54:57], v[170:173], v[186:189], v[54:57]
	v_mfma_f32_16x16x32_bf16 v[50:53], v[178:181], v[186:189], v[50:53]
	v_mfma_f32_16x16x32_bf16 v[38:41], v[170:173], v[208:211], v[38:41]
	v_mfma_f32_16x16x32_bf16 v[34:37], v[178:181], v[208:211], v[34:37]
	v_mfma_f32_16x16x32_bf16 v[22:25], v[170:173], v[216:219], v[22:25]
	v_mfma_f32_16x16x32_bf16 v[18:21], v[178:181], v[216:219], v[18:21]
	v_mfma_f32_16x16x32_bf16 v[6:9], v[170:173], v[228:231], v[6:9]
	v_mfma_f32_16x16x32_bf16 v[2:5], v[178:181], v[228:231], v[2:5]
	s_setprio 0
	s_barrier
	s_add_i32 s17, 0, 0x18000
	v_add_u32_e32 v98, s17, v154
	s_add_i32 s28, 0, 0x1c000
	ds_read_b128 v[144:147], v98
	ds_read_b128 v[148:151], v98 offset:1024
	ds_read_b128 v[158:161], v98 offset:2048
	ds_read_b128 v[162:165], v98 offset:3072
	v_add_u32_e32 v98, s28, v154
	ds_read_b128 v[166:169], v98
	ds_read_b128 v[170:173], v98 offset:1024
	ds_read_b128 v[174:177], v98 offset:2048
	ds_read_b128 v[178:181], v98 offset:3072
	s_add_u32 s30, s34, s14
	s_addc_u32 s31, s35, s15
	s_mov_b32 m0, s65
	v_lshl_add_u64 v[240:241], s[30:31], 0, v[132:133]
	ds_read_b128 v[182:185], v156 offset:32768
	ds_read_b128 v[186:189], v156 offset:33792
	ds_read_b128 v[190:193], v156 offset:34816
	ds_read_b128 v[208:211], v156 offset:35840
	ds_read_b128 v[212:215], v156 offset:36864
	ds_read_b128 v[216:219], v156 offset:37888
	ds_read_b128 v[220:223], v156 offset:38912
	ds_read_b128 v[228:231], v156 offset:39936
	global_load_lds_dwordx4 v[240:241], off
	v_lshl_add_u64 v[240:241], s[30:31], 0, v[136:137]
	s_mov_b32 m0, s66
	s_nop 0
	global_load_lds_dwordx4 v[240:241], off
	s_waitcnt vmcnt(8)
	s_waitcnt lgkmcnt(0)
	s_barrier
	s_setprio 1
	v_mfma_f32_16x16x32_bf16 v[124:127], v[144:147], v[182:185], v[124:127]
	v_mfma_f32_16x16x32_bf16 v[128:131], v[158:161], v[182:185], v[128:131]
	v_mfma_f32_16x16x32_bf16 v[112:115], v[144:147], v[190:193], v[112:115]
	v_mfma_f32_16x16x32_bf16 v[108:111], v[158:161], v[190:193], v[108:111]
	v_mfma_f32_16x16x32_bf16 v[94:97], v[144:147], v[212:215], v[94:97]
	v_mfma_f32_16x16x32_bf16 v[90:93], v[158:161], v[212:215], v[90:93]
	v_mfma_f32_16x16x32_bf16 v[78:81], v[144:147], v[220:223], v[78:81]
	v_mfma_f32_16x16x32_bf16 v[74:77], v[158:161], v[220:223], v[74:77]
	v_mfma_f32_16x16x32_bf16 v[124:127], v[148:151], v[186:189], v[124:127]
	v_mfma_f32_16x16x32_bf16 v[128:131], v[162:165], v[186:189], v[128:131]
	v_mfma_f32_16x16x32_bf16 v[112:115], v[148:151], v[208:211], v[112:115]
	v_mfma_f32_16x16x32_bf16 v[108:111], v[162:165], v[208:211], v[108:111]
	v_mfma_f32_16x16x32_bf16 v[94:97], v[148:151], v[216:219], v[94:97]
	v_mfma_f32_16x16x32_bf16 v[90:93], v[162:165], v[216:219], v[90:93]
	v_mfma_f32_16x16x32_bf16 v[78:81], v[148:151], v[228:231], v[78:81]
	v_mfma_f32_16x16x32_bf16 v[74:77], v[162:165], v[228:231], v[74:77]
	s_setprio 0
	s_setprio 1
	v_mfma_f32_16x16x32_bf16 v[120:123], v[166:169], v[182:185], v[120:123]
	v_mfma_f32_16x16x32_bf16 v[116:119], v[174:177], v[182:185], v[116:119]
	v_mfma_f32_16x16x32_bf16 v[104:107], v[166:169], v[190:193], v[104:107]
	v_mfma_f32_16x16x32_bf16 v[100:103], v[174:177], v[190:193], v[100:103]
	v_mfma_f32_16x16x32_bf16 v[86:89], v[166:169], v[212:215], v[86:89]
	v_mfma_f32_16x16x32_bf16 v[82:85], v[174:177], v[212:215], v[82:85]
	v_mfma_f32_16x16x32_bf16 v[70:73], v[166:169], v[220:223], v[70:73]
	v_mfma_f32_16x16x32_bf16 v[66:69], v[174:177], v[220:223], v[66:69]
	v_mfma_f32_16x16x32_bf16 v[120:123], v[170:173], v[186:189], v[120:123]
	v_mfma_f32_16x16x32_bf16 v[116:119], v[178:181], v[186:189], v[116:119]
	v_mfma_f32_16x16x32_bf16 v[104:107], v[170:173], v[208:211], v[104:107]
	v_mfma_f32_16x16x32_bf16 v[100:103], v[178:181], v[208:211], v[100:103]
	v_mfma_f32_16x16x32_bf16 v[86:89], v[170:173], v[216:219], v[86:89]
	v_mfma_f32_16x16x32_bf16 v[82:85], v[178:181], v[216:219], v[82:85]
	v_mfma_f32_16x16x32_bf16 v[70:73], v[170:173], v[228:231], v[70:73]
	v_mfma_f32_16x16x32_bf16 v[66:69], v[178:181], v[228:231], v[66:69]
	s_setprio 0
	s_barrier
; #define PG8_STAGE(bufoff, gbase, voff) do { _Pragma("unroll") for (int _i = 0; _i < 2; ++_i) \
;         __builtin_amdgcn_global_load_lds((const unsigned*)((const char*)(gbase) + (voff)[_i]), (PG8_LAS unsigned*)(lds + (bufoff) + ldsw + _i * 8192), 16, 0, 0); } while (0)
; #define PG8_LDA(dst, b, h) do { _Pragma("unroll") for (int m = 0; m < 4; ++m) _Pragma("unroll") for (int k = 0; k < 2; ++k) dst[m][k] = *(const PG8_LAS bf16x8*)(lds + PG8_SA(b, h) + aoff + m * 2048 + k * 1024); } while (0)
; #define PG8_MMA(ai, bj, At, Bt) do { __builtin_amdgcn_s_setprio(1); _Pragma("unroll") for (int m = 0; m < 4; ++m) _Pragma("unroll") for (int n = 0; n < 2; ++n) _Pragma("unroll") for (int k = 0; k < 2; ++k) \
;         acc[ai][bj][m][n] = __builtin_amdgcn_mfma_f32_16x16x32_bf16(Bt[n][k], At[m][k], acc[ai][bj][m][n], 0, 0, 0); __builtin_amdgcn_s_setprio(0); } while (0)
; #define PG8_WAIT_V(n) asm volatile("s_waitcnt vmcnt(" #n ")" ::: "memory")
; #define PG8_WAIT_L(n) asm volatile("s_waitcnt lgkmcnt(" #n ")" ::: "memory")
; #define PG8_BAR __builtin_amdgcn_s_barrier()
; #define PG8_SCHED __builtin_amdgcn_sched_barrier(0)
; template <class Epi, class Sched, bool ALIGN_EPI = false, bool SP2 = false>
; __device__ __forceinline__ void gemm_phase(PG8_LAS unsigned char* lds, const Gemm g, const Sched& S, const Epi& E) {
;     ...
;         for (int t = 0; t < nt; t += 2) {
;     ...
;             PG8_LDA(At, 1, 1); PG8_STAGE(PG8_SB(1, 0), b3, voffB); PG8_STAGE(PG8_SB(1, 1), b3 + hstep, voffB); PG8_STAGE(PG8_SA(1, 0), a3, voffA);
;             PG8_WAIT_V(8); PG8_WAIT_L(0); PG8_BAR; PG8_MMA(1, 0, At, B0); PG8_MMA(1, 1, At, B1); PG8_BAR; PG8_SCHED;
	s_add_i32 s17, s17, s62
	v_lshl_add_u64 v[152:153], v[152:153], 0, s[24:25]
	s_mov_b32 m0, s17
	ds_read_b128 v[182:185], v156 offset:49152
	ds_read_b128 v[186:189], v156 offset:50176
	ds_read_b128 v[190:193], v156 offset:51200
	ds_read_b128 v[208:211], v156 offset:52224
	ds_read_b128 v[212:215], v156 offset:53248
	ds_read_b128 v[216:219], v156 offset:54272
	ds_read_b128 v[220:223], v156 offset:55296
	ds_read_b128 v[228:231], v156 offset:56320
	global_load_lds_dwordx4 v[152:153], off
	v_lshl_add_u64 v[152:153], v[224:225], 0, s[24:25]
	s_add_i32 m0, s17, 0x2000
	s_add_i32 s17, s28, s62
	global_load_lds_dwordx4 v[152:153], off
	v_lshl_add_u64 v[152:153], v[232:233], 0, s[24:25]
	s_mov_b32 m0, s17
	s_nop 0
	global_load_lds_dwordx4 v[152:153], off
	v_lshl_add_u64 v[152:153], v[234:235], 0, s[24:25]
	s_add_i32 m0, s17, 0x2000
	s_nop 0
	global_load_lds_dwordx4 v[152:153], off
	v_lshl_add_u64 v[152:153], v[236:237], 0, s[24:25]
	s_mov_b32 m0, s68
	s_nop 0
	global_load_lds_dwordx4 v[152:153], off
	v_lshl_add_u64 v[152:153], v[238:239], 0, s[24:25]
	s_mov_b32 m0, s69
	s_nop 0
	global_load_lds_dwordx4 v[152:153], off
	s_waitcnt vmcnt(8)
	s_waitcnt lgkmcnt(0)
	s_barrier
	s_setprio 1
	v_mfma_f32_16x16x32_bf16 v[62:65], v[144:147], v[182:185], v[62:65]
	v_mfma_f32_16x16x32_bf16 v[58:61], v[158:161], v[182:185], v[58:61]
	v_mfma_f32_16x16x32_bf16 v[46:49], v[144:147], v[190:193], v[46:49]
	v_mfma_f32_16x16x32_bf16 v[42:45], v[158:161], v[190:193], v[42:45]
	v_mfma_f32_16x16x32_bf16 v[30:33], v[144:147], v[212:215], v[30:33]
	v_mfma_f32_16x16x32_bf16 v[26:29], v[158:161], v[212:215], v[26:29]
	v_mfma_f32_16x16x32_bf16 v[14:17], v[144:147], v[220:223], v[14:17]
	v_mfma_f32_16x16x32_bf16 v[10:13], v[158:161], v[220:223], v[10:13]
	v_mfma_f32_16x16x32_bf16 v[62:65], v[148:151], v[186:189], v[62:65]
	v_mfma_f32_16x16x32_bf16 v[58:61], v[162:165], v[186:189], v[58:61]
	v_mfma_f32_16x16x32_bf16 v[46:49], v[148:151], v[208:211], v[46:49]
	v_mfma_f32_16x16x32_bf16 v[42:45], v[162:165], v[208:211], v[42:45]
	v_mfma_f32_16x16x32_bf16 v[30:33], v[148:151], v[216:219], v[30:33]
	v_mfma_f32_16x16x32_bf16 v[26:29], v[162:165], v[216:219], v[26:29]
	v_mfma_f32_16x16x32_bf16 v[14:17], v[148:151], v[228:231], v[14:17]
	v_mfma_f32_16x16x32_bf16 v[10:13], v[162:165], v[228:231], v[10:13]
	s_setprio 0
	s_setprio 1
	v_mfma_f32_16x16x32_bf16 v[54:57], v[166:169], v[182:185], v[54:57]
	v_mfma_f32_16x16x32_bf16 v[50:53], v[174:177], v[182:185], v[50:53]
	v_mfma_f32_16x16x32_bf16 v[38:41], v[166:169], v[190:193], v[38:41]
	v_mfma_f32_16x16x32_bf16 v[34:37], v[174:177], v[190:193], v[34:37]
	v_mfma_f32_16x16x32_bf16 v[22:25], v[166:169], v[212:215], v[22:25]
	v_mfma_f32_16x16x32_bf16 v[18:21], v[174:177], v[212:215], v[18:21]
	v_mfma_f32_16x16x32_bf16 v[6:9], v[166:169], v[220:223], v[6:9]
	v_mfma_f32_16x16x32_bf16 v[2:5], v[174:177], v[220:223], v[2:5]
	v_mfma_f32_16x16x32_bf16 v[54:57], v[170:173], v[186:189], v[54:57]
	v_mfma_f32_16x16x32_bf16 v[50:53], v[178:181], v[186:189], v[50:53]
	v_mfma_f32_16x16x32_bf16 v[38:41], v[170:173], v[208:211], v[38:41]
	v_mfma_f32_16x16x32_bf16 v[34:37], v[178:181], v[208:211], v[34:37]
	v_mfma_f32_16x16x32_bf16 v[22:25], v[170:173], v[216:219], v[22:25]
	v_mfma_f32_16x16x32_bf16 v[18:21], v[178:181], v[216:219], v[18:21]
	v_mfma_f32_16x16x32_bf16 v[6:9], v[170:173], v[228:231], v[6:9]
	v_mfma_f32_16x16x32_bf16 v[2:5], v[178:181], v[228:231], v[2:5]
	s_setprio 0
	s_barrier
	s_add_u32 s2, s2, 0x100
	s_addc_u32 s3, s3, 0
	s_add_u32 s4, s4, 0x100
	s_addc_u32 s16, s16, 0
	s_cmp_ge_i32 s22, s67
	s_mov_b32 s17, s22
	s_cbranch_scc0 .LBB0_1127

; #define PG8_STAGE(bufoff, gbase, voff) do { _Pragma("unroll") for (int _i = 0; _i < 2; ++_i) \
;         __builtin_amdgcn_global_load_lds((const unsigned*)((const char*)(gbase) + (voff)[_i]), (PG8_LAS unsigned*)(lds + (bufoff) + ldsw + _i * 8192), 16, 0, 0); } while (0)
; #define PG8_LDA(dst, b, h) do { _Pragma("unroll") for (int m = 0; m < 4; ++m) _Pragma("unroll") for (int k = 0; k < 2; ++k) dst[m][k] = *(const PG8_LAS bf16x8*)(lds + PG8_SA(b, h) + aoff + m * 2048 + k * 1024); } while (0)
; #define PG8_LDB(dst, b, h) do { _Pragma("unroll") for (int n = 0; n < 2; ++n) _Pragma("unroll") for (int k = 0; k < 2; ++k) dst[n][k] = *(const PG8_LAS bf16x8*)(lds + PG8_SB(b, h) + boff + n * 2048 + k * 1024); } while (0)
; #define PG8_MMA(ai, bj, At, Bt) do { __builtin_amdgcn_s_setprio(1); _Pragma("unroll") for (int m = 0; m < 4; ++m) _Pragma("unroll") for (int n = 0; n < 2; ++n) _Pragma("unroll") for (int k = 0; k < 2; ++k) \
;         acc[ai][bj][m][n] = __builtin_amdgcn_mfma_f32_16x16x32_bf16(Bt[n][k], At[m][k], acc[ai][bj][m][n], 0, 0, 0); __builtin_amdgcn_s_setprio(0); } while (0)
; #define PG8_WAIT_V(n) asm volatile("s_waitcnt vmcnt(" #n ")" ::: "memory")
; #define PG8_WAIT_L(n) asm volatile("s_waitcnt lgkmcnt(" #n ")" ::: "memory")
; #define PG8_BAR __builtin_amdgcn_s_barrier()
; #define PG8_SCHED __builtin_amdgcn_sched_barrier(0)
; template <class Epi, class Sched, bool ALIGN_EPI = false, bool SP2 = false>
; __device__ __forceinline__ void gemm_phase(PG8_LAS unsigned char* lds, const Gemm g, const Sched& S, const Epi& E) {
;     ...
;             const bool last = (t == nt - 2);
;             const char* a1 = cA + (size_t)(t + 1) * kstep;
;             const char* a2 = last ? nA : cA + (size_t)(t + 2) * kstep; const char* b2 = last ? nB : cB + (size_t)(t + 2) * kstep;
;             const char* a3 = a2 + kstep; const char* b3 = b2 + kstep;
;             if (last && has_next) S.a_ready(nxt);
;             if constexpr (SP2) {
;             PG8_LDB(B0, 0, 0); PG8_LDB(B1, 0, 1); PG8_SCHED; PG8_LDA(At, 0, 0); PG8_STAGE(PG8_SA(1, 1), a1 + hstep, voffA);
;             PG8_WAIT_V(8); PG8_WAIT_L(0); PG8_BAR; PG8_MMA(0, 0, At, B0); PG8_MMA(0, 1, At, B1); PG8_BAR; PG8_SCHED;
;             PG8_LDA(At, 0, 1); PG8_STAGE(PG8_SB(0, 0), b2, voffB); PG8_STAGE(PG8_SB(0, 1), b2 + hstep, voffB); PG8_STAGE(PG8_SA(0, 0), a2, voffA);
.LBB0_1180:
	s_add_i32 s22, s17, 2
	s_add_u32 s28, s34, 0x80
	s_addc_u32 s30, s35, 0
	s_add_i32 s33, 0, 0x10000
	s_cmp_eq_u32 s73, s17
	s_cselect_b32 s37, s3, s30
	s_cselect_b32 s36, s2, s28
	s_cselect_b32 s31, s51, s16
	s_cselect_b32 s30, s50, s4
	s_add_i32 s17, 0, 0x14000
	v_add_u32_e32 v158, s33, v148
	v_add_u32_e32 v174, s17, v148
	ds_read_b128 v[144:147], v158
	ds_read_b128 v[150:153], v158 offset:1024
	ds_read_b128 v[154:157], v158 offset:2048
	ds_read_b128 v[158:161], v158 offset:3072
	ds_read_b128 v[162:165], v174
	ds_read_b128 v[166:169], v174 offset:1024
	ds_read_b128 v[170:173], v174 offset:2048
	ds_read_b128 v[174:177], v174 offset:3072
	v_lshl_add_u64 v[224:225], s[34:35], 0, v[140:141]
	s_add_i32 m0, s66, 0xc000
	ds_read_b128 v[178:181], v149
	ds_read_b128 v[182:185], v149 offset:1024
	ds_read_b128 v[186:189], v149 offset:2048
	ds_read_b128 v[190:193], v149 offset:3072
	ds_read_b128 v[208:211], v149 offset:4096
	ds_read_b128 v[212:215], v149 offset:5120
	ds_read_b128 v[216:219], v149 offset:6144
	ds_read_b128 v[220:223], v149 offset:7168
	global_load_lds_dwordx4 v[224:225], off
	v_lshl_add_u64 v[224:225], s[34:35], 0, v[142:143]
	s_add_i32 m0, s66, 0xe000
	s_nop 0
	global_load_lds_dwordx4 v[224:225], off
	s_waitcnt vmcnt(8)
	s_waitcnt lgkmcnt(0)
	s_barrier
	s_setprio 1
	v_mfma_f32_16x16x32_bf16 v[124:127], v[144:147], v[178:181], v[124:127]
	v_mfma_f32_16x16x32_bf16 v[128:131], v[154:157], v[178:181], v[128:131]
	v_mfma_f32_16x16x32_bf16 v[112:115], v[144:147], v[186:189], v[112:115]
	v_mfma_f32_16x16x32_bf16 v[108:111], v[154:157], v[186:189], v[108:111]
	v_mfma_f32_16x16x32_bf16 v[94:97], v[144:147], v[208:211], v[94:97]
	v_mfma_f32_16x16x32_bf16 v[90:93], v[154:157], v[208:211], v[90:93]
	v_mfma_f32_16x16x32_bf16 v[78:81], v[144:147], v[216:219], v[78:81]
	v_mfma_f32_16x16x32_bf16 v[74:77], v[154:157], v[216:219], v[74:77]
	v_mfma_f32_16x16x32_bf16 v[124:127], v[150:153], v[182:185], v[124:127]
	v_mfma_f32_16x16x32_bf16 v[128:131], v[158:161], v[182:185], v[128:131]
	v_mfma_f32_16x16x32_bf16 v[112:115], v[150:153], v[190:193], v[112:115]
	v_mfma_f32_16x16x32_bf16 v[108:111], v[158:161], v[190:193], v[108:111]
	v_mfma_f32_16x16x32_bf16 v[94:97], v[150:153], v[212:215], v[94:97]
	v_mfma_f32_16x16x32_bf16 v[90:93], v[158:161], v[212:215], v[90:93]
	v_mfma_f32_16x16x32_bf16 v[78:81], v[150:153], v[220:223], v[78:81]
	v_mfma_f32_16x16x32_bf16 v[74:77], v[158:161], v[220:223], v[74:77]
	s_setprio 0
	s_setprio 1
	v_mfma_f32_16x16x32_bf16 v[120:123], v[162:165], v[178:181], v[120:123]
	v_mfma_f32_16x16x32_bf16 v[116:119], v[170:173], v[178:181], v[116:119]
	v_mfma_f32_16x16x32_bf16 v[104:107], v[162:165], v[186:189], v[104:107]
	v_mfma_f32_16x16x32_bf16 v[100:103], v[170:173], v[186:189], v[100:103]
	v_mfma_f32_16x16x32_bf16 v[86:89], v[162:165], v[208:211], v[86:89]
	v_mfma_f32_16x16x32_bf16 v[82:85], v[170:173], v[208:211], v[82:85]
	v_mfma_f32_16x16x32_bf16 v[70:73], v[162:165], v[216:219], v[70:73]
	v_mfma_f32_16x16x32_bf16 v[66:69], v[170:173], v[216:219], v[66:69]
	v_mfma_f32_16x16x32_bf16 v[120:123], v[166:169], v[182:185], v[120:123]
	v_mfma_f32_16x16x32_bf16 v[116:119], v[174:177], v[182:185], v[116:119]
	v_mfma_f32_16x16x32_bf16 v[104:107], v[166:169], v[190:193], v[104:107]
	v_mfma_f32_16x16x32_bf16 v[100:103], v[174:177], v[190:193], v[100:103]
	v_mfma_f32_16x16x32_bf16 v[86:89], v[166:169], v[212:215], v[86:89]
	v_mfma_f32_16x16x32_bf16 v[82:85], v[174:177], v[212:215], v[82:85]
	v_mfma_f32_16x16x32_bf16 v[70:73], v[166:169], v[220:223], v[70:73]
	v_mfma_f32_16x16x32_bf16 v[66:69], v[174:177], v[220:223], v[66:69]
	s_setprio 0
	s_barrier
	s_add_i32 s28, s33, s59
	v_lshl_add_u64 v[224:225], s[30:31], 0, v[98:99]
	s_mov_b32 m0, s28
	ds_read_b128 v[178:181], v149 offset:16384
	ds_read_b128 v[182:185], v149 offset:17408
	ds_read_b128 v[186:189], v149 offset:18432
	ds_read_b128 v[190:193], v149 offset:19456
	ds_read_b128 v[208:211], v149 offset:20480
	ds_read_b128 v[212:215], v149 offset:21504
	ds_read_b128 v[216:219], v149 offset:22528
	ds_read_b128 v[220:223], v149 offset:23552
	global_load_lds_dwordx4 v[224:225], off
	s_add_i32 m0, s28, 0x2000
	v_lshl_add_u64 v[228:229], s[30:31], 0, v[132:133]
	s_add_u32 s30, s30, s10
	s_addc_u32 s31, s31, s11
	s_add_i32 s17, s17, s59
	global_load_lds_dwordx4 v[228:229], off
	v_lshl_add_u64 v[230:231], s[30:31], 0, v[98:99]
	s_mov_b32 m0, s17
	v_lshl_add_u64 v[232:233], s[30:31], 0, v[132:133]
	global_load_lds_dwordx4 v[230:231], off
	s_add_i32 m0, s17, 0x2000
	v_lshl_add_u64 v[234:235], s[36:37], 0, v[136:137]
	global_load_lds_dwordx4 v[232:233], off
	s_mov_b32 m0, s66
	v_lshl_add_u64 v[236:237], s[36:37], 0, v[134:135]
	global_load_lds_dwordx4 v[234:235], off
	s_mov_b32 m0, s67
	s_nop 0
	global_load_lds_dwordx4 v[236:237], off
	s_waitcnt vmcnt(8)
	s_waitcnt lgkmcnt(0)
	s_barrier
; #define PG8_STAGE(bufoff, gbase, voff) do { _Pragma("unroll") for (int _i = 0; _i < 2; ++_i) \
;         __builtin_amdgcn_global_load_lds((const unsigned*)((const char*)(gbase) + (voff)[_i]), (PG8_LAS unsigned*)(lds + (bufoff) + ldsw + _i * 8192), 16, 0, 0); } while (0)
; #define PG8_LDA(dst, b, h) do { _Pragma("unroll") for (int m = 0; m < 4; ++m) _Pragma("unroll") for (int k = 0; k < 2; ++k) dst[m][k] = *(const PG8_LAS bf16x8*)(lds + PG8_SA(b, h) + aoff + m * 2048 + k * 1024); } while (0)
; #define PG8_LDB(dst, b, h) do { _Pragma("unroll") for (int n = 0; n < 2; ++n) _Pragma("unroll") for (int k = 0; k < 2; ++k) dst[n][k] = *(const PG8_LAS bf16x8*)(lds + PG8_SB(b, h) + boff + n * 2048 + k * 1024); } while (0)
; #define PG8_MMA(ai, bj, At, Bt) do { __builtin_amdgcn_s_setprio(1); _Pragma("unroll") for (int m = 0; m < 4; ++m) _Pragma("unroll") for (int n = 0; n < 2; ++n) _Pragma("unroll") for (int k = 0; k < 2; ++k) \
;         acc[ai][bj][m][n] = __builtin_amdgcn_mfma_f32_16x16x32_bf16(Bt[n][k], At[m][k], acc[ai][bj][m][n], 0, 0, 0); __builtin_amdgcn_s_setprio(0); } while (0)
; #define PG8_WAIT_V(n) asm volatile("s_waitcnt vmcnt(" #n ")" ::: "memory")
; #define PG8_WAIT_L(n) asm volatile("s_waitcnt lgkmcnt(" #n ")" ::: "memory")
; #define PG8_BAR __builtin_amdgcn_s_barrier()
; #define PG8_SCHED __builtin_amdgcn_sched_barrier(0)
; template <class Epi, class Sched, bool ALIGN_EPI = false, bool SP2 = false>
; __device__ __forceinline__ void gemm_phase(PG8_LAS unsigned char* lds, const Gemm g, const Sched& S, const Epi& E) {
;     ...
;             PG8_WAIT_V(8); PG8_WAIT_L(0); PG8_BAR; PG8_MMA(1, 0, At, B0); PG8_MMA(1, 1, At, B1); PG8_BAR; PG8_SCHED;
;             PG8_LDB(B0, 1, 0); PG8_LDB(B1, 1, 1); PG8_SCHED; PG8_LDA(At, 1, 0); PG8_STAGE(PG8_SA(0, 1), a2 + hstep, voffA);
;             PG8_WAIT_V(8); PG8_WAIT_L(0); PG8_BAR; PG8_MMA(0, 0, At, B0); PG8_MMA(0, 1, At, B1); PG8_BAR; PG8_SCHED;
	s_setprio 1
	v_mfma_f32_16x16x32_bf16 v[62:65], v[144:147], v[178:181], v[62:65]
	v_mfma_f32_16x16x32_bf16 v[58:61], v[154:157], v[178:181], v[58:61]
	v_mfma_f32_16x16x32_bf16 v[46:49], v[144:147], v[186:189], v[46:49]
	v_mfma_f32_16x16x32_bf16 v[42:45], v[154:157], v[186:189], v[42:45]
	v_mfma_f32_16x16x32_bf16 v[30:33], v[144:147], v[208:211], v[30:33]
	v_mfma_f32_16x16x32_bf16 v[26:29], v[154:157], v[208:211], v[26:29]
	v_mfma_f32_16x16x32_bf16 v[14:17], v[144:147], v[216:219], v[14:17]
	v_mfma_f32_16x16x32_bf16 v[10:13], v[154:157], v[216:219], v[10:13]
	v_mfma_f32_16x16x32_bf16 v[62:65], v[150:153], v[182:185], v[62:65]
	v_mfma_f32_16x16x32_bf16 v[58:61], v[158:161], v[182:185], v[58:61]
	v_mfma_f32_16x16x32_bf16 v[46:49], v[150:153], v[190:193], v[46:49]
	v_mfma_f32_16x16x32_bf16 v[42:45], v[158:161], v[190:193], v[42:45]
	v_mfma_f32_16x16x32_bf16 v[30:33], v[150:153], v[212:215], v[30:33]
	v_mfma_f32_16x16x32_bf16 v[26:29], v[158:161], v[212:215], v[26:29]
	v_mfma_f32_16x16x32_bf16 v[14:17], v[150:153], v[220:223], v[14:17]
	v_mfma_f32_16x16x32_bf16 v[10:13], v[158:161], v[220:223], v[10:13]
	s_setprio 0
	s_setprio 1
	v_mfma_f32_16x16x32_bf16 v[54:57], v[162:165], v[178:181], v[54:57]
	v_mfma_f32_16x16x32_bf16 v[50:53], v[170:173], v[178:181], v[50:53]
	v_mfma_f32_16x16x32_bf16 v[38:41], v[162:165], v[186:189], v[38:41]
	v_mfma_f32_16x16x32_bf16 v[34:37], v[170:173], v[186:189], v[34:37]
	v_mfma_f32_16x16x32_bf16 v[22:25], v[162:165], v[208:211], v[22:25]
	v_mfma_f32_16x16x32_bf16 v[18:21], v[170:173], v[208:211], v[18:21]
	v_mfma_f32_16x16x32_bf16 v[6:9], v[162:165], v[216:219], v[6:9]
	v_mfma_f32_16x16x32_bf16 v[2:5], v[170:173], v[216:219], v[2:5]
	v_mfma_f32_16x16x32_bf16 v[54:57], v[166:169], v[182:185], v[54:57]
	v_mfma_f32_16x16x32_bf16 v[50:53], v[174:177], v[182:185], v[50:53]
	v_mfma_f32_16x16x32_bf16 v[38:41], v[166:169], v[190:193], v[38:41]
	v_mfma_f32_16x16x32_bf16 v[34:37], v[174:177], v[190:193], v[34:37]
	v_mfma_f32_16x16x32_bf16 v[22:25], v[166:169], v[212:215], v[22:25]
	v_mfma_f32_16x16x32_bf16 v[18:21], v[174:177], v[212:215], v[18:21]
	v_mfma_f32_16x16x32_bf16 v[6:9], v[166:169], v[220:223], v[6:9]
	v_mfma_f32_16x16x32_bf16 v[2:5], v[174:177], v[220:223], v[2:5]
	s_setprio 0
	s_barrier
	s_add_i32 s17, 0, 0x18000
	s_add_i32 s28, 0, 0x1c000
	v_add_u32_e32 v158, s17, v148
	v_add_u32_e32 v174, s28, v148
	ds_read_b128 v[144:147], v158
	ds_read_b128 v[150:153], v158 offset:1024
	ds_read_b128 v[154:157], v158 offset:2048
	ds_read_b128 v[158:161], v158 offset:3072
	ds_read_b128 v[162:165], v174
	ds_read_b128 v[166:169], v174 offset:1024
	ds_read_b128 v[170:173], v174 offset:2048
	ds_read_b128 v[174:177], v174 offset:3072
	s_add_u32 s30, s36, s10
	s_addc_u32 s31, s37, s11
	s_mov_b32 m0, s68
	v_lshl_add_u64 v[238:239], s[30:31], 0, v[136:137]
	ds_read_b128 v[178:181], v149 offset:32768
	ds_read_b128 v[182:185], v149 offset:33792
	ds_read_b128 v[186:189], v149 offset:34816
	ds_read_b128 v[190:193], v149 offset:35840
	ds_read_b128 v[208:211], v149 offset:36864
	ds_read_b128 v[212:215], v149 offset:37888
	ds_read_b128 v[216:219], v149 offset:38912
	ds_read_b128 v[220:223], v149 offset:39936
	global_load_lds_dwordx4 v[238:239], off
	v_lshl_add_u64 v[238:239], s[30:31], 0, v[134:135]
	s_mov_b32 m0, s69
	s_nop 0
	global_load_lds_dwordx4 v[238:239], off
	s_waitcnt vmcnt(8)
	s_waitcnt lgkmcnt(0)
	s_barrier
	s_setprio 1
	v_mfma_f32_16x16x32_bf16 v[124:127], v[144:147], v[178:181], v[124:127]
	v_mfma_f32_16x16x32_bf16 v[128:131], v[154:157], v[178:181], v[128:131]
	v_mfma_f32_16x16x32_bf16 v[112:115], v[144:147], v[186:189], v[112:115]
	v_mfma_f32_16x16x32_bf16 v[108:111], v[154:157], v[186:189], v[108:111]
	v_mfma_f32_16x16x32_bf16 v[94:97], v[144:147], v[208:211], v[94:97]
	v_mfma_f32_16x16x32_bf16 v[90:93], v[154:157], v[208:211], v[90:93]
	v_mfma_f32_16x16x32_bf16 v[78:81], v[144:147], v[216:219], v[78:81]
	v_mfma_f32_16x16x32_bf16 v[74:77], v[154:157], v[216:219], v[74:77]
	v_mfma_f32_16x16x32_bf16 v[124:127], v[150:153], v[182:185], v[124:127]
	v_mfma_f32_16x16x32_bf16 v[128:131], v[158:161], v[182:185], v[128:131]
	v_mfma_f32_16x16x32_bf16 v[112:115], v[150:153], v[190:193], v[112:115]
	v_mfma_f32_16x16x32_bf16 v[108:111], v[158:161], v[190:193], v[108:111]
	v_mfma_f32_16x16x32_bf16 v[94:97], v[150:153], v[212:215], v[94:97]
	v_mfma_f32_16x16x32_bf16 v[90:93], v[158:161], v[212:215], v[90:93]
	v_mfma_f32_16x16x32_bf16 v[78:81], v[150:153], v[220:223], v[78:81]
	v_mfma_f32_16x16x32_bf16 v[74:77], v[158:161], v[220:223], v[74:77]
	s_setprio 0
	s_setprio 1
	v_mfma_f32_16x16x32_bf16 v[120:123], v[162:165], v[178:181], v[120:123]
	v_mfma_f32_16x16x32_bf16 v[116:119], v[170:173], v[178:181], v[116:119]
	v_mfma_f32_16x16x32_bf16 v[104:107], v[162:165], v[186:189], v[104:107]
	v_mfma_f32_16x16x32_bf16 v[100:103], v[170:173], v[186:189], v[100:103]
	v_mfma_f32_16x16x32_bf16 v[86:89], v[162:165], v[208:211], v[86:89]
	v_mfma_f32_16x16x32_bf16 v[82:85], v[170:173], v[208:211], v[82:85]
	v_mfma_f32_16x16x32_bf16 v[70:73], v[162:165], v[216:219], v[70:73]
	v_mfma_f32_16x16x32_bf16 v[66:69], v[170:173], v[216:219], v[66:69]
	v_mfma_f32_16x16x32_bf16 v[120:123], v[166:169], v[182:185], v[120:123]
	v_mfma_f32_16x16x32_bf16 v[116:119], v[174:177], v[182:185], v[116:119]
	v_mfma_f32_16x16x32_bf16 v[104:107], v[166:169], v[190:193], v[104:107]
	v_mfma_f32_16x16x32_bf16 v[100:103], v[174:177], v[190:193], v[100:103]
	v_mfma_f32_16x16x32_bf16 v[86:89], v[166:169], v[212:215], v[86:89]
	v_mfma_f32_16x16x32_bf16 v[82:85], v[174:177], v[212:215], v[82:85]
	v_mfma_f32_16x16x32_bf16 v[70:73], v[166:169], v[220:223], v[70:73]
	v_mfma_f32_16x16x32_bf16 v[66:69], v[174:177], v[220:223], v[66:69]
	s_setprio 0
	s_barrier
; #define PG8_STAGE(bufoff, gbase, voff) do { _Pragma("unroll") for (int _i = 0; _i < 2; ++_i) \
;         __builtin_amdgcn_global_load_lds((const unsigned*)((const char*)(gbase) + (voff)[_i]), (PG8_LAS unsigned*)(lds + (bufoff) + ldsw + _i * 8192), 16, 0, 0); } while (0)
; #define PG8_LDA(dst, b, h) do { _Pragma("unroll") for (int m = 0; m < 4; ++m) _Pragma("unroll") for (int k = 0; k < 2; ++k) dst[m][k] = *(const PG8_LAS bf16x8*)(lds + PG8_SA(b, h) + aoff + m * 2048 + k * 1024); } while (0)
; #define PG8_MMA(ai, bj, At, Bt) do { __builtin_amdgcn_s_setprio(1); _Pragma("unroll") for (int m = 0; m < 4; ++m) _Pragma("unroll") for (int n = 0; n < 2; ++n) _Pragma("unroll") for (int k = 0; k < 2; ++k) \
;         acc[ai][bj][m][n] = __builtin_amdgcn_mfma_f32_16x16x32_bf16(Bt[n][k], At[m][k], acc[ai][bj][m][n], 0, 0, 0); __builtin_amdgcn_s_setprio(0); } while (0)
; #define PG8_WAIT_V(n) asm volatile("s_waitcnt vmcnt(" #n ")" ::: "memory")
; #define PG8_WAIT_L(n) asm volatile("s_waitcnt lgkmcnt(" #n ")" ::: "memory")
; #define PG8_BAR __builtin_amdgcn_s_barrier()
; #define PG8_SCHED __builtin_amdgcn_sched_barrier(0)
; template <class Epi, class Sched, bool ALIGN_EPI = false, bool SP2 = false>
; __device__ __forceinline__ void gemm_phase(PG8_LAS unsigned char* lds, const Gemm g, const Sched& S, const Epi& E) {
;     ...
;         for (int t = 0; t < nt; t += 2) {
;     ...
;             PG8_LDA(At, 1, 1); PG8_STAGE(PG8_SB(1, 0), b3, voffB); PG8_STAGE(PG8_SB(1, 1), b3 + hstep, voffB); PG8_STAGE(PG8_SA(1, 0), a3, voffA);
;             PG8_WAIT_V(8); PG8_WAIT_L(0); PG8_BAR; PG8_MMA(1, 0, At, B0); PG8_MMA(1, 1, At, B1); PG8_BAR; PG8_SCHED;
	s_add_i32 s17, s17, s59
	v_lshl_add_u64 v[224:225], v[224:225], 0, s[24:25]
	s_mov_b32 m0, s17
	ds_read_b128 v[178:181], v149 offset:49152
	ds_read_b128 v[182:185], v149 offset:50176
	ds_read_b128 v[186:189], v149 offset:51200
	ds_read_b128 v[190:193], v149 offset:52224
	ds_read_b128 v[208:211], v149 offset:53248
	ds_read_b128 v[212:215], v149 offset:54272
	ds_read_b128 v[216:219], v149 offset:55296
	ds_read_b128 v[220:223], v149 offset:56320
	global_load_lds_dwordx4 v[224:225], off
	v_lshl_add_u64 v[224:225], v[228:229], 0, s[24:25]
	s_add_i32 m0, s17, 0x2000
	s_add_i32 s17, s28, s59
	global_load_lds_dwordx4 v[224:225], off
	v_lshl_add_u64 v[224:225], v[230:231], 0, s[24:25]
	s_mov_b32 m0, s17
	s_nop 0
	global_load_lds_dwordx4 v[224:225], off
	v_lshl_add_u64 v[224:225], v[232:233], 0, s[24:25]
	s_add_i32 m0, s17, 0x2000
	s_nop 0
	global_load_lds_dwordx4 v[224:225], off
	v_lshl_add_u64 v[224:225], v[234:235], 0, s[24:25]
	s_mov_b32 m0, s71
	s_nop 0
	global_load_lds_dwordx4 v[224:225], off
	v_lshl_add_u64 v[224:225], v[236:237], 0, s[24:25]
	s_mov_b32 m0, s72
	s_nop 0
	global_load_lds_dwordx4 v[224:225], off
	s_waitcnt vmcnt(8)
	s_waitcnt lgkmcnt(0)
	s_barrier
	s_setprio 1
	v_mfma_f32_16x16x32_bf16 v[62:65], v[144:147], v[178:181], v[62:65]
	v_mfma_f32_16x16x32_bf16 v[58:61], v[154:157], v[178:181], v[58:61]
	v_mfma_f32_16x16x32_bf16 v[46:49], v[144:147], v[186:189], v[46:49]
	v_mfma_f32_16x16x32_bf16 v[42:45], v[154:157], v[186:189], v[42:45]
	v_mfma_f32_16x16x32_bf16 v[30:33], v[144:147], v[208:211], v[30:33]
	v_mfma_f32_16x16x32_bf16 v[26:29], v[154:157], v[208:211], v[26:29]
	v_mfma_f32_16x16x32_bf16 v[14:17], v[144:147], v[216:219], v[14:17]
	v_mfma_f32_16x16x32_bf16 v[10:13], v[154:157], v[216:219], v[10:13]
	v_mfma_f32_16x16x32_bf16 v[62:65], v[150:153], v[182:185], v[62:65]
	v_mfma_f32_16x16x32_bf16 v[58:61], v[158:161], v[182:185], v[58:61]
	v_mfma_f32_16x16x32_bf16 v[46:49], v[150:153], v[190:193], v[46:49]
	v_mfma_f32_16x16x32_bf16 v[42:45], v[158:161], v[190:193], v[42:45]
	v_mfma_f32_16x16x32_bf16 v[30:33], v[150:153], v[212:215], v[30:33]
	v_mfma_f32_16x16x32_bf16 v[26:29], v[158:161], v[212:215], v[26:29]
	v_mfma_f32_16x16x32_bf16 v[14:17], v[150:153], v[220:223], v[14:17]
	v_mfma_f32_16x16x32_bf16 v[10:13], v[158:161], v[220:223], v[10:13]
	s_setprio 0
	s_setprio 1
	v_mfma_f32_16x16x32_bf16 v[54:57], v[162:165], v[178:181], v[54:57]
	v_mfma_f32_16x16x32_bf16 v[50:53], v[170:173], v[178:181], v[50:53]
	v_mfma_f32_16x16x32_bf16 v[38:41], v[162:165], v[186:189], v[38:41]
	v_mfma_f32_16x16x32_bf16 v[34:37], v[170:173], v[186:189], v[34:37]
	v_mfma_f32_16x16x32_bf16 v[22:25], v[162:165], v[208:211], v[22:25]
	v_mfma_f32_16x16x32_bf16 v[18:21], v[170:173], v[208:211], v[18:21]
	v_mfma_f32_16x16x32_bf16 v[6:9], v[162:165], v[216:219], v[6:9]
	v_mfma_f32_16x16x32_bf16 v[2:5], v[170:173], v[216:219], v[2:5]
	v_mfma_f32_16x16x32_bf16 v[54:57], v[166:169], v[182:185], v[54:57]
	v_mfma_f32_16x16x32_bf16 v[50:53], v[174:177], v[182:185], v[50:53]
	v_mfma_f32_16x16x32_bf16 v[38:41], v[166:169], v[190:193], v[38:41]
	v_mfma_f32_16x16x32_bf16 v[34:37], v[174:177], v[190:193], v[34:37]
	v_mfma_f32_16x16x32_bf16 v[22:25], v[166:169], v[212:215], v[22:25]
	v_mfma_f32_16x16x32_bf16 v[18:21], v[174:177], v[212:215], v[18:21]
	v_mfma_f32_16x16x32_bf16 v[6:9], v[166:169], v[220:223], v[6:9]
	v_mfma_f32_16x16x32_bf16 v[2:5], v[174:177], v[220:223], v[2:5]
	s_setprio 0
	s_barrier
	s_add_u32 s34, s34, 0x100
	s_addc_u32 s35, s35, 0
	s_add_u32 s4, s4, 0x100
	s_addc_u32 s16, s16, 0
	s_cmp_ge_i32 s22, s70
	s_mov_b32 s17, s22
	s_cbranch_scc0 .LBB0_1180

; #define PG8_STAGE(bufoff, gbase, voff) do { _Pragma("unroll") for (int _i = 0; _i < 2; ++_i) \
;         __builtin_amdgcn_global_load_lds((const unsigned*)((const char*)(gbase) + (voff)[_i]), (PG8_LAS unsigned*)(lds + (bufoff) + ldsw + _i * 8192), 16, 0, 0); } while (0)
; #define PG8_LDA(dst, b, h) do { _Pragma("unroll") for (int m = 0; m < 4; ++m) _Pragma("unroll") for (int k = 0; k < 2; ++k) dst[m][k] = *(const PG8_LAS bf16x8*)(lds + PG8_SA(b, h) + aoff + m * 2048 + k * 1024); } while (0)
; #define PG8_LDB(dst, b, h) do { _Pragma("unroll") for (int n = 0; n < 2; ++n) _Pragma("unroll") for (int k = 0; k < 2; ++k) dst[n][k] = *(const PG8_LAS bf16x8*)(lds + PG8_SB(b, h) + boff + n * 2048 + k * 1024); } while (0)
; #define PG8_MMA(ai, bj, At, Bt) do { __builtin_amdgcn_s_setprio(1); _Pragma("unroll") for (int m = 0; m < 4; ++m) _Pragma("unroll") for (int n = 0; n < 2; ++n) _Pragma("unroll") for (int k = 0; k < 2; ++k) \
;         acc[ai][bj][m][n] = __builtin_amdgcn_mfma_f32_16x16x32_bf16(Bt[n][k], At[m][k], acc[ai][bj][m][n], 0, 0, 0); __builtin_amdgcn_s_setprio(0); } while (0)
; #define PG8_WAIT_V(n) asm volatile("s_waitcnt vmcnt(" #n ")" ::: "memory")
; #define PG8_WAIT_L(n) asm volatile("s_waitcnt lgkmcnt(" #n ")" ::: "memory")
; #define PG8_BAR __builtin_amdgcn_s_barrier()
; #define PG8_SCHED __builtin_amdgcn_sched_barrier(0)
; template <class Epi, class Sched, bool ALIGN_EPI = false, bool SP2 = false>
; __device__ __forceinline__ void gemm_phase(PG8_LAS unsigned char* lds, const Gemm g, const Sched& S, const Epi& E) {
;     ...
;             const bool last = (t == nt - 2);
;             const char* a1 = cA + (size_t)(t + 1) * kstep;
;             const char* a2 = last ? nA : cA + (size_t)(t + 2) * kstep; const char* b2 = last ? nB : cB + (size_t)(t + 2) * kstep;
;             const char* a3 = a2 + kstep; const char* b3 = b2 + kstep;
;             if (last && has_next) S.a_ready(nxt);
;             if constexpr (SP2) {
;             PG8_LDB(B0, 0, 0); PG8_LDB(B1, 0, 1); PG8_SCHED; PG8_LDA(At, 0, 0); PG8_STAGE(PG8_SA(1, 1), a1 + hstep, voffA);
;             PG8_WAIT_V(8); PG8_WAIT_L(0); PG8_BAR; PG8_MMA(0, 0, At, B0); PG8_MMA(0, 1, At, B1); PG8_BAR; PG8_SCHED;
;             PG8_LDA(At, 0, 1); PG8_STAGE(PG8_SB(0, 0), b2, voffB); PG8_STAGE(PG8_SB(0, 1), b2 + hstep, voffB); PG8_STAGE(PG8_SA(0, 0), a2, voffA);
.LBB0_1209:
	s_add_i32 s22, s17, 2
	s_add_u32 s28, s2, 0x80
	s_addc_u32 s30, s3, 0
	s_add_i32 s33, 0, 0x10000
	s_cmp_eq_u32 s74, s17
	s_cselect_b32 s35, s51, s30
	s_cselect_b32 s34, s50, s28
	v_add_u32_e32 v98, s33, v166
	s_cselect_b32 s31, s53, s16
	s_cselect_b32 s30, s52, s4
	s_add_i32 s17, 0, 0x14000
	ds_read_b128 v[132:135], v98
	ds_read_b128 v[136:139], v98 offset:1024
	ds_read_b128 v[140:143], v98 offset:2048
	ds_read_b128 v[156:159], v98 offset:3072
	v_add_u32_e32 v98, s17, v166
	ds_read_b128 v[160:163], v98
	ds_read_b128 v[170:173], v98 offset:1024
	ds_read_b128 v[174:177], v98 offset:2048
	ds_read_b128 v[178:181], v98 offset:3072
	v_lshl_add_u64 v[164:165], s[2:3], 0, v[152:153]
	s_add_i32 m0, s67, 0xc000
	ds_read_b128 v[182:185], v168
	ds_read_b128 v[186:189], v168 offset:1024
	ds_read_b128 v[190:193], v168 offset:2048
	ds_read_b128 v[208:211], v168 offset:3072
	ds_read_b128 v[212:215], v168 offset:4096
	ds_read_b128 v[216:219], v168 offset:5120
	ds_read_b128 v[220:223], v168 offset:6144
	ds_read_b128 v[228:231], v168 offset:7168
	global_load_lds_dwordx4 v[164:165], off
	v_lshl_add_u64 v[164:165], s[2:3], 0, v[154:155]
	s_add_i32 m0, s67, 0xe000
	s_nop 0
	global_load_lds_dwordx4 v[164:165], off
	s_waitcnt vmcnt(8)
	s_waitcnt lgkmcnt(0)
	s_barrier
	s_setprio 1
	v_mfma_f32_16x16x32_bf16 v[128:131], v[132:135], v[182:185], v[128:131]
	v_mfma_f32_16x16x32_bf16 v[124:127], v[140:143], v[182:185], v[124:127]
	v_mfma_f32_16x16x32_bf16 v[120:123], v[132:135], v[190:193], v[120:123]
	v_mfma_f32_16x16x32_bf16 v[116:119], v[140:143], v[190:193], v[116:119]
	v_mfma_f32_16x16x32_bf16 v[112:115], v[132:135], v[212:215], v[112:115]
	v_mfma_f32_16x16x32_bf16 v[108:111], v[140:143], v[212:215], v[108:111]
	v_mfma_f32_16x16x32_bf16 v[104:107], v[132:135], v[220:223], v[104:107]
	v_mfma_f32_16x16x32_bf16 v[100:103], v[140:143], v[220:223], v[100:103]
	v_mfma_f32_16x16x32_bf16 v[128:131], v[136:139], v[186:189], v[128:131]
	v_mfma_f32_16x16x32_bf16 v[124:127], v[156:159], v[186:189], v[124:127]
	v_mfma_f32_16x16x32_bf16 v[120:123], v[136:139], v[208:211], v[120:123]
	v_mfma_f32_16x16x32_bf16 v[116:119], v[156:159], v[208:211], v[116:119]
	v_mfma_f32_16x16x32_bf16 v[112:115], v[136:139], v[216:219], v[112:115]
	v_mfma_f32_16x16x32_bf16 v[108:111], v[156:159], v[216:219], v[108:111]
	v_mfma_f32_16x16x32_bf16 v[104:107], v[136:139], v[228:231], v[104:107]
	v_mfma_f32_16x16x32_bf16 v[100:103], v[156:159], v[228:231], v[100:103]
	s_setprio 0
	s_setprio 1
	v_mfma_f32_16x16x32_bf16 v[62:65], v[160:163], v[182:185], v[62:65]
	v_mfma_f32_16x16x32_bf16 v[58:61], v[174:177], v[182:185], v[58:61]
	v_mfma_f32_16x16x32_bf16 v[54:57], v[160:163], v[190:193], v[54:57]
	v_mfma_f32_16x16x32_bf16 v[50:53], v[174:177], v[190:193], v[50:53]
	v_mfma_f32_16x16x32_bf16 v[46:49], v[160:163], v[212:215], v[46:49]
	v_mfma_f32_16x16x32_bf16 v[42:45], v[174:177], v[212:215], v[42:45]
	v_mfma_f32_16x16x32_bf16 v[38:41], v[160:163], v[220:223], v[38:41]
	v_mfma_f32_16x16x32_bf16 v[34:37], v[174:177], v[220:223], v[34:37]
	v_mfma_f32_16x16x32_bf16 v[62:65], v[170:173], v[186:189], v[62:65]
	v_mfma_f32_16x16x32_bf16 v[58:61], v[178:181], v[186:189], v[58:61]
	v_mfma_f32_16x16x32_bf16 v[54:57], v[170:173], v[208:211], v[54:57]
	v_mfma_f32_16x16x32_bf16 v[50:53], v[178:181], v[208:211], v[50:53]
	v_mfma_f32_16x16x32_bf16 v[46:49], v[170:173], v[216:219], v[46:49]
	v_mfma_f32_16x16x32_bf16 v[42:45], v[178:181], v[216:219], v[42:45]
	v_mfma_f32_16x16x32_bf16 v[38:41], v[170:173], v[228:231], v[38:41]
	v_mfma_f32_16x16x32_bf16 v[34:37], v[178:181], v[228:231], v[34:37]
	s_setprio 0
	s_barrier
	s_add_i32 s28, s33, s62
	v_lshl_add_u64 v[164:165], s[30:31], 0, v[146:147]
	s_mov_b32 m0, s28
	ds_read_b128 v[182:185], v168 offset:16384
	ds_read_b128 v[186:189], v168 offset:17408
	ds_read_b128 v[190:193], v168 offset:18432
	ds_read_b128 v[208:211], v168 offset:19456
	ds_read_b128 v[212:215], v168 offset:20480
	ds_read_b128 v[216:219], v168 offset:21504
	ds_read_b128 v[220:223], v168 offset:22528
	ds_read_b128 v[228:231], v168 offset:23552
	global_load_lds_dwordx4 v[164:165], off
	s_add_i32 m0, s28, 0x2000
	v_lshl_add_u64 v[224:225], s[30:31], 0, v[150:151]
	s_add_u32 s30, s30, s10
	s_addc_u32 s31, s31, s11
	s_add_i32 s17, s17, s62
	global_load_lds_dwordx4 v[224:225], off
	v_lshl_add_u64 v[232:233], s[30:31], 0, v[146:147]
	s_mov_b32 m0, s17
	v_lshl_add_u64 v[234:235], s[30:31], 0, v[150:151]
	global_load_lds_dwordx4 v[232:233], off
	s_add_i32 m0, s17, 0x2000
	v_lshl_add_u64 v[236:237], s[34:35], 0, v[144:145]
	global_load_lds_dwordx4 v[234:235], off
	s_mov_b32 m0, s67
	v_lshl_add_u64 v[238:239], s[34:35], 0, v[148:149]
	global_load_lds_dwordx4 v[236:237], off
	s_mov_b32 m0, s68
	s_nop 0
	global_load_lds_dwordx4 v[238:239], off
	s_waitcnt vmcnt(8)
	s_waitcnt lgkmcnt(0)
	s_barrier
; #define PG8_STAGE(bufoff, gbase, voff) do { _Pragma("unroll") for (int _i = 0; _i < 2; ++_i) \
;         __builtin_amdgcn_global_load_lds((const unsigned*)((const char*)(gbase) + (voff)[_i]), (PG8_LAS unsigned*)(lds + (bufoff) + ldsw + _i * 8192), 16, 0, 0); } while (0)
; #define PG8_LDA(dst, b, h) do { _Pragma("unroll") for (int m = 0; m < 4; ++m) _Pragma("unroll") for (int k = 0; k < 2; ++k) dst[m][k] = *(const PG8_LAS bf16x8*)(lds + PG8_SA(b, h) + aoff + m * 2048 + k * 1024); } while (0)
; #define PG8_LDB(dst, b, h) do { _Pragma("unroll") for (int n = 0; n < 2; ++n) _Pragma("unroll") for (int k = 0; k < 2; ++k) dst[n][k] = *(const PG8_LAS bf16x8*)(lds + PG8_SB(b, h) + boff + n * 2048 + k * 1024); } while (0)
; #define PG8_MMA(ai, bj, At, Bt) do { __builtin_amdgcn_s_setprio(1); _Pragma("unroll") for (int m = 0; m < 4; ++m) _Pragma("unroll") for (int n = 0; n < 2; ++n) _Pragma("unroll") for (int k = 0; k < 2; ++k) \
;         acc[ai][bj][m][n] = __builtin_amdgcn_mfma_f32_16x16x32_bf16(Bt[n][k], At[m][k], acc[ai][bj][m][n], 0, 0, 0); __builtin_amdgcn_s_setprio(0); } while (0)
; #define PG8_WAIT_V(n) asm volatile("s_waitcnt vmcnt(" #n ")" ::: "memory")
; #define PG8_WAIT_L(n) asm volatile("s_waitcnt lgkmcnt(" #n ")" ::: "memory")
; #define PG8_BAR __builtin_amdgcn_s_barrier()
; #define PG8_SCHED __builtin_amdgcn_sched_barrier(0)
; template <class Epi, class Sched, bool ALIGN_EPI = false, bool SP2 = false>
; __device__ __forceinline__ void gemm_phase(PG8_LAS unsigned char* lds, const Gemm g, const Sched& S, const Epi& E) {
;     ...
;             PG8_WAIT_V(8); PG8_WAIT_L(0); PG8_BAR; PG8_MMA(1, 0, At, B0); PG8_MMA(1, 1, At, B1); PG8_BAR; PG8_SCHED;
;             PG8_LDB(B0, 1, 0); PG8_LDB(B1, 1, 1); PG8_SCHED; PG8_LDA(At, 1, 0); PG8_STAGE(PG8_SA(0, 1), a2 + hstep, voffA);
;             PG8_WAIT_V(8); PG8_WAIT_L(0); PG8_BAR; PG8_MMA(0, 0, At, B0); PG8_MMA(0, 1, At, B1); PG8_BAR; PG8_SCHED;
	s_setprio 1
	v_mfma_f32_16x16x32_bf16 v[94:97], v[132:135], v[182:185], v[94:97]
	v_mfma_f32_16x16x32_bf16 v[90:93], v[140:143], v[182:185], v[90:93]
	v_mfma_f32_16x16x32_bf16 v[86:89], v[132:135], v[190:193], v[86:89]
	v_mfma_f32_16x16x32_bf16 v[82:85], v[140:143], v[190:193], v[82:85]
	v_mfma_f32_16x16x32_bf16 v[78:81], v[132:135], v[212:215], v[78:81]
	v_mfma_f32_16x16x32_bf16 v[74:77], v[140:143], v[212:215], v[74:77]
	v_mfma_f32_16x16x32_bf16 v[70:73], v[132:135], v[220:223], v[70:73]
	v_mfma_f32_16x16x32_bf16 v[66:69], v[140:143], v[220:223], v[66:69]
	v_mfma_f32_16x16x32_bf16 v[94:97], v[136:139], v[186:189], v[94:97]
	v_mfma_f32_16x16x32_bf16 v[90:93], v[156:159], v[186:189], v[90:93]
	v_mfma_f32_16x16x32_bf16 v[86:89], v[136:139], v[208:211], v[86:89]
	v_mfma_f32_16x16x32_bf16 v[82:85], v[156:159], v[208:211], v[82:85]
	v_mfma_f32_16x16x32_bf16 v[78:81], v[136:139], v[216:219], v[78:81]
	v_mfma_f32_16x16x32_bf16 v[74:77], v[156:159], v[216:219], v[74:77]
	v_mfma_f32_16x16x32_bf16 v[70:73], v[136:139], v[228:231], v[70:73]
	v_mfma_f32_16x16x32_bf16 v[66:69], v[156:159], v[228:231], v[66:69]
	s_setprio 0
	s_setprio 1
	v_mfma_f32_16x16x32_bf16 v[30:33], v[160:163], v[182:185], v[30:33]
	v_mfma_f32_16x16x32_bf16 v[26:29], v[174:177], v[182:185], v[26:29]
	v_mfma_f32_16x16x32_bf16 v[22:25], v[160:163], v[190:193], v[22:25]
	v_mfma_f32_16x16x32_bf16 v[18:21], v[174:177], v[190:193], v[18:21]
	v_mfma_f32_16x16x32_bf16 v[14:17], v[160:163], v[212:215], v[14:17]
	v_mfma_f32_16x16x32_bf16 v[10:13], v[174:177], v[212:215], v[10:13]
	v_mfma_f32_16x16x32_bf16 v[6:9], v[160:163], v[220:223], v[6:9]
	v_mfma_f32_16x16x32_bf16 v[2:5], v[174:177], v[220:223], v[2:5]
	v_mfma_f32_16x16x32_bf16 v[30:33], v[170:173], v[186:189], v[30:33]
	v_mfma_f32_16x16x32_bf16 v[26:29], v[178:181], v[186:189], v[26:29]
	v_mfma_f32_16x16x32_bf16 v[22:25], v[170:173], v[208:211], v[22:25]
	v_mfma_f32_16x16x32_bf16 v[18:21], v[178:181], v[208:211], v[18:21]
	v_mfma_f32_16x16x32_bf16 v[14:17], v[170:173], v[216:219], v[14:17]
	v_mfma_f32_16x16x32_bf16 v[10:13], v[178:181], v[216:219], v[10:13]
	v_mfma_f32_16x16x32_bf16 v[6:9], v[170:173], v[228:231], v[6:9]
	v_mfma_f32_16x16x32_bf16 v[2:5], v[178:181], v[228:231], v[2:5]
	s_setprio 0
	s_barrier
	s_add_i32 s17, 0, 0x18000
	v_add_u32_e32 v98, s17, v166
	s_add_i32 s28, 0, 0x1c000
	ds_read_b128 v[132:135], v98
	ds_read_b128 v[136:139], v98 offset:1024
	ds_read_b128 v[140:143], v98 offset:2048
	ds_read_b128 v[156:159], v98 offset:3072
	v_add_u32_e32 v98, s28, v166
	ds_read_b128 v[160:163], v98
	ds_read_b128 v[170:173], v98 offset:1024
	ds_read_b128 v[174:177], v98 offset:2048
	ds_read_b128 v[178:181], v98 offset:3072
	s_add_u32 s30, s34, s10
	s_addc_u32 s31, s35, s11
	s_mov_b32 m0, s69
	v_lshl_add_u64 v[240:241], s[30:31], 0, v[144:145]
	ds_read_b128 v[182:185], v168 offset:32768
	ds_read_b128 v[186:189], v168 offset:33792
	ds_read_b128 v[190:193], v168 offset:34816
	ds_read_b128 v[208:211], v168 offset:35840
	ds_read_b128 v[212:215], v168 offset:36864
	ds_read_b128 v[216:219], v168 offset:37888
	ds_read_b128 v[220:223], v168 offset:38912
	ds_read_b128 v[228:231], v168 offset:39936
	global_load_lds_dwordx4 v[240:241], off
	v_lshl_add_u64 v[240:241], s[30:31], 0, v[148:149]
	s_mov_b32 m0, s70
	s_nop 0
	global_load_lds_dwordx4 v[240:241], off
	s_waitcnt vmcnt(8)
	s_waitcnt lgkmcnt(0)
	s_barrier
	s_setprio 1
	v_mfma_f32_16x16x32_bf16 v[128:131], v[132:135], v[182:185], v[128:131]
	v_mfma_f32_16x16x32_bf16 v[124:127], v[140:143], v[182:185], v[124:127]
	v_mfma_f32_16x16x32_bf16 v[120:123], v[132:135], v[190:193], v[120:123]
	v_mfma_f32_16x16x32_bf16 v[116:119], v[140:143], v[190:193], v[116:119]
	v_mfma_f32_16x16x32_bf16 v[112:115], v[132:135], v[212:215], v[112:115]
	v_mfma_f32_16x16x32_bf16 v[108:111], v[140:143], v[212:215], v[108:111]
	v_mfma_f32_16x16x32_bf16 v[104:107], v[132:135], v[220:223], v[104:107]
	v_mfma_f32_16x16x32_bf16 v[100:103], v[140:143], v[220:223], v[100:103]
	v_mfma_f32_16x16x32_bf16 v[128:131], v[136:139], v[186:189], v[128:131]
	v_mfma_f32_16x16x32_bf16 v[124:127], v[156:159], v[186:189], v[124:127]
	v_mfma_f32_16x16x32_bf16 v[120:123], v[136:139], v[208:211], v[120:123]
	v_mfma_f32_16x16x32_bf16 v[116:119], v[156:159], v[208:211], v[116:119]
	v_mfma_f32_16x16x32_bf16 v[112:115], v[136:139], v[216:219], v[112:115]
	v_mfma_f32_16x16x32_bf16 v[108:111], v[156:159], v[216:219], v[108:111]
	v_mfma_f32_16x16x32_bf16 v[104:107], v[136:139], v[228:231], v[104:107]
	v_mfma_f32_16x16x32_bf16 v[100:103], v[156:159], v[228:231], v[100:103]
	s_setprio 0
	s_setprio 1
	v_mfma_f32_16x16x32_bf16 v[62:65], v[160:163], v[182:185], v[62:65]
	v_mfma_f32_16x16x32_bf16 v[58:61], v[174:177], v[182:185], v[58:61]
	v_mfma_f32_16x16x32_bf16 v[54:57], v[160:163], v[190:193], v[54:57]
	v_mfma_f32_16x16x32_bf16 v[50:53], v[174:177], v[190:193], v[50:53]
	v_mfma_f32_16x16x32_bf16 v[46:49], v[160:163], v[212:215], v[46:49]
	v_mfma_f32_16x16x32_bf16 v[42:45], v[174:177], v[212:215], v[42:45]
	v_mfma_f32_16x16x32_bf16 v[38:41], v[160:163], v[220:223], v[38:41]
	v_mfma_f32_16x16x32_bf16 v[34:37], v[174:177], v[220:223], v[34:37]
	v_mfma_f32_16x16x32_bf16 v[62:65], v[170:173], v[186:189], v[62:65]
	v_mfma_f32_16x16x32_bf16 v[58:61], v[178:181], v[186:189], v[58:61]
	v_mfma_f32_16x16x32_bf16 v[54:57], v[170:173], v[208:211], v[54:57]
	v_mfma_f32_16x16x32_bf16 v[50:53], v[178:181], v[208:211], v[50:53]
	v_mfma_f32_16x16x32_bf16 v[46:49], v[170:173], v[216:219], v[46:49]
	v_mfma_f32_16x16x32_bf16 v[42:45], v[178:181], v[216:219], v[42:45]
	v_mfma_f32_16x16x32_bf16 v[38:41], v[170:173], v[228:231], v[38:41]
	v_mfma_f32_16x16x32_bf16 v[34:37], v[178:181], v[228:231], v[34:37]
	s_setprio 0
	s_barrier
; #define PG8_STAGE(bufoff, gbase, voff) do { _Pragma("unroll") for (int _i = 0; _i < 2; ++_i) \
;         __builtin_amdgcn_global_load_lds((const unsigned*)((const char*)(gbase) + (voff)[_i]), (PG8_LAS unsigned*)(lds + (bufoff) + ldsw + _i * 8192), 16, 0, 0); } while (0)
; #define PG8_LDA(dst, b, h) do { _Pragma("unroll") for (int m = 0; m < 4; ++m) _Pragma("unroll") for (int k = 0; k < 2; ++k) dst[m][k] = *(const PG8_LAS bf16x8*)(lds + PG8_SA(b, h) + aoff + m * 2048 + k * 1024); } while (0)
; #define PG8_MMA(ai, bj, At, Bt) do { __builtin_amdgcn_s_setprio(1); _Pragma("unroll") for (int m = 0; m < 4; ++m) _Pragma("unroll") for (int n = 0; n < 2; ++n) _Pragma("unroll") for (int k = 0; k < 2; ++k) \
;         acc[ai][bj][m][n] = __builtin_amdgcn_mfma_f32_16x16x32_bf16(Bt[n][k], At[m][k], acc[ai][bj][m][n], 0, 0, 0); __builtin_amdgcn_s_setprio(0); } while (0)
; #define PG8_WAIT_V(n) asm volatile("s_waitcnt vmcnt(" #n ")" ::: "memory")
; #define PG8_WAIT_L(n) asm volatile("s_waitcnt lgkmcnt(" #n ")" ::: "memory")
; #define PG8_BAR __builtin_amdgcn_s_barrier()
; #define PG8_SCHED __builtin_amdgcn_sched_barrier(0)
; template <class Epi, class Sched, bool ALIGN_EPI = false, bool SP2 = false>
; __device__ __forceinline__ void gemm_phase(PG8_LAS unsigned char* lds, const Gemm g, const Sched& S, const Epi& E) {
;     ...
;         for (int t = 0; t < nt; t += 2) {
;     ...
;             PG8_LDA(At, 1, 1); PG8_STAGE(PG8_SB(1, 0), b3, voffB); PG8_STAGE(PG8_SB(1, 1), b3 + hstep, voffB); PG8_STAGE(PG8_SA(1, 0), a3, voffA);
;             PG8_WAIT_V(8); PG8_WAIT_L(0); PG8_BAR; PG8_MMA(1, 0, At, B0); PG8_MMA(1, 1, At, B1); PG8_BAR; PG8_SCHED;
	s_add_i32 s17, s17, s62
	v_lshl_add_u64 v[164:165], v[164:165], 0, s[24:25]
	s_mov_b32 m0, s17
	ds_read_b128 v[182:185], v168 offset:49152
	ds_read_b128 v[186:189], v168 offset:50176
	ds_read_b128 v[190:193], v168 offset:51200
	ds_read_b128 v[208:211], v168 offset:52224
	ds_read_b128 v[212:215], v168 offset:53248
	ds_read_b128 v[216:219], v168 offset:54272
	ds_read_b128 v[220:223], v168 offset:55296
	ds_read_b128 v[228:231], v168 offset:56320
	global_load_lds_dwordx4 v[164:165], off
	v_lshl_add_u64 v[164:165], v[224:225], 0, s[24:25]
	s_add_i32 m0, s17, 0x2000
	s_add_i32 s17, s28, s62
	global_load_lds_dwordx4 v[164:165], off
	v_lshl_add_u64 v[164:165], v[232:233], 0, s[24:25]
	s_mov_b32 m0, s17
	s_nop 0
	global_load_lds_dwordx4 v[164:165], off
	v_lshl_add_u64 v[164:165], v[234:235], 0, s[24:25]
	s_add_i32 m0, s17, 0x2000
	s_nop 0
	global_load_lds_dwordx4 v[164:165], off
	v_lshl_add_u64 v[164:165], v[236:237], 0, s[24:25]
	s_mov_b32 m0, s72
	s_nop 0
	global_load_lds_dwordx4 v[164:165], off
	v_lshl_add_u64 v[164:165], v[238:239], 0, s[24:25]
	s_mov_b32 m0, s73
	s_nop 0
	global_load_lds_dwordx4 v[164:165], off
	s_waitcnt vmcnt(8)
	s_waitcnt lgkmcnt(0)
	s_barrier
	s_setprio 1
	v_mfma_f32_16x16x32_bf16 v[94:97], v[132:135], v[182:185], v[94:97]
	v_mfma_f32_16x16x32_bf16 v[90:93], v[140:143], v[182:185], v[90:93]
	v_mfma_f32_16x16x32_bf16 v[86:89], v[132:135], v[190:193], v[86:89]
	v_mfma_f32_16x16x32_bf16 v[82:85], v[140:143], v[190:193], v[82:85]
	v_mfma_f32_16x16x32_bf16 v[78:81], v[132:135], v[212:215], v[78:81]
	v_mfma_f32_16x16x32_bf16 v[74:77], v[140:143], v[212:215], v[74:77]
	v_mfma_f32_16x16x32_bf16 v[70:73], v[132:135], v[220:223], v[70:73]
	v_mfma_f32_16x16x32_bf16 v[66:69], v[140:143], v[220:223], v[66:69]
	v_mfma_f32_16x16x32_bf16 v[94:97], v[136:139], v[186:189], v[94:97]
	v_mfma_f32_16x16x32_bf16 v[90:93], v[156:159], v[186:189], v[90:93]
	v_mfma_f32_16x16x32_bf16 v[86:89], v[136:139], v[208:211], v[86:89]
	v_mfma_f32_16x16x32_bf16 v[82:85], v[156:159], v[208:211], v[82:85]
	v_mfma_f32_16x16x32_bf16 v[78:81], v[136:139], v[216:219], v[78:81]
	v_mfma_f32_16x16x32_bf16 v[74:77], v[156:159], v[216:219], v[74:77]
	v_mfma_f32_16x16x32_bf16 v[70:73], v[136:139], v[228:231], v[70:73]
	v_mfma_f32_16x16x32_bf16 v[66:69], v[156:159], v[228:231], v[66:69]
	s_setprio 0
	s_setprio 1
	v_mfma_f32_16x16x32_bf16 v[30:33], v[160:163], v[182:185], v[30:33]
	v_mfma_f32_16x16x32_bf16 v[26:29], v[174:177], v[182:185], v[26:29]
	v_mfma_f32_16x16x32_bf16 v[22:25], v[160:163], v[190:193], v[22:25]
	v_mfma_f32_16x16x32_bf16 v[18:21], v[174:177], v[190:193], v[18:21]
	v_mfma_f32_16x16x32_bf16 v[14:17], v[160:163], v[212:215], v[14:17]
	v_mfma_f32_16x16x32_bf16 v[10:13], v[174:177], v[212:215], v[10:13]
	v_mfma_f32_16x16x32_bf16 v[6:9], v[160:163], v[220:223], v[6:9]
	v_mfma_f32_16x16x32_bf16 v[2:5], v[174:177], v[220:223], v[2:5]
	v_mfma_f32_16x16x32_bf16 v[30:33], v[170:173], v[186:189], v[30:33]
	v_mfma_f32_16x16x32_bf16 v[26:29], v[178:181], v[186:189], v[26:29]
	v_mfma_f32_16x16x32_bf16 v[22:25], v[170:173], v[208:211], v[22:25]
	v_mfma_f32_16x16x32_bf16 v[18:21], v[178:181], v[208:211], v[18:21]
	v_mfma_f32_16x16x32_bf16 v[14:17], v[170:173], v[216:219], v[14:17]
	v_mfma_f32_16x16x32_bf16 v[10:13], v[178:181], v[216:219], v[10:13]
	v_mfma_f32_16x16x32_bf16 v[6:9], v[170:173], v[228:231], v[6:9]
	v_mfma_f32_16x16x32_bf16 v[2:5], v[178:181], v[228:231], v[2:5]
	s_setprio 0
	s_barrier
	s_add_u32 s2, s2, 0x100
	s_addc_u32 s3, s3, 0
	s_add_u32 s4, s4, 0x100
	s_addc_u32 s16, s16, 0
	s_cmp_ge_i32 s22, s71
	s_mov_b32 s17, s22
	s_cbranch_scc0 .LBB0_1209

; #define LAS __attribute__((address_space(3)))
; __device__ __forceinline__ float ex2(float x) { return __builtin_amdgcn_exp2f(x); }
; __device__ __forceinline__ float lg2(float x) { return __builtin_amdgcn_logf(x); }
; #define MFMA_BF(a, b, c) __builtin_amdgcn_mfma_f32_32x32x16_bf16((a), (b), (c), 0, 0, 0)
; __device__ __forceinline__ void sb_unit(LAS unsigned char* lds, int bh, int qb, const bf16* Q, const bf16* K, const bf16* VT, bf16* OUT, ssq_t* SSo, int tid, int lane, int wave) {
;     ...
;             for (int d0 = 0; d0 < 4; ++d0) {
;                 const bf16x8 a0 = *(const LAS bf16x8*)(Ks + r32 * 72 + 16 * d0 + 8 * hi);
;                 const bf16x8 a1 = *(const LAS bf16x8*)(Ks + (r32 + 32) * 72 + 16 * d0 + 8 * hi);
;                 p0 = MFMA_BF(a0, qr[d0], p0); p1 = MFMA_BF(a1, qr[d0], p1);
;             }
;             f16x8 la0, la1, lb0, lb1;
;             const int kbase = 64 * jt + 4 * hi;
; #pragma unroll
;             for (int r = 0; r < 16; ++r) {
;                 const int key = kbase + (r & 3) + 8 * (r >> 2);
;                 float z = p0[r]; float sp = fmaxf(z, 0.f) + lg2(1.0f + ex2(-fabsf(z)));
;                 float l = (key < qg) ? fmaxf(-sp, -60000.f) : 0.f;
;                 if (r < 8) la0[r] = (_Float16)l; else la1[r - 8] = (_Float16)l;
;                 z = p1[r]; sp = fmaxf(z, 0.f) + lg2(1.0f + ex2(-fabsf(z)));
;                 l = (key + 32 < qg) ? fmaxf(-sp, -60000.f) : 0.f;
;                 if (r < 8) lb0[r] = (_Float16)l; else lb1[r - 8] = (_Float16)l;
.LBB0_1277:
	ds_read_b128 v[36:39], v135
	ds_read_b128 v[40:43], v135 offset:32
	v_add_u32_e32 v141, s18, v132
	v_mov_b32_e32 v48, v34
	v_mov_b32_e32 v49, v34
	s_waitcnt lgkmcnt(1)
	v_mfma_f32_32x32x16_bf16 v[50:65], v[36:39], v[108:111], 0
	ds_read_b128 v[36:39], v148
	ds_read_b128 v[44:47], v148 offset:32
	s_mov_b32 s14, s12
	s_mov_b32 s15, s12
	s_mov_b32 s13, s12
	s_waitcnt lgkmcnt(2)
	v_mfma_f32_32x32x16_bf16 v[50:65], v[40:43], v[112:115], v[50:65]
	s_waitcnt lgkmcnt(1)
	v_mfma_f32_32x32x16_bf16 v[66:81], v[36:39], v[108:111], 0
	ds_read_b128 v[36:39], v135 offset:64
	ds_read_b128 v[40:43], v135 offset:96
	s_waitcnt lgkmcnt(1)
	v_mfma_f32_32x32x16_bf16 v[50:65], v[36:39], v[116:119], v[50:65]
	ds_read_b128 v[36:39], v148 offset:64
	v_mfma_f32_32x32x16_bf16 v[66:81], v[44:47], v[112:115], v[66:81]
	v_mov_b32_e32 v44, v34
	v_mov_b32_e32 v45, v34
	v_mov_b32_e32 v46, v34
	v_mov_b32_e32 v47, v34
	s_waitcnt lgkmcnt(1)
	v_mfma_f32_32x32x16_bf16 v[50:65], v[40:43], v[120:123], v[50:65]
	ds_read_b128 v[40:43], v148 offset:96
	s_waitcnt lgkmcnt(1)
	v_mfma_f32_32x32x16_bf16 v[66:81], v[36:39], v[116:119], v[66:81]
	s_nop 8
	v_exp_f32_e64 v35, -|v50|
	v_max_f32_e32 v37, 0, v50
	v_add_u32_e32 v36, 64, v141
	v_add_f32_e32 v35, 1.0, v35
	v_log_f32_e32 v35, v35
	v_cmp_lt_i32_e64 s[40:41], v36, v98
	s_waitcnt lgkmcnt(0)
	v_mfma_f32_32x32x16_bf16 v[66:81], v[40:43], v[120:123], v[66:81]
	v_exp_f32_e64 v38, -|v51|
	v_add_f32_e32 v35, v37, v35
	v_max_f32_e64 v35, -v35, s38
	v_cvt_f16_f32_e32 v35, v35
	v_mov_b32_e32 v39, v34
	v_mov_b32_e32 v40, v34
	v_mov_b32_e32 v41, v34
	s_nop 4
	v_exp_f32_e64 v37, -|v66|
	v_cndmask_b32_e64 v82, 0, v35, s[40:41]
	v_max_f32_e32 v35, 0, v66
	v_add_f32_e32 v36, 1.0, v37
	v_log_f32_e32 v36, v36
	v_add_u32_e32 v37, 0x60, v141
	v_cmp_lt_i32_e64 s[46:47], v37, v98
	v_exp_f32_e64 v37, -|v67|
	v_add_f32_e32 v35, v35, v36
	v_max_f32_e64 v35, -v35, s38
	v_cvt_f16_f32_e32 v35, v35
	v_add_f32_e32 v36, 1.0, v38
	v_log_f32_e32 v36, v36
	v_exp_f32_e64 v38, -|v52|
	v_cndmask_b32_e64 v143, 0, v35, s[46:47]
	v_max_f32_e32 v35, 0, v51
	v_add_f32_e32 v35, v35, v36
	v_max_f32_e64 v35, -v35, s38
	v_cvt_f16_f32_e32 v35, v35
	v_add_u32_e32 v36, 0x41, v141
	v_cmp_lt_i32_e64 s[48:49], v36, v98
	v_add_f32_e32 v36, 1.0, v37
	v_log_f32_e32 v36, v36
	v_cndmask_b32_e64 v83, 0, v35, s[48:49]
	v_max_f32_e32 v35, 0, v67
	v_add_f32_e32 v35, v35, v36
	v_max_f32_e64 v35, -v35, s38
	v_cvt_f16_f32_e32 v35, v35
	v_add_f32_e32 v36, 1.0, v38
	v_add_u32_e32 v37, 0x61, v141
	v_log_f32_e32 v36, v36
	v_cmp_lt_i32_e64 s[50:51], v37, v98
	v_exp_f32_e64 v37, -|v68|
	v_exp_f32_e64 v38, -|v53|
	v_cndmask_b32_e64 v154, 0, v35, s[50:51]
	v_max_f32_e32 v35, 0, v52
	v_add_f32_e32 v35, v35, v36
	v_max_f32_e64 v35, -v35, s38
	v_cvt_f16_f32_e32 v35, v35
	v_add_u32_e32 v36, 0x42, v141
	v_cmp_lt_i32_e64 s[52:53], v36, v98
	v_add_f32_e32 v36, 1.0, v37
	v_log_f32_e32 v36, v36
	v_cndmask_b32_e64 v84, 0, v35, s[52:53]
	v_max_f32_e32 v35, 0, v68
	v_add_f32_e32 v35, v35, v36
	v_max_f32_e64 v35, -v35, s38
	v_cvt_f16_f32_e32 v35, v35
	v_add_f32_e32 v36, 1.0, v38
	v_add_u32_e32 v37, 0x62, v141
	v_log_f32_e32 v36, v36
	v_cmp_lt_i32_e64 s[54:55], v37, v98
	v_exp_f32_e64 v37, -|v69|
	v_exp_f32_e64 v38, -|v54|
	v_cndmask_b32_e64 v155, 0, v35, s[54:55]
	v_max_f32_e32 v35, 0, v53
	v_add_f32_e32 v35, v35, v36
	v_max_f32_e64 v35, -v35, s38
	v_cvt_f16_f32_e32 v35, v35
	v_add_u32_e32 v36, 0x43, v141
	v_cmp_lt_i32_e64 s[56:57], v36, v98
	v_add_f32_e32 v36, 1.0, v37
	v_log_f32_e32 v36, v36
	v_cndmask_b32_e64 v85, 0, v35, s[56:57]
	v_max_f32_e32 v35, 0, v69
	v_add_f32_e32 v35, v35, v36
	v_max_f32_e64 v35, -v35, s38
	v_cvt_f16_f32_e32 v35, v35
	v_add_f32_e32 v36, 1.0, v38
	v_add_u32_e32 v37, 0x63, v141
	v_log_f32_e32 v36, v36
	v_cmp_lt_i32_e64 s[58:59], v37, v98
	v_exp_f32_e64 v37, -|v70|
	v_exp_f32_e64 v38, -|v55|
	v_cndmask_b32_e64 v160, 0, v35, s[58:59]
	v_max_f32_e32 v35, 0, v54
	v_add_f32_e32 v35, v35, v36
	v_max_f32_e64 v35, -v35, s38
	v_cvt_f16_f32_e32 v35, v35
	v_add_u32_e32 v36, 0x48, v141
	v_cmp_lt_i32_e64 s[60:61], v36, v98
	v_add_f32_e32 v36, 1.0, v37
	v_log_f32_e32 v36, v36
	v_cndmask_b32_e64 v86, 0, v35, s[60:61]
	v_max_f32_e32 v35, 0, v70
	v_add_f32_e32 v35, v35, v36
	v_max_f32_e64 v35, -v35, s38
	v_cvt_f16_f32_e32 v35, v35
	v_add_f32_e32 v36, 1.0, v38
	v_add_u32_e32 v37, 0x68, v141
	v_log_f32_e32 v36, v36
	v_cmp_lt_i32_e64 s[62:63], v37, v98
	v_exp_f32_e64 v37, -|v71|
	v_exp_f32_e64 v38, -|v56|
	v_cndmask_b32_e64 v161, 0, v35, s[62:63]
	v_max_f32_e32 v35, 0, v55
	v_add_f32_e32 v35, v35, v36
	v_max_f32_e64 v35, -v35, s38
	v_cvt_f16_f32_e32 v35, v35
	v_add_u32_e32 v36, 0x49, v141
	v_cmp_lt_i32_e64 s[64:65], v36, v98
	v_add_f32_e32 v36, 1.0, v37
	v_log_f32_e32 v36, v36
	v_cndmask_b32_e64 v87, 0, v35, s[64:65]
	v_max_f32_e32 v35, 0, v71
	v_add_f32_e32 v35, v35, v36
	v_max_f32_e64 v35, -v35, s38
	v_cvt_f16_f32_e32 v35, v35
	v_add_f32_e32 v36, 1.0, v38
	v_add_u32_e32 v37, 0x69, v141
	v_log_f32_e32 v36, v36
	v_cmp_lt_i32_e64 s[66:67], v37, v98
	v_exp_f32_e64 v37, -|v72|
	v_exp_f32_e64 v38, -|v57|
	v_cndmask_b32_e64 v162, 0, v35, s[66:67]
	v_max_f32_e32 v35, 0, v56
	v_add_f32_e32 v35, v35, v36
	v_max_f32_e64 v35, -v35, s38
	v_cvt_f16_f32_e32 v35, v35
	v_add_u32_e32 v36, 0x4a, v141
	v_cmp_lt_i32_e64 s[68:69], v36, v98
	v_add_f32_e32 v36, 1.0, v37
	v_log_f32_e32 v36, v36
	v_cndmask_b32_e64 v88, 0, v35, s[68:69]
	v_max_f32_e32 v35, 0, v72
	v_add_f32_e32 v35, v35, v36
	v_max_f32_e64 v35, -v35, s38
	v_cvt_f16_f32_e32 v35, v35
	v_add_f32_e32 v36, 1.0, v38
	v_add_u32_e32 v37, 0x6a, v141
	v_log_f32_e32 v36, v36
	v_cmp_lt_i32_e64 s[70:71], v37, v98
	v_exp_f32_e64 v37, -|v73|
	v_exp_f32_e64 v38, -|v58|
; __device__ __forceinline__ float ex2(float x) { return __builtin_amdgcn_exp2f(x); }
; __device__ __forceinline__ float lg2(float x) { return __builtin_amdgcn_logf(x); }
; __device__ __forceinline__ void sb_unit(LAS unsigned char* lds, int bh, int qb, const bf16* Q, const bf16* K, const bf16* VT, bf16* OUT, ssq_t* SSo, int tid, int lane, int wave) {
;     ...
;             for (int r = 0; r < 16; ++r) {
;                 const int key = kbase + (r & 3) + 8 * (r >> 2);
;                 float z = p0[r]; float sp = fmaxf(z, 0.f) + lg2(1.0f + ex2(-fabsf(z)));
;                 float l = (key < qg) ? fmaxf(-sp, -60000.f) : 0.f;
;                 if (r < 8) la0[r] = (_Float16)l; else la1[r - 8] = (_Float16)l;
;                 z = p1[r]; sp = fmaxf(z, 0.f) + lg2(1.0f + ex2(-fabsf(z)));
;                 l = (key + 32 < qg) ? fmaxf(-sp, -60000.f) : 0.f;
;                 if (r < 8) lb0[r] = (_Float16)l; else lb1[r - 8] = (_Float16)l;
;             }
	v_cndmask_b32_e64 v163, 0, v35, s[70:71]
	v_max_f32_e32 v35, 0, v57
	v_add_f32_e32 v35, v35, v36
	v_max_f32_e64 v35, -v35, s38
	v_cvt_f16_f32_e32 v35, v35
	v_add_u32_e32 v36, 0x4b, v141
	v_cmp_lt_i32_e64 s[72:73], v36, v98
	v_add_f32_e32 v36, 1.0, v37
	v_log_f32_e32 v36, v36
	v_cndmask_b32_e64 v89, 0, v35, s[72:73]
	v_max_f32_e32 v35, 0, v73
	v_add_f32_e32 v35, v35, v36
	v_max_f32_e64 v35, -v35, s38
	v_cvt_f16_f32_e32 v35, v35
	v_add_f32_e32 v36, 1.0, v38
	v_add_u32_e32 v37, 0x6b, v141
	v_log_f32_e32 v36, v36
	v_cmp_lt_i32_e64 s[74:75], v37, v98
	v_exp_f32_e64 v37, -|v74|
	v_exp_f32_e64 v38, -|v59|
	v_cndmask_b32_e64 v164, 0, v35, s[74:75]
	v_max_f32_e32 v35, 0, v58
	v_add_f32_e32 v35, v35, v36
	v_max_f32_e64 v35, -v35, s38
	v_cvt_f16_f32_e32 v35, v35
	v_add_u32_e32 v36, 0x50, v141
	v_cmp_lt_i32_e64 s[76:77], v36, v98
	v_add_f32_e32 v36, 1.0, v37
	v_log_f32_e32 v36, v36
	v_cndmask_b32_e64 v165, 0, v35, s[76:77]
	v_max_f32_e32 v35, 0, v74
	v_add_f32_e32 v35, v35, v36
	v_max_f32_e64 v35, -v35, s38
	v_cvt_f16_f32_e32 v35, v35
	v_add_f32_e32 v36, 1.0, v38
	v_add_u32_e32 v37, 0x70, v141
	v_log_f32_e32 v36, v36
	v_cmp_lt_i32_e64 s[78:79], v37, v98
	v_exp_f32_e64 v37, -|v75|
	v_exp_f32_e64 v38, -|v60|
	v_cndmask_b32_e64 v168, 0, v35, s[78:79]
	v_max_f32_e32 v35, 0, v59
	v_add_f32_e32 v35, v35, v36
	v_max_f32_e64 v35, -v35, s38
	v_cvt_f16_f32_e32 v35, v35
	v_add_u32_e32 v36, 0x51, v141
	v_cmp_lt_i32_e64 s[80:81], v36, v98
	v_add_f32_e32 v36, 1.0, v37
	v_log_f32_e32 v36, v36
	v_cndmask_b32_e64 v166, 0, v35, s[80:81]
	v_max_f32_e32 v35, 0, v75
	v_add_f32_e32 v35, v35, v36
	v_max_f32_e64 v35, -v35, s38
	v_cvt_f16_f32_e32 v35, v35
	v_add_f32_e32 v36, 1.0, v38
	v_add_u32_e32 v37, 0x71, v141
	v_log_f32_e32 v36, v36
	v_cmp_lt_i32_e64 s[82:83], v37, v98
	v_exp_f32_e64 v37, -|v76|
	v_exp_f32_e64 v38, -|v61|
	v_cndmask_b32_e64 v169, 0, v35, s[82:83]
	v_max_f32_e32 v35, 0, v60
	v_add_f32_e32 v35, v35, v36
	v_max_f32_e64 v35, -v35, s38
	v_cvt_f16_f32_e32 v35, v35
	v_add_u32_e32 v36, 0x52, v141
	v_cmp_lt_i32_e64 s[84:85], v36, v98
	v_add_f32_e32 v36, 1.0, v37
	v_log_f32_e32 v36, v36
	v_cndmask_b32_e64 v167, 0, v35, s[84:85]
	v_max_f32_e32 v35, 0, v76
	v_add_f32_e32 v35, v35, v36
	v_max_f32_e64 v35, -v35, s38
	v_cvt_f16_f32_e32 v35, v35
	v_add_f32_e32 v36, 1.0, v38
	v_add_u32_e32 v37, 0x72, v141
	v_log_f32_e32 v36, v36
	v_cmp_lt_i32_e64 s[86:87], v37, v98
	v_exp_f32_e64 v37, -|v77|
	v_exp_f32_e64 v38, -|v62|
	v_cndmask_b32_e64 v170, 0, v35, s[86:87]
	v_max_f32_e32 v35, 0, v61
	v_add_f32_e32 v35, v35, v36
	v_max_f32_e64 v35, -v35, s38
	v_cvt_f16_f32_e32 v35, v35
	v_add_u32_e32 v36, 0x53, v141
	v_cmp_lt_i32_e64 s[88:89], v36, v98
	v_add_f32_e32 v36, 1.0, v37
	v_log_f32_e32 v36, v36
	v_cndmask_b32_e64 v171, 0, v35, s[88:89]
	v_max_f32_e32 v35, 0, v77
	v_add_f32_e32 v35, v35, v36
	v_max_f32_e64 v35, -v35, s38
	v_cvt_f16_f32_e32 v35, v35
	v_add_f32_e32 v36, 1.0, v38
	v_add_u32_e32 v37, 0x73, v141
	v_log_f32_e32 v36, v36
	v_cmp_lt_i32_e64 s[90:91], v37, v98
	v_exp_f32_e64 v37, -|v78|
	v_exp_f32_e64 v38, -|v63|
	v_cndmask_b32_e64 v172, 0, v35, s[90:91]
	v_max_f32_e32 v35, 0, v62
	v_add_f32_e32 v35, v35, v36
	v_max_f32_e64 v35, -v35, s38
	v_cvt_f16_f32_e32 v35, v35
	v_add_u32_e32 v36, 0x58, v141
	v_cmp_lt_i32_e64 s[92:93], v36, v98
	v_add_f32_e32 v36, 1.0, v37
	v_log_f32_e32 v36, v36
	v_cndmask_b32_e64 v173, 0, v35, s[92:93]
	v_max_f32_e32 v35, 0, v78
	v_add_f32_e32 v35, v35, v36
	v_max_f32_e64 v35, -v35, s38
	v_cvt_f16_f32_e32 v35, v35
	v_add_f32_e32 v36, 1.0, v38
	v_add_u32_e32 v37, 0x78, v141
	v_log_f32_e32 v36, v36
	v_cmp_lt_i32_e64 s[94:95], v37, v98
	v_exp_f32_e64 v37, -|v79|
	v_exp_f32_e64 v38, -|v64|
	v_cndmask_b32_e64 v174, 0, v35, s[94:95]
	v_max_f32_e32 v35, 0, v63
	v_add_f32_e32 v35, v35, v36
	v_max_f32_e64 v35, -v35, s38
	v_cvt_f16_f32_e32 v35, v35
	v_add_u32_e32 v36, 0x59, v141
	v_cmp_lt_i32_e64 s[96:97], v36, v98
	v_add_f32_e32 v36, 1.0, v37
	v_log_f32_e32 v36, v36
	v_cndmask_b32_e64 v175, 0, v35, s[96:97]
	v_max_f32_e32 v35, 0, v79
	v_add_f32_e32 v35, v35, v36
	v_max_f32_e64 v35, -v35, s38
	v_cvt_f16_f32_e32 v35, v35
	v_add_f32_e32 v36, 1.0, v38
	v_add_u32_e32 v37, 0x79, v141
	v_log_f32_e32 v36, v36
	v_cmp_lt_i32_e64 s[6:7], v37, v98
	v_exp_f32_e64 v37, -|v80|
	v_exp_f32_e64 v38, -|v65|
	v_cndmask_b32_e64 v176, 0, v35, s[6:7]
	v_max_f32_e32 v35, 0, v64
	v_add_f32_e32 v35, v35, v36
	v_max_f32_e64 v35, -v35, s38
	v_cvt_f16_f32_e32 v35, v35
	v_add_u32_e32 v36, 0x5a, v141
	v_cmp_lt_i32_e64 s[2:3], v36, v98
	v_add_f32_e32 v36, 1.0, v37
	v_log_f32_e32 v36, v36
	v_cndmask_b32_e64 v177, 0, v35, s[2:3]
	v_max_f32_e32 v35, 0, v80
	v_add_f32_e32 v35, v35, v36
	v_max_f32_e64 v35, -v35, s38
	v_cvt_f16_f32_e32 v35, v35
	v_add_f32_e32 v36, 1.0, v38
	v_add_u32_e32 v37, 0x7a, v141
	v_log_f32_e32 v36, v36
	v_cmp_lt_i32_e64 s[8:9], v37, v98
	v_exp_f32_e64 v37, -|v81|
	v_mov_b32_e32 v38, v34
	v_cndmask_b32_e64 v178, 0, v35, s[8:9]
	v_max_f32_e32 v35, 0, v65
	v_add_f32_e32 v35, v35, v36
	v_max_f32_e64 v35, -v35, s38
	v_cvt_f16_f32_e32 v35, v35
	v_add_u32_e32 v36, 0x5b, v141
	v_cmp_lt_i32_e64 s[10:11], v36, v98
	v_mov_b32_e32 v36, v34
	v_mov_b32_e32 v42, v34
	v_cndmask_b32_e64 v179, 0, v35, s[10:11]
	v_max_f32_e32 v35, v81, v81
	v_max_f32_e32 v180, 0, v35
	v_add_f32_e32 v35, 1.0, v37
	v_log_f32_e32 v181, v35
	v_mov_b32_e32 v35, v34
	v_mov_b32_e32 v37, v34
	v_mov_b32_e32 v43, v34
	v_pack_b32_f16 v159, v88, v89
	v_pack_b32_f16 v158, v86, v87
	v_pack_b32_f16 v157, v84, v85
	v_pack_b32_f16 v156, v82, v83
	v_pack_b32_f16 v163, v163, v164
	v_pack_b32_f16 v162, v161, v162
	v_mfma_f32_32x32x16_f16 v[82:97], v[100:103], v[156:159], v[34:49]
	v_add_f32_e32 v156, v180, v181
; __device__ __forceinline__ void sb_unit(LAS unsigned char* lds, int bh, int qb, const bf16* Q, const bf16* K, const bf16* VT, bf16* OUT, ssq_t* SSo, int tid, int lane, int wave) {
;     ...
;             f32x16 ra, rb;
; #pragma unroll
;             for (int r = 0; r < 16; ++r) { ra[r] = C; rb[r] = C; }
;             ra = MFMA_H(tri0, la0, ra); ra = MFMA_H(tri1, la1, ra); ra = MFMA_H(ones, lb0, ra); ra = MFMA_H(ones, lb1, ra);
;             rb = MFMA_H(tri0, lb0, rb); rb = MFMA_H(tri1, lb1, rb);
; #pragma unroll
;             for (int r = 0; r < 16; ++r) {
;                 const int key = kbase + (r & 3) + 8 * (r >> 2);
;                 p0[r] = (key < qg) ? ex2(p0[r] + ra[r]) : 0.f;
;                 p1[r] = (key + 32 < qg) ? ex2(p1[r] + rb[r]) : 0.f;
;             }
;             C = lo32_bcast(ra[0]);
;             u32x4 w0, w1, w2, w3;
;             w0.x = pk2(p0[0], p0[1]); w0.y = pk2(p0[2], p0[3]); w0.z = pk2(p0[4], p0[5]); w0.w = pk2(p0[6], p0[7]);
;             w1.x = pk2(p0[8], p0[9]); w1.y = pk2(p0[10], p0[11]); w1.z = pk2(p0[12], p0[13]); w1.w = pk2(p0[14], p0[15]);
;             w2.x = pk2(p1[0], p1[1]); w2.y = pk2(p1[2], p1[3]); w2.z = pk2(p1[4], p1[5]); w2.w = pk2(p1[6], p1[7]);
;             w3.x = pk2(p1[8], p1[9]); w3.y = pk2(p1[10], p1[11]); w3.z = pk2(p1[12], p1[13]); w3.w = pk2(p1[14], p1[15]);
;             const bf16x8 f0 = __builtin_bit_cast(bf16x8, w0), f1 = __builtin_bit_cast(bf16x8, w1), f2 = __builtin_bit_cast(bf16x8, w2), f3 = __builtin_bit_cast(bf16x8, w3);
; #pragma unroll
;             for (int blk = 0; blk < 2; ++blk) {
;                 const LAS bf16* vr = Vs + (32 * blk + r32) * 72 + 4 * hi;
;                 const LAS bf16* vrh = vr + 8; asm volatile("" : "+v"(vrh));
;                 f32x16 o = blk ? o1 : o0;
; #pragma unroll
;                 for (int ks = 0; ks < 4; ++ks) {
;                     const s16x4 lo = *(const LAS s16x4*)(vr + 16 * ks), hh = *(const LAS s16x4*)(vrh + 16 * ks);
;                     const bf16x8 vf = __builtin_shufflevector(lo, hh, 0, 1, 2, 3, 4, 5, 6, 7);
;                     o = MFMA_BF(vf, ks == 0 ? f0 : ks == 1 ? f1 : ks == 2 ? f2 : f3, o);
;                 }
;                 if (blk) o1 = o; else o0 = o;
;             }
;             alive = __any(C > SB_EXIT) != 0;
;         }
;         if (lane == 0) flags[(jt & 1) * 8 + wave] = alive ? 1u : 0u;
	v_max_f32_e64 v156, -v156, s38
	v_cvt_f16_f32_e32 v180, v156
	v_pack_b32_f16 v159, v177, v179
	v_pack_b32_f16 v158, v173, v175
	v_pack_b32_f16 v157, v167, v171
	v_pack_b32_f16 v156, v165, v166
	v_pack_b32_f16 v161, v155, v160
	v_pack_b32_f16 v160, v143, v154
	v_mfma_f32_32x32x16_f16 v[82:97], v[104:107], v[156:159], v[82:97]
	v_mov_b64_e32 v[158:159], s[14:15]
	v_mov_b64_e32 v[156:157], s[12:13]
	v_add_u32_e32 v141, 0x7b, v141
	v_cmp_lt_i32_e32 vcc, v141, v98
	v_pack_b32_f16 v166, v174, v176
	v_pack_b32_f16 v165, v170, v172
	v_cndmask_b32_e32 v141, 0, v180, vcc
	v_mfma_f32_32x32x16_f16 v[34:49], v[100:103], v[160:163], v[34:49]
	v_pack_b32_f16 v167, v178, v141
	v_pack_b32_f16 v164, v168, v169
	v_mfma_f32_32x32x16_f16 v[82:97], v[156:159], v[160:163], v[82:97]
	s_nop 0
	v_mfma_f32_32x32x16_f16 v[34:49], v[104:107], v[164:167], v[34:49]
	v_mfma_f32_32x32x16_f16 v[82:97], v[156:159], v[164:167], v[82:97]
	s_nop 10
	v_add_f32_e32 v34, v66, v34
	v_add_f32_e32 v35, v67, v35
	v_exp_f32_e32 v34, v34
	v_exp_f32_e32 v35, v35
	v_add_f32_e32 v37, v69, v37
	v_exp_f32_e32 v37, v37
	v_cndmask_b32_e64 v66, 0, v34, s[46:47]
	v_cndmask_b32_e64 v67, 0, v35, s[50:51]
	v_add_f32_e32 v34, v52, v84
	v_add_f32_e32 v35, v68, v36
	v_add_f32_e32 v36, v53, v85
	v_exp_f32_e32 v34, v34
	v_exp_f32_e32 v35, v35
	v_exp_f32_e32 v36, v36
	v_cndmask_b32_e64 v69, 0, v37, s[58:59]
	v_cndmask_b32_e64 v52, 0, v34, s[52:53]
	v_cndmask_b32_e64 v68, 0, v35, s[54:55]
	v_cndmask_b32_e64 v53, 0, v36, s[56:57]
	v_add_f32_e32 v34, v54, v86
	v_add_f32_e32 v35, v70, v38
	v_add_f32_e32 v36, v55, v87
	v_add_f32_e32 v37, v71, v39
	v_exp_f32_e32 v34, v34
	v_exp_f32_e32 v35, v35
	v_exp_f32_e32 v36, v36
	v_exp_f32_e32 v37, v37
	v_cndmask_b32_e64 v54, 0, v34, s[60:61]
	v_cndmask_b32_e64 v70, 0, v35, s[62:63]
	v_cndmask_b32_e64 v55, 0, v36, s[64:65]
	v_cndmask_b32_e64 v71, 0, v37, s[66:67]
	v_add_f32_e32 v34, v56, v88
	v_add_f32_e32 v35, v72, v40
	v_add_f32_e32 v36, v57, v89
	v_add_f32_e32 v37, v73, v41
	v_exp_f32_e32 v34, v34
	v_exp_f32_e32 v35, v35
	v_exp_f32_e32 v36, v36
	v_exp_f32_e32 v37, v37
	v_cndmask_b32_e64 v41, 0, v34, s[68:69]
	v_cndmask_b32_e64 v72, 0, v35, s[70:71]
	v_cndmask_b32_e64 v56, 0, v36, s[72:73]
	v_cndmask_b32_e64 v73, 0, v37, s[74:75]
	v_add_f32_e32 v34, v58, v90
	v_add_f32_e32 v35, v74, v42
	v_add_f32_e32 v36, v59, v91
	v_add_f32_e32 v37, v75, v43
	v_exp_f32_e32 v34, v34
	v_exp_f32_e32 v35, v35
	v_exp_f32_e32 v36, v36
	v_exp_f32_e32 v37, v37
	v_cndmask_b32_e64 v57, 0, v34, s[76:77]
	v_cndmask_b32_e64 v58, 0, v35, s[78:79]
	v_cndmask_b32_e64 v59, 0, v36, s[80:81]
	v_cndmask_b32_e64 v74, 0, v37, s[82:83]
	v_add_f32_e32 v34, v60, v92
	v_add_f32_e32 v35, v76, v44
	v_add_f32_e32 v36, v61, v93
	v_add_f32_e32 v37, v77, v45
	v_exp_f32_e32 v34, v34
	v_exp_f32_e32 v35, v35
	v_exp_f32_e32 v36, v36
	v_exp_f32_e32 v37, v37
	v_cndmask_b32_e64 v60, 0, v34, s[84:85]
	v_cndmask_b32_e64 v61, 0, v35, s[86:87]
	v_cndmask_b32_e64 v75, 0, v36, s[88:89]
	v_cndmask_b32_e64 v76, 0, v37, s[90:91]
	v_add_f32_e32 v34, v62, v94
	v_add_f32_e32 v35, v78, v46
	v_add_f32_e32 v36, v63, v95
	v_add_f32_e32 v37, v79, v47
	v_exp_f32_e32 v34, v34
	v_exp_f32_e32 v35, v35
	v_exp_f32_e32 v36, v36
	v_exp_f32_e32 v37, v37
	v_cndmask_b32_e64 v62, 0, v34, s[92:93]
	v_cndmask_b32_e64 v63, 0, v35, s[94:95]
	v_cndmask_b32_e64 v77, 0, v36, s[96:97]
	v_cndmask_b32_e64 v78, 0, v37, s[6:7]
	v_add_f32_e32 v34, v64, v96
	v_add_f32_e32 v35, v80, v48
	v_add_f32_e32 v36, v65, v97
	v_add_f32_e32 v37, v81, v49
	v_exp_f32_e32 v34, v34
	v_exp_f32_e32 v35, v35
	v_exp_f32_e32 v36, v36
	v_exp_f32_e32 v37, v37
	v_add_f32_e32 v51, v51, v83
	v_mov_b32_e32 v81, v150
	v_add_u32_e32 v83, 0x2000, v149
	v_cndmask_b32_e64 v64, 0, v34, s[2:3]
	v_cndmask_b32_e64 v65, 0, v35, s[8:9]
	v_cndmask_b32_e64 v79, 0, v36, s[10:11]
	v_cndmask_b32_e32 v80, 0, v37, vcc
	ds_read2_b64 v[34:37], v83 offset0:128 offset1:132
	ds_read2_b64 v[42:45], v81 offset1:4
	v_add_f32_e32 v50, v50, v82
	v_exp_f32_e32 v50, v50
	v_exp_f32_e32 v51, v51
	s_waitcnt lgkmcnt(1)
	v_mov_b32_e32 v46, v34
	v_mov_b32_e32 v47, v35
	s_waitcnt lgkmcnt(0)
	v_mov_b32_e32 v48, v42
	v_mov_b32_e32 v49, v43
	v_cndmask_b32_e64 v50, 0, v50, s[40:41]
	v_cndmask_b32_e64 v51, 0, v51, s[48:49]
	v_cvt_pk_bf16_f32 v38, v50, v51
	v_cvt_pk_bf16_f32 v39, v52, v53
	v_cvt_pk_bf16_f32 v40, v54, v55
	v_cvt_pk_bf16_f32 v41, v41, v56
	v_mov_b32_e32 v42, v36
	v_mov_b32_e32 v43, v37
	v_mfma_f32_32x32x16_bf16 v[2:17], v[46:49], v[38:41], v[2:17]
	v_cvt_pk_bf16_f32 v50, v57, v59
	ds_read2_b64 v[34:37], v83 offset0:136 offset1:140
	ds_read2_b64 v[54:57], v81 offset0:8 offset1:12
	v_cvt_pk_bf16_f32 v51, v60, v75
	v_cvt_pk_bf16_f32 v52, v62, v77
	v_cvt_pk_bf16_f32 v53, v64, v79
	v_cvt_pk_bf16_f32 v46, v66, v67
	v_cvt_pk_bf16_f32 v47, v68, v69
	v_mfma_f32_32x32x16_bf16 v[2:17], v[42:45], v[50:53], v[2:17]
	s_waitcnt lgkmcnt(1)
	v_mov_b32_e32 v42, v34
	v_mov_b32_e32 v43, v35
	s_waitcnt lgkmcnt(0)
	v_mov_b32_e32 v44, v54
	v_mov_b32_e32 v45, v55
	v_cvt_pk_bf16_f32 v48, v70, v71
	v_cvt_pk_bf16_f32 v49, v72, v73
	v_mov_b32_e32 v62, v152
	v_add_u32_e32 v64, 0x2000, v151
	v_mfma_f32_32x32x16_bf16 v[2:17], v[42:45], v[46:49], v[2:17]
	v_cvt_pk_bf16_f32 v34, v58, v74
	v_cvt_pk_bf16_f32 v35, v61, v76
	v_mov_b32_e32 v54, v36
	v_mov_b32_e32 v55, v37
	ds_read2_b64 v[42:45], v64 offset0:128 offset1:132
	ds_read2_b64 v[58:61], v62 offset1:4
	v_cvt_pk_bf16_f32 v36, v63, v78
	v_cvt_pk_bf16_f32 v37, v65, v80
	s_mov_b32 s2, 0xc3480000
	v_readlane_b32 s88, v255, 38
	v_mfma_f32_32x32x16_bf16 v[2:17], v[54:57], v[34:37], v[2:17]
	s_waitcnt lgkmcnt(1)
	v_mov_b32_e32 v54, v42
	v_mov_b32_e32 v55, v43
	s_waitcnt lgkmcnt(0)
	v_mov_b32_e32 v56, v58
	v_mov_b32_e32 v57, v59
	v_mov_b32_e32 v58, v44
	v_mov_b32_e32 v59, v45
	v_readlane_b32 s90, v255, 40
	v_mfma_f32_32x32x16_bf16 v[18:33], v[54:57], v[38:41], v[18:33]
	ds_read2_b64 v[38:41], v64 offset0:136 offset1:140
	ds_read2_b64 v[42:45], v62 offset0:8 offset1:12
	v_readlane_b32 s92, v255, 42
	s_mov_b32 s94, 0x6dc9c883
	v_readlane_b32 s96, v255, 44
	v_readlane_b32 s89, v255, 39
	v_readlane_b32 s91, v255, 41
	s_mov_b32 s87, s0
	v_mfma_f32_32x32x16_bf16 v[18:33], v[58:61], v[50:53], v[18:33]
	s_waitcnt lgkmcnt(1)
	v_mov_b32_e32 v50, v38
	v_mov_b32_e32 v51, v39
	s_waitcnt lgkmcnt(0)
	v_mov_b32_e32 v52, v42
	v_mov_b32_e32 v53, v43
	v_mov_b32_e32 v42, v40
	v_mov_b32_e32 v43, v41
	v_mov_b32_e32 v38, v82
	v_mfma_f32_32x32x16_bf16 v[18:33], v[50:53], v[46:49], v[18:33]
	s_nop 0
	v_permlane32_swap_b32_e32 v82, v38
	v_cmp_lt_f32_e32 vcc, s2, v82
	s_cmp_lg_u64 vcc, 0
	s_cselect_b64 s[2:3], -1, 0
	v_readlane_b32 s93, v255, 43
	s_mov_b32 s95, 0x3fc45f30
	v_mfma_f32_32x32x16_bf16 v[18:33], v[42:45], v[34:37], v[18:33]
	v_readlane_b32 s97, v255, 45
	v_cndmask_b32_e64 v35, 0, 1, s[2:3]
	v_mov_b32_e32 v34, v82
	s_and_b32 s6, s33, 8
	s_and_saveexec_b64 s[2:3], s[42:43]
	s_cbranch_execz .LBB0_1272

; #define PG8_STAGE(bufoff, gbase, voff) do { _Pragma("unroll") for (int _i = 0; _i < 2; ++_i) \
;         __builtin_amdgcn_global_load_lds((const unsigned*)((const char*)(gbase) + (voff)[_i]), (PG8_LAS unsigned*)(lds + (bufoff) + ldsw + _i * 8192), 16, 0, 0); } while (0)
; #define PG8_LDA(dst, b, h) do { _Pragma("unroll") for (int m = 0; m < 4; ++m) _Pragma("unroll") for (int k = 0; k < 2; ++k) dst[m][k] = *(const PG8_LAS bf16x8*)(lds + PG8_SA(b, h) + aoff + m * 2048 + k * 1024); } while (0)
; #define PG8_LDB(dst, b, h) do { _Pragma("unroll") for (int n = 0; n < 2; ++n) _Pragma("unroll") for (int k = 0; k < 2; ++k) dst[n][k] = *(const PG8_LAS bf16x8*)(lds + PG8_SB(b, h) + boff + n * 2048 + k * 1024); } while (0)
; #define PG8_MMA(ai, bj, At, Bt) do { __builtin_amdgcn_s_setprio(1); _Pragma("unroll") for (int m = 0; m < 4; ++m) _Pragma("unroll") for (int n = 0; n < 2; ++n) _Pragma("unroll") for (int k = 0; k < 2; ++k) \
;         acc[ai][bj][m][n] = __builtin_amdgcn_mfma_f32_16x16x32_bf16(Bt[n][k], At[m][k], acc[ai][bj][m][n], 0, 0, 0); __builtin_amdgcn_s_setprio(0); } while (0)
; #define PG8_WAIT_V(n) asm volatile("s_waitcnt vmcnt(" #n ")" ::: "memory")
; #define PG8_WAIT_L(n) asm volatile("s_waitcnt lgkmcnt(" #n ")" ::: "memory")
; #define PG8_BAR __builtin_amdgcn_s_barrier()
; #define PG8_SCHED __builtin_amdgcn_sched_barrier(0)
; template <class Epi, class Sched, bool ALIGN_EPI = false, bool SP2 = false>
; __device__ __forceinline__ void gemm_phase(PG8_LAS unsigned char* lds, const Gemm g, const Sched& S, const Epi& E) {
;     ...
;             const char* a2 = last ? nA : cA + (size_t)(t + 2) * kstep; const char* b2 = last ? nB : cB + (size_t)(t + 2) * kstep;
;             const char* a3 = a2 + kstep; const char* b3 = b2 + kstep;
;             if (last && has_next) S.a_ready(nxt);
;             if constexpr (SP2) {
;             PG8_LDB(B0, 0, 0); PG8_LDB(B1, 0, 1); PG8_SCHED; PG8_LDA(At, 0, 0); PG8_STAGE(PG8_SA(1, 1), a1 + hstep, voffA);
;             PG8_WAIT_V(8); PG8_WAIT_L(0); PG8_BAR; PG8_MMA(0, 0, At, B0); PG8_MMA(0, 1, At, B1); PG8_BAR; PG8_SCHED;
;             PG8_LDA(At, 0, 1); PG8_STAGE(PG8_SB(0, 0), b2, voffB); PG8_STAGE(PG8_SB(0, 1), b2 + hstep, voffB); PG8_STAGE(PG8_SA(0, 0), a2, voffA);
;             PG8_WAIT_V(8); PG8_WAIT_L(0); PG8_BAR; PG8_MMA(1, 0, At, B0); PG8_MMA(1, 1, At, B1); PG8_BAR; PG8_SCHED;
.LBB0_1392:
	s_add_i32 s22, s17, 2
	s_add_u32 s28, s62, s2
	s_addc_u32 s30, s63, s3
	s_add_u32 s28, s28, 0x100
	s_addc_u32 s30, s30, 0
	s_add_u32 s33, s4, s2
	s_addc_u32 s31, s16, s3
	s_add_i32 s36, 0, 0x10000
	s_cmp_eq_u32 s76, s17
	s_cselect_b32 s35, s59, s30
	s_cselect_b32 s34, s58, s28
	v_add_u32_e32 v98, s36, v151
	s_cselect_b32 s31, s61, s31
	s_cselect_b32 s30, s60, s33
	s_add_i32 s17, 0, 0x14000
	ds_read_b128 v[156:159], v98
	ds_read_b128 v[160:163], v98 offset:1024
	ds_read_b128 v[164:167], v98 offset:2048
	ds_read_b128 v[168:171], v98 offset:3072
	v_add_u32_e32 v98, s17, v151
	ds_read_b128 v[172:175], v98
	ds_read_b128 v[176:179], v98 offset:1024
	ds_read_b128 v[180:183], v98 offset:2048
	ds_read_b128 v[184:187], v98 offset:3072
	v_lshl_add_u64 v[100:101], v[146:147], 0, s[2:3]
	s_add_i32 m0, s68, 0xc000
	ds_read_b128 v[188:191], v155
	ds_read_b128 v[208:211], v155 offset:1024
	ds_read_b128 v[212:215], v155 offset:2048
	ds_read_b128 v[216:219], v155 offset:3072
	ds_read_b128 v[220:223], v155 offset:4096
	ds_read_b128 v[228:231], v155 offset:5120
	ds_read_b128 v[232:235], v155 offset:6144
	ds_read_b128 v[236:239], v155 offset:7168
	global_load_lds_dwordx4 v[100:101], off
	v_lshl_add_u64 v[100:101], v[148:149], 0, s[2:3]
	s_add_i32 m0, s68, 0xe000
	s_nop 0
	global_load_lds_dwordx4 v[100:101], off
	s_waitcnt vmcnt(8)
	s_waitcnt lgkmcnt(0)
	s_barrier
	s_setprio 1
	v_mfma_f32_16x16x32_bf16 v[126:129], v[156:159], v[188:191], v[126:129]
	v_mfma_f32_16x16x32_bf16 v[130:133], v[164:167], v[188:191], v[130:133]
	v_mfma_f32_16x16x32_bf16 v[114:117], v[156:159], v[212:215], v[114:117]
	v_mfma_f32_16x16x32_bf16 v[110:113], v[164:167], v[212:215], v[110:113]
	v_mfma_f32_16x16x32_bf16 v[94:97], v[156:159], v[220:223], v[94:97]
	v_mfma_f32_16x16x32_bf16 v[90:93], v[164:167], v[220:223], v[90:93]
	v_mfma_f32_16x16x32_bf16 v[78:81], v[156:159], v[232:235], v[78:81]
	v_mfma_f32_16x16x32_bf16 v[74:77], v[164:167], v[232:235], v[74:77]
	v_mfma_f32_16x16x32_bf16 v[126:129], v[160:163], v[208:211], v[126:129]
	v_mfma_f32_16x16x32_bf16 v[130:133], v[168:171], v[208:211], v[130:133]
	v_mfma_f32_16x16x32_bf16 v[114:117], v[160:163], v[216:219], v[114:117]
	v_mfma_f32_16x16x32_bf16 v[110:113], v[168:171], v[216:219], v[110:113]
	v_mfma_f32_16x16x32_bf16 v[94:97], v[160:163], v[228:231], v[94:97]
	v_mfma_f32_16x16x32_bf16 v[90:93], v[168:171], v[228:231], v[90:93]
	v_mfma_f32_16x16x32_bf16 v[78:81], v[160:163], v[236:239], v[78:81]
	v_mfma_f32_16x16x32_bf16 v[74:77], v[168:171], v[236:239], v[74:77]
	s_setprio 0
	s_setprio 1
	v_mfma_f32_16x16x32_bf16 v[122:125], v[172:175], v[188:191], v[122:125]
	v_mfma_f32_16x16x32_bf16 v[118:121], v[180:183], v[188:191], v[118:121]
	v_mfma_f32_16x16x32_bf16 v[106:109], v[172:175], v[212:215], v[106:109]
	v_mfma_f32_16x16x32_bf16 v[100:103], v[180:183], v[212:215], v[102:105]
	v_mfma_f32_16x16x32_bf16 v[86:89], v[172:175], v[220:223], v[86:89]
	v_mfma_f32_16x16x32_bf16 v[82:85], v[180:183], v[220:223], v[82:85]
	v_mfma_f32_16x16x32_bf16 v[70:73], v[172:175], v[232:235], v[70:73]
	v_mfma_f32_16x16x32_bf16 v[66:69], v[180:183], v[232:235], v[66:69]
	v_mfma_f32_16x16x32_bf16 v[122:125], v[176:179], v[208:211], v[122:125]
	v_mfma_f32_16x16x32_bf16 v[118:121], v[184:187], v[208:211], v[118:121]
	v_mfma_f32_16x16x32_bf16 v[106:109], v[176:179], v[216:219], v[106:109]
	v_mfma_f32_16x16x32_bf16 v[100:103], v[184:187], v[216:219], v[100:103]
	v_mfma_f32_16x16x32_bf16 v[86:89], v[176:179], v[228:231], v[86:89]
	v_mfma_f32_16x16x32_bf16 v[82:85], v[184:187], v[228:231], v[82:85]
	v_mfma_f32_16x16x32_bf16 v[70:73], v[176:179], v[236:239], v[70:73]
	v_mfma_f32_16x16x32_bf16 v[66:69], v[184:187], v[236:239], v[66:69]
	s_setprio 0
	s_barrier
	s_add_i32 s28, s36, s67
	v_lshl_add_u64 v[192:193], s[30:31], 0, v[136:137]
	s_mov_b32 m0, s28
	ds_read_b128 v[188:191], v155 offset:16384
	ds_read_b128 v[208:211], v155 offset:17408
	ds_read_b128 v[212:215], v155 offset:18432
	ds_read_b128 v[216:219], v155 offset:19456
	ds_read_b128 v[220:223], v155 offset:20480
	ds_read_b128 v[228:231], v155 offset:21504
	ds_read_b128 v[232:235], v155 offset:22528
	ds_read_b128 v[236:239], v155 offset:23552
	global_load_lds_dwordx4 v[192:193], off
	s_add_i32 m0, s28, 0x2000
	v_lshl_add_u64 v[224:225], s[30:31], 0, v[140:141]
	s_add_u32 s30, s30, s14
	s_addc_u32 s31, s31, s15
	s_add_i32 s17, s17, s67
	global_load_lds_dwordx4 v[224:225], off
	v_lshl_add_u64 v[240:241], s[30:31], 0, v[136:137]
	s_mov_b32 m0, s17
	v_lshl_add_u64 v[242:243], s[30:31], 0, v[140:141]
	global_load_lds_dwordx4 v[240:241], off
	s_add_i32 m0, s17, 0x2000
	v_lshl_add_u64 v[244:245], s[34:35], 0, v[134:135]
	global_load_lds_dwordx4 v[242:243], off
	s_mov_b32 m0, s68
	v_lshl_add_u64 v[246:247], s[34:35], 0, v[138:139]
	global_load_lds_dwordx4 v[244:245], off
	s_mov_b32 m0, s69
	s_nop 0
	global_load_lds_dwordx4 v[246:247], off
	s_waitcnt vmcnt(8)
	s_waitcnt lgkmcnt(0)
	s_barrier
; #define PG8_STAGE(bufoff, gbase, voff) do { _Pragma("unroll") for (int _i = 0; _i < 2; ++_i) \
;         __builtin_amdgcn_global_load_lds((const unsigned*)((const char*)(gbase) + (voff)[_i]), (PG8_LAS unsigned*)(lds + (bufoff) + ldsw + _i * 8192), 16, 0, 0); } while (0)
; #define PG8_LDA(dst, b, h) do { _Pragma("unroll") for (int m = 0; m < 4; ++m) _Pragma("unroll") for (int k = 0; k < 2; ++k) dst[m][k] = *(const PG8_LAS bf16x8*)(lds + PG8_SA(b, h) + aoff + m * 2048 + k * 1024); } while (0)
; #define PG8_LDB(dst, b, h) do { _Pragma("unroll") for (int n = 0; n < 2; ++n) _Pragma("unroll") for (int k = 0; k < 2; ++k) dst[n][k] = *(const PG8_LAS bf16x8*)(lds + PG8_SB(b, h) + boff + n * 2048 + k * 1024); } while (0)
; #define PG8_MMA(ai, bj, At, Bt) do { __builtin_amdgcn_s_setprio(1); _Pragma("unroll") for (int m = 0; m < 4; ++m) _Pragma("unroll") for (int n = 0; n < 2; ++n) _Pragma("unroll") for (int k = 0; k < 2; ++k) \
;         acc[ai][bj][m][n] = __builtin_amdgcn_mfma_f32_16x16x32_bf16(Bt[n][k], At[m][k], acc[ai][bj][m][n], 0, 0, 0); __builtin_amdgcn_s_setprio(0); } while (0)
; #define PG8_WAIT_V(n) asm volatile("s_waitcnt vmcnt(" #n ")" ::: "memory")
; #define PG8_WAIT_L(n) asm volatile("s_waitcnt lgkmcnt(" #n ")" ::: "memory")
; #define PG8_BAR __builtin_amdgcn_s_barrier()
; #define PG8_SCHED __builtin_amdgcn_sched_barrier(0)
; template <class Epi, class Sched, bool ALIGN_EPI = false, bool SP2 = false>
; __device__ __forceinline__ void gemm_phase(PG8_LAS unsigned char* lds, const Gemm g, const Sched& S, const Epi& E) {
;     ...
;             PG8_WAIT_V(8); PG8_WAIT_L(0); PG8_BAR; PG8_MMA(1, 0, At, B0); PG8_MMA(1, 1, At, B1); PG8_BAR; PG8_SCHED;
;             PG8_LDB(B0, 1, 0); PG8_LDB(B1, 1, 1); PG8_SCHED; PG8_LDA(At, 1, 0); PG8_STAGE(PG8_SA(0, 1), a2 + hstep, voffA);
;             PG8_WAIT_V(8); PG8_WAIT_L(0); PG8_BAR; PG8_MMA(0, 0, At, B0); PG8_MMA(0, 1, At, B1); PG8_BAR; PG8_SCHED;
	s_setprio 1
	v_mfma_f32_16x16x32_bf16 v[62:65], v[156:159], v[188:191], v[62:65]
	v_mfma_f32_16x16x32_bf16 v[58:61], v[164:167], v[188:191], v[58:61]
	v_mfma_f32_16x16x32_bf16 v[46:49], v[156:159], v[212:215], v[46:49]
	v_mfma_f32_16x16x32_bf16 v[42:45], v[164:167], v[212:215], v[42:45]
	v_mfma_f32_16x16x32_bf16 v[30:33], v[156:159], v[220:223], v[30:33]
	v_mfma_f32_16x16x32_bf16 v[26:29], v[164:167], v[220:223], v[26:29]
	v_mfma_f32_16x16x32_bf16 v[14:17], v[156:159], v[232:235], v[14:17]
	v_mfma_f32_16x16x32_bf16 v[10:13], v[164:167], v[232:235], v[10:13]
	v_mfma_f32_16x16x32_bf16 v[62:65], v[160:163], v[208:211], v[62:65]
	v_mfma_f32_16x16x32_bf16 v[58:61], v[168:171], v[208:211], v[58:61]
	v_mfma_f32_16x16x32_bf16 v[46:49], v[160:163], v[216:219], v[46:49]
	v_mfma_f32_16x16x32_bf16 v[42:45], v[168:171], v[216:219], v[42:45]
	v_mfma_f32_16x16x32_bf16 v[30:33], v[160:163], v[228:231], v[30:33]
	v_mfma_f32_16x16x32_bf16 v[26:29], v[168:171], v[228:231], v[26:29]
	v_mfma_f32_16x16x32_bf16 v[14:17], v[160:163], v[236:239], v[14:17]
	v_mfma_f32_16x16x32_bf16 v[10:13], v[168:171], v[236:239], v[10:13]
	s_setprio 0
	s_setprio 1
	v_mfma_f32_16x16x32_bf16 v[54:57], v[172:175], v[188:191], v[54:57]
	v_mfma_f32_16x16x32_bf16 v[50:53], v[180:183], v[188:191], v[50:53]
	v_mfma_f32_16x16x32_bf16 v[38:41], v[172:175], v[212:215], v[38:41]
	v_mfma_f32_16x16x32_bf16 v[34:37], v[180:183], v[212:215], v[34:37]
	v_mfma_f32_16x16x32_bf16 v[22:25], v[172:175], v[220:223], v[22:25]
	v_mfma_f32_16x16x32_bf16 v[18:21], v[180:183], v[220:223], v[18:21]
	v_mfma_f32_16x16x32_bf16 v[6:9], v[172:175], v[232:235], v[6:9]
	v_mfma_f32_16x16x32_bf16 v[2:5], v[180:183], v[232:235], v[2:5]
	v_mfma_f32_16x16x32_bf16 v[54:57], v[176:179], v[208:211], v[54:57]
	v_mfma_f32_16x16x32_bf16 v[50:53], v[184:187], v[208:211], v[50:53]
	v_mfma_f32_16x16x32_bf16 v[38:41], v[176:179], v[216:219], v[38:41]
	v_mfma_f32_16x16x32_bf16 v[34:37], v[184:187], v[216:219], v[34:37]
	v_mfma_f32_16x16x32_bf16 v[22:25], v[176:179], v[228:231], v[22:25]
	v_mfma_f32_16x16x32_bf16 v[18:21], v[184:187], v[228:231], v[18:21]
	v_mfma_f32_16x16x32_bf16 v[6:9], v[176:179], v[236:239], v[6:9]
	v_mfma_f32_16x16x32_bf16 v[2:5], v[184:187], v[236:239], v[2:5]
	s_setprio 0
	s_barrier
	s_add_i32 s17, 0, 0x18000
	v_add_u32_e32 v98, s17, v151
	s_add_i32 s28, 0, 0x1c000
	ds_read_b128 v[156:159], v98
	ds_read_b128 v[160:163], v98 offset:1024
	ds_read_b128 v[164:167], v98 offset:2048
	ds_read_b128 v[168:171], v98 offset:3072
	v_add_u32_e32 v98, s28, v151
	ds_read_b128 v[172:175], v98
	ds_read_b128 v[176:179], v98 offset:1024
	ds_read_b128 v[180:183], v98 offset:2048
	ds_read_b128 v[184:187], v98 offset:3072
	s_add_u32 s30, s34, s14
	s_addc_u32 s31, s35, s15
	s_mov_b32 m0, s70
	v_lshl_add_u64 v[104:105], s[30:31], 0, v[134:135]
	ds_read_b128 v[188:191], v155 offset:32768
	ds_read_b128 v[208:211], v155 offset:33792
	ds_read_b128 v[212:215], v155 offset:34816
	ds_read_b128 v[216:219], v155 offset:35840
	ds_read_b128 v[220:223], v155 offset:36864
	ds_read_b128 v[228:231], v155 offset:37888
	ds_read_b128 v[232:235], v155 offset:38912
	ds_read_b128 v[236:239], v155 offset:39936
	global_load_lds_dwordx4 v[104:105], off
	v_lshl_add_u64 v[104:105], s[30:31], 0, v[138:139]
	s_mov_b32 m0, s71
	s_nop 0
	global_load_lds_dwordx4 v[104:105], off
	s_waitcnt vmcnt(8)
	s_waitcnt lgkmcnt(0)
	s_barrier
	s_setprio 1
	v_mfma_f32_16x16x32_bf16 v[126:129], v[156:159], v[188:191], v[126:129]
	v_mfma_f32_16x16x32_bf16 v[130:133], v[164:167], v[188:191], v[130:133]
	v_mfma_f32_16x16x32_bf16 v[114:117], v[156:159], v[212:215], v[114:117]
	v_mfma_f32_16x16x32_bf16 v[110:113], v[164:167], v[212:215], v[110:113]
	v_mfma_f32_16x16x32_bf16 v[94:97], v[156:159], v[220:223], v[94:97]
	v_mfma_f32_16x16x32_bf16 v[90:93], v[164:167], v[220:223], v[90:93]
	v_mfma_f32_16x16x32_bf16 v[78:81], v[156:159], v[232:235], v[78:81]
	v_mfma_f32_16x16x32_bf16 v[74:77], v[164:167], v[232:235], v[74:77]
	v_mfma_f32_16x16x32_bf16 v[126:129], v[160:163], v[208:211], v[126:129]
	v_mfma_f32_16x16x32_bf16 v[130:133], v[168:171], v[208:211], v[130:133]
	v_mfma_f32_16x16x32_bf16 v[114:117], v[160:163], v[216:219], v[114:117]
	v_mfma_f32_16x16x32_bf16 v[110:113], v[168:171], v[216:219], v[110:113]
	v_mfma_f32_16x16x32_bf16 v[94:97], v[160:163], v[228:231], v[94:97]
	v_mfma_f32_16x16x32_bf16 v[90:93], v[168:171], v[228:231], v[90:93]
	v_mfma_f32_16x16x32_bf16 v[78:81], v[160:163], v[236:239], v[78:81]
	v_mfma_f32_16x16x32_bf16 v[74:77], v[168:171], v[236:239], v[74:77]
	s_setprio 0
	s_setprio 1
	v_mfma_f32_16x16x32_bf16 v[122:125], v[172:175], v[188:191], v[122:125]
	v_mfma_f32_16x16x32_bf16 v[118:121], v[180:183], v[188:191], v[118:121]
	v_mfma_f32_16x16x32_bf16 v[104:107], v[172:175], v[212:215], v[106:109]
	v_mfma_f32_16x16x32_bf16 v[100:103], v[180:183], v[212:215], v[100:103]
	v_mfma_f32_16x16x32_bf16 v[86:89], v[172:175], v[220:223], v[86:89]
	v_mfma_f32_16x16x32_bf16 v[82:85], v[180:183], v[220:223], v[82:85]
	v_mfma_f32_16x16x32_bf16 v[70:73], v[172:175], v[232:235], v[70:73]
	v_mfma_f32_16x16x32_bf16 v[66:69], v[180:183], v[232:235], v[66:69]
	v_mfma_f32_16x16x32_bf16 v[122:125], v[176:179], v[208:211], v[122:125]
	v_mfma_f32_16x16x32_bf16 v[118:121], v[184:187], v[208:211], v[118:121]
	v_mfma_f32_16x16x32_bf16 v[106:109], v[176:179], v[216:219], v[104:107]
	v_mfma_f32_16x16x32_bf16 v[102:105], v[184:187], v[216:219], v[100:103]
	v_mfma_f32_16x16x32_bf16 v[86:89], v[176:179], v[228:231], v[86:89]
	v_mfma_f32_16x16x32_bf16 v[82:85], v[184:187], v[228:231], v[82:85]
	v_mfma_f32_16x16x32_bf16 v[70:73], v[176:179], v[236:239], v[70:73]
	v_mfma_f32_16x16x32_bf16 v[66:69], v[184:187], v[236:239], v[66:69]
	s_setprio 0
	s_barrier
; #define PG8_STAGE(bufoff, gbase, voff) do { _Pragma("unroll") for (int _i = 0; _i < 2; ++_i) \
;         __builtin_amdgcn_global_load_lds((const unsigned*)((const char*)(gbase) + (voff)[_i]), (PG8_LAS unsigned*)(lds + (bufoff) + ldsw + _i * 8192), 16, 0, 0); } while (0)
; #define PG8_LDA(dst, b, h) do { _Pragma("unroll") for (int m = 0; m < 4; ++m) _Pragma("unroll") for (int k = 0; k < 2; ++k) dst[m][k] = *(const PG8_LAS bf16x8*)(lds + PG8_SA(b, h) + aoff + m * 2048 + k * 1024); } while (0)
; #define PG8_MMA(ai, bj, At, Bt) do { __builtin_amdgcn_s_setprio(1); _Pragma("unroll") for (int m = 0; m < 4; ++m) _Pragma("unroll") for (int n = 0; n < 2; ++n) _Pragma("unroll") for (int k = 0; k < 2; ++k) \
;         acc[ai][bj][m][n] = __builtin_amdgcn_mfma_f32_16x16x32_bf16(Bt[n][k], At[m][k], acc[ai][bj][m][n], 0, 0, 0); __builtin_amdgcn_s_setprio(0); } while (0)
; #define PG8_WAIT_V(n) asm volatile("s_waitcnt vmcnt(" #n ")" ::: "memory")
; #define PG8_WAIT_L(n) asm volatile("s_waitcnt lgkmcnt(" #n ")" ::: "memory")
; #define PG8_BAR __builtin_amdgcn_s_barrier()
; #define PG8_SCHED __builtin_amdgcn_sched_barrier(0)
; template <class Epi, class Sched, bool ALIGN_EPI = false, bool SP2 = false>
; __device__ __forceinline__ void gemm_phase(PG8_LAS unsigned char* lds, const Gemm g, const Sched& S, const Epi& E) {
;     ...
;             PG8_LDA(At, 1, 1); PG8_STAGE(PG8_SB(1, 0), b3, voffB); PG8_STAGE(PG8_SB(1, 1), b3 + hstep, voffB); PG8_STAGE(PG8_SA(1, 0), a3, voffA);
;             PG8_WAIT_V(8); PG8_WAIT_L(0); PG8_BAR; PG8_MMA(1, 0, At, B0); PG8_MMA(1, 1, At, B1); PG8_BAR; PG8_SCHED;
	s_add_i32 s17, s17, s67
	v_lshl_add_u64 v[100:101], v[192:193], 0, s[24:25]
	s_mov_b32 m0, s17
	ds_read_b128 v[188:191], v155 offset:49152
	ds_read_b128 v[208:211], v155 offset:50176
	ds_read_b128 v[212:215], v155 offset:51200
	ds_read_b128 v[216:219], v155 offset:52224
	ds_read_b128 v[220:223], v155 offset:53248
	ds_read_b128 v[228:231], v155 offset:54272
	ds_read_b128 v[232:235], v155 offset:55296
	ds_read_b128 v[236:239], v155 offset:56320
	global_load_lds_dwordx4 v[100:101], off
	v_lshl_add_u64 v[100:101], v[224:225], 0, s[24:25]
	s_add_i32 m0, s17, 0x2000
	s_add_i32 s17, s28, s67
	global_load_lds_dwordx4 v[100:101], off
	v_lshl_add_u64 v[100:101], v[240:241], 0, s[24:25]
	s_mov_b32 m0, s17
	s_nop 0
	global_load_lds_dwordx4 v[100:101], off
	v_lshl_add_u64 v[100:101], v[242:243], 0, s[24:25]
	s_add_i32 m0, s17, 0x2000
	s_nop 0
	global_load_lds_dwordx4 v[100:101], off
	v_lshl_add_u64 v[100:101], v[244:245], 0, s[24:25]
	s_mov_b32 m0, s73
	s_nop 0
	global_load_lds_dwordx4 v[100:101], off
	v_lshl_add_u64 v[100:101], v[246:247], 0, s[24:25]
	s_mov_b32 m0, s74
	s_nop 0
	global_load_lds_dwordx4 v[100:101], off
	s_waitcnt vmcnt(8)
	s_waitcnt lgkmcnt(0)
	s_barrier
	s_setprio 1
	v_mfma_f32_16x16x32_bf16 v[62:65], v[156:159], v[188:191], v[62:65]
	v_mfma_f32_16x16x32_bf16 v[58:61], v[164:167], v[188:191], v[58:61]
	v_mfma_f32_16x16x32_bf16 v[46:49], v[156:159], v[212:215], v[46:49]
	v_mfma_f32_16x16x32_bf16 v[42:45], v[164:167], v[212:215], v[42:45]
	v_mfma_f32_16x16x32_bf16 v[30:33], v[156:159], v[220:223], v[30:33]
	v_mfma_f32_16x16x32_bf16 v[26:29], v[164:167], v[220:223], v[26:29]
	v_mfma_f32_16x16x32_bf16 v[14:17], v[156:159], v[232:235], v[14:17]
	v_mfma_f32_16x16x32_bf16 v[10:13], v[164:167], v[232:235], v[10:13]
	v_mfma_f32_16x16x32_bf16 v[62:65], v[160:163], v[208:211], v[62:65]
	v_mfma_f32_16x16x32_bf16 v[58:61], v[168:171], v[208:211], v[58:61]
	v_mfma_f32_16x16x32_bf16 v[46:49], v[160:163], v[216:219], v[46:49]
	v_mfma_f32_16x16x32_bf16 v[42:45], v[168:171], v[216:219], v[42:45]
	v_mfma_f32_16x16x32_bf16 v[30:33], v[160:163], v[228:231], v[30:33]
	v_mfma_f32_16x16x32_bf16 v[26:29], v[168:171], v[228:231], v[26:29]
	v_mfma_f32_16x16x32_bf16 v[14:17], v[160:163], v[236:239], v[14:17]
	v_mfma_f32_16x16x32_bf16 v[10:13], v[168:171], v[236:239], v[10:13]
	s_setprio 0
	s_setprio 1
	v_mfma_f32_16x16x32_bf16 v[54:57], v[172:175], v[188:191], v[54:57]
	v_mfma_f32_16x16x32_bf16 v[50:53], v[180:183], v[188:191], v[50:53]
	v_mfma_f32_16x16x32_bf16 v[38:41], v[172:175], v[212:215], v[38:41]
	v_mfma_f32_16x16x32_bf16 v[34:37], v[180:183], v[212:215], v[34:37]
	v_mfma_f32_16x16x32_bf16 v[22:25], v[172:175], v[220:223], v[22:25]
	v_mfma_f32_16x16x32_bf16 v[18:21], v[180:183], v[220:223], v[18:21]
	v_mfma_f32_16x16x32_bf16 v[6:9], v[172:175], v[232:235], v[6:9]
	v_mfma_f32_16x16x32_bf16 v[2:5], v[180:183], v[232:235], v[2:5]
	v_mfma_f32_16x16x32_bf16 v[54:57], v[176:179], v[208:211], v[54:57]
	v_mfma_f32_16x16x32_bf16 v[50:53], v[184:187], v[208:211], v[50:53]
	v_mfma_f32_16x16x32_bf16 v[38:41], v[176:179], v[216:219], v[38:41]
	v_mfma_f32_16x16x32_bf16 v[34:37], v[184:187], v[216:219], v[34:37]
	v_mfma_f32_16x16x32_bf16 v[22:25], v[176:179], v[228:231], v[22:25]
	v_mfma_f32_16x16x32_bf16 v[18:21], v[184:187], v[228:231], v[18:21]
	v_mfma_f32_16x16x32_bf16 v[6:9], v[176:179], v[236:239], v[6:9]
	v_mfma_f32_16x16x32_bf16 v[2:5], v[184:187], v[236:239], v[2:5]
	s_setprio 0
	s_barrier
	s_add_u32 s2, s2, 0x100
	s_addc_u32 s3, s3, 0
	s_cmp_ge_i32 s22, s72
	s_cbranch_scc0 .LBB0_1390

; #define PG8_STAGE(bufoff, gbase, voff) do { _Pragma("unroll") for (int _i = 0; _i < 2; ++_i) \
;         __builtin_amdgcn_global_load_lds((const unsigned*)((const char*)(gbase) + (voff)[_i]), (PG8_LAS unsigned*)(lds + (bufoff) + ldsw + _i * 8192), 16, 0, 0); } while (0)
; #define PG8_LDA(dst, b, h) do { _Pragma("unroll") for (int m = 0; m < 4; ++m) _Pragma("unroll") for (int k = 0; k < 2; ++k) dst[m][k] = *(const PG8_LAS bf16x8*)(lds + PG8_SA(b, h) + aoff + m * 2048 + k * 1024); } while (0)
; #define PG8_LDB(dst, b, h) do { _Pragma("unroll") for (int n = 0; n < 2; ++n) _Pragma("unroll") for (int k = 0; k < 2; ++k) dst[n][k] = *(const PG8_LAS bf16x8*)(lds + PG8_SB(b, h) + boff + n * 2048 + k * 1024); } while (0)
; #define PG8_MMA(ai, bj, At, Bt) do { __builtin_amdgcn_s_setprio(1); _Pragma("unroll") for (int m = 0; m < 4; ++m) _Pragma("unroll") for (int n = 0; n < 2; ++n) _Pragma("unroll") for (int k = 0; k < 2; ++k) \
;         acc[ai][bj][m][n] = __builtin_amdgcn_mfma_f32_16x16x32_bf16(Bt[n][k], At[m][k], acc[ai][bj][m][n], 0, 0, 0); __builtin_amdgcn_s_setprio(0); } while (0)
; #define PG8_WAIT_V(n) asm volatile("s_waitcnt vmcnt(" #n ")" ::: "memory")
; #define PG8_WAIT_L(n) asm volatile("s_waitcnt lgkmcnt(" #n ")" ::: "memory")
; #define PG8_BAR __builtin_amdgcn_s_barrier()
; #define PG8_SCHED __builtin_amdgcn_sched_barrier(0)
; template <class Epi, class Sched, bool ALIGN_EPI = false, bool SP2 = false>
; __device__ __forceinline__ void gemm_phase(PG8_LAS unsigned char* lds, const Gemm g, const Sched& S, const Epi& E) {
;     ...
;             const char* a2 = last ? nA : cA + (size_t)(t + 2) * kstep; const char* b2 = last ? nB : cB + (size_t)(t + 2) * kstep;
;             const char* a3 = a2 + kstep; const char* b3 = b2 + kstep;
;             if (last && has_next) S.a_ready(nxt);
;             if constexpr (SP2) {
;             PG8_LDB(B0, 0, 0); PG8_LDB(B1, 0, 1); PG8_SCHED; PG8_LDA(At, 0, 0); PG8_STAGE(PG8_SA(1, 1), a1 + hstep, voffA);
;             PG8_WAIT_V(8); PG8_WAIT_L(0); PG8_BAR; PG8_MMA(0, 0, At, B0); PG8_MMA(0, 1, At, B1); PG8_BAR; PG8_SCHED;
;             PG8_LDA(At, 0, 1); PG8_STAGE(PG8_SB(0, 0), b2, voffB); PG8_STAGE(PG8_SB(0, 1), b2 + hstep, voffB); PG8_STAGE(PG8_SA(0, 0), a2, voffA);
;             PG8_WAIT_V(8); PG8_WAIT_L(0); PG8_BAR; PG8_MMA(1, 0, At, B0); PG8_MMA(1, 1, At, B1); PG8_BAR; PG8_SCHED;
.LBB0_1483:
	s_add_i32 s22, s17, 2
	s_add_u32 s28, s2, 0x80
	s_addc_u32 s30, s3, 0
	s_add_i32 s33, 0, 0x10000
	s_cmp_eq_u32 s70, s17
	s_cselect_b32 s35, s51, s30
	s_cselect_b32 s34, s50, s28
	v_add_u32_e32 v146, s33, v148
	s_cselect_b32 s31, s53, s16
	s_cselect_b32 s30, s52, s4
	s_add_i32 s17, 0, 0x14000
	ds_read_b128 v[142:145], v146
	ds_read_b128 v[154:157], v146 offset:1024
	ds_read_b128 v[158:161], v146 offset:2048
	ds_read_b128 v[162:165], v146 offset:3072
	v_add_u32_e32 v146, s17, v148
	ds_read_b128 v[166:169], v146
	ds_read_b128 v[170:173], v146 offset:1024
	ds_read_b128 v[174:177], v146 offset:2048
	ds_read_b128 v[178:181], v146 offset:3072
	v_lshl_add_u64 v[146:147], s[2:3], 0, v[138:139]
	s_add_i32 m0, s64, 0xc000
	ds_read_b128 v[182:185], v153
	ds_read_b128 v[186:189], v153 offset:1024
	ds_read_b128 v[190:193], v153 offset:2048
	ds_read_b128 v[208:211], v153 offset:3072
	ds_read_b128 v[212:215], v153 offset:4096
	ds_read_b128 v[216:219], v153 offset:5120
	ds_read_b128 v[220:223], v153 offset:6144
	ds_read_b128 v[228:231], v153 offset:7168
	global_load_lds_dwordx4 v[146:147], off
	v_lshl_add_u64 v[146:147], s[2:3], 0, v[140:141]
	s_add_i32 m0, s64, 0xe000
	s_nop 0
	global_load_lds_dwordx4 v[146:147], off
	s_waitcnt vmcnt(8)
	s_waitcnt lgkmcnt(0)
	s_barrier
	s_setprio 1
	v_mfma_f32_16x16x32_bf16 v[124:127], v[142:145], v[182:185], v[124:127]
	v_mfma_f32_16x16x32_bf16 v[120:123], v[158:161], v[182:185], v[120:123]
	v_mfma_f32_16x16x32_bf16 v[112:115], v[142:145], v[190:193], v[112:115]
	v_mfma_f32_16x16x32_bf16 v[104:107], v[158:161], v[190:193], v[104:107]
	v_mfma_f32_16x16x32_bf16 v[94:97], v[142:145], v[212:215], v[94:97]
	v_mfma_f32_16x16x32_bf16 v[86:89], v[158:161], v[212:215], v[86:89]
	v_mfma_f32_16x16x32_bf16 v[78:81], v[142:145], v[220:223], v[78:81]
	v_mfma_f32_16x16x32_bf16 v[70:73], v[158:161], v[220:223], v[70:73]
	v_mfma_f32_16x16x32_bf16 v[124:127], v[154:157], v[186:189], v[124:127]
	v_mfma_f32_16x16x32_bf16 v[120:123], v[162:165], v[186:189], v[120:123]
	v_mfma_f32_16x16x32_bf16 v[112:115], v[154:157], v[208:211], v[112:115]
	v_mfma_f32_16x16x32_bf16 v[104:107], v[162:165], v[208:211], v[104:107]
	v_mfma_f32_16x16x32_bf16 v[94:97], v[154:157], v[216:219], v[94:97]
	v_mfma_f32_16x16x32_bf16 v[86:89], v[162:165], v[216:219], v[86:89]
	v_mfma_f32_16x16x32_bf16 v[78:81], v[154:157], v[228:231], v[78:81]
	v_mfma_f32_16x16x32_bf16 v[70:73], v[162:165], v[228:231], v[70:73]
	s_setprio 0
	s_setprio 1
	v_mfma_f32_16x16x32_bf16 v[128:131], v[166:169], v[182:185], v[128:131]
	v_mfma_f32_16x16x32_bf16 v[116:119], v[174:177], v[182:185], v[116:119]
	v_mfma_f32_16x16x32_bf16 v[108:111], v[166:169], v[190:193], v[108:111]
	v_mfma_f32_16x16x32_bf16 v[100:103], v[174:177], v[190:193], v[100:103]
	v_mfma_f32_16x16x32_bf16 v[90:93], v[166:169], v[212:215], v[90:93]
	v_mfma_f32_16x16x32_bf16 v[82:85], v[174:177], v[212:215], v[82:85]
	v_mfma_f32_16x16x32_bf16 v[74:77], v[166:169], v[220:223], v[74:77]
	v_mfma_f32_16x16x32_bf16 v[66:69], v[174:177], v[220:223], v[66:69]
	v_mfma_f32_16x16x32_bf16 v[128:131], v[170:173], v[186:189], v[128:131]
	v_mfma_f32_16x16x32_bf16 v[116:119], v[178:181], v[186:189], v[116:119]
	v_mfma_f32_16x16x32_bf16 v[108:111], v[170:173], v[208:211], v[108:111]
	v_mfma_f32_16x16x32_bf16 v[100:103], v[178:181], v[208:211], v[100:103]
	v_mfma_f32_16x16x32_bf16 v[90:93], v[170:173], v[216:219], v[90:93]
	v_mfma_f32_16x16x32_bf16 v[82:85], v[178:181], v[216:219], v[82:85]
	v_mfma_f32_16x16x32_bf16 v[74:77], v[170:173], v[228:231], v[74:77]
	v_mfma_f32_16x16x32_bf16 v[66:69], v[178:181], v[228:231], v[66:69]
	s_setprio 0
	s_barrier
	s_add_i32 s28, s33, s57
	v_lshl_add_u64 v[146:147], s[30:31], 0, v[98:99]
	s_mov_b32 m0, s28
	ds_read_b128 v[182:185], v153 offset:16384
	ds_read_b128 v[186:189], v153 offset:17408
	ds_read_b128 v[190:193], v153 offset:18432
	ds_read_b128 v[208:211], v153 offset:19456
	ds_read_b128 v[212:215], v153 offset:20480
	ds_read_b128 v[216:219], v153 offset:21504
	ds_read_b128 v[220:223], v153 offset:22528
	ds_read_b128 v[228:231], v153 offset:23552
	global_load_lds_dwordx4 v[146:147], off
	s_add_i32 m0, s28, 0x2000
	v_lshl_add_u64 v[224:225], s[30:31], 0, v[132:133]
	s_add_u32 s30, s30, s8
	s_addc_u32 s31, s31, s9
	s_add_i32 s17, s17, s57
	global_load_lds_dwordx4 v[224:225], off
	v_lshl_add_u64 v[232:233], s[30:31], 0, v[98:99]
	s_mov_b32 m0, s17
	v_lshl_add_u64 v[234:235], s[30:31], 0, v[132:133]
	global_load_lds_dwordx4 v[232:233], off
	s_add_i32 m0, s17, 0x2000
	v_lshl_add_u64 v[236:237], s[34:35], 0, v[136:137]
	global_load_lds_dwordx4 v[234:235], off
	s_mov_b32 m0, s64
	v_lshl_add_u64 v[238:239], s[34:35], 0, v[134:135]
	global_load_lds_dwordx4 v[236:237], off
	s_mov_b32 m0, s65
	s_nop 0
	global_load_lds_dwordx4 v[238:239], off
	s_waitcnt vmcnt(8)
	s_waitcnt lgkmcnt(0)
	s_barrier
; #define PG8_STAGE(bufoff, gbase, voff) do { _Pragma("unroll") for (int _i = 0; _i < 2; ++_i) \
;         __builtin_amdgcn_global_load_lds((const unsigned*)((const char*)(gbase) + (voff)[_i]), (PG8_LAS unsigned*)(lds + (bufoff) + ldsw + _i * 8192), 16, 0, 0); } while (0)
; #define PG8_LDA(dst, b, h) do { _Pragma("unroll") for (int m = 0; m < 4; ++m) _Pragma("unroll") for (int k = 0; k < 2; ++k) dst[m][k] = *(const PG8_LAS bf16x8*)(lds + PG8_SA(b, h) + aoff + m * 2048 + k * 1024); } while (0)
; #define PG8_LDB(dst, b, h) do { _Pragma("unroll") for (int n = 0; n < 2; ++n) _Pragma("unroll") for (int k = 0; k < 2; ++k) dst[n][k] = *(const PG8_LAS bf16x8*)(lds + PG8_SB(b, h) + boff + n * 2048 + k * 1024); } while (0)
; #define PG8_MMA(ai, bj, At, Bt) do { __builtin_amdgcn_s_setprio(1); _Pragma("unroll") for (int m = 0; m < 4; ++m) _Pragma("unroll") for (int n = 0; n < 2; ++n) _Pragma("unroll") for (int k = 0; k < 2; ++k) \
;         acc[ai][bj][m][n] = __builtin_amdgcn_mfma_f32_16x16x32_bf16(Bt[n][k], At[m][k], acc[ai][bj][m][n], 0, 0, 0); __builtin_amdgcn_s_setprio(0); } while (0)
; #define PG8_WAIT_V(n) asm volatile("s_waitcnt vmcnt(" #n ")" ::: "memory")
; #define PG8_WAIT_L(n) asm volatile("s_waitcnt lgkmcnt(" #n ")" ::: "memory")
; #define PG8_BAR __builtin_amdgcn_s_barrier()
; #define PG8_SCHED __builtin_amdgcn_sched_barrier(0)
; template <class Epi, class Sched, bool ALIGN_EPI = false, bool SP2 = false>
; __device__ __forceinline__ void gemm_phase(PG8_LAS unsigned char* lds, const Gemm g, const Sched& S, const Epi& E) {
;     ...
;             PG8_WAIT_V(8); PG8_WAIT_L(0); PG8_BAR; PG8_MMA(1, 0, At, B0); PG8_MMA(1, 1, At, B1); PG8_BAR; PG8_SCHED;
;             PG8_LDB(B0, 1, 0); PG8_LDB(B1, 1, 1); PG8_SCHED; PG8_LDA(At, 1, 0); PG8_STAGE(PG8_SA(0, 1), a2 + hstep, voffA);
;             PG8_WAIT_V(8); PG8_WAIT_L(0); PG8_BAR; PG8_MMA(0, 0, At, B0); PG8_MMA(0, 1, At, B1); PG8_BAR; PG8_SCHED;
	s_setprio 1
	v_mfma_f32_16x16x32_bf16 v[62:65], v[142:145], v[182:185], v[62:65]
	v_mfma_f32_16x16x32_bf16 v[54:57], v[158:161], v[182:185], v[54:57]
	v_mfma_f32_16x16x32_bf16 v[46:49], v[142:145], v[190:193], v[46:49]
	v_mfma_f32_16x16x32_bf16 v[38:41], v[158:161], v[190:193], v[38:41]
	v_mfma_f32_16x16x32_bf16 v[30:33], v[142:145], v[212:215], v[30:33]
	v_mfma_f32_16x16x32_bf16 v[22:25], v[158:161], v[212:215], v[22:25]
	v_mfma_f32_16x16x32_bf16 v[14:17], v[142:145], v[220:223], v[14:17]
	v_mfma_f32_16x16x32_bf16 v[6:9], v[158:161], v[220:223], v[6:9]
	v_mfma_f32_16x16x32_bf16 v[62:65], v[154:157], v[186:189], v[62:65]
	v_mfma_f32_16x16x32_bf16 v[54:57], v[162:165], v[186:189], v[54:57]
	v_mfma_f32_16x16x32_bf16 v[46:49], v[154:157], v[208:211], v[46:49]
	v_mfma_f32_16x16x32_bf16 v[38:41], v[162:165], v[208:211], v[38:41]
	v_mfma_f32_16x16x32_bf16 v[30:33], v[154:157], v[216:219], v[30:33]
	v_mfma_f32_16x16x32_bf16 v[22:25], v[162:165], v[216:219], v[22:25]
	v_mfma_f32_16x16x32_bf16 v[14:17], v[154:157], v[228:231], v[14:17]
	v_mfma_f32_16x16x32_bf16 v[6:9], v[162:165], v[228:231], v[6:9]
	s_setprio 0
	s_setprio 1
	v_mfma_f32_16x16x32_bf16 v[58:61], v[166:169], v[182:185], v[58:61]
	v_mfma_f32_16x16x32_bf16 v[50:53], v[174:177], v[182:185], v[50:53]
	v_mfma_f32_16x16x32_bf16 v[42:45], v[166:169], v[190:193], v[42:45]
	v_mfma_f32_16x16x32_bf16 v[34:37], v[174:177], v[190:193], v[34:37]
	v_mfma_f32_16x16x32_bf16 v[26:29], v[166:169], v[212:215], v[26:29]
	v_mfma_f32_16x16x32_bf16 v[18:21], v[174:177], v[212:215], v[18:21]
	v_mfma_f32_16x16x32_bf16 v[10:13], v[166:169], v[220:223], v[10:13]
	v_mfma_f32_16x16x32_bf16 v[2:5], v[174:177], v[220:223], v[2:5]
	v_mfma_f32_16x16x32_bf16 v[58:61], v[170:173], v[186:189], v[58:61]
	v_mfma_f32_16x16x32_bf16 v[50:53], v[178:181], v[186:189], v[50:53]
	v_mfma_f32_16x16x32_bf16 v[42:45], v[170:173], v[208:211], v[42:45]
	v_mfma_f32_16x16x32_bf16 v[34:37], v[178:181], v[208:211], v[34:37]
	v_mfma_f32_16x16x32_bf16 v[26:29], v[170:173], v[216:219], v[26:29]
	v_mfma_f32_16x16x32_bf16 v[18:21], v[178:181], v[216:219], v[18:21]
	v_mfma_f32_16x16x32_bf16 v[10:13], v[170:173], v[228:231], v[10:13]
	v_mfma_f32_16x16x32_bf16 v[2:5], v[178:181], v[228:231], v[2:5]
	s_setprio 0
	s_barrier
	s_add_i32 s17, 0, 0x18000
	s_add_i32 s28, 0, 0x1c000
	v_add_u32_e32 v162, s17, v148
	v_add_u32_e32 v178, s28, v148
	ds_read_b128 v[142:145], v162
	ds_read_b128 v[154:157], v162 offset:1024
	ds_read_b128 v[158:161], v162 offset:2048
	ds_read_b128 v[162:165], v162 offset:3072
	ds_read_b128 v[166:169], v178
	ds_read_b128 v[170:173], v178 offset:1024
	ds_read_b128 v[174:177], v178 offset:2048
	ds_read_b128 v[178:181], v178 offset:3072
	s_add_u32 s30, s34, s8
	s_addc_u32 s31, s35, s9
	s_mov_b32 m0, s66
	v_lshl_add_u64 v[240:241], s[30:31], 0, v[136:137]
	ds_read_b128 v[182:185], v153 offset:32768
	ds_read_b128 v[186:189], v153 offset:33792
	ds_read_b128 v[190:193], v153 offset:34816
	ds_read_b128 v[208:211], v153 offset:35840
	ds_read_b128 v[212:215], v153 offset:36864
	ds_read_b128 v[216:219], v153 offset:37888
	ds_read_b128 v[220:223], v153 offset:38912
	ds_read_b128 v[228:231], v153 offset:39936
	global_load_lds_dwordx4 v[240:241], off
	v_lshl_add_u64 v[240:241], s[30:31], 0, v[134:135]
	s_mov_b32 m0, s67
	s_nop 0
	global_load_lds_dwordx4 v[240:241], off
	s_waitcnt vmcnt(8)
	s_waitcnt lgkmcnt(0)
	s_barrier
	s_setprio 1
	v_mfma_f32_16x16x32_bf16 v[124:127], v[142:145], v[182:185], v[124:127]
	v_mfma_f32_16x16x32_bf16 v[120:123], v[158:161], v[182:185], v[120:123]
	v_mfma_f32_16x16x32_bf16 v[112:115], v[142:145], v[190:193], v[112:115]
	v_mfma_f32_16x16x32_bf16 v[104:107], v[158:161], v[190:193], v[104:107]
	v_mfma_f32_16x16x32_bf16 v[94:97], v[142:145], v[212:215], v[94:97]
	v_mfma_f32_16x16x32_bf16 v[86:89], v[158:161], v[212:215], v[86:89]
	v_mfma_f32_16x16x32_bf16 v[78:81], v[142:145], v[220:223], v[78:81]
	v_mfma_f32_16x16x32_bf16 v[70:73], v[158:161], v[220:223], v[70:73]
	v_mfma_f32_16x16x32_bf16 v[124:127], v[154:157], v[186:189], v[124:127]
	v_mfma_f32_16x16x32_bf16 v[120:123], v[162:165], v[186:189], v[120:123]
	v_mfma_f32_16x16x32_bf16 v[112:115], v[154:157], v[208:211], v[112:115]
	v_mfma_f32_16x16x32_bf16 v[104:107], v[162:165], v[208:211], v[104:107]
	v_mfma_f32_16x16x32_bf16 v[94:97], v[154:157], v[216:219], v[94:97]
	v_mfma_f32_16x16x32_bf16 v[86:89], v[162:165], v[216:219], v[86:89]
	v_mfma_f32_16x16x32_bf16 v[78:81], v[154:157], v[228:231], v[78:81]
	v_mfma_f32_16x16x32_bf16 v[70:73], v[162:165], v[228:231], v[70:73]
	s_setprio 0
	s_setprio 1
	v_mfma_f32_16x16x32_bf16 v[128:131], v[166:169], v[182:185], v[128:131]
	v_mfma_f32_16x16x32_bf16 v[116:119], v[174:177], v[182:185], v[116:119]
	v_mfma_f32_16x16x32_bf16 v[108:111], v[166:169], v[190:193], v[108:111]
	v_mfma_f32_16x16x32_bf16 v[100:103], v[174:177], v[190:193], v[100:103]
	v_mfma_f32_16x16x32_bf16 v[90:93], v[166:169], v[212:215], v[90:93]
	v_mfma_f32_16x16x32_bf16 v[82:85], v[174:177], v[212:215], v[82:85]
	v_mfma_f32_16x16x32_bf16 v[74:77], v[166:169], v[220:223], v[74:77]
	v_mfma_f32_16x16x32_bf16 v[66:69], v[174:177], v[220:223], v[66:69]
	v_mfma_f32_16x16x32_bf16 v[128:131], v[170:173], v[186:189], v[128:131]
	v_mfma_f32_16x16x32_bf16 v[116:119], v[178:181], v[186:189], v[116:119]
	v_mfma_f32_16x16x32_bf16 v[108:111], v[170:173], v[208:211], v[108:111]
	v_mfma_f32_16x16x32_bf16 v[100:103], v[178:181], v[208:211], v[100:103]
	v_mfma_f32_16x16x32_bf16 v[90:93], v[170:173], v[216:219], v[90:93]
	v_mfma_f32_16x16x32_bf16 v[82:85], v[178:181], v[216:219], v[82:85]
	v_mfma_f32_16x16x32_bf16 v[74:77], v[170:173], v[228:231], v[74:77]
	v_mfma_f32_16x16x32_bf16 v[66:69], v[178:181], v[228:231], v[66:69]
	s_setprio 0
	s_barrier
; #define PG8_STAGE(bufoff, gbase, voff) do { _Pragma("unroll") for (int _i = 0; _i < 2; ++_i) \
;         __builtin_amdgcn_global_load_lds((const unsigned*)((const char*)(gbase) + (voff)[_i]), (PG8_LAS unsigned*)(lds + (bufoff) + ldsw + _i * 8192), 16, 0, 0); } while (0)
; #define PG8_LDA(dst, b, h) do { _Pragma("unroll") for (int m = 0; m < 4; ++m) _Pragma("unroll") for (int k = 0; k < 2; ++k) dst[m][k] = *(const PG8_LAS bf16x8*)(lds + PG8_SA(b, h) + aoff + m * 2048 + k * 1024); } while (0)
; #define PG8_MMA(ai, bj, At, Bt) do { __builtin_amdgcn_s_setprio(1); _Pragma("unroll") for (int m = 0; m < 4; ++m) _Pragma("unroll") for (int n = 0; n < 2; ++n) _Pragma("unroll") for (int k = 0; k < 2; ++k) \
;         acc[ai][bj][m][n] = __builtin_amdgcn_mfma_f32_16x16x32_bf16(Bt[n][k], At[m][k], acc[ai][bj][m][n], 0, 0, 0); __builtin_amdgcn_s_setprio(0); } while (0)
; #define PG8_WAIT_V(n) asm volatile("s_waitcnt vmcnt(" #n ")" ::: "memory")
; #define PG8_WAIT_L(n) asm volatile("s_waitcnt lgkmcnt(" #n ")" ::: "memory")
; #define PG8_BAR __builtin_amdgcn_s_barrier()
; #define PG8_SCHED __builtin_amdgcn_sched_barrier(0)
; template <class Epi, class Sched, bool ALIGN_EPI = false, bool SP2 = false>
; __device__ __forceinline__ void gemm_phase(PG8_LAS unsigned char* lds, const Gemm g, const Sched& S, const Epi& E) {
;     ...
;             PG8_LDA(At, 1, 1); PG8_STAGE(PG8_SB(1, 0), b3, voffB); PG8_STAGE(PG8_SB(1, 1), b3 + hstep, voffB); PG8_STAGE(PG8_SA(1, 0), a3, voffA);
;             PG8_WAIT_V(8); PG8_WAIT_L(0); PG8_BAR; PG8_MMA(1, 0, At, B0); PG8_MMA(1, 1, At, B1); PG8_BAR; PG8_SCHED;
	s_add_i32 s17, s17, s57
	v_lshl_add_u64 v[146:147], v[146:147], 0, s[24:25]
	s_mov_b32 m0, s17
	ds_read_b128 v[182:185], v153 offset:49152
	ds_read_b128 v[186:189], v153 offset:50176
	ds_read_b128 v[190:193], v153 offset:51200
	ds_read_b128 v[208:211], v153 offset:52224
	ds_read_b128 v[212:215], v153 offset:53248
	ds_read_b128 v[216:219], v153 offset:54272
	ds_read_b128 v[220:223], v153 offset:55296
	ds_read_b128 v[228:231], v153 offset:56320
	global_load_lds_dwordx4 v[146:147], off
	v_lshl_add_u64 v[146:147], v[224:225], 0, s[24:25]
	s_add_i32 m0, s17, 0x2000
	s_add_i32 s17, s28, s57
	global_load_lds_dwordx4 v[146:147], off
	v_lshl_add_u64 v[146:147], v[232:233], 0, s[24:25]
	s_mov_b32 m0, s17
	s_nop 0
	global_load_lds_dwordx4 v[146:147], off
	v_lshl_add_u64 v[146:147], v[234:235], 0, s[24:25]
	s_add_i32 m0, s17, 0x2000
	s_nop 0
	global_load_lds_dwordx4 v[146:147], off
	v_lshl_add_u64 v[146:147], v[236:237], 0, s[24:25]
	s_mov_b32 m0, s68
	s_nop 0
	global_load_lds_dwordx4 v[146:147], off
	v_lshl_add_u64 v[146:147], v[238:239], 0, s[24:25]
	s_mov_b32 m0, s69
	s_nop 0
	global_load_lds_dwordx4 v[146:147], off
	s_waitcnt vmcnt(8)
	s_waitcnt lgkmcnt(0)
	s_barrier
	s_setprio 1
	v_mfma_f32_16x16x32_bf16 v[62:65], v[142:145], v[182:185], v[62:65]
	v_mfma_f32_16x16x32_bf16 v[54:57], v[158:161], v[182:185], v[54:57]
	v_mfma_f32_16x16x32_bf16 v[46:49], v[142:145], v[190:193], v[46:49]
	v_mfma_f32_16x16x32_bf16 v[38:41], v[158:161], v[190:193], v[38:41]
	v_mfma_f32_16x16x32_bf16 v[30:33], v[142:145], v[212:215], v[30:33]
	v_mfma_f32_16x16x32_bf16 v[22:25], v[158:161], v[212:215], v[22:25]
	v_mfma_f32_16x16x32_bf16 v[14:17], v[142:145], v[220:223], v[14:17]
	v_mfma_f32_16x16x32_bf16 v[6:9], v[158:161], v[220:223], v[6:9]
	v_mfma_f32_16x16x32_bf16 v[62:65], v[154:157], v[186:189], v[62:65]
	v_mfma_f32_16x16x32_bf16 v[54:57], v[162:165], v[186:189], v[54:57]
	v_mfma_f32_16x16x32_bf16 v[46:49], v[154:157], v[208:211], v[46:49]
	v_mfma_f32_16x16x32_bf16 v[38:41], v[162:165], v[208:211], v[38:41]
	v_mfma_f32_16x16x32_bf16 v[30:33], v[154:157], v[216:219], v[30:33]
	v_mfma_f32_16x16x32_bf16 v[22:25], v[162:165], v[216:219], v[22:25]
	v_mfma_f32_16x16x32_bf16 v[14:17], v[154:157], v[228:231], v[14:17]
	v_mfma_f32_16x16x32_bf16 v[6:9], v[162:165], v[228:231], v[6:9]
	s_setprio 0
	s_setprio 1
	v_mfma_f32_16x16x32_bf16 v[58:61], v[166:169], v[182:185], v[58:61]
	v_mfma_f32_16x16x32_bf16 v[50:53], v[174:177], v[182:185], v[50:53]
	v_mfma_f32_16x16x32_bf16 v[42:45], v[166:169], v[190:193], v[42:45]
	v_mfma_f32_16x16x32_bf16 v[34:37], v[174:177], v[190:193], v[34:37]
	v_mfma_f32_16x16x32_bf16 v[26:29], v[166:169], v[212:215], v[26:29]
	v_mfma_f32_16x16x32_bf16 v[18:21], v[174:177], v[212:215], v[18:21]
	v_mfma_f32_16x16x32_bf16 v[10:13], v[166:169], v[220:223], v[10:13]
	v_mfma_f32_16x16x32_bf16 v[2:5], v[174:177], v[220:223], v[2:5]
	v_mfma_f32_16x16x32_bf16 v[58:61], v[170:173], v[186:189], v[58:61]
	v_mfma_f32_16x16x32_bf16 v[50:53], v[178:181], v[186:189], v[50:53]
	v_mfma_f32_16x16x32_bf16 v[42:45], v[170:173], v[208:211], v[42:45]
	v_mfma_f32_16x16x32_bf16 v[34:37], v[178:181], v[208:211], v[34:37]
	v_mfma_f32_16x16x32_bf16 v[26:29], v[170:173], v[216:219], v[26:29]
	v_mfma_f32_16x16x32_bf16 v[18:21], v[178:181], v[216:219], v[18:21]
	v_mfma_f32_16x16x32_bf16 v[10:13], v[170:173], v[228:231], v[10:13]
	v_mfma_f32_16x16x32_bf16 v[2:5], v[178:181], v[228:231], v[2:5]
	s_setprio 0
	s_barrier
	s_add_u32 s2, s2, 0x100
	s_addc_u32 s3, s3, 0
	s_add_u32 s4, s4, 0x100
	s_addc_u32 s16, s16, 0
	s_cmp_ge_i32 s22, s18
	s_mov_b32 s17, s22
	s_cbranch_scc0 .LBB0_1483

; #define PG8_STAGE(bufoff, gbase, voff) do { _Pragma("unroll") for (int _i = 0; _i < 2; ++_i) \
;         __builtin_amdgcn_global_load_lds((const unsigned*)((const char*)(gbase) + (voff)[_i]), (PG8_LAS unsigned*)(lds + (bufoff) + ldsw + _i * 8192), 16, 0, 0); } while (0)
; #define PG8_LDA(dst, b, h) do { _Pragma("unroll") for (int m = 0; m < 4; ++m) _Pragma("unroll") for (int k = 0; k < 2; ++k) dst[m][k] = *(const PG8_LAS bf16x8*)(lds + PG8_SA(b, h) + aoff + m * 2048 + k * 1024); } while (0)
; #define PG8_LDB(dst, b, h) do { _Pragma("unroll") for (int n = 0; n < 2; ++n) _Pragma("unroll") for (int k = 0; k < 2; ++k) dst[n][k] = *(const PG8_LAS bf16x8*)(lds + PG8_SB(b, h) + boff + n * 2048 + k * 1024); } while (0)
; #define PG8_MMA(ai, bj, At, Bt) do { __builtin_amdgcn_s_setprio(1); _Pragma("unroll") for (int m = 0; m < 4; ++m) _Pragma("unroll") for (int n = 0; n < 2; ++n) _Pragma("unroll") for (int k = 0; k < 2; ++k) \
;         acc[ai][bj][m][n] = __builtin_amdgcn_mfma_f32_16x16x32_bf16(Bt[n][k], At[m][k], acc[ai][bj][m][n], 0, 0, 0); __builtin_amdgcn_s_setprio(0); } while (0)
; #define PG8_WAIT_V(n) asm volatile("s_waitcnt vmcnt(" #n ")" ::: "memory")
; #define PG8_WAIT_L(n) asm volatile("s_waitcnt lgkmcnt(" #n ")" ::: "memory")
; #define PG8_BAR __builtin_amdgcn_s_barrier()
; #define PG8_SCHED __builtin_amdgcn_sched_barrier(0)
; template <class Epi, class Sched, bool ALIGN_EPI = false, bool SP2 = false>
; __device__ __forceinline__ void gemm_phase(PG8_LAS unsigned char* lds, const Gemm g, const Sched& S, const Epi& E) {
;     ...
;             const char* a2 = last ? nA : cA + (size_t)(t + 2) * kstep; const char* b2 = last ? nB : cB + (size_t)(t + 2) * kstep;
;             const char* a3 = a2 + kstep; const char* b3 = b2 + kstep;
;             if (last && has_next) S.a_ready(nxt);
;             if constexpr (SP2) {
;             PG8_LDB(B0, 0, 0); PG8_LDB(B1, 0, 1); PG8_SCHED; PG8_LDA(At, 0, 0); PG8_STAGE(PG8_SA(1, 1), a1 + hstep, voffA);
;             PG8_WAIT_V(8); PG8_WAIT_L(0); PG8_BAR; PG8_MMA(0, 0, At, B0); PG8_MMA(0, 1, At, B1); PG8_BAR; PG8_SCHED;
;             PG8_LDA(At, 0, 1); PG8_STAGE(PG8_SB(0, 0), b2, voffB); PG8_STAGE(PG8_SB(0, 1), b2 + hstep, voffB); PG8_STAGE(PG8_SA(0, 0), a2, voffA);
;             PG8_WAIT_V(8); PG8_WAIT_L(0); PG8_BAR; PG8_MMA(1, 0, At, B0); PG8_MMA(1, 1, At, B1); PG8_BAR; PG8_SCHED;
.LBB0_1762:
	s_add_i32 s22, s17, 2
	s_add_u32 s28, s34, 0x80
	s_addc_u32 s30, s35, 0
	s_add_i32 s33, 0, 0x10000
	s_cmp_eq_u32 s65, s17
	s_cselect_b32 s37, s3, s30
	s_cselect_b32 s36, s2, s28
	v_add_u32_e32 v146, s33, v148
	s_cselect_b32 s31, s53, s16
	s_cselect_b32 s30, s52, s4
	s_add_i32 s17, 0, 0x14000
	ds_read_b128 v[142:145], v146
	ds_read_b128 v[152:155], v146 offset:1024
	ds_read_b128 v[156:159], v146 offset:2048
	ds_read_b128 v[160:163], v146 offset:3072
	v_add_u32_e32 v146, s17, v148
	ds_read_b128 v[164:167], v146
	ds_read_b128 v[168:171], v146 offset:1024
	ds_read_b128 v[172:175], v146 offset:2048
	ds_read_b128 v[176:179], v146 offset:3072
	v_lshl_add_u64 v[146:147], s[34:35], 0, v[138:139]
	s_add_i32 m0, s58, 0xc000
	ds_read_b128 v[180:183], v150
	ds_read_b128 v[184:187], v150 offset:1024
	ds_read_b128 v[188:191], v150 offset:2048
	ds_read_b128 v[208:211], v150 offset:3072
	ds_read_b128 v[212:215], v150 offset:4096
	ds_read_b128 v[216:219], v150 offset:5120
	ds_read_b128 v[220:223], v150 offset:6144
	ds_read_b128 v[228:231], v150 offset:7168
	global_load_lds_dwordx4 v[146:147], off
	v_lshl_add_u64 v[146:147], s[34:35], 0, v[140:141]
	s_add_i32 m0, s58, 0xe000
	s_nop 0
	global_load_lds_dwordx4 v[146:147], off
	s_waitcnt vmcnt(8)
	s_waitcnt lgkmcnt(0)
	s_barrier
	s_setprio 1
	v_mfma_f32_16x16x32_bf16 v[128:131], v[142:145], v[180:183], v[128:131]
	v_mfma_f32_16x16x32_bf16 v[124:127], v[156:159], v[180:183], v[124:127]
	v_mfma_f32_16x16x32_bf16 v[112:115], v[142:145], v[188:191], v[112:115]
	v_mfma_f32_16x16x32_bf16 v[108:111], v[156:159], v[188:191], v[108:111]
	v_mfma_f32_16x16x32_bf16 v[94:97], v[142:145], v[212:215], v[94:97]
	v_mfma_f32_16x16x32_bf16 v[90:93], v[156:159], v[212:215], v[90:93]
	v_mfma_f32_16x16x32_bf16 v[78:81], v[142:145], v[220:223], v[78:81]
	v_mfma_f32_16x16x32_bf16 v[74:77], v[156:159], v[220:223], v[74:77]
	v_mfma_f32_16x16x32_bf16 v[128:131], v[152:155], v[184:187], v[128:131]
	v_mfma_f32_16x16x32_bf16 v[124:127], v[160:163], v[184:187], v[124:127]
	v_mfma_f32_16x16x32_bf16 v[112:115], v[152:155], v[208:211], v[112:115]
	v_mfma_f32_16x16x32_bf16 v[108:111], v[160:163], v[208:211], v[108:111]
	v_mfma_f32_16x16x32_bf16 v[94:97], v[152:155], v[216:219], v[94:97]
	v_mfma_f32_16x16x32_bf16 v[90:93], v[160:163], v[216:219], v[90:93]
	v_mfma_f32_16x16x32_bf16 v[78:81], v[152:155], v[228:231], v[78:81]
	v_mfma_f32_16x16x32_bf16 v[74:77], v[160:163], v[228:231], v[74:77]
	s_setprio 0
	s_setprio 1
	v_mfma_f32_16x16x32_bf16 v[120:123], v[164:167], v[180:183], v[120:123]
	v_mfma_f32_16x16x32_bf16 v[116:119], v[172:175], v[180:183], v[116:119]
	v_mfma_f32_16x16x32_bf16 v[104:107], v[164:167], v[188:191], v[104:107]
	v_mfma_f32_16x16x32_bf16 v[100:103], v[172:175], v[188:191], v[100:103]
	v_mfma_f32_16x16x32_bf16 v[86:89], v[164:167], v[212:215], v[86:89]
	v_mfma_f32_16x16x32_bf16 v[82:85], v[172:175], v[212:215], v[82:85]
	v_mfma_f32_16x16x32_bf16 v[70:73], v[164:167], v[220:223], v[70:73]
	v_mfma_f32_16x16x32_bf16 v[66:69], v[172:175], v[220:223], v[66:69]
	v_mfma_f32_16x16x32_bf16 v[120:123], v[168:171], v[184:187], v[120:123]
	v_mfma_f32_16x16x32_bf16 v[116:119], v[176:179], v[184:187], v[116:119]
	v_mfma_f32_16x16x32_bf16 v[104:107], v[168:171], v[208:211], v[104:107]
	v_mfma_f32_16x16x32_bf16 v[100:103], v[176:179], v[208:211], v[100:103]
	v_mfma_f32_16x16x32_bf16 v[86:89], v[168:171], v[216:219], v[86:89]
	v_mfma_f32_16x16x32_bf16 v[82:85], v[176:179], v[216:219], v[82:85]
	v_mfma_f32_16x16x32_bf16 v[70:73], v[168:171], v[228:231], v[70:73]
	v_mfma_f32_16x16x32_bf16 v[66:69], v[176:179], v[228:231], v[66:69]
	s_setprio 0
	s_barrier
	s_add_i32 s28, s33, s57
	v_lshl_add_u64 v[146:147], s[30:31], 0, v[98:99]
	s_mov_b32 m0, s28
	ds_read_b128 v[180:183], v150 offset:16384
	ds_read_b128 v[184:187], v150 offset:17408
	ds_read_b128 v[188:191], v150 offset:18432
	ds_read_b128 v[208:211], v150 offset:19456
	ds_read_b128 v[212:215], v150 offset:20480
	ds_read_b128 v[216:219], v150 offset:21504
	ds_read_b128 v[220:223], v150 offset:22528
	ds_read_b128 v[228:231], v150 offset:23552
	global_load_lds_dwordx4 v[146:147], off
	s_add_i32 m0, s28, 0x2000
	v_lshl_add_u64 v[192:193], s[30:31], 0, v[136:137]
	s_add_u32 s30, s30, s8
	s_addc_u32 s31, s31, s9
	s_add_i32 s17, s17, s57
	global_load_lds_dwordx4 v[192:193], off
	v_lshl_add_u64 v[224:225], s[30:31], 0, v[98:99]
	s_mov_b32 m0, s17
	v_lshl_add_u64 v[232:233], s[30:31], 0, v[136:137]
	global_load_lds_dwordx4 v[224:225], off
	s_add_i32 m0, s17, 0x2000
	v_lshl_add_u64 v[234:235], s[36:37], 0, v[132:133]
	global_load_lds_dwordx4 v[232:233], off
	s_mov_b32 m0, s58
	v_lshl_add_u64 v[236:237], s[36:37], 0, v[134:135]
	global_load_lds_dwordx4 v[234:235], off
	s_mov_b32 m0, s59
	s_nop 0
	global_load_lds_dwordx4 v[236:237], off
	s_waitcnt vmcnt(8)
	s_waitcnt lgkmcnt(0)
	s_barrier
; #define PG8_STAGE(bufoff, gbase, voff) do { _Pragma("unroll") for (int _i = 0; _i < 2; ++_i) \
;         __builtin_amdgcn_global_load_lds((const unsigned*)((const char*)(gbase) + (voff)[_i]), (PG8_LAS unsigned*)(lds + (bufoff) + ldsw + _i * 8192), 16, 0, 0); } while (0)
; #define PG8_LDA(dst, b, h) do { _Pragma("unroll") for (int m = 0; m < 4; ++m) _Pragma("unroll") for (int k = 0; k < 2; ++k) dst[m][k] = *(const PG8_LAS bf16x8*)(lds + PG8_SA(b, h) + aoff + m * 2048 + k * 1024); } while (0)
; #define PG8_LDB(dst, b, h) do { _Pragma("unroll") for (int n = 0; n < 2; ++n) _Pragma("unroll") for (int k = 0; k < 2; ++k) dst[n][k] = *(const PG8_LAS bf16x8*)(lds + PG8_SB(b, h) + boff + n * 2048 + k * 1024); } while (0)
; #define PG8_MMA(ai, bj, At, Bt) do { __builtin_amdgcn_s_setprio(1); _Pragma("unroll") for (int m = 0; m < 4; ++m) _Pragma("unroll") for (int n = 0; n < 2; ++n) _Pragma("unroll") for (int k = 0; k < 2; ++k) \
;         acc[ai][bj][m][n] = __builtin_amdgcn_mfma_f32_16x16x32_bf16(Bt[n][k], At[m][k], acc[ai][bj][m][n], 0, 0, 0); __builtin_amdgcn_s_setprio(0); } while (0)
; #define PG8_WAIT_V(n) asm volatile("s_waitcnt vmcnt(" #n ")" ::: "memory")
; #define PG8_WAIT_L(n) asm volatile("s_waitcnt lgkmcnt(" #n ")" ::: "memory")
; #define PG8_BAR __builtin_amdgcn_s_barrier()
; #define PG8_SCHED __builtin_amdgcn_sched_barrier(0)
; template <class Epi, class Sched, bool ALIGN_EPI = false, bool SP2 = false>
; __device__ __forceinline__ void gemm_phase(PG8_LAS unsigned char* lds, const Gemm g, const Sched& S, const Epi& E) {
;     ...
;             PG8_WAIT_V(8); PG8_WAIT_L(0); PG8_BAR; PG8_MMA(1, 0, At, B0); PG8_MMA(1, 1, At, B1); PG8_BAR; PG8_SCHED;
;             PG8_LDB(B0, 1, 0); PG8_LDB(B1, 1, 1); PG8_SCHED; PG8_LDA(At, 1, 0); PG8_STAGE(PG8_SA(0, 1), a2 + hstep, voffA);
;             PG8_WAIT_V(8); PG8_WAIT_L(0); PG8_BAR; PG8_MMA(0, 0, At, B0); PG8_MMA(0, 1, At, B1); PG8_BAR; PG8_SCHED;
	s_setprio 1
	v_mfma_f32_16x16x32_bf16 v[62:65], v[142:145], v[180:183], v[62:65]
	v_mfma_f32_16x16x32_bf16 v[58:61], v[156:159], v[180:183], v[58:61]
	v_mfma_f32_16x16x32_bf16 v[46:49], v[142:145], v[188:191], v[46:49]
	v_mfma_f32_16x16x32_bf16 v[42:45], v[156:159], v[188:191], v[42:45]
	v_mfma_f32_16x16x32_bf16 v[30:33], v[142:145], v[212:215], v[30:33]
	v_mfma_f32_16x16x32_bf16 v[26:29], v[156:159], v[212:215], v[26:29]
	v_mfma_f32_16x16x32_bf16 v[14:17], v[142:145], v[220:223], v[14:17]
	v_mfma_f32_16x16x32_bf16 v[10:13], v[156:159], v[220:223], v[10:13]
	v_mfma_f32_16x16x32_bf16 v[62:65], v[152:155], v[184:187], v[62:65]
	v_mfma_f32_16x16x32_bf16 v[58:61], v[160:163], v[184:187], v[58:61]
	v_mfma_f32_16x16x32_bf16 v[46:49], v[152:155], v[208:211], v[46:49]
	v_mfma_f32_16x16x32_bf16 v[42:45], v[160:163], v[208:211], v[42:45]
	v_mfma_f32_16x16x32_bf16 v[30:33], v[152:155], v[216:219], v[30:33]
	v_mfma_f32_16x16x32_bf16 v[26:29], v[160:163], v[216:219], v[26:29]
	v_mfma_f32_16x16x32_bf16 v[14:17], v[152:155], v[228:231], v[14:17]
	v_mfma_f32_16x16x32_bf16 v[10:13], v[160:163], v[228:231], v[10:13]
	s_setprio 0
	s_setprio 1
	v_mfma_f32_16x16x32_bf16 v[54:57], v[164:167], v[180:183], v[54:57]
	v_mfma_f32_16x16x32_bf16 v[50:53], v[172:175], v[180:183], v[50:53]
	v_mfma_f32_16x16x32_bf16 v[38:41], v[164:167], v[188:191], v[38:41]
	v_mfma_f32_16x16x32_bf16 v[34:37], v[172:175], v[188:191], v[34:37]
	v_mfma_f32_16x16x32_bf16 v[22:25], v[164:167], v[212:215], v[22:25]
	v_mfma_f32_16x16x32_bf16 v[18:21], v[172:175], v[212:215], v[18:21]
	v_mfma_f32_16x16x32_bf16 v[6:9], v[164:167], v[220:223], v[6:9]
	v_mfma_f32_16x16x32_bf16 v[2:5], v[172:175], v[220:223], v[2:5]
	v_mfma_f32_16x16x32_bf16 v[54:57], v[168:171], v[184:187], v[54:57]
	v_mfma_f32_16x16x32_bf16 v[50:53], v[176:179], v[184:187], v[50:53]
	v_mfma_f32_16x16x32_bf16 v[38:41], v[168:171], v[208:211], v[38:41]
	v_mfma_f32_16x16x32_bf16 v[34:37], v[176:179], v[208:211], v[34:37]
	v_mfma_f32_16x16x32_bf16 v[22:25], v[168:171], v[216:219], v[22:25]
	v_mfma_f32_16x16x32_bf16 v[18:21], v[176:179], v[216:219], v[18:21]
	v_mfma_f32_16x16x32_bf16 v[6:9], v[168:171], v[228:231], v[6:9]
	v_mfma_f32_16x16x32_bf16 v[2:5], v[176:179], v[228:231], v[2:5]
	s_setprio 0
	s_barrier
	s_add_i32 s17, 0, 0x18000
	v_add_u32_e32 v151, s17, v148
	s_add_i32 s28, 0, 0x1c000
	ds_read_b128 v[142:145], v151
	ds_read_b128 v[152:155], v151 offset:1024
	ds_read_b128 v[156:159], v151 offset:2048
	ds_read_b128 v[160:163], v151 offset:3072
	v_add_u32_e32 v151, s28, v148
	ds_read_b128 v[164:167], v151
	ds_read_b128 v[168:171], v151 offset:1024
	ds_read_b128 v[172:175], v151 offset:2048
	ds_read_b128 v[176:179], v151 offset:3072
	s_add_u32 s30, s36, s8
	s_addc_u32 s31, s37, s9
	s_mov_b32 m0, s60
	v_lshl_add_u64 v[238:239], s[30:31], 0, v[132:133]
	ds_read_b128 v[180:183], v150 offset:32768
	ds_read_b128 v[184:187], v150 offset:33792
	ds_read_b128 v[188:191], v150 offset:34816
	ds_read_b128 v[208:211], v150 offset:35840
	ds_read_b128 v[212:215], v150 offset:36864
	ds_read_b128 v[216:219], v150 offset:37888
	ds_read_b128 v[220:223], v150 offset:38912
	ds_read_b128 v[228:231], v150 offset:39936
	global_load_lds_dwordx4 v[238:239], off
	v_lshl_add_u64 v[238:239], s[30:31], 0, v[134:135]
	s_mov_b32 m0, s61
	s_nop 0
	global_load_lds_dwordx4 v[238:239], off
	s_waitcnt vmcnt(8)
	s_waitcnt lgkmcnt(0)
	s_barrier
	s_setprio 1
	v_mfma_f32_16x16x32_bf16 v[128:131], v[142:145], v[180:183], v[128:131]
	v_mfma_f32_16x16x32_bf16 v[124:127], v[156:159], v[180:183], v[124:127]
	v_mfma_f32_16x16x32_bf16 v[112:115], v[142:145], v[188:191], v[112:115]
	v_mfma_f32_16x16x32_bf16 v[108:111], v[156:159], v[188:191], v[108:111]
	v_mfma_f32_16x16x32_bf16 v[94:97], v[142:145], v[212:215], v[94:97]
	v_mfma_f32_16x16x32_bf16 v[90:93], v[156:159], v[212:215], v[90:93]
	v_mfma_f32_16x16x32_bf16 v[78:81], v[142:145], v[220:223], v[78:81]
	v_mfma_f32_16x16x32_bf16 v[74:77], v[156:159], v[220:223], v[74:77]
	v_mfma_f32_16x16x32_bf16 v[128:131], v[152:155], v[184:187], v[128:131]
	v_mfma_f32_16x16x32_bf16 v[124:127], v[160:163], v[184:187], v[124:127]
	v_mfma_f32_16x16x32_bf16 v[112:115], v[152:155], v[208:211], v[112:115]
	v_mfma_f32_16x16x32_bf16 v[108:111], v[160:163], v[208:211], v[108:111]
	v_mfma_f32_16x16x32_bf16 v[94:97], v[152:155], v[216:219], v[94:97]
	v_mfma_f32_16x16x32_bf16 v[90:93], v[160:163], v[216:219], v[90:93]
	v_mfma_f32_16x16x32_bf16 v[78:81], v[152:155], v[228:231], v[78:81]
	v_mfma_f32_16x16x32_bf16 v[74:77], v[160:163], v[228:231], v[74:77]
	s_setprio 0
	s_setprio 1
	v_mfma_f32_16x16x32_bf16 v[120:123], v[164:167], v[180:183], v[120:123]
	v_mfma_f32_16x16x32_bf16 v[116:119], v[172:175], v[180:183], v[116:119]
	v_mfma_f32_16x16x32_bf16 v[104:107], v[164:167], v[188:191], v[104:107]
	v_mfma_f32_16x16x32_bf16 v[100:103], v[172:175], v[188:191], v[100:103]
	v_mfma_f32_16x16x32_bf16 v[86:89], v[164:167], v[212:215], v[86:89]
	v_mfma_f32_16x16x32_bf16 v[82:85], v[172:175], v[212:215], v[82:85]
	v_mfma_f32_16x16x32_bf16 v[70:73], v[164:167], v[220:223], v[70:73]
	v_mfma_f32_16x16x32_bf16 v[66:69], v[172:175], v[220:223], v[66:69]
	v_mfma_f32_16x16x32_bf16 v[120:123], v[168:171], v[184:187], v[120:123]
	v_mfma_f32_16x16x32_bf16 v[116:119], v[176:179], v[184:187], v[116:119]
	v_mfma_f32_16x16x32_bf16 v[104:107], v[168:171], v[208:211], v[104:107]
	v_mfma_f32_16x16x32_bf16 v[100:103], v[176:179], v[208:211], v[100:103]
	v_mfma_f32_16x16x32_bf16 v[86:89], v[168:171], v[216:219], v[86:89]
	v_mfma_f32_16x16x32_bf16 v[82:85], v[176:179], v[216:219], v[82:85]
	v_mfma_f32_16x16x32_bf16 v[70:73], v[168:171], v[228:231], v[70:73]
	v_mfma_f32_16x16x32_bf16 v[66:69], v[176:179], v[228:231], v[66:69]
	s_setprio 0
	s_barrier
; #define PG8_STAGE(bufoff, gbase, voff) do { _Pragma("unroll") for (int _i = 0; _i < 2; ++_i) \
;         __builtin_amdgcn_global_load_lds((const unsigned*)((const char*)(gbase) + (voff)[_i]), (PG8_LAS unsigned*)(lds + (bufoff) + ldsw + _i * 8192), 16, 0, 0); } while (0)
; #define PG8_LDA(dst, b, h) do { _Pragma("unroll") for (int m = 0; m < 4; ++m) _Pragma("unroll") for (int k = 0; k < 2; ++k) dst[m][k] = *(const PG8_LAS bf16x8*)(lds + PG8_SA(b, h) + aoff + m * 2048 + k * 1024); } while (0)
; #define PG8_MMA(ai, bj, At, Bt) do { __builtin_amdgcn_s_setprio(1); _Pragma("unroll") for (int m = 0; m < 4; ++m) _Pragma("unroll") for (int n = 0; n < 2; ++n) _Pragma("unroll") for (int k = 0; k < 2; ++k) \
;         acc[ai][bj][m][n] = __builtin_amdgcn_mfma_f32_16x16x32_bf16(Bt[n][k], At[m][k], acc[ai][bj][m][n], 0, 0, 0); __builtin_amdgcn_s_setprio(0); } while (0)
; #define PG8_WAIT_V(n) asm volatile("s_waitcnt vmcnt(" #n ")" ::: "memory")
; #define PG8_WAIT_L(n) asm volatile("s_waitcnt lgkmcnt(" #n ")" ::: "memory")
; #define PG8_BAR __builtin_amdgcn_s_barrier()
; #define PG8_SCHED __builtin_amdgcn_sched_barrier(0)
; template <class Epi, class Sched, bool ALIGN_EPI = false, bool SP2 = false>
; __device__ __forceinline__ void gemm_phase(PG8_LAS unsigned char* lds, const Gemm g, const Sched& S, const Epi& E) {
;     ...
;             PG8_LDA(At, 1, 1); PG8_STAGE(PG8_SB(1, 0), b3, voffB); PG8_STAGE(PG8_SB(1, 1), b3 + hstep, voffB); PG8_STAGE(PG8_SA(1, 0), a3, voffA);
;             PG8_WAIT_V(8); PG8_WAIT_L(0); PG8_BAR; PG8_MMA(1, 0, At, B0); PG8_MMA(1, 1, At, B1); PG8_BAR; PG8_SCHED;
	s_add_i32 s17, s17, s57
	v_lshl_add_u64 v[146:147], v[146:147], 0, s[24:25]
	s_mov_b32 m0, s17
	ds_read_b128 v[180:183], v150 offset:49152
	ds_read_b128 v[184:187], v150 offset:50176
	ds_read_b128 v[188:191], v150 offset:51200
	ds_read_b128 v[208:211], v150 offset:52224
	ds_read_b128 v[212:215], v150 offset:53248
	ds_read_b128 v[216:219], v150 offset:54272
	ds_read_b128 v[220:223], v150 offset:55296
	ds_read_b128 v[228:231], v150 offset:56320
	global_load_lds_dwordx4 v[146:147], off
	v_lshl_add_u64 v[146:147], v[192:193], 0, s[24:25]
	s_add_i32 m0, s17, 0x2000
	s_add_i32 s17, s28, s57
	global_load_lds_dwordx4 v[146:147], off
	v_lshl_add_u64 v[146:147], v[224:225], 0, s[24:25]
	s_mov_b32 m0, s17
	s_nop 0
	global_load_lds_dwordx4 v[146:147], off
	v_lshl_add_u64 v[146:147], v[232:233], 0, s[24:25]
	s_add_i32 m0, s17, 0x2000
	s_nop 0
	global_load_lds_dwordx4 v[146:147], off
	v_lshl_add_u64 v[146:147], v[234:235], 0, s[24:25]
	s_mov_b32 m0, s63
	s_nop 0
	global_load_lds_dwordx4 v[146:147], off
	v_lshl_add_u64 v[146:147], v[236:237], 0, s[24:25]
	s_mov_b32 m0, s64
	s_nop 0
	global_load_lds_dwordx4 v[146:147], off
	s_waitcnt vmcnt(8)
	s_waitcnt lgkmcnt(0)
	s_barrier
	s_setprio 1
	v_mfma_f32_16x16x32_bf16 v[62:65], v[142:145], v[180:183], v[62:65]
	v_mfma_f32_16x16x32_bf16 v[58:61], v[156:159], v[180:183], v[58:61]
	v_mfma_f32_16x16x32_bf16 v[46:49], v[142:145], v[188:191], v[46:49]
	v_mfma_f32_16x16x32_bf16 v[42:45], v[156:159], v[188:191], v[42:45]
	v_mfma_f32_16x16x32_bf16 v[30:33], v[142:145], v[212:215], v[30:33]
	v_mfma_f32_16x16x32_bf16 v[26:29], v[156:159], v[212:215], v[26:29]
	v_mfma_f32_16x16x32_bf16 v[14:17], v[142:145], v[220:223], v[14:17]
	v_mfma_f32_16x16x32_bf16 v[10:13], v[156:159], v[220:223], v[10:13]
	v_mfma_f32_16x16x32_bf16 v[62:65], v[152:155], v[184:187], v[62:65]
	v_mfma_f32_16x16x32_bf16 v[58:61], v[160:163], v[184:187], v[58:61]
	v_mfma_f32_16x16x32_bf16 v[46:49], v[152:155], v[208:211], v[46:49]
	v_mfma_f32_16x16x32_bf16 v[42:45], v[160:163], v[208:211], v[42:45]
	v_mfma_f32_16x16x32_bf16 v[30:33], v[152:155], v[216:219], v[30:33]
	v_mfma_f32_16x16x32_bf16 v[26:29], v[160:163], v[216:219], v[26:29]
	v_mfma_f32_16x16x32_bf16 v[14:17], v[152:155], v[228:231], v[14:17]
	v_mfma_f32_16x16x32_bf16 v[10:13], v[160:163], v[228:231], v[10:13]
	s_setprio 0
	s_setprio 1
	v_mfma_f32_16x16x32_bf16 v[54:57], v[164:167], v[180:183], v[54:57]
	v_mfma_f32_16x16x32_bf16 v[50:53], v[172:175], v[180:183], v[50:53]
	v_mfma_f32_16x16x32_bf16 v[38:41], v[164:167], v[188:191], v[38:41]
	v_mfma_f32_16x16x32_bf16 v[34:37], v[172:175], v[188:191], v[34:37]
	v_mfma_f32_16x16x32_bf16 v[22:25], v[164:167], v[212:215], v[22:25]
	v_mfma_f32_16x16x32_bf16 v[18:21], v[172:175], v[212:215], v[18:21]
	v_mfma_f32_16x16x32_bf16 v[6:9], v[164:167], v[220:223], v[6:9]
	v_mfma_f32_16x16x32_bf16 v[2:5], v[172:175], v[220:223], v[2:5]
	v_mfma_f32_16x16x32_bf16 v[54:57], v[168:171], v[184:187], v[54:57]
	v_mfma_f32_16x16x32_bf16 v[50:53], v[176:179], v[184:187], v[50:53]
	v_mfma_f32_16x16x32_bf16 v[38:41], v[168:171], v[208:211], v[38:41]
	v_mfma_f32_16x16x32_bf16 v[34:37], v[176:179], v[208:211], v[34:37]
	v_mfma_f32_16x16x32_bf16 v[22:25], v[168:171], v[216:219], v[22:25]
	v_mfma_f32_16x16x32_bf16 v[18:21], v[176:179], v[216:219], v[18:21]
	v_mfma_f32_16x16x32_bf16 v[6:9], v[168:171], v[228:231], v[6:9]
	v_mfma_f32_16x16x32_bf16 v[2:5], v[176:179], v[228:231], v[2:5]
	s_setprio 0
	s_barrier
	s_add_u32 s34, s34, 0x100
	s_addc_u32 s35, s35, 0
	s_add_u32 s4, s4, 0x100
	s_addc_u32 s16, s16, 0
	s_cmp_ge_i32 s22, s62
	s_mov_b32 s17, s22
	s_cbranch_scc0 .LBB0_1762

; #define PG8_STAGE(bufoff, gbase, voff) do { _Pragma("unroll") for (int _i = 0; _i < 2; ++_i) \
;         __builtin_amdgcn_global_load_lds((const unsigned*)((const char*)(gbase) + (voff)[_i]), (PG8_LAS unsigned*)(lds + (bufoff) + ldsw + _i * 8192), 16, 0, 0); } while (0)
; #define PG8_LDA(dst, b, h) do { _Pragma("unroll") for (int m = 0; m < 4; ++m) _Pragma("unroll") for (int k = 0; k < 2; ++k) dst[m][k] = *(const PG8_LAS bf16x8*)(lds + PG8_SA(b, h) + aoff + m * 2048 + k * 1024); } while (0)
; #define PG8_LDB(dst, b, h) do { _Pragma("unroll") for (int n = 0; n < 2; ++n) _Pragma("unroll") for (int k = 0; k < 2; ++k) dst[n][k] = *(const PG8_LAS bf16x8*)(lds + PG8_SB(b, h) + boff + n * 2048 + k * 1024); } while (0)
; #define PG8_MMA(ai, bj, At, Bt) do { __builtin_amdgcn_s_setprio(1); _Pragma("unroll") for (int m = 0; m < 4; ++m) _Pragma("unroll") for (int n = 0; n < 2; ++n) _Pragma("unroll") for (int k = 0; k < 2; ++k) \
;         acc[ai][bj][m][n] = __builtin_amdgcn_mfma_f32_16x16x32_bf16(Bt[n][k], At[m][k], acc[ai][bj][m][n], 0, 0, 0); __builtin_amdgcn_s_setprio(0); } while (0)
; #define PG8_WAIT_V(n) asm volatile("s_waitcnt vmcnt(" #n ")" ::: "memory")
; #define PG8_WAIT_L(n) asm volatile("s_waitcnt lgkmcnt(" #n ")" ::: "memory")
; #define PG8_BAR __builtin_amdgcn_s_barrier()
; #define PG8_SCHED __builtin_amdgcn_sched_barrier(0)
; template <class Epi, class Sched, bool ALIGN_EPI = false, bool SP2 = false>
; __device__ __forceinline__ void gemm_phase(PG8_LAS unsigned char* lds, const Gemm g, const Sched& S, const Epi& E) {
;     ...
;             const char* a2 = last ? nA : cA + (size_t)(t + 2) * kstep; const char* b2 = last ? nB : cB + (size_t)(t + 2) * kstep;
;             const char* a3 = a2 + kstep; const char* b3 = b2 + kstep;
;             if (last && has_next) S.a_ready(nxt);
;             if constexpr (SP2) {
;             PG8_LDB(B0, 0, 0); PG8_LDB(B1, 0, 1); PG8_SCHED; PG8_LDA(At, 0, 0); PG8_STAGE(PG8_SA(1, 1), a1 + hstep, voffA);
;             PG8_WAIT_V(8); PG8_WAIT_L(0); PG8_BAR; PG8_MMA(0, 0, At, B0); PG8_MMA(0, 1, At, B1); PG8_BAR; PG8_SCHED;
;             PG8_LDA(At, 0, 1); PG8_STAGE(PG8_SB(0, 0), b2, voffB); PG8_STAGE(PG8_SB(0, 1), b2 + hstep, voffB); PG8_STAGE(PG8_SA(0, 0), a2, voffA);
;             PG8_WAIT_V(8); PG8_WAIT_L(0); PG8_BAR; PG8_MMA(1, 0, At, B0); PG8_MMA(1, 1, At, B1); PG8_BAR; PG8_SCHED;
.LBB0_1853:
	s_add_i32 s22, s17, 2
	s_add_u32 s28, s34, 0x80
	s_addc_u32 s30, s35, 0
	s_add_i32 s33, 0, 0x10000
	s_cmp_eq_u32 s68, s17
	s_cselect_b32 s37, s3, s30
	s_cselect_b32 s36, s2, s28
	v_add_u32_e32 v150, s33, v153
	s_cselect_b32 s31, s59, s16
	s_cselect_b32 s30, s58, s4
	s_add_i32 s17, 0, 0x14000
	ds_read_b128 v[142:145], v150
	ds_read_b128 v[146:149], v150 offset:1024
	ds_read_b128 v[154:157], v150 offset:2048
	ds_read_b128 v[160:163], v150 offset:3072
	v_add_u32_e32 v150, s17, v153
	ds_read_b128 v[164:167], v150
	ds_read_b128 v[168:171], v150 offset:1024
	ds_read_b128 v[172:175], v150 offset:2048
	ds_read_b128 v[176:179], v150 offset:3072
	v_lshl_add_u64 v[150:151], s[34:35], 0, v[138:139]
	s_add_i32 m0, s62, 0xc000
	ds_read_b128 v[180:183], v159
	ds_read_b128 v[184:187], v159 offset:1024
	ds_read_b128 v[188:191], v159 offset:2048
	ds_read_b128 v[208:211], v159 offset:3072
	ds_read_b128 v[212:215], v159 offset:4096
	ds_read_b128 v[216:219], v159 offset:5120
	ds_read_b128 v[220:223], v159 offset:6144
	ds_read_b128 v[228:231], v159 offset:7168
	global_load_lds_dwordx4 v[150:151], off
	v_lshl_add_u64 v[150:151], s[34:35], 0, v[140:141]
	s_add_i32 m0, s62, 0xe000
	s_nop 0
	global_load_lds_dwordx4 v[150:151], off
	s_waitcnt vmcnt(8)
	s_waitcnt lgkmcnt(0)
	s_barrier
	s_setprio 1
	v_mfma_f32_16x16x32_bf16 v[124:127], v[142:145], v[180:183], v[124:127]
	v_mfma_f32_16x16x32_bf16 v[128:131], v[154:157], v[180:183], v[128:131]
	v_mfma_f32_16x16x32_bf16 v[112:115], v[142:145], v[188:191], v[112:115]
	v_mfma_f32_16x16x32_bf16 v[108:111], v[154:157], v[188:191], v[108:111]
	v_mfma_f32_16x16x32_bf16 v[94:97], v[142:145], v[212:215], v[94:97]
	v_mfma_f32_16x16x32_bf16 v[90:93], v[154:157], v[212:215], v[90:93]
	v_mfma_f32_16x16x32_bf16 v[78:81], v[142:145], v[220:223], v[78:81]
	v_mfma_f32_16x16x32_bf16 v[74:77], v[154:157], v[220:223], v[74:77]
	v_mfma_f32_16x16x32_bf16 v[124:127], v[146:149], v[184:187], v[124:127]
	v_mfma_f32_16x16x32_bf16 v[128:131], v[160:163], v[184:187], v[128:131]
	v_mfma_f32_16x16x32_bf16 v[112:115], v[146:149], v[208:211], v[112:115]
	v_mfma_f32_16x16x32_bf16 v[108:111], v[160:163], v[208:211], v[108:111]
	v_mfma_f32_16x16x32_bf16 v[94:97], v[146:149], v[216:219], v[94:97]
	v_mfma_f32_16x16x32_bf16 v[90:93], v[160:163], v[216:219], v[90:93]
	v_mfma_f32_16x16x32_bf16 v[78:81], v[146:149], v[228:231], v[78:81]
	v_mfma_f32_16x16x32_bf16 v[74:77], v[160:163], v[228:231], v[74:77]
	s_setprio 0
	s_setprio 1
	v_mfma_f32_16x16x32_bf16 v[120:123], v[164:167], v[180:183], v[120:123]
	v_mfma_f32_16x16x32_bf16 v[116:119], v[172:175], v[180:183], v[116:119]
	v_mfma_f32_16x16x32_bf16 v[104:107], v[164:167], v[188:191], v[104:107]
	v_mfma_f32_16x16x32_bf16 v[100:103], v[172:175], v[188:191], v[100:103]
	v_mfma_f32_16x16x32_bf16 v[86:89], v[164:167], v[212:215], v[86:89]
	v_mfma_f32_16x16x32_bf16 v[82:85], v[172:175], v[212:215], v[82:85]
	v_mfma_f32_16x16x32_bf16 v[70:73], v[164:167], v[220:223], v[70:73]
	v_mfma_f32_16x16x32_bf16 v[66:69], v[172:175], v[220:223], v[66:69]
	v_mfma_f32_16x16x32_bf16 v[120:123], v[168:171], v[184:187], v[120:123]
	v_mfma_f32_16x16x32_bf16 v[116:119], v[176:179], v[184:187], v[116:119]
	v_mfma_f32_16x16x32_bf16 v[104:107], v[168:171], v[208:211], v[104:107]
	v_mfma_f32_16x16x32_bf16 v[100:103], v[176:179], v[208:211], v[100:103]
	v_mfma_f32_16x16x32_bf16 v[86:89], v[168:171], v[216:219], v[86:89]
	v_mfma_f32_16x16x32_bf16 v[82:85], v[176:179], v[216:219], v[82:85]
	v_mfma_f32_16x16x32_bf16 v[70:73], v[168:171], v[228:231], v[70:73]
	v_mfma_f32_16x16x32_bf16 v[66:69], v[176:179], v[228:231], v[66:69]
	s_setprio 0
	s_barrier
	s_add_i32 s28, s33, s61
	v_lshl_add_u64 v[150:151], s[30:31], 0, v[98:99]
	s_mov_b32 m0, s28
	ds_read_b128 v[180:183], v159 offset:16384
	ds_read_b128 v[184:187], v159 offset:17408
	ds_read_b128 v[188:191], v159 offset:18432
	ds_read_b128 v[208:211], v159 offset:19456
	ds_read_b128 v[212:215], v159 offset:20480
	ds_read_b128 v[216:219], v159 offset:21504
	ds_read_b128 v[220:223], v159 offset:22528
	ds_read_b128 v[228:231], v159 offset:23552
	global_load_lds_dwordx4 v[150:151], off
	s_add_i32 m0, s28, 0x2000
	v_lshl_add_u64 v[192:193], s[30:31], 0, v[136:137]
	s_add_u32 s30, s30, s10
	s_addc_u32 s31, s31, s11
	s_add_i32 s17, s17, s61
	global_load_lds_dwordx4 v[192:193], off
	v_lshl_add_u64 v[224:225], s[30:31], 0, v[98:99]
	s_mov_b32 m0, s17
	v_lshl_add_u64 v[232:233], s[30:31], 0, v[136:137]
	global_load_lds_dwordx4 v[224:225], off
	s_add_i32 m0, s17, 0x2000
	v_lshl_add_u64 v[234:235], s[36:37], 0, v[132:133]
	global_load_lds_dwordx4 v[232:233], off
	s_mov_b32 m0, s62
	v_lshl_add_u64 v[236:237], s[36:37], 0, v[134:135]
	global_load_lds_dwordx4 v[234:235], off
	s_mov_b32 m0, s63
	s_nop 0
	global_load_lds_dwordx4 v[236:237], off
	s_waitcnt vmcnt(8)
	s_waitcnt lgkmcnt(0)
	s_barrier
; #define PG8_STAGE(bufoff, gbase, voff) do { _Pragma("unroll") for (int _i = 0; _i < 2; ++_i) \
;         __builtin_amdgcn_global_load_lds((const unsigned*)((const char*)(gbase) + (voff)[_i]), (PG8_LAS unsigned*)(lds + (bufoff) + ldsw + _i * 8192), 16, 0, 0); } while (0)
; #define PG8_LDA(dst, b, h) do { _Pragma("unroll") for (int m = 0; m < 4; ++m) _Pragma("unroll") for (int k = 0; k < 2; ++k) dst[m][k] = *(const PG8_LAS bf16x8*)(lds + PG8_SA(b, h) + aoff + m * 2048 + k * 1024); } while (0)
; #define PG8_LDB(dst, b, h) do { _Pragma("unroll") for (int n = 0; n < 2; ++n) _Pragma("unroll") for (int k = 0; k < 2; ++k) dst[n][k] = *(const PG8_LAS bf16x8*)(lds + PG8_SB(b, h) + boff + n * 2048 + k * 1024); } while (0)
; #define PG8_MMA(ai, bj, At, Bt) do { __builtin_amdgcn_s_setprio(1); _Pragma("unroll") for (int m = 0; m < 4; ++m) _Pragma("unroll") for (int n = 0; n < 2; ++n) _Pragma("unroll") for (int k = 0; k < 2; ++k) \
;         acc[ai][bj][m][n] = __builtin_amdgcn_mfma_f32_16x16x32_bf16(Bt[n][k], At[m][k], acc[ai][bj][m][n], 0, 0, 0); __builtin_amdgcn_s_setprio(0); } while (0)
; #define PG8_WAIT_V(n) asm volatile("s_waitcnt vmcnt(" #n ")" ::: "memory")
; #define PG8_WAIT_L(n) asm volatile("s_waitcnt lgkmcnt(" #n ")" ::: "memory")
; #define PG8_BAR __builtin_amdgcn_s_barrier()
; #define PG8_SCHED __builtin_amdgcn_sched_barrier(0)
; template <class Epi, class Sched, bool ALIGN_EPI = false, bool SP2 = false>
; __device__ __forceinline__ void gemm_phase(PG8_LAS unsigned char* lds, const Gemm g, const Sched& S, const Epi& E) {
;     ...
;             PG8_WAIT_V(8); PG8_WAIT_L(0); PG8_BAR; PG8_MMA(1, 0, At, B0); PG8_MMA(1, 1, At, B1); PG8_BAR; PG8_SCHED;
;             PG8_LDB(B0, 1, 0); PG8_LDB(B1, 1, 1); PG8_SCHED; PG8_LDA(At, 1, 0); PG8_STAGE(PG8_SA(0, 1), a2 + hstep, voffA);
;             PG8_WAIT_V(8); PG8_WAIT_L(0); PG8_BAR; PG8_MMA(0, 0, At, B0); PG8_MMA(0, 1, At, B1); PG8_BAR; PG8_SCHED;
	s_setprio 1
	v_mfma_f32_16x16x32_bf16 v[62:65], v[142:145], v[180:183], v[62:65]
	v_mfma_f32_16x16x32_bf16 v[58:61], v[154:157], v[180:183], v[58:61]
	v_mfma_f32_16x16x32_bf16 v[46:49], v[142:145], v[188:191], v[46:49]
	v_mfma_f32_16x16x32_bf16 v[42:45], v[154:157], v[188:191], v[42:45]
	v_mfma_f32_16x16x32_bf16 v[30:33], v[142:145], v[212:215], v[30:33]
	v_mfma_f32_16x16x32_bf16 v[26:29], v[154:157], v[212:215], v[26:29]
	v_mfma_f32_16x16x32_bf16 v[14:17], v[142:145], v[220:223], v[14:17]
	v_mfma_f32_16x16x32_bf16 v[10:13], v[154:157], v[220:223], v[10:13]
	v_mfma_f32_16x16x32_bf16 v[62:65], v[146:149], v[184:187], v[62:65]
	v_mfma_f32_16x16x32_bf16 v[58:61], v[160:163], v[184:187], v[58:61]
	v_mfma_f32_16x16x32_bf16 v[46:49], v[146:149], v[208:211], v[46:49]
	v_mfma_f32_16x16x32_bf16 v[42:45], v[160:163], v[208:211], v[42:45]
	v_mfma_f32_16x16x32_bf16 v[30:33], v[146:149], v[216:219], v[30:33]
	v_mfma_f32_16x16x32_bf16 v[26:29], v[160:163], v[216:219], v[26:29]
	v_mfma_f32_16x16x32_bf16 v[14:17], v[146:149], v[228:231], v[14:17]
	v_mfma_f32_16x16x32_bf16 v[10:13], v[160:163], v[228:231], v[10:13]
	s_setprio 0
	s_setprio 1
	v_mfma_f32_16x16x32_bf16 v[54:57], v[164:167], v[180:183], v[54:57]
	v_mfma_f32_16x16x32_bf16 v[50:53], v[172:175], v[180:183], v[50:53]
	v_mfma_f32_16x16x32_bf16 v[38:41], v[164:167], v[188:191], v[38:41]
	v_mfma_f32_16x16x32_bf16 v[34:37], v[172:175], v[188:191], v[34:37]
	v_mfma_f32_16x16x32_bf16 v[22:25], v[164:167], v[212:215], v[22:25]
	v_mfma_f32_16x16x32_bf16 v[18:21], v[172:175], v[212:215], v[18:21]
	v_mfma_f32_16x16x32_bf16 v[6:9], v[164:167], v[220:223], v[6:9]
	v_mfma_f32_16x16x32_bf16 v[2:5], v[172:175], v[220:223], v[2:5]
	v_mfma_f32_16x16x32_bf16 v[54:57], v[168:171], v[184:187], v[54:57]
	v_mfma_f32_16x16x32_bf16 v[50:53], v[176:179], v[184:187], v[50:53]
	v_mfma_f32_16x16x32_bf16 v[38:41], v[168:171], v[208:211], v[38:41]
	v_mfma_f32_16x16x32_bf16 v[34:37], v[176:179], v[208:211], v[34:37]
	v_mfma_f32_16x16x32_bf16 v[22:25], v[168:171], v[216:219], v[22:25]
	v_mfma_f32_16x16x32_bf16 v[18:21], v[176:179], v[216:219], v[18:21]
	v_mfma_f32_16x16x32_bf16 v[6:9], v[168:171], v[228:231], v[6:9]
	v_mfma_f32_16x16x32_bf16 v[2:5], v[176:179], v[228:231], v[2:5]
	s_setprio 0
	s_barrier
	s_add_i32 s17, 0, 0x18000
	v_add_u32_e32 v152, s17, v153
	s_add_i32 s28, 0, 0x1c000
	ds_read_b128 v[142:145], v152
	ds_read_b128 v[146:149], v152 offset:1024
	ds_read_b128 v[154:157], v152 offset:2048
	ds_read_b128 v[160:163], v152 offset:3072
	v_add_u32_e32 v152, s28, v153
	ds_read_b128 v[164:167], v152
	ds_read_b128 v[168:171], v152 offset:1024
	ds_read_b128 v[172:175], v152 offset:2048
	ds_read_b128 v[176:179], v152 offset:3072
	s_add_u32 s30, s36, s10
	s_addc_u32 s31, s37, s11
	s_mov_b32 m0, s64
	v_lshl_add_u64 v[238:239], s[30:31], 0, v[132:133]
	ds_read_b128 v[180:183], v159 offset:32768
	ds_read_b128 v[184:187], v159 offset:33792
	ds_read_b128 v[188:191], v159 offset:34816
	ds_read_b128 v[208:211], v159 offset:35840
	ds_read_b128 v[212:215], v159 offset:36864
	ds_read_b128 v[216:219], v159 offset:37888
	ds_read_b128 v[220:223], v159 offset:38912
	ds_read_b128 v[228:231], v159 offset:39936
	global_load_lds_dwordx4 v[238:239], off
	v_lshl_add_u64 v[238:239], s[30:31], 0, v[134:135]
	s_mov_b32 m0, s65
	s_nop 0
	global_load_lds_dwordx4 v[238:239], off
	s_waitcnt vmcnt(8)
	s_waitcnt lgkmcnt(0)
	s_barrier
	s_setprio 1
	v_mfma_f32_16x16x32_bf16 v[124:127], v[142:145], v[180:183], v[124:127]
	v_mfma_f32_16x16x32_bf16 v[128:131], v[154:157], v[180:183], v[128:131]
	v_mfma_f32_16x16x32_bf16 v[112:115], v[142:145], v[188:191], v[112:115]
	v_mfma_f32_16x16x32_bf16 v[108:111], v[154:157], v[188:191], v[108:111]
	v_mfma_f32_16x16x32_bf16 v[94:97], v[142:145], v[212:215], v[94:97]
	v_mfma_f32_16x16x32_bf16 v[90:93], v[154:157], v[212:215], v[90:93]
	v_mfma_f32_16x16x32_bf16 v[78:81], v[142:145], v[220:223], v[78:81]
	v_mfma_f32_16x16x32_bf16 v[74:77], v[154:157], v[220:223], v[74:77]
	v_mfma_f32_16x16x32_bf16 v[124:127], v[146:149], v[184:187], v[124:127]
	v_mfma_f32_16x16x32_bf16 v[128:131], v[160:163], v[184:187], v[128:131]
	v_mfma_f32_16x16x32_bf16 v[112:115], v[146:149], v[208:211], v[112:115]
	v_mfma_f32_16x16x32_bf16 v[108:111], v[160:163], v[208:211], v[108:111]
	v_mfma_f32_16x16x32_bf16 v[94:97], v[146:149], v[216:219], v[94:97]
	v_mfma_f32_16x16x32_bf16 v[90:93], v[160:163], v[216:219], v[90:93]
	v_mfma_f32_16x16x32_bf16 v[78:81], v[146:149], v[228:231], v[78:81]
	v_mfma_f32_16x16x32_bf16 v[74:77], v[160:163], v[228:231], v[74:77]
	s_setprio 0
	s_setprio 1
	v_mfma_f32_16x16x32_bf16 v[120:123], v[164:167], v[180:183], v[120:123]
	v_mfma_f32_16x16x32_bf16 v[116:119], v[172:175], v[180:183], v[116:119]
	v_mfma_f32_16x16x32_bf16 v[104:107], v[164:167], v[188:191], v[104:107]
	v_mfma_f32_16x16x32_bf16 v[100:103], v[172:175], v[188:191], v[100:103]
	v_mfma_f32_16x16x32_bf16 v[86:89], v[164:167], v[212:215], v[86:89]
	v_mfma_f32_16x16x32_bf16 v[82:85], v[172:175], v[212:215], v[82:85]
	v_mfma_f32_16x16x32_bf16 v[70:73], v[164:167], v[220:223], v[70:73]
	v_mfma_f32_16x16x32_bf16 v[66:69], v[172:175], v[220:223], v[66:69]
	v_mfma_f32_16x16x32_bf16 v[120:123], v[168:171], v[184:187], v[120:123]
	v_mfma_f32_16x16x32_bf16 v[116:119], v[176:179], v[184:187], v[116:119]
	v_mfma_f32_16x16x32_bf16 v[104:107], v[168:171], v[208:211], v[104:107]
	v_mfma_f32_16x16x32_bf16 v[100:103], v[176:179], v[208:211], v[100:103]
	v_mfma_f32_16x16x32_bf16 v[86:89], v[168:171], v[216:219], v[86:89]
	v_mfma_f32_16x16x32_bf16 v[82:85], v[176:179], v[216:219], v[82:85]
	v_mfma_f32_16x16x32_bf16 v[70:73], v[168:171], v[228:231], v[70:73]
	v_mfma_f32_16x16x32_bf16 v[66:69], v[176:179], v[228:231], v[66:69]
	s_setprio 0
	s_barrier
; #define PG8_STAGE(bufoff, gbase, voff) do { _Pragma("unroll") for (int _i = 0; _i < 2; ++_i) \
;         __builtin_amdgcn_global_load_lds((const unsigned*)((const char*)(gbase) + (voff)[_i]), (PG8_LAS unsigned*)(lds + (bufoff) + ldsw + _i * 8192), 16, 0, 0); } while (0)
; #define PG8_LDA(dst, b, h) do { _Pragma("unroll") for (int m = 0; m < 4; ++m) _Pragma("unroll") for (int k = 0; k < 2; ++k) dst[m][k] = *(const PG8_LAS bf16x8*)(lds + PG8_SA(b, h) + aoff + m * 2048 + k * 1024); } while (0)
; #define PG8_MMA(ai, bj, At, Bt) do { __builtin_amdgcn_s_setprio(1); _Pragma("unroll") for (int m = 0; m < 4; ++m) _Pragma("unroll") for (int n = 0; n < 2; ++n) _Pragma("unroll") for (int k = 0; k < 2; ++k) \
;         acc[ai][bj][m][n] = __builtin_amdgcn_mfma_f32_16x16x32_bf16(Bt[n][k], At[m][k], acc[ai][bj][m][n], 0, 0, 0); __builtin_amdgcn_s_setprio(0); } while (0)
; #define PG8_WAIT_V(n) asm volatile("s_waitcnt vmcnt(" #n ")" ::: "memory")
; #define PG8_WAIT_L(n) asm volatile("s_waitcnt lgkmcnt(" #n ")" ::: "memory")
; #define PG8_BAR __builtin_amdgcn_s_barrier()
; #define PG8_SCHED __builtin_amdgcn_sched_barrier(0)
; template <class Epi, class Sched, bool ALIGN_EPI = false, bool SP2 = false>
; __device__ __forceinline__ void gemm_phase(PG8_LAS unsigned char* lds, const Gemm g, const Sched& S, const Epi& E) {
;     ...
;             PG8_LDA(At, 1, 1); PG8_STAGE(PG8_SB(1, 0), b3, voffB); PG8_STAGE(PG8_SB(1, 1), b3 + hstep, voffB); PG8_STAGE(PG8_SA(1, 0), a3, voffA);
;             PG8_WAIT_V(8); PG8_WAIT_L(0); PG8_BAR; PG8_MMA(1, 0, At, B0); PG8_MMA(1, 1, At, B1); PG8_BAR; PG8_SCHED;
	s_add_i32 s17, s17, s61
	v_lshl_add_u64 v[150:151], v[150:151], 0, s[24:25]
	s_mov_b32 m0, s17
	ds_read_b128 v[180:183], v159 offset:49152
	ds_read_b128 v[184:187], v159 offset:50176
	ds_read_b128 v[188:191], v159 offset:51200
	ds_read_b128 v[208:211], v159 offset:52224
	ds_read_b128 v[212:215], v159 offset:53248
	ds_read_b128 v[216:219], v159 offset:54272
	ds_read_b128 v[220:223], v159 offset:55296
	ds_read_b128 v[228:231], v159 offset:56320
	global_load_lds_dwordx4 v[150:151], off
	v_lshl_add_u64 v[150:151], v[192:193], 0, s[24:25]
	s_add_i32 m0, s17, 0x2000
	s_add_i32 s17, s28, s61
	global_load_lds_dwordx4 v[150:151], off
	v_lshl_add_u64 v[150:151], v[224:225], 0, s[24:25]
	s_mov_b32 m0, s17
	s_nop 0
	global_load_lds_dwordx4 v[150:151], off
	v_lshl_add_u64 v[150:151], v[232:233], 0, s[24:25]
	s_add_i32 m0, s17, 0x2000
	s_nop 0
	global_load_lds_dwordx4 v[150:151], off
	v_lshl_add_u64 v[150:151], v[234:235], 0, s[24:25]
	s_mov_b32 m0, s66
	s_nop 0
	global_load_lds_dwordx4 v[150:151], off
	v_lshl_add_u64 v[150:151], v[236:237], 0, s[24:25]
	s_mov_b32 m0, s67
	s_nop 0
	global_load_lds_dwordx4 v[150:151], off
	s_waitcnt vmcnt(8)
	s_waitcnt lgkmcnt(0)
	s_barrier
	s_setprio 1
	v_mfma_f32_16x16x32_bf16 v[62:65], v[142:145], v[180:183], v[62:65]
	v_mfma_f32_16x16x32_bf16 v[58:61], v[154:157], v[180:183], v[58:61]
	v_mfma_f32_16x16x32_bf16 v[46:49], v[142:145], v[188:191], v[46:49]
	v_mfma_f32_16x16x32_bf16 v[42:45], v[154:157], v[188:191], v[42:45]
	v_mfma_f32_16x16x32_bf16 v[30:33], v[142:145], v[212:215], v[30:33]
	v_mfma_f32_16x16x32_bf16 v[26:29], v[154:157], v[212:215], v[26:29]
	v_mfma_f32_16x16x32_bf16 v[14:17], v[142:145], v[220:223], v[14:17]
	v_mfma_f32_16x16x32_bf16 v[10:13], v[154:157], v[220:223], v[10:13]
	v_mfma_f32_16x16x32_bf16 v[62:65], v[146:149], v[184:187], v[62:65]
	v_mfma_f32_16x16x32_bf16 v[58:61], v[160:163], v[184:187], v[58:61]
	v_mfma_f32_16x16x32_bf16 v[46:49], v[146:149], v[208:211], v[46:49]
	v_mfma_f32_16x16x32_bf16 v[42:45], v[160:163], v[208:211], v[42:45]
	v_mfma_f32_16x16x32_bf16 v[30:33], v[146:149], v[216:219], v[30:33]
	v_mfma_f32_16x16x32_bf16 v[26:29], v[160:163], v[216:219], v[26:29]
	v_mfma_f32_16x16x32_bf16 v[14:17], v[146:149], v[228:231], v[14:17]
	v_mfma_f32_16x16x32_bf16 v[10:13], v[160:163], v[228:231], v[10:13]
	s_setprio 0
	s_setprio 1
	v_mfma_f32_16x16x32_bf16 v[54:57], v[164:167], v[180:183], v[54:57]
	v_mfma_f32_16x16x32_bf16 v[50:53], v[172:175], v[180:183], v[50:53]
	v_mfma_f32_16x16x32_bf16 v[38:41], v[164:167], v[188:191], v[38:41]
	v_mfma_f32_16x16x32_bf16 v[34:37], v[172:175], v[188:191], v[34:37]
	v_mfma_f32_16x16x32_bf16 v[22:25], v[164:167], v[212:215], v[22:25]
	v_mfma_f32_16x16x32_bf16 v[18:21], v[172:175], v[212:215], v[18:21]
	v_mfma_f32_16x16x32_bf16 v[6:9], v[164:167], v[220:223], v[6:9]
	v_mfma_f32_16x16x32_bf16 v[2:5], v[172:175], v[220:223], v[2:5]
	v_mfma_f32_16x16x32_bf16 v[54:57], v[168:171], v[184:187], v[54:57]
	v_mfma_f32_16x16x32_bf16 v[50:53], v[176:179], v[184:187], v[50:53]
	v_mfma_f32_16x16x32_bf16 v[38:41], v[168:171], v[208:211], v[38:41]
	v_mfma_f32_16x16x32_bf16 v[34:37], v[176:179], v[208:211], v[34:37]
	v_mfma_f32_16x16x32_bf16 v[22:25], v[168:171], v[216:219], v[22:25]
	v_mfma_f32_16x16x32_bf16 v[18:21], v[176:179], v[216:219], v[18:21]
	v_mfma_f32_16x16x32_bf16 v[6:9], v[168:171], v[228:231], v[6:9]
	v_mfma_f32_16x16x32_bf16 v[2:5], v[176:179], v[228:231], v[2:5]
	s_setprio 0
	s_barrier
	s_add_u32 s34, s34, 0x100
	s_addc_u32 s35, s35, 0
	s_add_u32 s4, s4, 0x100
	s_addc_u32 s16, s16, 0
	s_cmp_ge_i32 s22, s18
	s_mov_b32 s17, s22
	s_cbranch_scc0 .LBB0_1853
